# CSE of the repeated rstd load+rsqrt chains in the GEMM epilogues (kept in spare VGPRs), epilogue loads software-pipelined with counted vmcnt
# speedup vs baseline: 1.0230x; 1.0149x over previous
; DI u32x2 pack4(float a, float b, float c, float d) { u32x2 r; r.x = pack2(a, b); r.y = pack2(c, d); return r; }
; #define EPI_END if (i == 3 && (j & 3) == 3) __builtin_amdgcn_sched_barrier(0); }
; DI float rstd_of(const float* ssq, int m, float invn) { return rsqrtf(ssq[m] * invn + 1e-6f); }
; template <int MODE>
; DI void gemm_phase(const Params& p, const GP& g, unsigned char* smem) {
;     ...
;       } else {
;         u16* z = (u16*)g.d1;
;         EPI_STD_BEGIN
;           const float rs = rstd_of(g.ssq_in, m, 1.f / 1024);
;           *(u32x2*)(z + (long)m * 1024 + (n4 - 2048)) = pack4(v[0] * rs, v[1] * rs, v[2] * rs, v[3] * rs);
;         EPI_END
.LBB0_93:
	v_or_b32_e32 v128, s8, v150
	s_waitcnt lgkmcnt(0)
	v_lshl_add_u64 v[132:133], v[128:129], 2, s[14:15]
	global_load_dword v131, v[132:133], off
	global_load_dword v185, v[132:133], off offset:64
	global_load_dword v186, v[132:133], off offset:128
	global_load_dword v187, v[132:133], off offset:192
	global_load_dword v188, v[132:133], off offset:256
	global_load_dword v189, v[132:133], off offset:320
	global_load_dword v190, v[132:133], off offset:384
	global_load_dword v191, v[132:133], off offset:448
	v_add_u32_e32 v134, s6, v149
	v_lshlrev_b64 v[136:137], 11, v[128:129]
	v_ashrrev_i32_e32 v135, 31, v134
	v_lshl_add_u64 v[136:137], s[50:51], 0, v[136:137]
	v_lshlrev_b64 v[134:135], 1, v[134:135]
	v_lshl_add_u64 v[136:137], v[136:137], 0, v[134:135]
	s_waitcnt vmcnt(7)
	v_fmamk_f32 v131, v131, 0x3a800000, v155
	global_load_dword v192, v[132:133], off offset:448
	v_mul_f32_e32 v138, 0x4b800000, v131
	v_cmp_gt_f32_e32 vcc, s64, v131
	s_nop 1
	v_cndmask_b32_e32 v131, v131, v138, vcc
	v_rsq_f32_e32 v131, v131
	s_nop 0
	v_mul_f32_e32 v138, 0x45800000, v131
	v_cndmask_b32_e32 v138, v131, v138, vcc
	v_mov_b32_e32 v158, v138
	v_pk_mul_f32 v[140:141], v[124:125], v[138:139] op_sel_hi:[1,0]
	v_pk_mul_f32 v[138:139], v[126:127], v[158:159] op_sel_hi:[1,0]
	v_cvt_pk_bf16_f32 v140, v140, v141
	v_cvt_pk_bf16_f32 v141, v138, v139
	global_store_dwordx2 v[136:137], v[140:141], off offset:-4096
	s_nop 1
	s_nop 0
	v_pk_mul_f32 v[140:141], v[120:121], v[158:159] op_sel_hi:[1,0]
	v_pk_mul_f32 v[138:139], v[122:123], v[158:159] op_sel_hi:[1,0]
	v_cvt_pk_bf16_f32 v140, v140, v141
	v_cvt_pk_bf16_f32 v141, v138, v139
	global_store_dwordx2 v[136:137], v[140:141], off offset:-4064
	s_nop 1
	s_nop 0
	v_pk_mul_f32 v[140:141], v[116:117], v[158:159] op_sel_hi:[1,0]
	v_pk_mul_f32 v[138:139], v[118:119], v[158:159] op_sel_hi:[1,0]
	v_cvt_pk_bf16_f32 v140, v140, v141
	v_cvt_pk_bf16_f32 v141, v138, v139
	global_store_dwordx2 v[136:137], v[140:141], off offset:-4032
	s_nop 1
	s_nop 0
	v_pk_mul_f32 v[140:141], v[108:109], v[158:159] op_sel_hi:[1,0]
	v_pk_mul_f32 v[138:139], v[110:111], v[158:159] op_sel_hi:[1,0]
	v_cvt_pk_bf16_f32 v140, v140, v141
	v_cvt_pk_bf16_f32 v141, v138, v139
	global_store_dwordx2 v[136:137], v[140:141], off offset:-4000
	s_nop 0
	v_mov_b32_e32 v137, v129
	v_or_b32_e32 v136, 16, v128
	v_lshlrev_b64 v[136:137], 11, v[136:137]
	v_lshl_add_u64 v[136:137], s[50:51], 0, v[136:137]
	v_lshl_add_u64 v[136:137], v[136:137], 0, v[134:135]
	s_waitcnt vmcnt(11)
	v_fmamk_f32 v131, v185, 0x3a800000, v155
	v_mul_f32_e32 v138, 0x4b800000, v131
	v_cmp_gt_f32_e32 vcc, s64, v131
	s_nop 1
	v_cndmask_b32_e32 v131, v131, v138, vcc
	v_rsq_f32_e32 v131, v131
	s_nop 0
	v_mul_f32_e32 v138, 0x45800000, v131
	v_cndmask_b32_e32 v138, v131, v138, vcc
	v_mov_b32_e32 v160, v138
	v_pk_mul_f32 v[140:141], v[112:113], v[138:139] op_sel_hi:[1,0]
	v_pk_mul_f32 v[138:139], v[114:115], v[160:161] op_sel_hi:[1,0]
	v_cvt_pk_bf16_f32 v140, v140, v141
	v_cvt_pk_bf16_f32 v141, v138, v139
	global_store_dwordx2 v[136:137], v[140:141], off offset:-4096
	s_nop 1
	s_nop 0
	v_pk_mul_f32 v[140:141], v[104:105], v[160:161] op_sel_hi:[1,0]
	v_pk_mul_f32 v[138:139], v[106:107], v[160:161] op_sel_hi:[1,0]
	v_cvt_pk_bf16_f32 v140, v140, v141
	v_cvt_pk_bf16_f32 v141, v138, v139
	global_store_dwordx2 v[136:137], v[140:141], off offset:-4064
	s_nop 1
	s_nop 0
	v_pk_mul_f32 v[140:141], v[100:101], v[160:161] op_sel_hi:[1,0]
	v_pk_mul_f32 v[138:139], v[102:103], v[160:161] op_sel_hi:[1,0]
	v_cvt_pk_bf16_f32 v140, v140, v141
	v_cvt_pk_bf16_f32 v141, v138, v139
	global_store_dwordx2 v[136:137], v[140:141], off offset:-4032
	s_nop 1
	s_nop 0
	v_pk_mul_f32 v[140:141], v[92:93], v[160:161] op_sel_hi:[1,0]
	v_pk_mul_f32 v[138:139], v[94:95], v[160:161] op_sel_hi:[1,0]
	v_cvt_pk_bf16_f32 v140, v140, v141
	v_cvt_pk_bf16_f32 v141, v138, v139
	global_store_dwordx2 v[136:137], v[140:141], off offset:-4000
	s_nop 0
	v_mov_b32_e32 v137, v129
	v_or_b32_e32 v136, 32, v128
	v_lshlrev_b64 v[136:137], 11, v[136:137]
	v_lshl_add_u64 v[136:137], s[50:51], 0, v[136:137]
	v_lshl_add_u64 v[136:137], v[136:137], 0, v[134:135]
	s_waitcnt vmcnt(14)
	v_fmamk_f32 v131, v186, 0x3a800000, v155
	v_mul_f32_e32 v138, 0x4b800000, v131
	v_cmp_gt_f32_e32 vcc, s64, v131
	s_nop 1
	v_cndmask_b32_e32 v131, v131, v138, vcc
	v_rsq_f32_e32 v131, v131
	s_nop 0
	v_mul_f32_e32 v138, 0x45800000, v131
	v_cndmask_b32_e32 v138, v131, v138, vcc
	v_mov_b32_e32 v162, v138
	v_pk_mul_f32 v[140:141], v[96:97], v[138:139] op_sel_hi:[1,0]
	v_pk_mul_f32 v[138:139], v[98:99], v[162:163] op_sel_hi:[1,0]
	v_cvt_pk_bf16_f32 v140, v140, v141
	v_cvt_pk_bf16_f32 v141, v138, v139
	global_store_dwordx2 v[136:137], v[140:141], off offset:-4096
	s_nop 1
	s_nop 0
	v_pk_mul_f32 v[140:141], v[88:89], v[162:163] op_sel_hi:[1,0]
	v_pk_mul_f32 v[138:139], v[90:91], v[162:163] op_sel_hi:[1,0]
	v_cvt_pk_bf16_f32 v140, v140, v141
	v_cvt_pk_bf16_f32 v141, v138, v139
	global_store_dwordx2 v[136:137], v[140:141], off offset:-4064
	s_nop 1
	s_nop 0
	v_pk_mul_f32 v[140:141], v[84:85], v[162:163] op_sel_hi:[1,0]
	v_pk_mul_f32 v[138:139], v[86:87], v[162:163] op_sel_hi:[1,0]
	v_cvt_pk_bf16_f32 v140, v140, v141
	v_cvt_pk_bf16_f32 v141, v138, v139
	global_store_dwordx2 v[136:137], v[140:141], off offset:-4032
	s_nop 1
	s_nop 0
	v_pk_mul_f32 v[140:141], v[76:77], v[162:163] op_sel_hi:[1,0]
	v_pk_mul_f32 v[138:139], v[78:79], v[162:163] op_sel_hi:[1,0]
	v_cvt_pk_bf16_f32 v140, v140, v141
	v_cvt_pk_bf16_f32 v141, v138, v139
	global_store_dwordx2 v[136:137], v[140:141], off offset:-4000
	s_nop 0
	v_mov_b32_e32 v137, v129
	v_or_b32_e32 v136, 48, v128
	v_lshlrev_b64 v[136:137], 11, v[136:137]
	v_lshl_add_u64 v[136:137], s[50:51], 0, v[136:137]
	v_lshl_add_u64 v[136:137], v[136:137], 0, v[134:135]
	s_waitcnt vmcnt(17)
; DI u32x2 pack4(float a, float b, float c, float d) { u32x2 r; r.x = pack2(a, b); r.y = pack2(c, d); return r; }
; #define EPI_END if (i == 3 && (j & 3) == 3) __builtin_amdgcn_sched_barrier(0); }
; DI float rstd_of(const float* ssq, int m, float invn) { return rsqrtf(ssq[m] * invn + 1e-6f); }
; template <int MODE>
; DI void gemm_phase(const Params& p, const GP& g, unsigned char* smem) {
;     ...
;       } else {
;         u16* z = (u16*)g.d1;
;         EPI_STD_BEGIN
;           const float rs = rstd_of(g.ssq_in, m, 1.f / 1024);
;           *(u32x2*)(z + (long)m * 1024 + (n4 - 2048)) = pack4(v[0] * rs, v[1] * rs, v[2] * rs, v[3] * rs);
;         EPI_END
	v_fmamk_f32 v131, v187, 0x3a800000, v155
	v_mul_f32_e32 v138, 0x4b800000, v131
	v_cmp_gt_f32_e32 vcc, s64, v131
	s_nop 1
	v_cndmask_b32_e32 v131, v131, v138, vcc
	v_rsq_f32_e32 v131, v131
	s_nop 0
	v_mul_f32_e32 v138, 0x45800000, v131
	v_cndmask_b32_e32 v138, v131, v138, vcc
	v_mov_b32_e32 v164, v138
	v_pk_mul_f32 v[140:141], v[80:81], v[138:139] op_sel_hi:[1,0]
	v_pk_mul_f32 v[138:139], v[82:83], v[164:165] op_sel_hi:[1,0]
	v_cvt_pk_bf16_f32 v140, v140, v141
	v_cvt_pk_bf16_f32 v141, v138, v139
	global_store_dwordx2 v[136:137], v[140:141], off offset:-4096
	s_nop 1
	s_nop 0
	v_pk_mul_f32 v[140:141], v[72:73], v[164:165] op_sel_hi:[1,0]
	v_pk_mul_f32 v[138:139], v[74:75], v[164:165] op_sel_hi:[1,0]
	v_cvt_pk_bf16_f32 v140, v140, v141
	v_cvt_pk_bf16_f32 v141, v138, v139
	global_store_dwordx2 v[136:137], v[140:141], off offset:-4064
	s_nop 1
	s_nop 0
	v_pk_mul_f32 v[140:141], v[68:69], v[164:165] op_sel_hi:[1,0]
	v_pk_mul_f32 v[138:139], v[70:71], v[164:165] op_sel_hi:[1,0]
	v_cvt_pk_bf16_f32 v140, v140, v141
	v_cvt_pk_bf16_f32 v141, v138, v139
	global_store_dwordx2 v[136:137], v[140:141], off offset:-4032
	s_nop 1
	s_nop 0
	v_pk_mul_f32 v[140:141], v[60:61], v[164:165] op_sel_hi:[1,0]
	v_pk_mul_f32 v[138:139], v[62:63], v[164:165] op_sel_hi:[1,0]
	v_cvt_pk_bf16_f32 v140, v140, v141
	v_cvt_pk_bf16_f32 v141, v138, v139
	global_store_dwordx2 v[136:137], v[140:141], off offset:-4000
	s_nop 0
	v_or_b32_e32 v136, 64, v128
	v_mov_b32_e32 v137, v129
	v_lshlrev_b64 v[136:137], 11, v[136:137]
	v_lshl_add_u64 v[136:137], s[50:51], 0, v[136:137]
	v_lshl_add_u64 v[136:137], v[136:137], 0, v[134:135]
	s_waitcnt vmcnt(20)
	v_fmamk_f32 v131, v188, 0x3a800000, v155
	v_mul_f32_e32 v138, 0x4b800000, v131
	v_cmp_gt_f32_e32 vcc, s64, v131
	s_nop 1
	v_cndmask_b32_e32 v131, v131, v138, vcc
	v_rsq_f32_e32 v131, v131
	s_nop 0
	v_mul_f32_e32 v138, 0x45800000, v131
	v_cndmask_b32_e32 v138, v131, v138, vcc
	v_mov_b32_e32 v166, v138
	v_pk_mul_f32 v[140:141], v[64:65], v[138:139] op_sel_hi:[1,0]
	v_pk_mul_f32 v[138:139], v[66:67], v[166:167] op_sel_hi:[1,0]
	v_cvt_pk_bf16_f32 v140, v140, v141
	v_cvt_pk_bf16_f32 v141, v138, v139
	global_store_dwordx2 v[136:137], v[140:141], off offset:-4096
	s_nop 1
	s_nop 0
	v_pk_mul_f32 v[140:141], v[56:57], v[166:167] op_sel_hi:[1,0]
	v_pk_mul_f32 v[138:139], v[58:59], v[166:167] op_sel_hi:[1,0]
	v_cvt_pk_bf16_f32 v140, v140, v141
	v_cvt_pk_bf16_f32 v141, v138, v139
	global_store_dwordx2 v[136:137], v[140:141], off offset:-4064
	s_nop 1
	s_nop 0
	v_pk_mul_f32 v[140:141], v[52:53], v[166:167] op_sel_hi:[1,0]
	v_pk_mul_f32 v[138:139], v[54:55], v[166:167] op_sel_hi:[1,0]
	v_cvt_pk_bf16_f32 v140, v140, v141
	v_cvt_pk_bf16_f32 v141, v138, v139
	global_store_dwordx2 v[136:137], v[140:141], off offset:-4032
	s_nop 1
	s_nop 0
	v_pk_mul_f32 v[140:141], v[44:45], v[166:167] op_sel_hi:[1,0]
	v_pk_mul_f32 v[138:139], v[46:47], v[166:167] op_sel_hi:[1,0]
	v_cvt_pk_bf16_f32 v140, v140, v141
	v_cvt_pk_bf16_f32 v141, v138, v139
	global_store_dwordx2 v[136:137], v[140:141], off offset:-4000
	s_nop 0
	v_or_b32_e32 v136, 0x50, v128
	v_mov_b32_e32 v137, v129
	v_lshlrev_b64 v[136:137], 11, v[136:137]
	v_lshl_add_u64 v[136:137], s[50:51], 0, v[136:137]
	v_lshl_add_u64 v[136:137], v[136:137], 0, v[134:135]
	s_waitcnt vmcnt(23)
	v_fmamk_f32 v131, v189, 0x3a800000, v155
	v_mul_f32_e32 v138, 0x4b800000, v131
	v_cmp_gt_f32_e32 vcc, s64, v131
	s_nop 1
	v_cndmask_b32_e32 v131, v131, v138, vcc
	v_rsq_f32_e32 v131, v131
	s_nop 0
	v_mul_f32_e32 v138, 0x45800000, v131
	v_cndmask_b32_e32 v138, v131, v138, vcc
	v_mov_b32_e32 v168, v138
	v_pk_mul_f32 v[140:141], v[48:49], v[138:139] op_sel_hi:[1,0]
	v_pk_mul_f32 v[138:139], v[50:51], v[168:169] op_sel_hi:[1,0]
	v_cvt_pk_bf16_f32 v140, v140, v141
	v_cvt_pk_bf16_f32 v141, v138, v139
	global_store_dwordx2 v[136:137], v[140:141], off offset:-4096
	s_nop 1
	s_nop 0
	v_pk_mul_f32 v[140:141], v[40:41], v[168:169] op_sel_hi:[1,0]
	v_pk_mul_f32 v[138:139], v[42:43], v[168:169] op_sel_hi:[1,0]
	v_cvt_pk_bf16_f32 v140, v140, v141
	v_cvt_pk_bf16_f32 v141, v138, v139
	global_store_dwordx2 v[136:137], v[140:141], off offset:-4064
	s_nop 1
	s_nop 0
	v_pk_mul_f32 v[140:141], v[36:37], v[168:169] op_sel_hi:[1,0]
	v_pk_mul_f32 v[138:139], v[38:39], v[168:169] op_sel_hi:[1,0]
	v_cvt_pk_bf16_f32 v140, v140, v141
	v_cvt_pk_bf16_f32 v141, v138, v139
	global_store_dwordx2 v[136:137], v[140:141], off offset:-4032
	s_nop 1
	s_nop 0
	v_pk_mul_f32 v[140:141], v[28:29], v[168:169] op_sel_hi:[1,0]
	v_pk_mul_f32 v[138:139], v[30:31], v[168:169] op_sel_hi:[1,0]
	v_cvt_pk_bf16_f32 v140, v140, v141
	v_cvt_pk_bf16_f32 v141, v138, v139
	global_store_dwordx2 v[136:137], v[140:141], off offset:-4000
	s_nop 0
	v_or_b32_e32 v136, 0x60, v128
	v_mov_b32_e32 v137, v129
	v_lshlrev_b64 v[136:137], 11, v[136:137]
	v_lshl_add_u64 v[136:137], s[50:51], 0, v[136:137]
	v_lshl_add_u64 v[136:137], v[136:137], 0, v[134:135]
	v_or_b32_e32 v128, 0x70, v128
	s_waitcnt vmcnt(26)
; DI u32x2 pack4(float a, float b, float c, float d) { u32x2 r; r.x = pack2(a, b); r.y = pack2(c, d); return r; }
; #define EPI_END if (i == 3 && (j & 3) == 3) __builtin_amdgcn_sched_barrier(0); }
; DI float rstd_of(const float* ssq, int m, float invn) { return rsqrtf(ssq[m] * invn + 1e-6f); }
; template <int MODE>
; DI void gemm_phase(const Params& p, const GP& g, unsigned char* smem) {
;     ...
;         u16* Pt = (u16*)g.d0;
;         const int bt = mt >> 4, a = (mt & 15) * 4 + wx;
;         EPI_TR_BEGIN
;           const int grp = n >> 8, half = (n >> 7) & 1, c = grp * 128 + (n & 127);
;           const int b0 = i * 16 + lg * 4;
;           const int tok = bt * 4096 + a + 64 * b0;
;           (void)m4;
;           *(u32x2*)(Pt + (((long)bt * 1024 + c) * 2 + half) * 4096 + a * 64 + b0) =
;               pack4(v[0] * rstd_of(g.ssq_in, tok, 1.f / 1024), v[1] * rstd_of(g.ssq_in, tok + 64, 1.f / 1024),
;                     v[2] * rstd_of(g.ssq_in, tok + 128, 1.f / 1024), v[3] * rstd_of(g.ssq_in, tok + 192, 1.f / 1024));
;     ...
;         EPI_STD_BEGIN
;           const float rs = rstd_of(g.ssq_in, m, 1.f / 1024);
;           *(u32x2*)(z + (long)m * 1024 + (n4 - 2048)) = pack4(v[0] * rs, v[1] * rs, v[2] * rs, v[3] * rs);
;         EPI_END
	v_fmamk_f32 v131, v190, 0x3a800000, v155
	v_mul_f32_e32 v138, 0x4b800000, v131
	v_cmp_gt_f32_e32 vcc, s64, v131
	s_nop 1
	v_cndmask_b32_e32 v131, v131, v138, vcc
	v_rsq_f32_e32 v131, v131
	s_nop 0
	v_mul_f32_e32 v138, 0x45800000, v131
	v_cndmask_b32_e32 v138, v131, v138, vcc
	v_mov_b32_e32 v170, v138
	v_pk_mul_f32 v[140:141], v[32:33], v[138:139] op_sel_hi:[1,0]
	v_pk_mul_f32 v[138:139], v[34:35], v[170:171] op_sel_hi:[1,0]
	v_cvt_pk_bf16_f32 v140, v140, v141
	v_cvt_pk_bf16_f32 v141, v138, v139
	global_store_dwordx2 v[136:137], v[140:141], off offset:-4096
	s_nop 1
	s_nop 0
	v_pk_mul_f32 v[140:141], v[24:25], v[170:171] op_sel_hi:[1,0]
	v_pk_mul_f32 v[138:139], v[26:27], v[170:171] op_sel_hi:[1,0]
	v_cvt_pk_bf16_f32 v140, v140, v141
	v_cvt_pk_bf16_f32 v141, v138, v139
	global_store_dwordx2 v[136:137], v[140:141], off offset:-4064
	s_nop 1
	s_nop 0
	v_pk_mul_f32 v[140:141], v[20:21], v[170:171] op_sel_hi:[1,0]
	v_pk_mul_f32 v[138:139], v[22:23], v[170:171] op_sel_hi:[1,0]
	v_cvt_pk_bf16_f32 v140, v140, v141
	v_cvt_pk_bf16_f32 v141, v138, v139
	global_store_dwordx2 v[136:137], v[140:141], off offset:-4032
	s_nop 1
	s_nop 0
	v_pk_mul_f32 v[140:141], v[12:13], v[170:171] op_sel_hi:[1,0]
	v_pk_mul_f32 v[138:139], v[14:15], v[170:171] op_sel_hi:[1,0]
	v_cvt_pk_bf16_f32 v140, v140, v141
	v_cvt_pk_bf16_f32 v141, v138, v139
	global_store_dwordx2 v[136:137], v[140:141], off offset:-4000
	s_nop 0
	s_waitcnt vmcnt(29)
	v_fmamk_f32 v131, v191, 0x3a800000, v155
	v_mul_f32_e32 v136, 0x4b800000, v131
	v_cmp_gt_f32_e32 vcc, s64, v131
	s_nop 1
	v_cndmask_b32_e32 v131, v131, v136, vcc
	v_rsq_f32_e32 v131, v131
	v_lshlrev_b64 v[136:137], 11, v[128:129]
	v_lshl_add_u64 v[136:137], s[50:51], 0, v[136:137]
	v_lshl_add_u64 v[134:135], v[136:137], 0, v[134:135]
	v_mul_f32_e32 v128, 0x45800000, v131
	v_cndmask_b32_e32 v128, v131, v128, vcc
	v_mov_b32_e32 v172, v128
	v_pk_mul_f32 v[136:137], v[16:17], v[128:129] op_sel_hi:[1,0]
	v_pk_mul_f32 v[138:139], v[18:19], v[172:173] op_sel_hi:[1,0]
	v_cvt_pk_bf16_f32 v136, v136, v137
	v_cvt_pk_bf16_f32 v137, v138, v139
	global_store_dwordx2 v[134:135], v[136:137], off offset:-4096
	s_nop 1
	s_nop 0
	v_pk_mul_f32 v[136:137], v[4:5], v[172:173] op_sel_hi:[1,0]
	v_pk_mul_f32 v[138:139], v[6:7], v[172:173] op_sel_hi:[1,0]
	v_cvt_pk_bf16_f32 v136, v136, v137
	v_cvt_pk_bf16_f32 v137, v138, v139
	global_store_dwordx2 v[134:135], v[136:137], off offset:-4064
	s_nop 1
	s_nop 0
	v_pk_mul_f32 v[136:137], v[0:1], v[172:173] op_sel_hi:[1,0]
	v_pk_mul_f32 v[138:139], v[2:3], v[172:173] op_sel_hi:[1,0]
	v_cvt_pk_bf16_f32 v136, v136, v137
	v_cvt_pk_bf16_f32 v137, v138, v139
	global_store_dwordx2 v[134:135], v[136:137], off offset:-4032
	s_nop 0
	s_waitcnt vmcnt(31)
	v_fmamk_f32 v128, v192, 0x3a800000, v155
	v_mul_f32_e32 v131, 0x4b800000, v128
	v_cmp_gt_f32_e32 vcc, s64, v128
	s_nop 1
	v_cndmask_b32_e32 v128, v128, v131, vcc
	v_rsq_f32_e32 v128, v128
	s_nop 0
	v_mul_f32_e32 v131, 0x45800000, v128
	v_cndmask_b32_e32 v128, v128, v131, vcc
	v_pk_mul_f32 v[132:133], v[8:9], v[172:173] op_sel_hi:[1,0]
	v_pk_mul_f32 v[136:137], v[10:11], v[172:173] op_sel_hi:[1,0]
	v_cvt_pk_bf16_f32 v132, v132, v133
	v_cvt_pk_bf16_f32 v133, v136, v137
	global_store_dwordx2 v[134:135], v[132:133], off offset:-4000
	s_cbranch_execnz .LBB0_79
.LBB0_94:
	s_lshl_b32 s6, s66, 2
	s_lshr_b32 s18, s63, 1
	s_and_b32 s6, s6, 60
	s_add_i32 s6, s6, s55
	s_lshl_b32 s7, s18, 12
	s_add_i32 s33, s6, s7
	v_add_u32_e32 v132, s33, v151
	v_ashrrev_i32_e32 v133, 31, v132
	s_waitcnt lgkmcnt(0)
	v_lshl_add_u64 v[136:137], v[132:133], 2, s[14:15]
	global_load_dword v140, v[136:137], off
	global_load_dword v141, v[136:137], off offset:256
	global_load_dword v142, v[136:137], off offset:512
	global_load_dword v143, v[136:137], off offset:768
	s_lshl_b32 s6, s6, 6
	s_ashr_i32 s7, s6, 31
	v_lshl_or_b32 v138, s62, 7, v148
	v_mov_b64_e32 v[132:133], s[56:57]
	s_lshl_b64 s[6:7], s[6:7], 1
	v_ashrrev_i32_e32 v139, 31, v138
	s_add_u32 s60, s20, s6
	v_lshlrev_b64 v[144:145], 14, v[138:139]
	s_addc_u32 s61, s21, s7
	s_lshl_b64 s[62:63], s[18:19], 24
	v_lshl_add_u64 v[144:145], s[60:61], 0, v[144:145]
	v_lshl_add_u64 v[144:145], v[144:145], 0, s[62:63]
	v_mov_b32_e32 v131, v129
	v_add_u32_e32 v134, s33, v152
	v_lshl_add_u64 v[144:145], v[144:145], 0, s[16:17]
	v_ashrrev_i32_e32 v135, 31, v134
	v_lshl_add_u64 v[144:145], v[144:145], 0, v[130:131]
	v_lshl_add_u64 v[134:135], v[134:135], 2, s[14:15]
	s_waitcnt vmcnt(2)
	v_pk_fma_f32 v[140:141], v[140:141], s[52:53], v[132:133] op_sel_hi:[1,0,0]
	s_nop 0
	v_mul_f32_e32 v128, 0x4b800000, v140
	s_waitcnt vmcnt(0)
	v_pk_fma_f32 v[142:143], v[142:143], s[52:53], v[132:133] op_sel_hi:[1,0,0]
	v_mul_f32_e32 v139, 0x4b800000, v141
	v_mul_f32_e32 v146, 0x4b800000, v142
	v_mul_f32_e32 v147, 0x4b800000, v143
	v_cmp_gt_f32_e32 vcc, s64, v140
	v_cmp_gt_f32_e64 s[6:7], s64, v141
	v_cmp_gt_f32_e64 s[8:9], s64, v142
	v_cmp_gt_f32_e64 s[10:11], s64, v143
	v_cndmask_b32_e32 v128, v140, v128, vcc
	v_cndmask_b32_e64 v139, v141, v139, s[6:7]
	v_cndmask_b32_e64 v142, v142, v146, s[8:9]
	v_cndmask_b32_e64 v143, v143, v147, s[10:11]
	v_rsq_f32_e32 v140, v128
	v_rsq_f32_e32 v141, v139
	v_rsq_f32_e32 v142, v142
	v_rsq_f32_e32 v143, v143
	v_pk_mul_f32 v[146:147], v[140:141], s[54:55] op_sel_hi:[1,0]
	s_nop 0
	v_cndmask_b32_e64 v141, v141, v147, s[6:7]
	v_pk_mul_f32 v[156:157], v[142:143], s[54:55] op_sel_hi:[1,0]
	v_cndmask_b32_e32 v140, v140, v146, vcc
	v_cndmask_b32_e64 v143, v143, v157, s[10:11]
	v_cndmask_b32_e64 v142, v142, v156, s[8:9]
	v_mov_b32_e32 v158, v140
	v_mov_b32_e32 v159, v141
	v_pk_mul_f32 v[124:125], v[124:125], v[140:141]
	v_mov_b32_e32 v160, v142
	v_mov_b32_e32 v161, v143
	v_pk_mul_f32 v[126:127], v[126:127], v[142:143]
	v_cvt_pk_bf16_f32 v124, v124, v125
	v_cvt_pk_bf16_f32 v125, v126, v127
	global_store_dwordx2 v[144:145], v[124:125], off
	global_load_dword v124, v[134:135], off
	global_load_dword v125, v[134:135], off offset:256
	global_load_dword v126, v[134:135], off offset:512
	global_load_dword v127, v[134:135], off offset:768
	s_nop 0
	s_nop 0
	s_nop 0
	s_nop 0
	v_add_u32_e32 v140, s33, v153
	s_waitcnt vmcnt(2)
; DI u32x2 pack4(float a, float b, float c, float d) { u32x2 r; r.x = pack2(a, b); r.y = pack2(c, d); return r; }
; #define EPI_END if (i == 3 && (j & 3) == 3) __builtin_amdgcn_sched_barrier(0); }
; DI float rstd_of(const float* ssq, int m, float invn) { return rsqrtf(ssq[m] * invn + 1e-6f); }
; template <int MODE>
; DI void gemm_phase(const Params& p, const GP& g, unsigned char* smem) {
;     ...
;         EPI_TR_BEGIN
;           const int grp = n >> 8, half = (n >> 7) & 1, c = grp * 128 + (n & 127);
;           const int b0 = i * 16 + lg * 4;
;           const int tok = bt * 4096 + a + 64 * b0;
;           (void)m4;
;           *(u32x2*)(Pt + (((long)bt * 1024 + c) * 2 + half) * 4096 + a * 64 + b0) =
;               pack4(v[0] * rstd_of(g.ssq_in, tok, 1.f / 1024), v[1] * rstd_of(g.ssq_in, tok + 64, 1.f / 1024),
;                     v[2] * rstd_of(g.ssq_in, tok + 128, 1.f / 1024), v[3] * rstd_of(g.ssq_in, tok + 192, 1.f / 1024));
;         EPI_END
	v_pk_fma_f32 v[124:125], v[124:125], s[52:53], v[132:133] op_sel_hi:[1,0,0]
	s_nop 0
	v_mul_f32_e32 v128, 0x4b800000, v124
	s_waitcnt vmcnt(0)
	v_pk_fma_f32 v[126:127], v[126:127], s[52:53], v[132:133] op_sel_hi:[1,0,0]
	v_mul_f32_e32 v139, 0x4b800000, v125
	v_mul_f32_e32 v141, 0x4b800000, v126
	v_mul_f32_e32 v142, 0x4b800000, v127
	v_cmp_gt_f32_e32 vcc, s64, v124
	v_cmp_gt_f32_e64 s[6:7], s64, v125
	v_cmp_gt_f32_e64 s[8:9], s64, v126
	v_cmp_gt_f32_e64 s[10:11], s64, v127
	v_cndmask_b32_e32 v124, v124, v128, vcc
	v_cndmask_b32_e64 v125, v125, v139, s[6:7]
	v_cndmask_b32_e64 v128, v126, v141, s[8:9]
	v_cndmask_b32_e64 v139, v127, v142, s[10:11]
	v_rsq_f32_e32 v126, v124
	v_rsq_f32_e32 v127, v125
	v_rsq_f32_e32 v142, v128
	v_rsq_f32_e32 v143, v139
	v_ashrrev_i32_e32 v141, 31, v140
	v_lshl_add_u64 v[124:125], v[140:141], 2, s[14:15]
	v_pk_mul_f32 v[140:141], v[126:127], s[54:55] op_sel_hi:[1,0]
	v_pk_mul_f32 v[146:147], v[142:143], s[54:55] op_sel_hi:[1,0]
	v_cndmask_b32_e64 v127, v127, v141, s[6:7]
	v_cndmask_b32_e32 v126, v126, v140, vcc
	v_cndmask_b32_e64 v141, v143, v147, s[10:11]
	v_cndmask_b32_e64 v140, v142, v146, s[8:9]
	v_mov_b32_e32 v162, v126
	v_mov_b32_e32 v163, v127
	v_pk_mul_f32 v[120:121], v[120:121], v[126:127]
	v_mov_b32_e32 v164, v140
	v_mov_b32_e32 v165, v141
	v_pk_mul_f32 v[122:123], v[122:123], v[140:141]
	v_cvt_pk_bf16_f32 v120, v120, v121
	v_cvt_pk_bf16_f32 v121, v122, v123
	global_store_dwordx2 v[144:145], v[120:121], off offset:32
	global_load_dword v120, v[124:125], off
	global_load_dword v121, v[124:125], off offset:256
	global_load_dword v122, v[124:125], off offset:512
	global_load_dword v123, v[124:125], off offset:768
	s_nop 0
	s_nop 0
	s_nop 0
	s_nop 0
	v_add_u32_e32 v126, s33, v154
	s_waitcnt vmcnt(2)
	v_pk_fma_f32 v[120:121], v[120:121], s[52:53], v[132:133] op_sel_hi:[1,0,0]
	s_nop 0
	v_mul_f32_e32 v127, 0x4b800000, v120
	s_waitcnt vmcnt(0)
	v_pk_fma_f32 v[122:123], v[122:123], s[52:53], v[132:133] op_sel_hi:[1,0,0]
	v_mul_f32_e32 v128, 0x4b800000, v121
	v_mul_f32_e32 v139, 0x4b800000, v122
	v_mul_f32_e32 v140, 0x4b800000, v123
	v_cmp_gt_f32_e32 vcc, s64, v120
	v_cmp_gt_f32_e64 s[6:7], s64, v121
	v_cmp_gt_f32_e64 s[8:9], s64, v122
	v_cmp_gt_f32_e64 s[10:11], s64, v123
	v_cndmask_b32_e32 v120, v120, v127, vcc
	v_cndmask_b32_e64 v121, v121, v128, s[6:7]
	v_cndmask_b32_e64 v127, v122, v139, s[8:9]
	v_cndmask_b32_e64 v128, v123, v140, s[10:11]
	v_rsq_f32_e32 v122, v120
	v_rsq_f32_e32 v123, v121
	v_rsq_f32_e32 v140, v127
	v_rsq_f32_e32 v141, v128
	v_ashrrev_i32_e32 v127, 31, v126
	v_lshl_add_u64 v[120:121], v[126:127], 2, s[14:15]
	v_pk_mul_f32 v[126:127], v[122:123], s[54:55] op_sel_hi:[1,0]
	v_pk_mul_f32 v[142:143], v[140:141], s[54:55] op_sel_hi:[1,0]
	v_cndmask_b32_e64 v123, v123, v127, s[6:7]
	v_cndmask_b32_e32 v122, v122, v126, vcc
	v_cndmask_b32_e64 v127, v141, v143, s[10:11]
	v_cndmask_b32_e64 v126, v140, v142, s[8:9]
	v_mov_b32_e32 v166, v122
	v_mov_b32_e32 v167, v123
	v_pk_mul_f32 v[116:117], v[116:117], v[122:123]
	v_mov_b32_e32 v168, v126
	v_mov_b32_e32 v169, v127
	v_pk_mul_f32 v[118:119], v[118:119], v[126:127]
	v_cvt_pk_bf16_f32 v116, v116, v117
	v_cvt_pk_bf16_f32 v117, v118, v119
	global_store_dwordx2 v[144:145], v[116:117], off offset:64
	global_load_dword v116, v[120:121], off
	global_load_dword v117, v[120:121], off offset:256
	global_load_dword v118, v[120:121], off offset:512
	global_load_dword v119, v[120:121], off offset:768
	s_nop 0
	s_nop 0
	s_nop 0
	s_nop 0
	s_waitcnt vmcnt(2)
	v_pk_fma_f32 v[116:117], v[116:117], s[52:53], v[132:133] op_sel_hi:[1,0,0]
	s_nop 0
	v_mul_f32_e32 v122, 0x4b800000, v116
	s_waitcnt vmcnt(0)
	v_pk_fma_f32 v[118:119], v[118:119], s[52:53], v[132:133] op_sel_hi:[1,0,0]
	v_mul_f32_e32 v123, 0x4b800000, v117
	v_mul_f32_e32 v126, 0x4b800000, v118
	v_mul_f32_e32 v127, 0x4b800000, v119
	v_cmp_gt_f32_e32 vcc, s64, v116
	v_cmp_gt_f32_e64 s[6:7], s64, v117
	v_cmp_gt_f32_e64 s[8:9], s64, v118
	v_cmp_gt_f32_e64 s[10:11], s64, v119
	v_cndmask_b32_e32 v116, v116, v122, vcc
	v_cndmask_b32_e64 v117, v117, v123, s[6:7]
	v_cndmask_b32_e64 v118, v118, v126, s[8:9]
	v_cndmask_b32_e64 v119, v119, v127, s[10:11]
	v_rsq_f32_e32 v116, v116
	v_rsq_f32_e32 v117, v117
	v_rsq_f32_e32 v118, v118
	v_rsq_f32_e32 v119, v119
	v_pk_mul_f32 v[122:123], v[116:117], s[54:55] op_sel_hi:[1,0]
	s_nop 0
	v_cndmask_b32_e64 v117, v117, v123, s[6:7]
	v_pk_mul_f32 v[126:127], v[118:119], s[54:55] op_sel_hi:[1,0]
	v_cndmask_b32_e32 v116, v116, v122, vcc
	v_cndmask_b32_e64 v119, v119, v127, s[10:11]
	v_cndmask_b32_e64 v118, v118, v126, s[8:9]
	v_mov_b32_e32 v170, v116
	v_mov_b32_e32 v171, v117
	v_pk_mul_f32 v[108:109], v[108:109], v[116:117]
	v_mov_b32_e32 v172, v118
	v_mov_b32_e32 v173, v119
	v_pk_mul_f32 v[110:111], v[110:111], v[118:119]
	v_cvt_pk_bf16_f32 v108, v108, v109
	v_cvt_pk_bf16_f32 v109, v110, v111
	global_store_dwordx2 v[144:145], v[108:109], off offset:96
	s_nop 0
	v_or_b32_e32 v116, 16, v138
	v_ashrrev_i32_e32 v117, 31, v116
	v_lshlrev_b64 v[116:117], 14, v[116:117]
	v_lshl_add_u64 v[116:117], s[60:61], 0, v[116:117]
	v_lshl_add_u64 v[116:117], v[116:117], 0, s[62:63]
	v_lshl_add_u64 v[116:117], v[116:117], 0, s[16:17]
	v_lshl_add_u64 v[116:117], v[116:117], 0, v[130:131]
	s_nop 0
	v_pk_mul_f32 v[108:109], v[112:113], v[158:159]
	v_pk_mul_f32 v[110:111], v[114:115], v[160:161]
	v_cvt_pk_bf16_f32 v108, v108, v109
	v_cvt_pk_bf16_f32 v109, v110, v111
	global_store_dwordx2 v[116:117], v[108:109], off
	s_nop 0
	s_nop 0
	v_pk_mul_f32 v[104:105], v[104:105], v[162:163]
	v_pk_mul_f32 v[106:107], v[106:107], v[164:165]
	v_cvt_pk_bf16_f32 v104, v104, v105
	v_cvt_pk_bf16_f32 v105, v106, v107
; DI u32x2 pack4(float a, float b, float c, float d) { u32x2 r; r.x = pack2(a, b); r.y = pack2(c, d); return r; }
; #define EPI_END if (i == 3 && (j & 3) == 3) __builtin_amdgcn_sched_barrier(0); }
; DI float rstd_of(const float* ssq, int m, float invn) { return rsqrtf(ssq[m] * invn + 1e-6f); }
; template <int MODE>
; DI void gemm_phase(const Params& p, const GP& g, unsigned char* smem) {
;     ...
;         EPI_TR_BEGIN
;           const int grp = n >> 8, half = (n >> 7) & 1, c = grp * 128 + (n & 127);
;           const int b0 = i * 16 + lg * 4;
;           const int tok = bt * 4096 + a + 64 * b0;
;           (void)m4;
;           *(u32x2*)(Pt + (((long)bt * 1024 + c) * 2 + half) * 4096 + a * 64 + b0) =
;               pack4(v[0] * rstd_of(g.ssq_in, tok, 1.f / 1024), v[1] * rstd_of(g.ssq_in, tok + 64, 1.f / 1024),
;                     v[2] * rstd_of(g.ssq_in, tok + 128, 1.f / 1024), v[3] * rstd_of(g.ssq_in, tok + 192, 1.f / 1024));
;         EPI_END
	global_store_dwordx2 v[116:117], v[104:105], off offset:32
	s_nop 0
	s_nop 0
	v_pk_mul_f32 v[100:101], v[100:101], v[166:167]
	v_pk_mul_f32 v[102:103], v[102:103], v[168:169]
	v_cvt_pk_bf16_f32 v100, v100, v101
	v_cvt_pk_bf16_f32 v101, v102, v103
	global_store_dwordx2 v[116:117], v[100:101], off offset:64
	s_nop 0
	s_nop 0
	v_pk_mul_f32 v[92:93], v[92:93], v[170:171]
	v_pk_mul_f32 v[94:95], v[94:95], v[172:173]
	v_cvt_pk_bf16_f32 v92, v92, v93
	v_cvt_pk_bf16_f32 v93, v94, v95
	global_store_dwordx2 v[116:117], v[92:93], off offset:96
	s_nop 0
	v_or_b32_e32 v100, 32, v138
	v_ashrrev_i32_e32 v101, 31, v100
	v_lshlrev_b64 v[100:101], 14, v[100:101]
	v_lshl_add_u64 v[100:101], s[60:61], 0, v[100:101]
	v_lshl_add_u64 v[100:101], v[100:101], 0, s[62:63]
	v_lshl_add_u64 v[100:101], v[100:101], 0, s[16:17]
	v_lshl_add_u64 v[100:101], v[100:101], 0, v[130:131]
	s_nop 0
	v_pk_mul_f32 v[92:93], v[96:97], v[158:159]
	v_pk_mul_f32 v[94:95], v[98:99], v[160:161]
	v_cvt_pk_bf16_f32 v92, v92, v93
	v_cvt_pk_bf16_f32 v93, v94, v95
	global_store_dwordx2 v[100:101], v[92:93], off
	s_nop 0
	s_nop 0
	v_pk_mul_f32 v[88:89], v[88:89], v[162:163]
	v_pk_mul_f32 v[90:91], v[90:91], v[164:165]
	v_cvt_pk_bf16_f32 v88, v88, v89
	v_cvt_pk_bf16_f32 v89, v90, v91
	global_store_dwordx2 v[100:101], v[88:89], off offset:32
	s_nop 0
	s_nop 0
	v_pk_mul_f32 v[84:85], v[84:85], v[166:167]
	v_pk_mul_f32 v[86:87], v[86:87], v[168:169]
	v_cvt_pk_bf16_f32 v84, v84, v85
	v_cvt_pk_bf16_f32 v85, v86, v87
	global_store_dwordx2 v[100:101], v[84:85], off offset:64
	s_nop 0
	s_nop 0
	v_pk_mul_f32 v[76:77], v[76:77], v[170:171]
	v_pk_mul_f32 v[78:79], v[78:79], v[172:173]
	v_cvt_pk_bf16_f32 v76, v76, v77
	v_cvt_pk_bf16_f32 v77, v78, v79
	global_store_dwordx2 v[100:101], v[76:77], off offset:96
	s_nop 0
	v_or_b32_e32 v84, 48, v138
	v_ashrrev_i32_e32 v85, 31, v84
	v_lshlrev_b64 v[84:85], 14, v[84:85]
	v_lshl_add_u64 v[84:85], s[60:61], 0, v[84:85]
	v_lshl_add_u64 v[84:85], v[84:85], 0, s[62:63]
	v_lshl_add_u64 v[84:85], v[84:85], 0, s[16:17]
	v_lshl_add_u64 v[84:85], v[84:85], 0, v[130:131]
	s_nop 0
	v_pk_mul_f32 v[76:77], v[80:81], v[158:159]
	v_pk_mul_f32 v[78:79], v[82:83], v[160:161]
	v_cvt_pk_bf16_f32 v76, v76, v77
	v_cvt_pk_bf16_f32 v77, v78, v79
	global_store_dwordx2 v[84:85], v[76:77], off
	s_nop 0
	s_nop 0
	v_pk_mul_f32 v[72:73], v[72:73], v[162:163]
	v_pk_mul_f32 v[74:75], v[74:75], v[164:165]
	v_cvt_pk_bf16_f32 v72, v72, v73
	v_cvt_pk_bf16_f32 v73, v74, v75
	global_store_dwordx2 v[84:85], v[72:73], off offset:32
	s_nop 0
	s_nop 0
	v_pk_mul_f32 v[68:69], v[68:69], v[166:167]
	v_pk_mul_f32 v[70:71], v[70:71], v[168:169]
	v_cvt_pk_bf16_f32 v68, v68, v69
	v_cvt_pk_bf16_f32 v69, v70, v71
	global_store_dwordx2 v[84:85], v[68:69], off offset:64
	s_nop 0
	s_nop 0
	v_pk_mul_f32 v[60:61], v[60:61], v[170:171]
	v_pk_mul_f32 v[62:63], v[62:63], v[172:173]
	v_cvt_pk_bf16_f32 v60, v60, v61
	v_cvt_pk_bf16_f32 v61, v62, v63
	global_store_dwordx2 v[84:85], v[60:61], off offset:96
	s_nop 0
	v_or_b32_e32 v68, 64, v138
	v_ashrrev_i32_e32 v69, 31, v68
	v_lshlrev_b64 v[68:69], 14, v[68:69]
	v_lshl_add_u64 v[68:69], s[60:61], 0, v[68:69]
	v_lshl_add_u64 v[68:69], v[68:69], 0, s[62:63]
	v_lshl_add_u64 v[68:69], v[68:69], 0, s[16:17]
	v_lshl_add_u64 v[68:69], v[68:69], 0, v[130:131]
	s_nop 0
	s_nop 0
	v_pk_mul_f32 v[60:61], v[64:65], v[158:159]
	v_pk_mul_f32 v[62:63], v[66:67], v[160:161]
	v_cvt_pk_bf16_f32 v60, v60, v61
	v_cvt_pk_bf16_f32 v61, v62, v63
	global_store_dwordx2 v[68:69], v[60:61], off
	s_nop 0
	s_nop 0
	v_pk_mul_f32 v[56:57], v[56:57], v[162:163]
	v_pk_mul_f32 v[58:59], v[58:59], v[164:165]
	v_cvt_pk_bf16_f32 v56, v56, v57
	v_cvt_pk_bf16_f32 v57, v58, v59
	global_store_dwordx2 v[68:69], v[56:57], off offset:32
	s_nop 0
	s_nop 0
	v_pk_mul_f32 v[52:53], v[52:53], v[166:167]
	v_pk_mul_f32 v[54:55], v[54:55], v[168:169]
	v_cvt_pk_bf16_f32 v52, v52, v53
	v_cvt_pk_bf16_f32 v53, v54, v55
	global_store_dwordx2 v[68:69], v[52:53], off offset:64
	s_nop 0
	s_nop 0
	v_pk_mul_f32 v[44:45], v[44:45], v[170:171]
	v_pk_mul_f32 v[46:47], v[46:47], v[172:173]
	v_cvt_pk_bf16_f32 v44, v44, v45
	v_cvt_pk_bf16_f32 v45, v46, v47
; DI u32x2 pack4(float a, float b, float c, float d) { u32x2 r; r.x = pack2(a, b); r.y = pack2(c, d); return r; }
; #define EPI_END if (i == 3 && (j & 3) == 3) __builtin_amdgcn_sched_barrier(0); }
; DI float rstd_of(const float* ssq, int m, float invn) { return rsqrtf(ssq[m] * invn + 1e-6f); }
; template <int MODE>
; DI void gemm_phase(const Params& p, const GP& g, unsigned char* smem) {
;     ...
;         EPI_TR_BEGIN
;           const int grp = n >> 8, half = (n >> 7) & 1, c = grp * 128 + (n & 127);
;           const int b0 = i * 16 + lg * 4;
;           const int tok = bt * 4096 + a + 64 * b0;
;           (void)m4;
;           *(u32x2*)(Pt + (((long)bt * 1024 + c) * 2 + half) * 4096 + a * 64 + b0) =
;               pack4(v[0] * rstd_of(g.ssq_in, tok, 1.f / 1024), v[1] * rstd_of(g.ssq_in, tok + 64, 1.f / 1024),
;                     v[2] * rstd_of(g.ssq_in, tok + 128, 1.f / 1024), v[3] * rstd_of(g.ssq_in, tok + 192, 1.f / 1024));
;         EPI_END
	global_store_dwordx2 v[68:69], v[44:45], off offset:96
	s_nop 0
	v_or_b32_e32 v52, 0x50, v138
	v_ashrrev_i32_e32 v53, 31, v52
	v_lshlrev_b64 v[52:53], 14, v[52:53]
	v_lshl_add_u64 v[52:53], s[60:61], 0, v[52:53]
	v_lshl_add_u64 v[52:53], v[52:53], 0, s[62:63]
	v_lshl_add_u64 v[52:53], v[52:53], 0, s[16:17]
	v_lshl_add_u64 v[52:53], v[52:53], 0, v[130:131]
	s_nop 0
	v_pk_mul_f32 v[44:45], v[48:49], v[158:159]
	v_pk_mul_f32 v[46:47], v[50:51], v[160:161]
	v_cvt_pk_bf16_f32 v44, v44, v45
	v_cvt_pk_bf16_f32 v45, v46, v47
	global_store_dwordx2 v[52:53], v[44:45], off
	s_nop 0
	s_nop 0
	v_pk_mul_f32 v[40:41], v[40:41], v[162:163]
	v_pk_mul_f32 v[42:43], v[42:43], v[164:165]
	v_cvt_pk_bf16_f32 v40, v40, v41
	v_cvt_pk_bf16_f32 v41, v42, v43
	global_store_dwordx2 v[52:53], v[40:41], off offset:32
	s_nop 0
	s_nop 0
	v_pk_mul_f32 v[36:37], v[36:37], v[166:167]
	v_pk_mul_f32 v[38:39], v[38:39], v[168:169]
	v_cvt_pk_bf16_f32 v36, v36, v37
	v_cvt_pk_bf16_f32 v37, v38, v39
	global_store_dwordx2 v[52:53], v[36:37], off offset:64
	s_nop 0
	s_nop 0
	v_pk_mul_f32 v[28:29], v[28:29], v[170:171]
	v_pk_mul_f32 v[30:31], v[30:31], v[172:173]
	v_cvt_pk_bf16_f32 v28, v28, v29
	v_cvt_pk_bf16_f32 v29, v30, v31
	global_store_dwordx2 v[52:53], v[28:29], off offset:96
	s_nop 0
	v_or_b32_e32 v36, 0x60, v138
	v_ashrrev_i32_e32 v37, 31, v36
	v_lshlrev_b64 v[36:37], 14, v[36:37]
	v_lshl_add_u64 v[36:37], s[60:61], 0, v[36:37]
	v_lshl_add_u64 v[36:37], v[36:37], 0, s[62:63]
	v_lshl_add_u64 v[36:37], v[36:37], 0, s[16:17]
	v_lshl_add_u64 v[36:37], v[36:37], 0, v[130:131]
	s_nop 0
	v_pk_mul_f32 v[28:29], v[32:33], v[158:159]
	v_pk_mul_f32 v[30:31], v[34:35], v[160:161]
	v_cvt_pk_bf16_f32 v28, v28, v29
	v_cvt_pk_bf16_f32 v29, v30, v31
	global_store_dwordx2 v[36:37], v[28:29], off
	s_nop 0
	s_nop 0
	v_pk_mul_f32 v[24:25], v[24:25], v[162:163]
	v_pk_mul_f32 v[26:27], v[26:27], v[164:165]
	v_cvt_pk_bf16_f32 v24, v24, v25
	v_cvt_pk_bf16_f32 v25, v26, v27
	global_store_dwordx2 v[36:37], v[24:25], off offset:32
	s_nop 0
	s_nop 0
	v_pk_mul_f32 v[20:21], v[20:21], v[166:167]
	v_pk_mul_f32 v[22:23], v[22:23], v[168:169]
	v_cvt_pk_bf16_f32 v20, v20, v21
	v_cvt_pk_bf16_f32 v21, v22, v23
	global_store_dwordx2 v[36:37], v[20:21], off offset:64
	s_nop 0
	s_nop 0
	v_pk_mul_f32 v[12:13], v[12:13], v[170:171]
	v_pk_mul_f32 v[14:15], v[14:15], v[172:173]
	v_cvt_pk_bf16_f32 v12, v12, v13
	v_cvt_pk_bf16_f32 v13, v14, v15
	global_store_dwordx2 v[36:37], v[12:13], off offset:96
	s_nop 0
	v_or_b32_e32 v20, 0x70, v138
	v_ashrrev_i32_e32 v21, 31, v20
	v_lshlrev_b64 v[20:21], 14, v[20:21]
	v_lshl_add_u64 v[20:21], s[60:61], 0, v[20:21]
	v_lshl_add_u64 v[20:21], v[20:21], 0, s[62:63]
	v_lshl_add_u64 v[20:21], v[20:21], 0, s[16:17]
	v_lshl_add_u64 v[20:21], v[20:21], 0, v[130:131]
	s_nop 0
	v_pk_mul_f32 v[12:13], v[16:17], v[158:159]
	v_pk_mul_f32 v[14:15], v[18:19], v[160:161]
	v_cvt_pk_bf16_f32 v12, v12, v13
	v_cvt_pk_bf16_f32 v13, v14, v15
	global_store_dwordx2 v[20:21], v[12:13], off
	s_nop 0
	s_nop 0
	v_pk_mul_f32 v[4:5], v[4:5], v[162:163]
	v_pk_mul_f32 v[6:7], v[6:7], v[164:165]
	v_cvt_pk_bf16_f32 v4, v4, v5
	v_cvt_pk_bf16_f32 v5, v6, v7
	global_store_dwordx2 v[20:21], v[4:5], off offset:32
	s_nop 0
	s_nop 0
	v_pk_mul_f32 v[0:1], v[0:1], v[166:167]
	v_pk_mul_f32 v[2:3], v[2:3], v[168:169]
	v_cvt_pk_bf16_f32 v0, v0, v1
	v_cvt_pk_bf16_f32 v1, v2, v3
	global_store_dwordx2 v[20:21], v[0:1], off offset:64
	global_load_dword v1, v[120:121], off offset:768
	global_load_dword v3, v[120:121], off offset:256
	global_load_dword v2, v[120:121], off
	global_load_dword v0, v[120:121], off offset:512
	s_nop 0
	s_nop 0
	s_nop 0
	s_nop 0
	s_waitcnt vmcnt(1)
	v_pk_fma_f32 v[2:3], v[2:3], s[52:53], v[132:133] op_sel_hi:[1,0,0]
	s_waitcnt vmcnt(0)
	v_pk_fma_f32 v[0:1], v[0:1], s[52:53], v[132:133] op_sel_hi:[1,0,0]
	v_cmp_gt_f32_e32 vcc, s64, v2
	v_cmp_gt_f32_e64 s[6:7], s64, v3
	v_cmp_gt_f32_e64 s[8:9], s64, v0
	v_cmp_gt_f32_e64 s[10:11], s64, v1
	s_nop 0
	v_pk_mul_f32 v[0:1], v[8:9], v[170:171]
	v_pk_mul_f32 v[2:3], v[10:11], v[172:173]
	v_cvt_pk_bf16_f32 v0, v0, v1
	v_cvt_pk_bf16_f32 v1, v2, v3
	global_store_dwordx2 v[20:21], v[0:1], off offset:96
	s_branch .LBB0_79

; DI u32x2 pack4(float a, float b, float c, float d) { u32x2 r; r.x = pack2(a, b); r.y = pack2(c, d); return r; }
; #define EPI_END if (i == 3 && (j & 3) == 3) __builtin_amdgcn_sched_barrier(0); }
; DI float rstd_of(const float* ssq, int m, float invn) { return rsqrtf(ssq[m] * invn + 1e-6f); }
; template <int MODE>
; DI void gemm_phase(const Params& p, const GP& g, unsigned char* smem) {
;     ...
;         u16* dst = (u16*)((unsigned char*)g.d0 + (nt < 4 ? 0L : (nt < 8 ? SL : 3 * SL)));
;         const int nb = nt < 4 ? 0 : (nt < 8 ? 1024 : 3072);
;         EPI_STD_BEGIN
;           const float rs = rstd_of(g.ssq_in, m, 1.f / 1024);
;           *(u32x2*)(dst + (long)m * 1024 + (n4 - nb)) = pack4(v[0] * rs, v[1] * rs, v[2] * rs, v[3] * rs);
;         EPI_END
.LBB0_216:
	v_or_b32_e32 v130, s12, v147
	v_ashrrev_i32_e32 v131, 31, v130
	v_lshl_add_u64 v[134:135], v[130:131], 2, s[26:27]
	global_load_dword v128, v[134:135], off
	s_cmp_lt_u32 s91, 4
	s_cselect_b64 s[8:9], -1, 0
	s_cmp_lt_u32 s91, 8
	s_cselect_b64 s[10:11], -1, 0
	s_and_b64 s[14:15], s[10:11], exec
	s_cselect_b32 s7, s84, 0x1e000000
	s_and_b64 s[14:15], s[8:9], exec
	s_cselect_b32 s7, 0, s7
	v_lshlrev_b64 v[132:133], 11, v[130:131]
	s_add_u32 s14, s20, s7
	s_addc_u32 s15, s21, 0
	s_and_b64 s[10:11], s[10:11], exec
	s_cselect_b32 s7, s85, 0xfffff400
	s_and_b64 s[8:9], s[8:9], exec
	s_cselect_b32 s7, 0, s7
	s_add_i32 s7, s7, s6
	v_lshl_add_u64 v[136:137], s[14:15], 0, v[132:133]
	v_add_u32_e32 v132, s7, v148
	v_ashrrev_i32_e32 v133, 31, v132
	v_lshlrev_b64 v[132:133], 1, v[132:133]
	v_lshl_add_u64 v[136:137], v[136:137], 0, v[132:133]
	s_waitcnt vmcnt(0)
	v_fmamk_f32 v128, v128, 0x3a800000, v149
	v_mul_f32_e32 v131, 0x4b800000, v128
	v_cmp_gt_f32_e32 vcc, s86, v128
	s_nop 1
	v_cndmask_b32_e32 v128, v128, v131, vcc
	v_rsq_f32_e32 v128, v128
	s_nop 0
	v_mul_f32_e32 v131, 0x45800000, v128
	v_cndmask_b32_e32 v128, v128, v131, vcc
	v_mov_b32_e32 v154, v128
	v_pk_mul_f32 v[138:139], v[124:125], v[128:129] op_sel_hi:[1,0]
	v_pk_mul_f32 v[140:141], v[126:127], v[154:155] op_sel_hi:[1,0]
	v_cvt_pk_bf16_f32 v138, v138, v139
	v_cvt_pk_bf16_f32 v139, v140, v141
	global_store_dwordx2 v[136:137], v[138:139], off
	s_nop 1
	s_nop 0
	v_pk_mul_f32 v[138:139], v[120:121], v[154:155] op_sel_hi:[1,0]
	v_pk_mul_f32 v[140:141], v[122:123], v[154:155] op_sel_hi:[1,0]
	v_cvt_pk_bf16_f32 v138, v138, v139
	v_cvt_pk_bf16_f32 v139, v140, v141
	global_store_dwordx2 v[136:137], v[138:139], off offset:32
	s_nop 1
	s_nop 0
	v_pk_mul_f32 v[138:139], v[116:117], v[154:155] op_sel_hi:[1,0]
	v_pk_mul_f32 v[140:141], v[118:119], v[154:155] op_sel_hi:[1,0]
	v_cvt_pk_bf16_f32 v138, v138, v139
	v_cvt_pk_bf16_f32 v139, v140, v141
	global_store_dwordx2 v[136:137], v[138:139], off offset:64
	v_or_b32_e32 v134, 16, v130
	v_ashrrev_i32_e32 v135, 31, v134
	v_lshl_add_u64 v[138:139], v[134:135], 2, s[26:27]
	global_load_dword v128, v[138:139], off
	v_lshlrev_b64 v[134:135], 11, v[134:135]
	v_lshl_add_u64 v[134:135], s[14:15], 0, v[134:135]
	v_lshl_add_u64 v[134:135], v[134:135], 0, v[132:133]
	s_nop 1
	s_nop 0
	v_pk_mul_f32 v[140:141], v[108:109], v[154:155] op_sel_hi:[1,0]
	v_pk_mul_f32 v[142:143], v[110:111], v[154:155] op_sel_hi:[1,0]
	v_cvt_pk_bf16_f32 v140, v140, v141
	v_cvt_pk_bf16_f32 v141, v142, v143
	global_store_dwordx2 v[136:137], v[140:141], off offset:96
	s_nop 0
	s_waitcnt vmcnt(1)
	v_fmamk_f32 v128, v128, 0x3a800000, v149
	v_mul_f32_e32 v131, 0x4b800000, v128
	v_cmp_gt_f32_e32 vcc, s86, v128
	s_nop 1
	v_cndmask_b32_e32 v128, v128, v131, vcc
	v_rsq_f32_e32 v128, v128
	s_nop 0
	v_mul_f32_e32 v131, 0x45800000, v128
	v_cndmask_b32_e32 v128, v128, v131, vcc
	v_mov_b32_e32 v156, v128
	v_pk_mul_f32 v[136:137], v[112:113], v[128:129] op_sel_hi:[1,0]
	v_pk_mul_f32 v[140:141], v[114:115], v[156:157] op_sel_hi:[1,0]
	v_cvt_pk_bf16_f32 v136, v136, v137
	v_cvt_pk_bf16_f32 v137, v140, v141
	global_store_dwordx2 v[134:135], v[136:137], off
	s_nop 1
	s_nop 0
	v_pk_mul_f32 v[136:137], v[104:105], v[156:157] op_sel_hi:[1,0]
	v_pk_mul_f32 v[140:141], v[106:107], v[156:157] op_sel_hi:[1,0]
	v_cvt_pk_bf16_f32 v136, v136, v137
	v_cvt_pk_bf16_f32 v137, v140, v141
	global_store_dwordx2 v[134:135], v[136:137], off offset:32
	s_nop 1
	s_nop 0
	v_pk_mul_f32 v[136:137], v[100:101], v[156:157] op_sel_hi:[1,0]
	v_pk_mul_f32 v[140:141], v[102:103], v[156:157] op_sel_hi:[1,0]
	v_cvt_pk_bf16_f32 v136, v136, v137
	v_cvt_pk_bf16_f32 v137, v140, v141
	global_store_dwordx2 v[134:135], v[136:137], off offset:64
	v_or_b32_e32 v136, 32, v130
	v_ashrrev_i32_e32 v137, 31, v136
	v_lshl_add_u64 v[138:139], v[136:137], 2, s[26:27]
	global_load_dword v128, v[138:139], off
	s_nop 1
	s_nop 0
	v_pk_mul_f32 v[140:141], v[92:93], v[156:157] op_sel_hi:[1,0]
	v_pk_mul_f32 v[142:143], v[94:95], v[156:157] op_sel_hi:[1,0]
	v_cvt_pk_bf16_f32 v140, v140, v141
	v_cvt_pk_bf16_f32 v141, v142, v143
	global_store_dwordx2 v[134:135], v[140:141], off offset:96
	s_nop 0
	v_lshlrev_b64 v[134:135], 11, v[136:137]
	v_lshl_add_u64 v[134:135], s[14:15], 0, v[134:135]
	v_lshl_add_u64 v[134:135], v[134:135], 0, v[132:133]
	s_waitcnt vmcnt(1)
	v_fmamk_f32 v128, v128, 0x3a800000, v149
	v_mul_f32_e32 v131, 0x4b800000, v128
	v_cmp_gt_f32_e32 vcc, s86, v128
	s_nop 1
	v_cndmask_b32_e32 v128, v128, v131, vcc
	v_rsq_f32_e32 v128, v128
	s_nop 0
	v_mul_f32_e32 v131, 0x45800000, v128
	v_cndmask_b32_e32 v128, v128, v131, vcc
	v_mov_b32_e32 v158, v128
	v_pk_mul_f32 v[136:137], v[96:97], v[128:129] op_sel_hi:[1,0]
	v_pk_mul_f32 v[140:141], v[98:99], v[158:159] op_sel_hi:[1,0]
	v_cvt_pk_bf16_f32 v136, v136, v137
	v_cvt_pk_bf16_f32 v137, v140, v141
	global_store_dwordx2 v[134:135], v[136:137], off
	s_nop 1
	s_nop 0
	v_pk_mul_f32 v[136:137], v[88:89], v[158:159] op_sel_hi:[1,0]
	v_pk_mul_f32 v[140:141], v[90:91], v[158:159] op_sel_hi:[1,0]
	v_cvt_pk_bf16_f32 v136, v136, v137
	v_cvt_pk_bf16_f32 v137, v140, v141
	global_store_dwordx2 v[134:135], v[136:137], off offset:32
	s_nop 1
	s_nop 0
	v_pk_mul_f32 v[136:137], v[84:85], v[158:159] op_sel_hi:[1,0]
	v_pk_mul_f32 v[140:141], v[86:87], v[158:159] op_sel_hi:[1,0]
	v_cvt_pk_bf16_f32 v136, v136, v137
	v_cvt_pk_bf16_f32 v137, v140, v141
	global_store_dwordx2 v[134:135], v[136:137], off offset:64
	v_or_b32_e32 v136, 48, v130
	v_ashrrev_i32_e32 v137, 31, v136
	v_lshl_add_u64 v[138:139], v[136:137], 2, s[26:27]
	global_load_dword v128, v[138:139], off
	s_nop 1
	s_nop 0
	v_pk_mul_f32 v[140:141], v[76:77], v[158:159] op_sel_hi:[1,0]
	v_pk_mul_f32 v[142:143], v[78:79], v[158:159] op_sel_hi:[1,0]
	v_cvt_pk_bf16_f32 v140, v140, v141
	v_cvt_pk_bf16_f32 v141, v142, v143
	global_store_dwordx2 v[134:135], v[140:141], off offset:96
	s_nop 0
	v_lshlrev_b64 v[134:135], 11, v[136:137]
	v_lshl_add_u64 v[134:135], s[14:15], 0, v[134:135]
	v_lshl_add_u64 v[134:135], v[134:135], 0, v[132:133]
	s_waitcnt vmcnt(1)
; DI u32x2 pack4(float a, float b, float c, float d) { u32x2 r; r.x = pack2(a, b); r.y = pack2(c, d); return r; }
; #define EPI_END if (i == 3 && (j & 3) == 3) __builtin_amdgcn_sched_barrier(0); }
; DI float rstd_of(const float* ssq, int m, float invn) { return rsqrtf(ssq[m] * invn + 1e-6f); }
; template <int MODE>
; DI void gemm_phase(const Params& p, const GP& g, unsigned char* smem) {
;     ...
;         u16* dst = (u16*)((unsigned char*)g.d0 + (nt < 4 ? 0L : (nt < 8 ? SL : 3 * SL)));
;         const int nb = nt < 4 ? 0 : (nt < 8 ? 1024 : 3072);
;         EPI_STD_BEGIN
;           const float rs = rstd_of(g.ssq_in, m, 1.f / 1024);
;           *(u32x2*)(dst + (long)m * 1024 + (n4 - nb)) = pack4(v[0] * rs, v[1] * rs, v[2] * rs, v[3] * rs);
;         EPI_END
	v_fmamk_f32 v128, v128, 0x3a800000, v149
	v_mul_f32_e32 v131, 0x4b800000, v128
	v_cmp_gt_f32_e32 vcc, s86, v128
	s_nop 1
	v_cndmask_b32_e32 v128, v128, v131, vcc
	v_rsq_f32_e32 v128, v128
	s_nop 0
	v_mul_f32_e32 v131, 0x45800000, v128
	v_cndmask_b32_e32 v128, v128, v131, vcc
	v_mov_b32_e32 v160, v128
	v_pk_mul_f32 v[136:137], v[80:81], v[128:129] op_sel_hi:[1,0]
	v_pk_mul_f32 v[140:141], v[82:83], v[160:161] op_sel_hi:[1,0]
	v_cvt_pk_bf16_f32 v136, v136, v137
	v_cvt_pk_bf16_f32 v137, v140, v141
	global_store_dwordx2 v[134:135], v[136:137], off
	s_nop 1
	s_nop 0
	v_pk_mul_f32 v[136:137], v[72:73], v[160:161] op_sel_hi:[1,0]
	v_pk_mul_f32 v[140:141], v[74:75], v[160:161] op_sel_hi:[1,0]
	v_cvt_pk_bf16_f32 v136, v136, v137
	v_cvt_pk_bf16_f32 v137, v140, v141
	global_store_dwordx2 v[134:135], v[136:137], off offset:32
	s_nop 1
	s_nop 0
	v_pk_mul_f32 v[136:137], v[68:69], v[160:161] op_sel_hi:[1,0]
	v_pk_mul_f32 v[140:141], v[70:71], v[160:161] op_sel_hi:[1,0]
	v_cvt_pk_bf16_f32 v136, v136, v137
	v_cvt_pk_bf16_f32 v137, v140, v141
	global_store_dwordx2 v[134:135], v[136:137], off offset:64
	s_nop 1
	s_nop 0
	v_pk_mul_f32 v[136:137], v[60:61], v[160:161] op_sel_hi:[1,0]
	v_pk_mul_f32 v[138:139], v[62:63], v[160:161] op_sel_hi:[1,0]
	v_cvt_pk_bf16_f32 v136, v136, v137
	v_cvt_pk_bf16_f32 v137, v138, v139
	global_store_dwordx2 v[134:135], v[136:137], off offset:96
	v_or_b32_e32 v134, 64, v130
	v_ashrrev_i32_e32 v135, 31, v134
	v_lshl_add_u64 v[136:137], v[134:135], 2, s[26:27]
	global_load_dword v128, v[136:137], off
	v_lshlrev_b64 v[134:135], 11, v[134:135]
	v_lshl_add_u64 v[134:135], s[14:15], 0, v[134:135]
	v_lshl_add_u64 v[134:135], v[134:135], 0, v[132:133]
	s_waitcnt vmcnt(0)
	v_fmamk_f32 v128, v128, 0x3a800000, v149
	v_mul_f32_e32 v131, 0x4b800000, v128
	v_cmp_gt_f32_e32 vcc, s86, v128
	s_nop 1
	v_cndmask_b32_e32 v128, v128, v131, vcc
	v_rsq_f32_e32 v128, v128
	s_nop 0
	v_mul_f32_e32 v131, 0x45800000, v128
	v_cndmask_b32_e32 v128, v128, v131, vcc
	v_mov_b32_e32 v162, v128
	v_pk_mul_f32 v[138:139], v[64:65], v[128:129] op_sel_hi:[1,0]
	v_pk_mul_f32 v[140:141], v[66:67], v[162:163] op_sel_hi:[1,0]
	v_cvt_pk_bf16_f32 v138, v138, v139
	v_cvt_pk_bf16_f32 v139, v140, v141
	global_store_dwordx2 v[134:135], v[138:139], off
	s_nop 1
	s_nop 0
	v_pk_mul_f32 v[138:139], v[56:57], v[162:163] op_sel_hi:[1,0]
	v_pk_mul_f32 v[140:141], v[58:59], v[162:163] op_sel_hi:[1,0]
	v_cvt_pk_bf16_f32 v138, v138, v139
	v_cvt_pk_bf16_f32 v139, v140, v141
	global_store_dwordx2 v[134:135], v[138:139], off offset:32
	s_nop 1
	s_nop 0
	v_pk_mul_f32 v[138:139], v[52:53], v[162:163] op_sel_hi:[1,0]
	v_pk_mul_f32 v[140:141], v[54:55], v[162:163] op_sel_hi:[1,0]
	v_cvt_pk_bf16_f32 v138, v138, v139
	v_cvt_pk_bf16_f32 v139, v140, v141
	global_store_dwordx2 v[134:135], v[138:139], off offset:64
	v_or_b32_e32 v136, 0x50, v130
	v_ashrrev_i32_e32 v137, 31, v136
	v_lshl_add_u64 v[138:139], v[136:137], 2, s[26:27]
	global_load_dword v128, v[138:139], off
	s_nop 1
	s_nop 0
	v_pk_mul_f32 v[140:141], v[44:45], v[162:163] op_sel_hi:[1,0]
	v_pk_mul_f32 v[142:143], v[46:47], v[162:163] op_sel_hi:[1,0]
	v_cvt_pk_bf16_f32 v140, v140, v141
	v_cvt_pk_bf16_f32 v141, v142, v143
	global_store_dwordx2 v[134:135], v[140:141], off offset:96
	s_nop 0
	v_lshlrev_b64 v[134:135], 11, v[136:137]
	v_lshl_add_u64 v[134:135], s[14:15], 0, v[134:135]
	v_lshl_add_u64 v[134:135], v[134:135], 0, v[132:133]
	s_waitcnt vmcnt(1)
	v_fmamk_f32 v128, v128, 0x3a800000, v149
	v_mul_f32_e32 v131, 0x4b800000, v128
	v_cmp_gt_f32_e32 vcc, s86, v128
	s_nop 1
	v_cndmask_b32_e32 v128, v128, v131, vcc
	v_rsq_f32_e32 v128, v128
	s_nop 0
	v_mul_f32_e32 v131, 0x45800000, v128
	v_cndmask_b32_e32 v128, v128, v131, vcc
	v_mov_b32_e32 v164, v128
	v_pk_mul_f32 v[136:137], v[48:49], v[128:129] op_sel_hi:[1,0]
	v_pk_mul_f32 v[140:141], v[50:51], v[164:165] op_sel_hi:[1,0]
	v_cvt_pk_bf16_f32 v136, v136, v137
	v_cvt_pk_bf16_f32 v137, v140, v141
	global_store_dwordx2 v[134:135], v[136:137], off
	s_nop 1
	s_nop 0
	v_pk_mul_f32 v[136:137], v[40:41], v[164:165] op_sel_hi:[1,0]
	v_pk_mul_f32 v[140:141], v[42:43], v[164:165] op_sel_hi:[1,0]
	v_cvt_pk_bf16_f32 v136, v136, v137
	v_cvt_pk_bf16_f32 v137, v140, v141
	global_store_dwordx2 v[134:135], v[136:137], off offset:32
	s_nop 1
	s_nop 0
	v_pk_mul_f32 v[136:137], v[36:37], v[164:165] op_sel_hi:[1,0]
	v_pk_mul_f32 v[140:141], v[38:39], v[164:165] op_sel_hi:[1,0]
	v_cvt_pk_bf16_f32 v136, v136, v137
	v_cvt_pk_bf16_f32 v137, v140, v141
	global_store_dwordx2 v[134:135], v[136:137], off offset:64
	v_or_b32_e32 v136, 0x60, v130
	v_ashrrev_i32_e32 v137, 31, v136
	v_lshl_add_u64 v[138:139], v[136:137], 2, s[26:27]
	global_load_dword v128, v[138:139], off
	v_or_b32_e32 v130, 0x70, v130
	s_nop 1
	s_nop 0
	v_pk_mul_f32 v[140:141], v[28:29], v[164:165] op_sel_hi:[1,0]
	v_pk_mul_f32 v[142:143], v[30:31], v[164:165] op_sel_hi:[1,0]
	v_cvt_pk_bf16_f32 v140, v140, v141
	v_cvt_pk_bf16_f32 v141, v142, v143
	global_store_dwordx2 v[134:135], v[140:141], off offset:96
	s_nop 0
	v_lshlrev_b64 v[134:135], 11, v[136:137]
	v_lshl_add_u64 v[134:135], s[14:15], 0, v[134:135]
	v_lshl_add_u64 v[134:135], v[134:135], 0, v[132:133]
	s_waitcnt vmcnt(1)
; DI u32x2 pack4(float a, float b, float c, float d) { u32x2 r; r.x = pack2(a, b); r.y = pack2(c, d); return r; }
; #define EPI_END if (i == 3 && (j & 3) == 3) __builtin_amdgcn_sched_barrier(0); }
; DI float rstd_of(const float* ssq, int m, float invn) { return rsqrtf(ssq[m] * invn + 1e-6f); }
; template <int MODE>
; DI void gemm_phase(const Params& p, const GP& g, unsigned char* smem) {
;     ...
;         EPI_TR_BEGIN
;           const int b = m4 >> 12, s = m4 & 4095;
;           *(u32x2*)(Vt + ((long)b * 1024 + (n - 2048)) * 4096 + s) =
;               pack4(v[0] * rstd_of(g.ssq_in, m4, 1.f / 1024), v[1] * rstd_of(g.ssq_in, m4 + 1, 1.f / 1024),
;                     v[2] * rstd_of(g.ssq_in, m4 + 2, 1.f / 1024), v[3] * rstd_of(g.ssq_in, m4 + 3, 1.f / 1024));
;         EPI_END
;     ...
;         u16* dst = (u16*)((unsigned char*)g.d0 + (nt < 4 ? 0L : (nt < 8 ? SL : 3 * SL)));
;         const int nb = nt < 4 ? 0 : (nt < 8 ? 1024 : 3072);
;         EPI_STD_BEGIN
;           const float rs = rstd_of(g.ssq_in, m, 1.f / 1024);
;           *(u32x2*)(dst + (long)m * 1024 + (n4 - nb)) = pack4(v[0] * rs, v[1] * rs, v[2] * rs, v[3] * rs);
;         EPI_END
	v_fmamk_f32 v128, v128, 0x3a800000, v149
	v_mul_f32_e32 v131, 0x4b800000, v128
	v_cmp_gt_f32_e32 vcc, s86, v128
	s_nop 1
	v_cndmask_b32_e32 v128, v128, v131, vcc
	v_rsq_f32_e32 v128, v128
	s_nop 0
	v_mul_f32_e32 v131, 0x45800000, v128
	v_cndmask_b32_e32 v128, v128, v131, vcc
	v_mov_b32_e32 v166, v128
	v_pk_mul_f32 v[136:137], v[32:33], v[128:129] op_sel_hi:[1,0]
	v_pk_mul_f32 v[140:141], v[34:35], v[166:167] op_sel_hi:[1,0]
	v_cvt_pk_bf16_f32 v136, v136, v137
	v_cvt_pk_bf16_f32 v137, v140, v141
	global_store_dwordx2 v[134:135], v[136:137], off
	s_nop 1
	s_nop 0
	v_pk_mul_f32 v[136:137], v[24:25], v[166:167] op_sel_hi:[1,0]
	v_pk_mul_f32 v[140:141], v[26:27], v[166:167] op_sel_hi:[1,0]
	v_cvt_pk_bf16_f32 v136, v136, v137
	v_cvt_pk_bf16_f32 v137, v140, v141
	global_store_dwordx2 v[134:135], v[136:137], off offset:32
	s_nop 1
	s_nop 0
	v_pk_mul_f32 v[136:137], v[20:21], v[166:167] op_sel_hi:[1,0]
	v_pk_mul_f32 v[140:141], v[22:23], v[166:167] op_sel_hi:[1,0]
	v_cvt_pk_bf16_f32 v136, v136, v137
	v_cvt_pk_bf16_f32 v137, v140, v141
	global_store_dwordx2 v[134:135], v[136:137], off offset:64
	s_nop 1
	v_ashrrev_i32_e32 v131, 31, v130
	v_lshl_add_u64 v[136:137], v[130:131], 2, s[26:27]
	global_load_dword v128, v[136:137], off
	global_load_dword v177, v[136:137], off
	v_lshlrev_b64 v[130:131], 11, v[130:131]
	v_pk_mul_f32 v[138:139], v[12:13], v[166:167] op_sel_hi:[1,0]
	v_pk_mul_f32 v[140:141], v[14:15], v[166:167] op_sel_hi:[1,0]
	v_cvt_pk_bf16_f32 v138, v138, v139
	v_cvt_pk_bf16_f32 v139, v140, v141
	global_store_dwordx2 v[134:135], v[138:139], off offset:96
	s_nop 0
	v_lshl_add_u64 v[130:131], s[14:15], 0, v[130:131]
	v_lshl_add_u64 v[130:131], v[130:131], 0, v[132:133]
	s_waitcnt vmcnt(2)
	v_fmamk_f32 v128, v128, 0x3a800000, v149
	v_mul_f32_e32 v134, 0x4b800000, v128
	v_cmp_gt_f32_e32 vcc, s86, v128
	s_nop 1
	v_cndmask_b32_e32 v128, v128, v134, vcc
	v_rsq_f32_e32 v128, v128
	s_nop 0
	v_mul_f32_e32 v132, 0x45800000, v128
	v_cndmask_b32_e32 v128, v128, v132, vcc
	v_mov_b32_e32 v168, v128
	v_pk_mul_f32 v[132:133], v[16:17], v[128:129] op_sel_hi:[1,0]
	v_pk_mul_f32 v[134:135], v[18:19], v[168:169] op_sel_hi:[1,0]
	v_cvt_pk_bf16_f32 v132, v132, v133
	v_cvt_pk_bf16_f32 v133, v134, v135
	global_store_dwordx2 v[130:131], v[132:133], off
	s_nop 1
	s_nop 0
	v_pk_mul_f32 v[132:133], v[4:5], v[168:169] op_sel_hi:[1,0]
	v_pk_mul_f32 v[134:135], v[6:7], v[168:169] op_sel_hi:[1,0]
	v_cvt_pk_bf16_f32 v132, v132, v133
	v_cvt_pk_bf16_f32 v133, v134, v135
	global_store_dwordx2 v[130:131], v[132:133], off offset:32
	s_nop 1
	s_nop 0
	v_pk_mul_f32 v[132:133], v[0:1], v[168:169] op_sel_hi:[1,0]
	v_pk_mul_f32 v[134:135], v[2:3], v[168:169] op_sel_hi:[1,0]
	v_cvt_pk_bf16_f32 v132, v132, v133
	v_cvt_pk_bf16_f32 v133, v134, v135
	global_store_dwordx2 v[130:131], v[132:133], off offset:64
	s_nop 0
	s_waitcnt vmcnt(4)
	v_fmamk_f32 v128, v177, 0x3a800000, v149
	v_mul_f32_e32 v132, 0x4b800000, v128
	v_cmp_gt_f32_e32 vcc, s86, v128
	s_nop 1
	v_cndmask_b32_e32 v128, v128, v132, vcc
	v_rsq_f32_e32 v128, v128
	s_nop 0
	v_mul_f32_e32 v132, 0x45800000, v128
	v_cndmask_b32_e32 v128, v128, v132, vcc
	v_pk_mul_f32 v[132:133], v[8:9], v[168:169] op_sel_hi:[1,0]
	v_pk_mul_f32 v[134:135], v[10:11], v[168:169] op_sel_hi:[1,0]
	v_cvt_pk_bf16_f32 v132, v132, v133
	v_cvt_pk_bf16_f32 v133, v134, v135
	global_store_dwordx2 v[130:131], v[132:133], off offset:96
	s_cbranch_execnz .LBB0_202
.LBB0_217:
	s_add_i32 s7, s12, s61
	v_or_b32_e32 v138, s7, v146
	v_ashrrev_i32_e32 v139, 31, v138
	v_lshl_add_u64 v[134:135], v[138:139], 2, s[26:27]
	global_load_dwordx4 v[140:143], v[134:135], off
	v_or_b32_e32 v128, s6, v147
	s_ashr_i32 s6, s7, 12
	v_bitop3_b32 v139, s7, v150, v146 bitop3:0xc8
	s_ashr_i32 s7, s6, 31
	s_lshl_b64 s[6:7], s[6:7], 23
	v_mov_b64_e32 v[130:131], s[64:65]
	s_add_u32 s6, s50, s6
	v_lshlrev_b32_e32 v128, 13, v128
	s_addc_u32 s7, s51, s7
	v_lshl_add_u64 v[136:137], s[6:7], 0, v[128:129]
	v_lshlrev_b32_e32 v128, 1, v139
	v_or_b32_e32 v132, 16, v138
	v_ashrrev_i32_e32 v133, 31, v132
	v_lshl_add_u64 v[132:133], v[132:133], 2, s[26:27]
	global_load_dwordx2 v[186:187], v[132:133], off
	global_load_dwordx2 v[188:189], v[132:133], off offset:8
	s_waitcnt vmcnt(2)
	v_pk_fma_f32 v[140:141], v[140:141], s[58:59], v[130:131] op_sel_hi:[1,0,0]
	v_pk_fma_f32 v[142:143], v[142:143], s[58:59], v[130:131] op_sel_hi:[1,0,0]
	v_mul_f32_e32 v139, 0x4b800000, v140
	v_mul_f32_e32 v144, 0x4b800000, v141
	v_mul_f32_e32 v145, 0x4b800000, v142
	v_mul_f32_e32 v151, 0x4b800000, v143
	v_cmp_gt_f32_e32 vcc, s86, v140
	v_cmp_gt_f32_e64 s[12:13], s86, v141
	v_cmp_gt_f32_e64 s[14:15], s86, v142
	v_cmp_gt_f32_e64 s[16:17], s86, v143
	v_cndmask_b32_e32 v139, v140, v139, vcc
	v_cndmask_b32_e64 v141, v141, v144, s[12:13]
	v_cndmask_b32_e64 v142, v142, v145, s[14:15]
	v_cndmask_b32_e64 v143, v143, v151, s[16:17]
	v_rsq_f32_e32 v140, v139
	v_rsq_f32_e32 v141, v141
	v_rsq_f32_e32 v142, v142
	v_rsq_f32_e32 v143, v143
	v_lshl_add_u64 v[144:145], v[136:137], 0, s[62:63]
	v_pk_mul_f32 v[154:155], v[140:141], s[60:61] op_sel_hi:[1,0]
	v_lshl_add_u64 v[152:153], v[144:145], 0, v[128:129]
	v_pk_mul_f32 v[156:157], v[142:143], s[60:61] op_sel_hi:[1,0]
	v_cndmask_b32_e64 v141, v141, v155, s[12:13]
	v_cndmask_b32_e32 v140, v140, v154, vcc
	v_cndmask_b32_e64 v143, v143, v157, s[16:17]
	v_cndmask_b32_e64 v142, v142, v156, s[14:15]
	v_mov_b32_e32 v158, v140
	v_mov_b32_e32 v159, v141
	v_pk_mul_f32 v[124:125], v[124:125], v[140:141]
	v_mov_b32_e32 v160, v142
	v_mov_b32_e32 v161, v143
	v_pk_mul_f32 v[126:127], v[126:127], v[142:143]
	v_cvt_pk_bf16_f32 v124, v124, v125
	v_cvt_pk_bf16_f32 v125, v126, v127
	global_store_dwordx2 v[152:153], v[124:125], off
	s_nop 0
	s_nop 0
	s_nop 0
	v_bitop3_b32 v126, v138, s87, 16 bitop3:0xc8
	v_or_b32_e32 v142, 32, v138
	v_mov_b32_e32 v127, v129
	v_lshlrev_b32_e32 v126, 1, v126
	v_ashrrev_i32_e32 v143, 31, v142
	s_waitcnt vmcnt(2)
; DI u32x2 pack4(float a, float b, float c, float d) { u32x2 r; r.x = pack2(a, b); r.y = pack2(c, d); return r; }
; #define EPI_END if (i == 3 && (j & 3) == 3) __builtin_amdgcn_sched_barrier(0); }
; DI float rstd_of(const float* ssq, int m, float invn) { return rsqrtf(ssq[m] * invn + 1e-6f); }
; template <int MODE>
; DI void gemm_phase(const Params& p, const GP& g, unsigned char* smem) {
;     ...
;         EPI_TR_BEGIN
;           const int b = m4 >> 12, s = m4 & 4095;
;           *(u32x2*)(Vt + ((long)b * 1024 + (n - 2048)) * 4096 + s) =
;               pack4(v[0] * rstd_of(g.ssq_in, m4, 1.f / 1024), v[1] * rstd_of(g.ssq_in, m4 + 1, 1.f / 1024),
;                     v[2] * rstd_of(g.ssq_in, m4 + 2, 1.f / 1024), v[3] * rstd_of(g.ssq_in, m4 + 3, 1.f / 1024));
;         EPI_END
	v_pk_fma_f32 v[124:125], v[186:187], s[58:59], v[130:131] op_sel_hi:[1,0,0]
	s_waitcnt vmcnt(1)
	v_pk_fma_f32 v[140:141], v[188:189], s[58:59], v[130:131] op_sel_hi:[1,0,0]
	v_mul_f32_e32 v139, 0x4b800000, v124
	v_mul_f32_e32 v151, 0x4b800000, v125
	v_mul_f32_e32 v152, 0x4b800000, v140
	v_mul_f32_e32 v153, 0x4b800000, v141
	v_cmp_gt_f32_e32 vcc, s86, v124
	v_cmp_gt_f32_e64 s[12:13], s86, v125
	v_cmp_gt_f32_e64 s[14:15], s86, v140
	v_cmp_gt_f32_e64 s[16:17], s86, v141
	v_cndmask_b32_e32 v124, v124, v139, vcc
	v_cndmask_b32_e64 v125, v125, v151, s[12:13]
	v_cndmask_b32_e64 v139, v140, v152, s[14:15]
	v_cndmask_b32_e64 v151, v141, v153, s[16:17]
	v_rsq_f32_e32 v140, v124
	v_rsq_f32_e32 v141, v125
	v_rsq_f32_e32 v152, v139
	v_rsq_f32_e32 v153, v151
	v_lshl_add_u64 v[124:125], v[142:143], 2, s[26:27]
	global_load_dwordx2 v[186:187], v[124:125], off
	global_load_dwordx2 v[188:189], v[124:125], off offset:8
	v_pk_mul_f32 v[154:155], v[140:141], s[60:61] op_sel_hi:[1,0]
	v_lshl_add_u64 v[142:143], v[144:145], 0, v[126:127]
	v_pk_mul_f32 v[156:157], v[152:153], s[60:61] op_sel_hi:[1,0]
	v_cndmask_b32_e64 v141, v141, v155, s[12:13]
	v_cndmask_b32_e32 v140, v140, v154, vcc
	v_cndmask_b32_e64 v153, v153, v157, s[16:17]
	v_cndmask_b32_e64 v152, v152, v156, s[14:15]
	v_mov_b32_e32 v162, v140
	v_mov_b32_e32 v163, v141
	v_pk_mul_f32 v[120:121], v[120:121], v[140:141]
	v_mov_b32_e32 v164, v152
	v_mov_b32_e32 v165, v153
	v_pk_mul_f32 v[122:123], v[122:123], v[152:153]
	v_cvt_pk_bf16_f32 v120, v120, v121
	v_cvt_pk_bf16_f32 v121, v122, v123
	global_store_dwordx2 v[142:143], v[120:121], off
	s_nop 0
	s_nop 0
	s_nop 0
	v_bitop3_b32 v122, v138, s88, 32 bitop3:0xc8
	v_or_b32_e32 v142, 48, v138
	v_mov_b32_e32 v123, v129
	v_lshlrev_b32_e32 v122, 1, v122
	v_ashrrev_i32_e32 v143, 31, v142
	s_waitcnt vmcnt(2)
	v_pk_fma_f32 v[120:121], v[186:187], s[58:59], v[130:131] op_sel_hi:[1,0,0]
	s_waitcnt vmcnt(1)
	v_pk_fma_f32 v[140:141], v[188:189], s[58:59], v[130:131] op_sel_hi:[1,0,0]
	v_mul_f32_e32 v139, 0x4b800000, v120
	v_mul_f32_e32 v151, 0x4b800000, v121
	v_mul_f32_e32 v152, 0x4b800000, v140
	v_mul_f32_e32 v153, 0x4b800000, v141
	v_cmp_gt_f32_e32 vcc, s86, v120
	v_cmp_gt_f32_e64 s[12:13], s86, v121
	v_cmp_gt_f32_e64 s[14:15], s86, v140
	v_cmp_gt_f32_e64 s[16:17], s86, v141
	v_cndmask_b32_e32 v120, v120, v139, vcc
	v_cndmask_b32_e64 v121, v121, v151, s[12:13]
	v_cndmask_b32_e64 v139, v140, v152, s[14:15]
	v_cndmask_b32_e64 v151, v141, v153, s[16:17]
	v_rsq_f32_e32 v140, v120
	v_rsq_f32_e32 v141, v121
	v_rsq_f32_e32 v152, v139
	v_rsq_f32_e32 v153, v151
	v_lshl_add_u64 v[120:121], v[142:143], 2, s[26:27]
	global_load_dwordx2 v[186:187], v[120:121], off
	global_load_dwordx2 v[188:189], v[120:121], off offset:8
	global_load_dwordx4 v[192:195], v[134:135], off
	global_load_dwordx2 v[190:191], v[132:133], off offset:8
	global_load_dwordx2 v[196:197], v[120:121], off
	global_load_dwordx2 v[198:199], v[120:121], off offset:8
	v_pk_mul_f32 v[154:155], v[140:141], s[60:61] op_sel_hi:[1,0]
	v_lshl_add_u64 v[142:143], v[144:145], 0, v[122:123]
	v_pk_mul_f32 v[156:157], v[152:153], s[60:61] op_sel_hi:[1,0]
	v_cndmask_b32_e64 v141, v141, v155, s[12:13]
	v_cndmask_b32_e32 v140, v140, v154, vcc
	v_cndmask_b32_e64 v153, v153, v157, s[16:17]
	v_cndmask_b32_e64 v152, v152, v156, s[14:15]
	v_mov_b32_e32 v166, v140
	v_mov_b32_e32 v167, v141
	v_pk_mul_f32 v[116:117], v[116:117], v[140:141]
	v_mov_b32_e32 v168, v152
	v_mov_b32_e32 v169, v153
	v_pk_mul_f32 v[118:119], v[118:119], v[152:153]
	v_cvt_pk_bf16_f32 v116, v116, v117
	v_cvt_pk_bf16_f32 v117, v118, v119
	global_store_dwordx2 v[142:143], v[116:117], off
	s_nop 0
	s_nop 0
	v_bitop3_b32 v116, v138, s89, 48 bitop3:0xc8
	v_mov_b32_e32 v117, v129
	v_lshlrev_b32_e32 v116, 1, v116
	s_waitcnt vmcnt(6)
	v_pk_fma_f32 v[118:119], v[186:187], s[58:59], v[130:131] op_sel_hi:[1,0,0]
	s_waitcnt vmcnt(5)
	v_pk_fma_f32 v[138:139], v[188:189], s[58:59], v[130:131] op_sel_hi:[1,0,0]
	v_mul_f32_e32 v140, 0x4b800000, v118
	v_mul_f32_e32 v141, 0x4b800000, v119
	v_mul_f32_e32 v142, 0x4b800000, v138
	v_mul_f32_e32 v143, 0x4b800000, v139
	v_cmp_gt_f32_e32 vcc, s86, v118
	v_cmp_gt_f32_e64 s[12:13], s86, v119
	v_cmp_gt_f32_e64 s[14:15], s86, v138
	v_cmp_gt_f32_e64 s[16:17], s86, v139
	v_cndmask_b32_e32 v118, v118, v140, vcc
	v_cndmask_b32_e64 v119, v119, v141, s[12:13]
	v_cndmask_b32_e64 v138, v138, v142, s[14:15]
	v_cndmask_b32_e64 v139, v139, v143, s[16:17]
	v_rsq_f32_e32 v118, v118
	v_rsq_f32_e32 v119, v119
	v_rsq_f32_e32 v138, v138
	v_rsq_f32_e32 v139, v139
	v_lshl_add_u64 v[140:141], v[144:145], 0, v[116:117]
	v_pk_mul_f32 v[142:143], v[118:119], s[60:61] op_sel_hi:[1,0]
	v_pk_mul_f32 v[144:145], v[138:139], s[60:61] op_sel_hi:[1,0]
	v_cndmask_b32_e64 v119, v119, v143, s[12:13]
	v_cndmask_b32_e32 v118, v118, v142, vcc
	v_cndmask_b32_e64 v139, v139, v145, s[16:17]
	v_cndmask_b32_e64 v138, v138, v144, s[14:15]
	v_mov_b32_e32 v170, v118
	v_mov_b32_e32 v171, v119
	v_pk_mul_f32 v[108:109], v[108:109], v[118:119]
	v_mov_b32_e32 v172, v138
	v_mov_b32_e32 v173, v139
	v_pk_mul_f32 v[110:111], v[110:111], v[138:139]
	v_cvt_pk_bf16_f32 v108, v108, v109
	v_cvt_pk_bf16_f32 v109, v110, v111
	global_store_dwordx2 v[140:141], v[108:109], off
	s_nop 0
	s_waitcnt vmcnt(5)
; DI u32x2 pack4(float a, float b, float c, float d) { u32x2 r; r.x = pack2(a, b); r.y = pack2(c, d); return r; }
; #define EPI_END if (i == 3 && (j & 3) == 3) __builtin_amdgcn_sched_barrier(0); }
; DI float rstd_of(const float* ssq, int m, float invn) { return rsqrtf(ssq[m] * invn + 1e-6f); }
; template <int MODE>
; DI void gemm_phase(const Params& p, const GP& g, unsigned char* smem) {
;     ...
;         EPI_TR_BEGIN
;           const int b = m4 >> 12, s = m4 & 4095;
;           *(u32x2*)(Vt + ((long)b * 1024 + (n - 2048)) * 4096 + s) =
;               pack4(v[0] * rstd_of(g.ssq_in, m4, 1.f / 1024), v[1] * rstd_of(g.ssq_in, m4 + 1, 1.f / 1024),
;                     v[2] * rstd_of(g.ssq_in, m4 + 2, 1.f / 1024), v[3] * rstd_of(g.ssq_in, m4 + 3, 1.f / 1024));
;         EPI_END
	v_pk_fma_f32 v[108:109], v[192:193], s[58:59], v[130:131] op_sel_hi:[1,0,0]
	v_pk_fma_f32 v[110:111], v[194:195], s[58:59], v[130:131] op_sel_hi:[1,0,0]
	v_mul_f32_e32 v118, 0x4b800000, v108
	v_mul_f32_e32 v119, 0x4b800000, v109
	v_mul_f32_e32 v138, 0x4b800000, v110
	v_mul_f32_e32 v139, 0x4b800000, v111
	v_cmp_gt_f32_e32 vcc, s86, v108
	v_cmp_gt_f32_e64 s[12:13], s86, v109
	v_cmp_gt_f32_e64 s[14:15], s86, v110
	v_cmp_gt_f32_e64 s[16:17], s86, v111
	v_cndmask_b32_e32 v108, v108, v118, vcc
	v_cndmask_b32_e64 v109, v109, v119, s[12:13]
	v_cndmask_b32_e64 v110, v110, v138, s[14:15]
	v_cndmask_b32_e64 v111, v111, v139, s[16:17]
	v_rsq_f32_e32 v108, v108
	v_rsq_f32_e32 v109, v109
	v_rsq_f32_e32 v110, v110
	v_rsq_f32_e32 v111, v111
	v_lshl_add_u64 v[118:119], v[136:137], 0, s[66:67]
	v_pk_mul_f32 v[140:141], v[108:109], s[60:61] op_sel_hi:[1,0]
	v_lshl_add_u64 v[138:139], v[118:119], 0, v[128:129]
	v_pk_mul_f32 v[142:143], v[110:111], s[60:61] op_sel_hi:[1,0]
	v_pk_mul_f32 v[108:109], v[112:113], v[158:159]
	v_pk_mul_f32 v[110:111], v[114:115], v[160:161]
	v_cvt_pk_bf16_f32 v108, v108, v109
	v_cvt_pk_bf16_f32 v109, v110, v111
	global_store_dwordx2 v[138:139], v[108:109], off
	s_nop 0
	s_nop 0
	s_waitcnt vmcnt(5)
	v_pk_fma_f32 v[110:111], v[190:191], s[58:59], v[130:131] op_sel_hi:[1,0,0]
	v_mul_f32_e32 v114, 0x4b800000, v110
	v_mul_f32_e32 v115, 0x4b800000, v111
	v_cmp_gt_f32_e64 s[14:15], s86, v110
	v_cmp_gt_f32_e64 s[16:17], s86, v111
	v_cndmask_b32_e64 v110, v110, v114, s[14:15]
	v_cndmask_b32_e64 v111, v111, v115, s[16:17]
	v_rsq_f32_e32 v110, v110
	v_rsq_f32_e32 v111, v111
	v_lshl_add_u64 v[112:113], v[118:119], 0, v[126:127]
	v_pk_mul_f32 v[138:139], v[110:111], s[60:61] op_sel_hi:[1,0]
	v_pk_mul_f32 v[104:105], v[104:105], v[162:163]
	v_pk_mul_f32 v[106:107], v[106:107], v[164:165]
	v_cvt_pk_bf16_f32 v104, v104, v105
	v_cvt_pk_bf16_f32 v105, v106, v107
	global_store_dwordx2 v[112:113], v[104:105], off
	s_nop 0
	v_lshl_add_u64 v[108:109], v[118:119], 0, v[122:123]
	v_pk_mul_f32 v[100:101], v[100:101], v[166:167]
	v_pk_mul_f32 v[102:103], v[102:103], v[168:169]
	v_cvt_pk_bf16_f32 v100, v100, v101
	v_cvt_pk_bf16_f32 v101, v102, v103
	global_store_dwordx2 v[108:109], v[100:101], off
	s_nop 0
	v_lshl_add_u64 v[104:105], v[118:119], 0, v[116:117]
	v_pk_mul_f32 v[92:93], v[92:93], v[170:171]
	v_pk_mul_f32 v[94:95], v[94:95], v[172:173]
	v_cvt_pk_bf16_f32 v92, v92, v93
	v_cvt_pk_bf16_f32 v93, v94, v95
	global_store_dwordx2 v[104:105], v[92:93], off
	v_lshl_add_u64 v[100:101], v[136:137], 0, s[68:69]
	v_lshl_add_u64 v[102:103], v[100:101], 0, v[128:129]
	v_pk_mul_f32 v[92:93], v[96:97], v[158:159]
	v_pk_mul_f32 v[94:95], v[98:99], v[160:161]
	v_cvt_pk_bf16_f32 v92, v92, v93
	v_cvt_pk_bf16_f32 v93, v94, v95
	global_store_dwordx2 v[102:103], v[92:93], off
	s_nop 0
	v_lshl_add_u64 v[96:97], v[100:101], 0, v[126:127]
	v_pk_mul_f32 v[88:89], v[88:89], v[162:163]
	v_pk_mul_f32 v[90:91], v[90:91], v[164:165]
	v_cvt_pk_bf16_f32 v88, v88, v89
	v_cvt_pk_bf16_f32 v89, v90, v91
	global_store_dwordx2 v[96:97], v[88:89], off
	s_nop 0
	v_lshl_add_u64 v[92:93], v[100:101], 0, v[122:123]
	v_pk_mul_f32 v[84:85], v[84:85], v[166:167]
	v_pk_mul_f32 v[86:87], v[86:87], v[168:169]
	v_cvt_pk_bf16_f32 v84, v84, v85
	v_cvt_pk_bf16_f32 v85, v86, v87
	global_store_dwordx2 v[92:93], v[84:85], off
	s_nop 0
	v_lshl_add_u64 v[88:89], v[100:101], 0, v[116:117]
	v_pk_mul_f32 v[76:77], v[76:77], v[170:171]
	v_pk_mul_f32 v[78:79], v[78:79], v[172:173]
	v_cvt_pk_bf16_f32 v76, v76, v77
	v_cvt_pk_bf16_f32 v77, v78, v79
	global_store_dwordx2 v[88:89], v[76:77], off
	v_lshl_add_u64 v[84:85], v[136:137], 0, s[70:71]
	v_lshl_add_u64 v[86:87], v[84:85], 0, v[128:129]
	v_pk_mul_f32 v[76:77], v[80:81], v[158:159]
	v_pk_mul_f32 v[78:79], v[82:83], v[160:161]
	v_cvt_pk_bf16_f32 v76, v76, v77
	v_cvt_pk_bf16_f32 v77, v78, v79
	global_store_dwordx2 v[86:87], v[76:77], off
	s_nop 0
	v_lshl_add_u64 v[80:81], v[84:85], 0, v[126:127]
	v_pk_mul_f32 v[72:73], v[72:73], v[162:163]
	v_pk_mul_f32 v[74:75], v[74:75], v[164:165]
	v_cvt_pk_bf16_f32 v72, v72, v73
	v_cvt_pk_bf16_f32 v73, v74, v75
	global_store_dwordx2 v[80:81], v[72:73], off
	s_nop 0
	v_lshl_add_u64 v[76:77], v[84:85], 0, v[122:123]
	v_pk_mul_f32 v[68:69], v[68:69], v[166:167]
	v_pk_mul_f32 v[70:71], v[70:71], v[168:169]
	v_cvt_pk_bf16_f32 v68, v68, v69
	v_cvt_pk_bf16_f32 v69, v70, v71
	global_store_dwordx2 v[76:77], v[68:69], off
	s_nop 0
	s_nop 0
	v_pk_mul_f32 v[60:61], v[60:61], v[170:171]
	v_pk_mul_f32 v[62:63], v[62:63], v[172:173]
	v_cvt_pk_bf16_f32 v60, v60, v61
	v_cvt_pk_bf16_f32 v61, v62, v63
	v_lshl_add_u64 v[62:63], v[84:85], 0, v[116:117]
	global_store_dwordx2 v[62:63], v[60:61], off
; DI u32x2 pack4(float a, float b, float c, float d) { u32x2 r; r.x = pack2(a, b); r.y = pack2(c, d); return r; }
; #define EPI_END if (i == 3 && (j & 3) == 3) __builtin_amdgcn_sched_barrier(0); }
; DI float rstd_of(const float* ssq, int m, float invn) { return rsqrtf(ssq[m] * invn + 1e-6f); }
; template <int MODE>
; DI void gemm_phase(const Params& p, const GP& g, unsigned char* smem) {
;     ...
;         EPI_TR_BEGIN
;           const int b = m4 >> 12, s = m4 & 4095;
;           *(u32x2*)(Vt + ((long)b * 1024 + (n - 2048)) * 4096 + s) =
;               pack4(v[0] * rstd_of(g.ssq_in, m4, 1.f / 1024), v[1] * rstd_of(g.ssq_in, m4 + 1, 1.f / 1024),
;                     v[2] * rstd_of(g.ssq_in, m4 + 2, 1.f / 1024), v[3] * rstd_of(g.ssq_in, m4 + 3, 1.f / 1024));
;         EPI_END
	v_lshl_add_u64 v[68:69], v[136:137], 0, s[72:73]
	v_lshl_add_u64 v[70:71], v[68:69], 0, v[128:129]
	v_pk_mul_f32 v[60:61], v[64:65], v[158:159]
	v_pk_mul_f32 v[62:63], v[66:67], v[160:161]
	v_cvt_pk_bf16_f32 v60, v60, v61
	v_cvt_pk_bf16_f32 v61, v62, v63
	global_store_dwordx2 v[70:71], v[60:61], off
	s_nop 0
	v_lshl_add_u64 v[64:65], v[68:69], 0, v[126:127]
	v_pk_mul_f32 v[56:57], v[56:57], v[162:163]
	v_pk_mul_f32 v[58:59], v[58:59], v[164:165]
	v_cvt_pk_bf16_f32 v56, v56, v57
	v_cvt_pk_bf16_f32 v57, v58, v59
	global_store_dwordx2 v[64:65], v[56:57], off
	s_nop 0
	v_lshl_add_u64 v[60:61], v[68:69], 0, v[122:123]
	v_pk_mul_f32 v[52:53], v[52:53], v[166:167]
	v_pk_mul_f32 v[54:55], v[54:55], v[168:169]
	v_cvt_pk_bf16_f32 v52, v52, v53
	v_cvt_pk_bf16_f32 v53, v54, v55
	global_store_dwordx2 v[60:61], v[52:53], off
	s_nop 0
	v_lshl_add_u64 v[56:57], v[68:69], 0, v[116:117]
	v_pk_mul_f32 v[44:45], v[44:45], v[170:171]
	v_pk_mul_f32 v[46:47], v[46:47], v[172:173]
	v_cvt_pk_bf16_f32 v44, v44, v45
	v_cvt_pk_bf16_f32 v45, v46, v47
	global_store_dwordx2 v[56:57], v[44:45], off
	v_lshl_add_u64 v[52:53], v[136:137], 0, s[74:75]
	v_lshl_add_u64 v[54:55], v[52:53], 0, v[128:129]
	v_pk_mul_f32 v[44:45], v[48:49], v[158:159]
	v_pk_mul_f32 v[46:47], v[50:51], v[160:161]
	v_cvt_pk_bf16_f32 v44, v44, v45
	v_cvt_pk_bf16_f32 v45, v46, v47
	global_store_dwordx2 v[54:55], v[44:45], off
	s_nop 0
	v_lshl_add_u64 v[48:49], v[52:53], 0, v[126:127]
	v_pk_mul_f32 v[40:41], v[40:41], v[162:163]
	v_pk_mul_f32 v[42:43], v[42:43], v[164:165]
	v_cvt_pk_bf16_f32 v40, v40, v41
	v_cvt_pk_bf16_f32 v41, v42, v43
	global_store_dwordx2 v[48:49], v[40:41], off
	s_nop 0
	v_lshl_add_u64 v[44:45], v[52:53], 0, v[122:123]
	v_pk_mul_f32 v[36:37], v[36:37], v[166:167]
	v_pk_mul_f32 v[38:39], v[38:39], v[168:169]
	v_cvt_pk_bf16_f32 v36, v36, v37
	v_cvt_pk_bf16_f32 v37, v38, v39
	global_store_dwordx2 v[44:45], v[36:37], off
	s_nop 0
	v_lshl_add_u64 v[40:41], v[52:53], 0, v[116:117]
	v_pk_mul_f32 v[28:29], v[28:29], v[170:171]
	v_pk_mul_f32 v[30:31], v[30:31], v[172:173]
	v_cvt_pk_bf16_f32 v28, v28, v29
	v_cvt_pk_bf16_f32 v29, v30, v31
	global_store_dwordx2 v[40:41], v[28:29], off
	v_lshl_add_u64 v[36:37], v[136:137], 0, s[76:77]
	v_lshl_add_u64 v[38:39], v[36:37], 0, v[128:129]
	v_pk_mul_f32 v[28:29], v[32:33], v[158:159]
	v_pk_mul_f32 v[30:31], v[34:35], v[160:161]
	v_cvt_pk_bf16_f32 v28, v28, v29
	v_cvt_pk_bf16_f32 v29, v30, v31
	global_store_dwordx2 v[38:39], v[28:29], off
	s_nop 0
	v_lshl_add_u64 v[32:33], v[36:37], 0, v[126:127]
	v_pk_mul_f32 v[24:25], v[24:25], v[162:163]
	v_pk_mul_f32 v[26:27], v[26:27], v[164:165]
	v_cvt_pk_bf16_f32 v24, v24, v25
	v_cvt_pk_bf16_f32 v25, v26, v27
	global_store_dwordx2 v[32:33], v[24:25], off
	s_nop 0
	v_lshl_add_u64 v[28:29], v[36:37], 0, v[122:123]
	v_pk_mul_f32 v[20:21], v[20:21], v[166:167]
	v_pk_mul_f32 v[22:23], v[22:23], v[168:169]
	v_cvt_pk_bf16_f32 v20, v20, v21
	v_cvt_pk_bf16_f32 v21, v22, v23
	global_store_dwordx2 v[28:29], v[20:21], off
	s_nop 0
	v_lshl_add_u64 v[24:25], v[36:37], 0, v[116:117]
	v_pk_mul_f32 v[12:13], v[12:13], v[170:171]
	v_pk_mul_f32 v[14:15], v[14:15], v[172:173]
	v_cvt_pk_bf16_f32 v12, v12, v13
	v_cvt_pk_bf16_f32 v13, v14, v15
	global_store_dwordx2 v[24:25], v[12:13], off
	v_lshl_add_u64 v[20:21], v[136:137], 0, s[78:79]
	v_lshl_add_u64 v[22:23], v[20:21], 0, v[128:129]
	v_pk_mul_f32 v[12:13], v[16:17], v[158:159]
	v_pk_mul_f32 v[14:15], v[18:19], v[160:161]
	v_cvt_pk_bf16_f32 v12, v12, v13
	v_cvt_pk_bf16_f32 v13, v14, v15
	global_store_dwordx2 v[22:23], v[12:13], off
	s_nop 0
	v_lshl_add_u64 v[16:17], v[20:21], 0, v[126:127]
	v_pk_mul_f32 v[4:5], v[4:5], v[162:163]
	v_pk_mul_f32 v[6:7], v[6:7], v[164:165]
	v_cvt_pk_bf16_f32 v4, v4, v5
	v_cvt_pk_bf16_f32 v5, v6, v7
	global_store_dwordx2 v[16:17], v[4:5], off
	s_nop 0
	v_lshl_add_u64 v[12:13], v[20:21], 0, v[122:123]
	v_pk_mul_f32 v[0:1], v[0:1], v[166:167]
	v_pk_mul_f32 v[2:3], v[2:3], v[168:169]
	v_cvt_pk_bf16_f32 v0, v0, v1
	v_cvt_pk_bf16_f32 v1, v2, v3
	global_store_dwordx2 v[12:13], v[0:1], off
	s_nop 0
	s_nop 0
	s_nop 0
	s_waitcnt vmcnt(30)
	v_pk_fma_f32 v[0:1], v[196:197], s[58:59], v[130:131] op_sel_hi:[1,0,0]
	s_waitcnt vmcnt(29)
	v_pk_fma_f32 v[2:3], v[198:199], s[58:59], v[130:131] op_sel_hi:[1,0,0]
	v_cmp_gt_f32_e32 vcc, s86, v0
	v_cmp_gt_f32_e64 s[12:13], s86, v1
	v_cmp_gt_f32_e64 s[14:15], s86, v2
	v_cmp_gt_f32_e64 s[16:17], s86, v3
	s_nop 0
	v_pk_mul_f32 v[0:1], v[8:9], v[170:171]
	v_pk_mul_f32 v[2:3], v[10:11], v[172:173]
	v_cvt_pk_bf16_f32 v0, v0, v1
	v_cvt_pk_bf16_f32 v1, v2, v3
	v_lshl_add_u64 v[2:3], v[20:21], 0, v[116:117]
	global_store_dwordx2 v[2:3], v[0:1], off
	s_branch .LBB0_202

; #define MFMA16(a, b, c) __builtin_amdgcn_mfma_f32_16x16x32_bf16((a), (b), (c), 0, 0, 0)
; DI bf16x8 cat8(s16x4 lo, s16x4 hi) { return __builtin_shufflevector(lo, hi, 0, 1, 2, 3, 4, 5, 6, 7); }
; DI void na_phase(const Params& p, const u16* q, const u16* k, const u16* vt, const u16* z, u16* og, unsigned char* smem) {
;     ...
;       const unsigned char* Ks = smem + (ri & 3) * NSTG;
;       const unsigned char* Vs = Ks + 16384;
;       const int ro = rs + ri - r + 7;
; #pragma unroll
;       for (int jj = 0; jj < 2; ++jj) {
;         const int j = jb + jj;
;         const int kcs = min(max(j * 16 - 8, 0), 32);
;         f32x4 sc[2];
; #pragma unroll
;         for (int c2 = 0; c2 < 2; ++c2) {
;           const int row = kcs + c2 * 16 + lq;
;           const bf16x8 kf = *(const bf16x8*)(Ks + row * 256 + (((hh * 4 + lg) ^ (row & 15)) << 4));
;           sc[c2] = MFMA16(kf, qf[jj], (f32x4{0.f, 0.f, 0.f, 0.f}));
;         }
;         const int qcol = j * 16 + lq, win = min(max(qcol - 8, 0), 48);
;         float ps = 0.f;
; #pragma unroll
;         for (int c2 = 0; c2 < 2; ++c2)
; #pragma unroll
;           for (int rr = 0; rr < 4; ++rr) {
;             const int kcol = kcs + c2 * 16 + lg * 4 + rr;
;             const bool valid = (kcol >= win) && (kcol < win + 16);
;             const int co = min(max(kcol - qcol + 15, 0), 30);
;             const float e = valid ? __expf(fminf(sc[c2][rr] + rp[ro * 31 + co], 80.f)) : 0.f;
;             sc[c2][rr] = e;
;             ps += e;
;           }
;         lrun[jj] += ps;
;         const bf16x8 pf = pack8(sc[0], sc[1]);
; #pragma unroll
;         for (int dt = 0; dt < 2; ++dt) {
;           const int vrow = hh * 32 + dt * 16 + lq, vsw = (vrow >> 1) & 7, ch = (kcs >> 3) + (lg >> 1);
;           const unsigned char* vr = Vs + vrow * 128 + (lg & 1) * 8;
;           const s16x4 lo = *(const s16x4*)(vr + ((ch ^ vsw) << 4));
;           const s16x4 hi = *(const s16x4*)(vr + (((ch + 2) ^ vsw) << 4));
;           o[jj][dt] = MFMA16(cat8(lo, hi), pf, o[jj][dt]);
;         }
.LBB0_248:
	s_add_i32 s40, s18, 0xfffe8000
	s_and_b32 vcc_lo, s40, 0x18000
	v_or_b32_e32 v176, vcc_lo, v41
	v_add3_u32 v177, vcc_lo, v45, v46
	v_add_u32_e32 v176, v176, v42
	ds_read_b128 v[108:111], v176
	ds_read_b128 v[112:115], v176 offset:4096
	ds_read_b128 v[116:119], v177
	ds_read_b128 v[120:123], v177 offset:4096
	v_add_u32_e32 v140, s8, v86
	v_add_u32_e32 v141, s8, v85
	v_add_u32_e32 v142, s8, v84
	v_add_u32_e32 v143, s8, v83
	v_add_u32_e32 v144, s8, v82
	v_add_u32_e32 v145, s8, v81
	v_add_u32_e32 v146, s8, v80
	v_add_u32_e32 v147, s8, v79
	ds_read_b32 v140, v140
	ds_read_b32 v141, v141
	ds_read_b32 v142, v142
	ds_read_b32 v143, v143
	ds_read_b32 v144, v144
	ds_read_b32 v145, v145
	ds_read_b32 v146, v146
	ds_read_b32 v147, v147
	s_waitcnt lgkmcnt(11)
	v_mfma_f32_16x16x32_bf16 v[124:127], v[108:111], v[4:7], 0
	s_waitcnt lgkmcnt(10)
	v_mfma_f32_16x16x32_bf16 v[128:131], v[112:115], v[4:7], 0
	s_waitcnt lgkmcnt(9)
	v_mfma_f32_16x16x32_bf16 v[132:135], v[116:119], v[8:11], 0
	s_waitcnt lgkmcnt(8)
	v_mfma_f32_16x16x32_bf16 v[136:139], v[120:123], v[8:11], 0
	v_add_u32_e32 v148, s8, v78
	v_add_u32_e32 v149, s8, v77
	v_add_u32_e32 v150, s8, v76
	v_add_u32_e32 v151, s8, v75
	v_add_u32_e32 v152, s8, v74
	v_add_u32_e32 v153, s8, v73
	v_add_u32_e32 v154, s8, v72
	v_add_u32_e32 v155, s8, v71
	s_waitcnt lgkmcnt(7)
	ds_read_b32 v148, v148
	ds_read_b32 v149, v149
	ds_read_b32 v150, v150
	ds_read_b32 v151, v151
	ds_read_b32 v152, v152
	ds_read_b32 v153, v153
	ds_read_b32 v154, v154
	s_waitcnt lgkmcnt(14)
	ds_read_b32 v155, v155
	s_add_i32 s40, s10, vcc_lo
	v_add3_u32 v172, s40, v39, v40
	v_add_u32_e32 v173, v172, v44
	v_add_u32_e32 v174, v172, v47
	v_add_u32_e32 v175, v172, v48
	v_add_u32_e32 v172, v172, v43
	s_waitcnt lgkmcnt(8)
	v_add_f32_e32 v124, v124, v140
	v_add_f32_e32 v125, v125, v141
	v_add_f32_e32 v126, v126, v142
	v_add_f32_e32 v127, v127, v143
	v_add_f32_e32 v128, v128, v144
	v_add_f32_e32 v129, v129, v145
	v_add_f32_e32 v130, v130, v146
	v_add_f32_e32 v131, v131, v147
	v_min_f32_e32 v124, 0x42a00000, v124
	v_min_f32_e32 v125, 0x42a00000, v125
	v_min_f32_e32 v126, 0x42a00000, v126
	v_min_f32_e32 v127, 0x42a00000, v127
	v_min_f32_e32 v128, 0x42a00000, v128
	v_min_f32_e32 v129, 0x42a00000, v129
	v_min_f32_e32 v130, 0x42a00000, v130
	v_min_f32_e32 v131, 0x42a00000, v131
	v_mul_f32_e32 v124, 0x3fb8aa3b, v124
	v_mul_f32_e32 v125, 0x3fb8aa3b, v125
	v_mul_f32_e32 v126, 0x3fb8aa3b, v126
	v_mul_f32_e32 v127, 0x3fb8aa3b, v127
	v_mul_f32_e32 v128, 0x3fb8aa3b, v128
	v_mul_f32_e32 v129, 0x3fb8aa3b, v129
	v_mul_f32_e32 v130, 0x3fb8aa3b, v130
	v_mul_f32_e32 v131, 0x3fb8aa3b, v131
	v_exp_f32_e32 v124, v124
	v_exp_f32_e32 v125, v125
	v_exp_f32_e32 v126, v126
	v_exp_f32_e32 v127, v127
	v_exp_f32_e32 v128, v128
	v_exp_f32_e32 v129, v129
	v_exp_f32_e32 v130, v130
	v_exp_f32_e32 v131, v131
	v_cndmask_b32_e64 v124, 0, v124, s[24:25]
	v_cndmask_b32_e64 v125, 0, v125, s[26:27]
	v_cndmask_b32_e64 v126, 0, v126, s[28:29]
	v_cndmask_b32_e64 v127, 0, v127, s[30:31]
	v_cndmask_b32_e64 v128, 0, v128, s[54:55]
	v_cndmask_b32_e64 v129, 0, v129, s[56:57]
	v_cndmask_b32_e64 v130, 0, v130, s[58:59]
	v_cndmask_b32_e64 v131, 0, v131, s[60:61]
	ds_read_b64 v[156:157], v172 offset:16384
	ds_read_b64 v[158:159], v173 offset:16384
	ds_read_b64 v[160:161], v172 offset:18432
	ds_read_b64 v[162:163], v173 offset:18432
	v_add_f32_e32 v192, v124, v125
	v_add_f32_e32 v193, v126, v127
	v_add_f32_e32 v194, v128, v129
	v_add_f32_e32 v195, v130, v131
	v_cvt_pk_bf16_f32 v184, v124, v125
	v_cvt_pk_bf16_f32 v185, v126, v127
	v_cvt_pk_bf16_f32 v186, v128, v129
	v_cvt_pk_bf16_f32 v187, v130, v131
	v_add_f32_e32 v192, v192, v193
	v_add_f32_e32 v194, v194, v195
	v_add_f32_e32 v192, v192, v194
	v_add_f32_e32 v88, v88, v192
	s_waitcnt lgkmcnt(2)
	v_mfma_f32_16x16x32_bf16 v[20:23], v[156:159], v[184:187], v[20:23]
	s_waitcnt lgkmcnt(0)
	v_mfma_f32_16x16x32_bf16 v[16:19], v[160:163], v[184:187], v[16:19]
	ds_read_b64 v[164:165], v174 offset:16384
	ds_read_b64 v[166:167], v175 offset:16384
	ds_read_b64 v[168:169], v174 offset:18432
	ds_read_b64 v[170:171], v175 offset:18432
	v_add_f32_e32 v132, v132, v148
	v_add_f32_e32 v133, v133, v149
	v_add_f32_e32 v134, v134, v150
	v_add_f32_e32 v135, v135, v151
	v_add_f32_e32 v136, v136, v152
	v_add_f32_e32 v137, v137, v153
	v_add_f32_e32 v138, v138, v154
	v_add_f32_e32 v139, v139, v155
	v_min_f32_e32 v132, 0x42a00000, v132
	v_min_f32_e32 v133, 0x42a00000, v133
	v_min_f32_e32 v134, 0x42a00000, v134
	v_min_f32_e32 v135, 0x42a00000, v135
	v_min_f32_e32 v136, 0x42a00000, v136
	v_min_f32_e32 v137, 0x42a00000, v137
	v_min_f32_e32 v138, 0x42a00000, v138
	v_min_f32_e32 v139, 0x42a00000, v139
	v_mul_f32_e32 v132, 0x3fb8aa3b, v132
	v_mul_f32_e32 v133, 0x3fb8aa3b, v133
	v_mul_f32_e32 v134, 0x3fb8aa3b, v134
	v_mul_f32_e32 v135, 0x3fb8aa3b, v135
	v_mul_f32_e32 v136, 0x3fb8aa3b, v136
	v_mul_f32_e32 v137, 0x3fb8aa3b, v137
	v_mul_f32_e32 v138, 0x3fb8aa3b, v138
	v_mul_f32_e32 v139, 0x3fb8aa3b, v139
	v_exp_f32_e32 v132, v132
	v_exp_f32_e32 v133, v133
	v_exp_f32_e32 v134, v134
	v_exp_f32_e32 v135, v135
	v_exp_f32_e32 v136, v136
	v_exp_f32_e32 v137, v137
	v_exp_f32_e32 v138, v138
	v_exp_f32_e32 v139, v139
	v_cndmask_b32_e64 v132, 0, v132, s[62:63]
	v_cndmask_b32_e64 v133, 0, v133, s[64:65]
	v_cndmask_b32_e64 v134, 0, v134, s[66:67]
	v_cndmask_b32_e64 v135, 0, v135, s[68:69]
	v_cndmask_b32_e64 v136, 0, v136, s[70:71]
	v_cndmask_b32_e64 v137, 0, v137, s[72:73]
	v_cndmask_b32_e64 v138, 0, v138, s[74:75]
	v_cndmask_b32_e64 v139, 0, v139, s[76:77]
	v_add_f32_e32 v192, v132, v133
	v_add_f32_e32 v193, v134, v135
	v_add_f32_e32 v194, v136, v137
	v_add_f32_e32 v195, v138, v139
	v_cvt_pk_bf16_f32 v188, v132, v133
	v_cvt_pk_bf16_f32 v189, v134, v135
	v_cvt_pk_bf16_f32 v190, v136, v137
	v_cvt_pk_bf16_f32 v191, v138, v139
	v_add_f32_e32 v192, v192, v193
	v_add_f32_e32 v194, v194, v195
	v_add_f32_e32 v192, v192, v194
	v_add_f32_e32 v87, v87, v192
	s_waitcnt lgkmcnt(2)
	v_mfma_f32_16x16x32_bf16 v[12:15], v[164:167], v[188:191], v[12:15]
	s_waitcnt lgkmcnt(0)
	v_mfma_f32_16x16x32_bf16 v[0:3], v[168:171], v[188:191], v[0:3]
	s_add_i32 s9, s9, 1
	s_add_u32 s84, s84, 0x80
	s_addc_u32 s85, s85, 0
	s_add_u32 s90, s90, 64
	s_addc_u32 s91, s91, 0
	s_add_i32 s18, s18, 0x8000
	s_addk_i32 s8, 0x7c
	s_cmpk_eq_i32 s8, 0x3e0
	s_cbranch_scc1 .LBB0_231
	s_branch .LBB0_238

; DI u32x2 pack4(float a, float b, float c, float d) { u32x2 r; r.x = pack2(a, b); r.y = pack2(c, d); return r; }
; DI float rstd_of(const float* ssq, int m, float invn) { return rsqrtf(ssq[m] * invn + 1e-6f); }
; template <int MODE>
; DI void gemm_phase(const Params& p, const GP& g, unsigned char* smem) {
;     ...
;       } else if (u == 10) {
;         u16* kpe = (u16*)g.d2;
; #pragma unroll
;         for (int j = 0; j < 8; ++j)
; #pragma unroll
;           for (int i = 0; i < 2; ++i) {
;             const int m = m0 + wy * 128 + j * 16 + lq, pos = m & 4095;
;             const float rs = rstd_of(g.ssq_in, m, 1.f / 1024);
;             const int f0 = i * 16 + lg * 4;
;             const f32x4 a = acc[i][j], bq = acc[i + 2][j];
;             float lo[4], hi[4];
; #pragma unroll
;             for (int r = 0; r < 4; ++r) {
;               const float2 cssn = *(const float2*)(p.rope + ((long)pos * 32 + f0 + r) * 2);
;               const float x1 = a[r] * rs, x2 = bq[r] * rs;
;               lo[r] = x1 * cssn.x - x2 * cssn.y;
;               hi[r] = x1 * cssn.y + x2 * cssn.x;
;             }
;             *(u32x2*)(kpe + (long)m * 64 + f0) = pack4(lo[0], lo[1], lo[2], lo[3]);
;             *(u32x2*)(kpe + (long)m * 64 + 32 + f0) = pack4(hi[0], hi[1], hi[2], hi[3]);
;           }
.LBB0_358:
	s_cmp_lg_u32 s6, 10
	s_cbranch_scc1 .LBB0_360
	v_or_b32_e32 v132, s60, v148
	v_ashrrev_i32_e32 v133, 31, v132
	v_lshl_add_u64 v[142:143], v[132:133], 2, s[16:17]
	global_load_dword v146, v[142:143], off
	v_lshlrev_b32_e32 v128, 5, v132
	v_and_b32_e32 v128, 0x1f1e0, v128
	v_or_b32_e32 v134, v128, v149
	v_lshlrev_b32_e32 v138, 3, v134
	global_load_dwordx4 v[134:137], v138, s[28:29]
	global_load_dwordx4 v[138:141], v138, s[28:29] offset:16
	s_nop 0
	s_nop 0
	v_or_b32_e32 v128, v128, v151
	v_lshlrev_b64 v[144:145], 7, v[132:133]
	v_lshlrev_b32_e32 v133, 3, v128
	v_lshl_add_u64 v[144:145], v[130:131], 0, v[144:145]
	s_waitcnt vmcnt(2)
	v_fmamk_f32 v128, v146, 0x3a800000, v152
	v_mul_f32_e32 v146, 0x4b800000, v128
	v_cmp_gt_f32_e32 vcc, s67, v128
	s_waitcnt vmcnt(1)
	v_mov_b32_e32 v147, v136
	v_cndmask_b32_e32 v128, v128, v146, vcc
	v_rsq_f32_e32 v128, v128
	v_mov_b32_e32 v146, v134
	s_waitcnt vmcnt(0)
	v_mov_b32_e32 v134, v138
	v_mov_b32_e32 v136, v135
	v_mul_f32_e32 v138, 0x45800000, v128
	v_cndmask_b32_e32 v128, v128, v138, vcc
	v_mov_b32_e32 v135, v140
	v_mov_b32_e32 v140, v139
	v_mov_b32_e32 v168, v128
	v_pk_mul_f32 v[138:139], v[124:125], v[128:129] op_sel_hi:[1,0]
	v_pk_mul_f32 v[154:155], v[116:117], v[168:169] op_sel_hi:[1,0]
	v_pk_mul_f32 v[158:159], v[118:119], v[168:169] op_sel_hi:[1,0]
	v_pk_mul_f32 v[156:157], v[126:127], v[168:169] op_sel_hi:[1,0]
	v_pk_mul_f32 v[160:161], v[136:137], v[154:155]
	v_pk_mul_f32 v[136:137], v[136:137], v[138:139]
	v_pk_mul_f32 v[162:163], v[140:141], v[158:159]
	v_pk_mul_f32 v[140:141], v[156:157], v[140:141]
	v_pk_fma_f32 v[138:139], v[146:147], v[138:139], v[160:161] neg_lo:[0,0,1] neg_hi:[0,0,1]
	v_pk_fma_f32 v[136:137], v[146:147], v[154:155], v[136:137]
	v_pk_fma_f32 v[146:147], v[134:135], v[156:157], v[162:163] neg_lo:[0,0,1] neg_hi:[0,0,1]
	v_pk_fma_f32 v[134:135], v[158:159], v[134:135], v[140:141]
	v_cvt_pk_bf16_f32 v138, v138, v139
	v_cvt_pk_bf16_f32 v139, v146, v147
	v_cvt_pk_bf16_f32 v136, v136, v137
	v_cvt_pk_bf16_f32 v137, v134, v135
	global_store_dwordx2 v[144:145], v[138:139], off
	global_store_dwordx2 v[144:145], v[136:137], off offset:64
	global_load_dwordx4 v[134:137], v133, s[28:29]
	global_load_dwordx4 v[138:141], v133, s[28:29] offset:16
	s_nop 0
	s_nop 0
	s_nop 0
	v_or_b32_e32 v142, 16, v132
	v_lshlrev_b32_e32 v133, 5, v142
	v_and_b32_e32 v133, 0x1f3e0, v133
	v_or_b32_e32 v154, v133, v149
	v_lshlrev_b32_e32 v166, 3, v154
	v_ashrrev_i32_e32 v143, 31, v142
	v_lshl_add_u64 v[146:147], v[142:143], 2, s[16:17]
	global_load_dword v128, v[146:147], off
	v_lshlrev_b64 v[142:143], 7, v[142:143]
	v_lshl_add_u64 v[142:143], v[130:131], 0, v[142:143]
	v_or_b32_e32 v133, v133, v151
	v_lshlrev_b32_e32 v133, 3, v133
	s_waitcnt vmcnt(2)
	v_mov_b32_e32 v154, v134
	v_mov_b32_e32 v155, v136
	v_mov_b32_e32 v136, v135
	s_waitcnt vmcnt(1)
	v_mov_b32_e32 v134, v138
	v_mov_b32_e32 v135, v140
	v_mov_b32_e32 v140, v139
	v_pk_mul_f32 v[138:139], v[120:121], v[168:169] op_sel_hi:[1,0]
	v_pk_mul_f32 v[156:157], v[108:109], v[168:169] op_sel_hi:[1,0]
	v_pk_mul_f32 v[160:161], v[110:111], v[168:169] op_sel_hi:[1,0]
	v_pk_mul_f32 v[158:159], v[122:123], v[168:169] op_sel_hi:[1,0]
	v_pk_mul_f32 v[162:163], v[136:137], v[156:157]
	v_pk_mul_f32 v[136:137], v[136:137], v[138:139]
	v_pk_mul_f32 v[164:165], v[140:141], v[160:161]
	v_pk_mul_f32 v[140:141], v[158:159], v[140:141]
	v_pk_fma_f32 v[138:139], v[154:155], v[138:139], v[162:163] neg_lo:[0,0,1] neg_hi:[0,0,1]
	v_pk_fma_f32 v[136:137], v[154:155], v[156:157], v[136:137]
	v_pk_fma_f32 v[154:155], v[134:135], v[158:159], v[164:165] neg_lo:[0,0,1] neg_hi:[0,0,1]
	v_pk_fma_f32 v[134:135], v[160:161], v[134:135], v[140:141]
	v_cvt_pk_bf16_f32 v138, v138, v139
	v_cvt_pk_bf16_f32 v139, v154, v155
	v_cvt_pk_bf16_f32 v136, v136, v137
	v_cvt_pk_bf16_f32 v137, v134, v135
	global_store_dwordx2 v[144:145], v[138:139], off offset:32
	global_store_dwordx2 v[144:145], v[136:137], off offset:96
	global_load_dwordx4 v[134:137], v166, s[28:29]
	global_load_dwordx4 v[138:141], v166, s[28:29] offset:16
	s_nop 0
	s_nop 0
	s_nop 0
	s_nop 0
	s_waitcnt vmcnt(4)
	v_fmamk_f32 v128, v128, 0x3a800000, v152
	s_waitcnt vmcnt(1)
	v_mov_b32_e32 v144, v134
	v_mul_f32_e32 v134, 0x4b800000, v128
	v_cmp_gt_f32_e32 vcc, s67, v128
	v_mov_b32_e32 v145, v136
	v_mov_b32_e32 v136, v135
	v_cndmask_b32_e32 v128, v128, v134, vcc
	v_rsq_f32_e32 v128, v128
	s_waitcnt vmcnt(0)
	v_mov_b32_e32 v134, v138
	v_mov_b32_e32 v135, v140
	v_mov_b32_e32 v140, v139
	v_mul_f32_e32 v138, 0x45800000, v128
	v_cndmask_b32_e32 v128, v128, v138, vcc
	v_mov_b32_e32 v170, v128
	v_pk_mul_f32 v[138:139], v[112:113], v[128:129] op_sel_hi:[1,0]
	v_pk_mul_f32 v[154:155], v[100:101], v[170:171] op_sel_hi:[1,0]
	v_pk_mul_f32 v[158:159], v[102:103], v[170:171] op_sel_hi:[1,0]
	v_pk_mul_f32 v[156:157], v[114:115], v[170:171] op_sel_hi:[1,0]
	v_pk_mul_f32 v[160:161], v[136:137], v[154:155]
	v_pk_mul_f32 v[136:137], v[136:137], v[138:139]
	v_pk_mul_f32 v[162:163], v[140:141], v[158:159]
	v_pk_mul_f32 v[140:141], v[156:157], v[140:141]
	v_pk_fma_f32 v[138:139], v[144:145], v[138:139], v[160:161] neg_lo:[0,0,1] neg_hi:[0,0,1]
	v_pk_fma_f32 v[136:137], v[144:145], v[154:155], v[136:137]
	v_pk_fma_f32 v[144:145], v[134:135], v[156:157], v[162:163] neg_lo:[0,0,1] neg_hi:[0,0,1]
	v_pk_fma_f32 v[134:135], v[158:159], v[134:135], v[140:141]
	v_cvt_pk_bf16_f32 v138, v138, v139
	v_cvt_pk_bf16_f32 v139, v144, v145
	v_cvt_pk_bf16_f32 v136, v136, v137
	v_cvt_pk_bf16_f32 v137, v134, v135
	global_store_dwordx2 v[142:143], v[138:139], off
	global_store_dwordx2 v[142:143], v[136:137], off offset:64
	global_load_dwordx4 v[134:137], v133, s[28:29]
	global_load_dwordx4 v[138:141], v133, s[28:29] offset:16
	s_nop 0
	s_nop 0
	s_nop 0
	v_or_b32_e32 v144, 32, v132
	v_lshlrev_b32_e32 v133, 5, v144
	v_and_b32_e32 v133, 0x1f5e0, v133
	v_or_b32_e32 v154, v133, v149
	v_lshlrev_b32_e32 v166, 3, v154
	v_ashrrev_i32_e32 v145, 31, v144
	v_lshl_add_u64 v[146:147], v[144:145], 2, s[16:17]
	global_load_dword v128, v[146:147], off
	v_or_b32_e32 v133, v133, v151
	v_lshlrev_b32_e32 v133, 3, v133
	s_waitcnt vmcnt(2)
; DI u32x2 pack4(float a, float b, float c, float d) { u32x2 r; r.x = pack2(a, b); r.y = pack2(c, d); return r; }
; DI float rstd_of(const float* ssq, int m, float invn) { return rsqrtf(ssq[m] * invn + 1e-6f); }
; template <int MODE>
; DI void gemm_phase(const Params& p, const GP& g, unsigned char* smem) {
;     ...
; #pragma unroll
;         for (int j = 0; j < 8; ++j)
; #pragma unroll
;           for (int i = 0; i < 2; ++i) {
;             const int m = m0 + wy * 128 + j * 16 + lq, pos = m & 4095;
;             const float rs = rstd_of(g.ssq_in, m, 1.f / 1024);
;             const int f0 = i * 16 + lg * 4;
;             const f32x4 a = acc[i][j], bq = acc[i + 2][j];
;             float lo[4], hi[4];
; #pragma unroll
;             for (int r = 0; r < 4; ++r) {
;               const float2 cssn = *(const float2*)(p.rope + ((long)pos * 32 + f0 + r) * 2);
;               const float x1 = a[r] * rs, x2 = bq[r] * rs;
;               lo[r] = x1 * cssn.x - x2 * cssn.y;
;               hi[r] = x1 * cssn.y + x2 * cssn.x;
;             }
;             *(u32x2*)(kpe + (long)m * 64 + f0) = pack4(lo[0], lo[1], lo[2], lo[3]);
;             *(u32x2*)(kpe + (long)m * 64 + 32 + f0) = pack4(hi[0], hi[1], hi[2], hi[3]);
;           }
	v_mov_b32_e32 v154, v134
	v_mov_b32_e32 v155, v136
	v_mov_b32_e32 v136, v135
	s_waitcnt vmcnt(1)
	v_mov_b32_e32 v134, v138
	v_mov_b32_e32 v135, v140
	v_mov_b32_e32 v140, v139
	v_pk_mul_f32 v[138:139], v[104:105], v[170:171] op_sel_hi:[1,0]
	v_pk_mul_f32 v[156:157], v[92:93], v[170:171] op_sel_hi:[1,0]
	v_pk_mul_f32 v[160:161], v[94:95], v[170:171] op_sel_hi:[1,0]
	v_pk_mul_f32 v[158:159], v[106:107], v[170:171] op_sel_hi:[1,0]
	v_pk_mul_f32 v[162:163], v[136:137], v[156:157]
	v_pk_mul_f32 v[136:137], v[136:137], v[138:139]
	v_pk_mul_f32 v[164:165], v[140:141], v[160:161]
	v_pk_mul_f32 v[140:141], v[158:159], v[140:141]
	v_pk_fma_f32 v[138:139], v[154:155], v[138:139], v[162:163] neg_lo:[0,0,1] neg_hi:[0,0,1]
	v_pk_fma_f32 v[136:137], v[154:155], v[156:157], v[136:137]
	v_pk_fma_f32 v[154:155], v[134:135], v[158:159], v[164:165] neg_lo:[0,0,1] neg_hi:[0,0,1]
	v_pk_fma_f32 v[134:135], v[160:161], v[134:135], v[140:141]
	v_cvt_pk_bf16_f32 v138, v138, v139
	v_cvt_pk_bf16_f32 v139, v154, v155
	v_cvt_pk_bf16_f32 v136, v136, v137
	v_cvt_pk_bf16_f32 v137, v134, v135
	global_store_dwordx2 v[142:143], v[138:139], off offset:32
	global_store_dwordx2 v[142:143], v[136:137], off offset:96
	global_load_dwordx4 v[134:137], v166, s[28:29]
	global_load_dwordx4 v[138:141], v166, s[28:29] offset:16
	s_nop 0
	s_nop 0
	s_nop 0
	s_nop 0
	v_lshlrev_b64 v[142:143], 7, v[144:145]
	v_lshl_add_u64 v[142:143], v[130:131], 0, v[142:143]
	s_waitcnt vmcnt(4)
	v_fmamk_f32 v128, v128, 0x3a800000, v152
	s_waitcnt vmcnt(1)
	v_mov_b32_e32 v144, v134
	v_mul_f32_e32 v134, 0x4b800000, v128
	v_cmp_gt_f32_e32 vcc, s67, v128
	v_mov_b32_e32 v145, v136
	v_mov_b32_e32 v136, v135
	v_cndmask_b32_e32 v128, v128, v134, vcc
	v_rsq_f32_e32 v128, v128
	s_waitcnt vmcnt(0)
	v_mov_b32_e32 v134, v138
	v_mov_b32_e32 v135, v140
	v_mov_b32_e32 v140, v139
	v_mul_f32_e32 v138, 0x45800000, v128
	v_cndmask_b32_e32 v128, v128, v138, vcc
	v_mov_b32_e32 v172, v128
	v_pk_mul_f32 v[138:139], v[96:97], v[128:129] op_sel_hi:[1,0]
	v_pk_mul_f32 v[154:155], v[84:85], v[172:173] op_sel_hi:[1,0]
	v_pk_mul_f32 v[158:159], v[86:87], v[172:173] op_sel_hi:[1,0]
	v_pk_mul_f32 v[156:157], v[98:99], v[172:173] op_sel_hi:[1,0]
	v_pk_mul_f32 v[160:161], v[136:137], v[154:155]
	v_pk_mul_f32 v[136:137], v[136:137], v[138:139]
	v_pk_mul_f32 v[162:163], v[140:141], v[158:159]
	v_pk_mul_f32 v[140:141], v[156:157], v[140:141]
	v_pk_fma_f32 v[138:139], v[144:145], v[138:139], v[160:161] neg_lo:[0,0,1] neg_hi:[0,0,1]
	v_pk_fma_f32 v[136:137], v[144:145], v[154:155], v[136:137]
	v_pk_fma_f32 v[144:145], v[134:135], v[156:157], v[162:163] neg_lo:[0,0,1] neg_hi:[0,0,1]
	v_pk_fma_f32 v[134:135], v[158:159], v[134:135], v[140:141]
	v_cvt_pk_bf16_f32 v138, v138, v139
	v_cvt_pk_bf16_f32 v139, v144, v145
	v_cvt_pk_bf16_f32 v136, v136, v137
	v_cvt_pk_bf16_f32 v137, v134, v135
	global_store_dwordx2 v[142:143], v[138:139], off
	global_store_dwordx2 v[142:143], v[136:137], off offset:64
	global_load_dwordx4 v[134:137], v133, s[28:29]
	global_load_dwordx4 v[138:141], v133, s[28:29] offset:16
	s_nop 0
	s_nop 0
	s_nop 0
	v_or_b32_e32 v144, 48, v132
	v_lshlrev_b32_e32 v133, 5, v144
	v_and_b32_e32 v133, 0x1f7e0, v133
	v_or_b32_e32 v154, v133, v149
	v_lshlrev_b32_e32 v166, 3, v154
	v_ashrrev_i32_e32 v145, 31, v144
	v_lshl_add_u64 v[146:147], v[144:145], 2, s[16:17]
	global_load_dword v128, v[146:147], off
	v_or_b32_e32 v133, v133, v151
	v_lshlrev_b32_e32 v133, 3, v133
	s_waitcnt vmcnt(2)
	v_mov_b32_e32 v154, v134
	v_mov_b32_e32 v155, v136
	v_mov_b32_e32 v136, v135
	s_waitcnt vmcnt(1)
	v_mov_b32_e32 v134, v138
	v_mov_b32_e32 v135, v140
	v_mov_b32_e32 v140, v139
	v_pk_mul_f32 v[138:139], v[88:89], v[172:173] op_sel_hi:[1,0]
	v_pk_mul_f32 v[156:157], v[76:77], v[172:173] op_sel_hi:[1,0]
	v_pk_mul_f32 v[160:161], v[78:79], v[172:173] op_sel_hi:[1,0]
	v_pk_mul_f32 v[158:159], v[90:91], v[172:173] op_sel_hi:[1,0]
	v_pk_mul_f32 v[162:163], v[136:137], v[156:157]
	v_pk_mul_f32 v[136:137], v[136:137], v[138:139]
	v_pk_mul_f32 v[164:165], v[140:141], v[160:161]
	v_pk_mul_f32 v[140:141], v[158:159], v[140:141]
	v_pk_fma_f32 v[138:139], v[154:155], v[138:139], v[162:163] neg_lo:[0,0,1] neg_hi:[0,0,1]
	v_pk_fma_f32 v[136:137], v[154:155], v[156:157], v[136:137]
	v_pk_fma_f32 v[154:155], v[134:135], v[158:159], v[164:165] neg_lo:[0,0,1] neg_hi:[0,0,1]
	v_pk_fma_f32 v[134:135], v[160:161], v[134:135], v[140:141]
	v_cvt_pk_bf16_f32 v138, v138, v139
	v_cvt_pk_bf16_f32 v139, v154, v155
	v_cvt_pk_bf16_f32 v136, v136, v137
	v_cvt_pk_bf16_f32 v137, v134, v135
	global_store_dwordx2 v[142:143], v[138:139], off offset:32
	global_store_dwordx2 v[142:143], v[136:137], off offset:96
	global_load_dwordx4 v[134:137], v166, s[28:29]
	global_load_dwordx4 v[138:141], v166, s[28:29] offset:16
	s_nop 0
	s_nop 0
	s_nop 0
	s_nop 0
	v_lshlrev_b64 v[142:143], 7, v[144:145]
	v_lshl_add_u64 v[142:143], v[130:131], 0, v[142:143]
	s_waitcnt vmcnt(4)
	v_fmamk_f32 v128, v128, 0x3a800000, v152
	s_waitcnt vmcnt(1)
	v_mov_b32_e32 v144, v134
	v_mul_f32_e32 v134, 0x4b800000, v128
	v_cmp_gt_f32_e32 vcc, s67, v128
	v_mov_b32_e32 v145, v136
	v_mov_b32_e32 v136, v135
	v_cndmask_b32_e32 v128, v128, v134, vcc
	v_rsq_f32_e32 v128, v128
	s_waitcnt vmcnt(0)
; DI u32x2 pack4(float a, float b, float c, float d) { u32x2 r; r.x = pack2(a, b); r.y = pack2(c, d); return r; }
; DI float rstd_of(const float* ssq, int m, float invn) { return rsqrtf(ssq[m] * invn + 1e-6f); }
; template <int MODE>
; DI void gemm_phase(const Params& p, const GP& g, unsigned char* smem) {
;     ...
; #pragma unroll
;         for (int j = 0; j < 8; ++j)
; #pragma unroll
;           for (int i = 0; i < 2; ++i) {
;             const int m = m0 + wy * 128 + j * 16 + lq, pos = m & 4095;
;             const float rs = rstd_of(g.ssq_in, m, 1.f / 1024);
;             const int f0 = i * 16 + lg * 4;
;             const f32x4 a = acc[i][j], bq = acc[i + 2][j];
;             float lo[4], hi[4];
; #pragma unroll
;             for (int r = 0; r < 4; ++r) {
;               const float2 cssn = *(const float2*)(p.rope + ((long)pos * 32 + f0 + r) * 2);
;               const float x1 = a[r] * rs, x2 = bq[r] * rs;
;               lo[r] = x1 * cssn.x - x2 * cssn.y;
;               hi[r] = x1 * cssn.y + x2 * cssn.x;
;             }
;             *(u32x2*)(kpe + (long)m * 64 + f0) = pack4(lo[0], lo[1], lo[2], lo[3]);
;             *(u32x2*)(kpe + (long)m * 64 + 32 + f0) = pack4(hi[0], hi[1], hi[2], hi[3]);
;           }
	v_mov_b32_e32 v134, v138
	v_mov_b32_e32 v135, v140
	v_mov_b32_e32 v140, v139
	v_mul_f32_e32 v138, 0x45800000, v128
	v_cndmask_b32_e32 v128, v128, v138, vcc
	v_mov_b32_e32 v174, v128
	v_pk_mul_f32 v[138:139], v[80:81], v[128:129] op_sel_hi:[1,0]
	v_pk_mul_f32 v[154:155], v[68:69], v[174:175] op_sel_hi:[1,0]
	v_pk_mul_f32 v[158:159], v[70:71], v[174:175] op_sel_hi:[1,0]
	v_pk_mul_f32 v[156:157], v[82:83], v[174:175] op_sel_hi:[1,0]
	v_pk_mul_f32 v[160:161], v[136:137], v[154:155]
	v_pk_mul_f32 v[136:137], v[136:137], v[138:139]
	v_pk_mul_f32 v[162:163], v[140:141], v[158:159]
	v_pk_mul_f32 v[140:141], v[156:157], v[140:141]
	v_pk_fma_f32 v[138:139], v[144:145], v[138:139], v[160:161] neg_lo:[0,0,1] neg_hi:[0,0,1]
	v_pk_fma_f32 v[136:137], v[144:145], v[154:155], v[136:137]
	v_pk_fma_f32 v[144:145], v[134:135], v[156:157], v[162:163] neg_lo:[0,0,1] neg_hi:[0,0,1]
	v_pk_fma_f32 v[134:135], v[158:159], v[134:135], v[140:141]
	v_cvt_pk_bf16_f32 v138, v138, v139
	v_cvt_pk_bf16_f32 v139, v144, v145
	v_cvt_pk_bf16_f32 v136, v136, v137
	v_cvt_pk_bf16_f32 v137, v134, v135
	global_store_dwordx2 v[142:143], v[138:139], off
	global_store_dwordx2 v[142:143], v[136:137], off offset:64
	global_load_dwordx4 v[134:137], v133, s[28:29]
	global_load_dwordx4 v[138:141], v133, s[28:29] offset:16
	s_nop 0
	s_nop 0
	s_nop 0
	v_or_b32_e32 v144, 64, v132
	v_lshlrev_b32_e32 v133, 5, v144
	v_and_b32_e32 v133, 0x1f9e0, v133
	v_or_b32_e32 v154, v133, v149
	v_lshlrev_b32_e32 v166, 3, v154
	v_ashrrev_i32_e32 v145, 31, v144
	v_lshl_add_u64 v[146:147], v[144:145], 2, s[16:17]
	global_load_dword v128, v[146:147], off
	v_or_b32_e32 v133, v133, v151
	v_lshlrev_b32_e32 v133, 3, v133
	s_waitcnt vmcnt(2)
	v_mov_b32_e32 v154, v134
	v_mov_b32_e32 v155, v136
	v_mov_b32_e32 v136, v135
	s_waitcnt vmcnt(1)
	v_mov_b32_e32 v134, v138
	v_mov_b32_e32 v135, v140
	v_mov_b32_e32 v140, v139
	v_pk_mul_f32 v[138:139], v[72:73], v[174:175] op_sel_hi:[1,0]
	v_pk_mul_f32 v[156:157], v[60:61], v[174:175] op_sel_hi:[1,0]
	v_pk_mul_f32 v[160:161], v[62:63], v[174:175] op_sel_hi:[1,0]
	v_pk_mul_f32 v[158:159], v[74:75], v[174:175] op_sel_hi:[1,0]
	v_pk_mul_f32 v[162:163], v[136:137], v[156:157]
	v_pk_mul_f32 v[136:137], v[136:137], v[138:139]
	v_pk_mul_f32 v[164:165], v[140:141], v[160:161]
	v_pk_mul_f32 v[140:141], v[158:159], v[140:141]
	v_pk_fma_f32 v[138:139], v[154:155], v[138:139], v[162:163] neg_lo:[0,0,1] neg_hi:[0,0,1]
	v_pk_fma_f32 v[136:137], v[154:155], v[156:157], v[136:137]
	v_pk_fma_f32 v[154:155], v[134:135], v[158:159], v[164:165] neg_lo:[0,0,1] neg_hi:[0,0,1]
	v_pk_fma_f32 v[134:135], v[160:161], v[134:135], v[140:141]
	v_cvt_pk_bf16_f32 v138, v138, v139
	v_cvt_pk_bf16_f32 v139, v154, v155
	v_cvt_pk_bf16_f32 v136, v136, v137
	v_cvt_pk_bf16_f32 v137, v134, v135
	global_store_dwordx2 v[142:143], v[138:139], off offset:32
	global_store_dwordx2 v[142:143], v[136:137], off offset:96
	global_load_dwordx4 v[134:137], v166, s[28:29]
	global_load_dwordx4 v[138:141], v166, s[28:29] offset:16
	s_nop 0
	s_nop 0
	s_nop 0
	s_nop 0
	v_lshlrev_b64 v[142:143], 7, v[144:145]
	v_lshl_add_u64 v[142:143], v[130:131], 0, v[142:143]
	s_waitcnt vmcnt(4)
	v_fmamk_f32 v128, v128, 0x3a800000, v152
	s_waitcnt vmcnt(1)
	v_mov_b32_e32 v144, v134
	v_mul_f32_e32 v134, 0x4b800000, v128
	v_cmp_gt_f32_e32 vcc, s67, v128
	v_mov_b32_e32 v145, v136
	v_mov_b32_e32 v136, v135
	v_cndmask_b32_e32 v128, v128, v134, vcc
	v_rsq_f32_e32 v128, v128
	s_waitcnt vmcnt(0)
	v_mov_b32_e32 v134, v138
	v_mov_b32_e32 v135, v140
	v_mov_b32_e32 v140, v139
	v_mul_f32_e32 v138, 0x45800000, v128
	v_cndmask_b32_e32 v128, v128, v138, vcc
	v_mov_b32_e32 v176, v128
	v_pk_mul_f32 v[138:139], v[64:65], v[128:129] op_sel_hi:[1,0]
	v_pk_mul_f32 v[154:155], v[52:53], v[176:177] op_sel_hi:[1,0]
	v_pk_mul_f32 v[158:159], v[54:55], v[176:177] op_sel_hi:[1,0]
	v_pk_mul_f32 v[156:157], v[66:67], v[176:177] op_sel_hi:[1,0]
	v_pk_mul_f32 v[160:161], v[136:137], v[154:155]
	v_pk_mul_f32 v[136:137], v[136:137], v[138:139]
	v_pk_mul_f32 v[162:163], v[140:141], v[158:159]
	v_pk_mul_f32 v[140:141], v[156:157], v[140:141]
	v_pk_fma_f32 v[138:139], v[144:145], v[138:139], v[160:161] neg_lo:[0,0,1] neg_hi:[0,0,1]
	v_pk_fma_f32 v[136:137], v[144:145], v[154:155], v[136:137]
	v_pk_fma_f32 v[144:145], v[134:135], v[156:157], v[162:163] neg_lo:[0,0,1] neg_hi:[0,0,1]
	v_pk_fma_f32 v[134:135], v[158:159], v[134:135], v[140:141]
	v_cvt_pk_bf16_f32 v138, v138, v139
	v_cvt_pk_bf16_f32 v139, v144, v145
	v_cvt_pk_bf16_f32 v136, v136, v137
	v_cvt_pk_bf16_f32 v137, v134, v135
	global_store_dwordx2 v[142:143], v[138:139], off
	global_store_dwordx2 v[142:143], v[136:137], off offset:64
	global_load_dwordx4 v[134:137], v133, s[28:29]
	global_load_dwordx4 v[138:141], v133, s[28:29] offset:16
	s_nop 0
	s_nop 0
	s_nop 0
	v_or_b32_e32 v144, 0x50, v132
	v_lshlrev_b32_e32 v133, 5, v144
	v_and_b32_e32 v133, 0x1fbe0, v133
	v_or_b32_e32 v154, v133, v149
	v_lshlrev_b32_e32 v166, 3, v154
	v_ashrrev_i32_e32 v145, 31, v144
	v_lshl_add_u64 v[146:147], v[144:145], 2, s[16:17]
	global_load_dword v128, v[146:147], off
	v_or_b32_e32 v133, v133, v151
	v_lshlrev_b32_e32 v133, 3, v133
	s_waitcnt vmcnt(2)
	v_mov_b32_e32 v154, v134
	v_mov_b32_e32 v155, v136
	v_mov_b32_e32 v136, v135
	s_waitcnt vmcnt(1)
; DI u32x2 pack4(float a, float b, float c, float d) { u32x2 r; r.x = pack2(a, b); r.y = pack2(c, d); return r; }
; DI float rstd_of(const float* ssq, int m, float invn) { return rsqrtf(ssq[m] * invn + 1e-6f); }
; template <int MODE>
; DI void gemm_phase(const Params& p, const GP& g, unsigned char* smem) {
;     ...
; #pragma unroll
;         for (int j = 0; j < 8; ++j)
; #pragma unroll
;           for (int i = 0; i < 2; ++i) {
;             const int m = m0 + wy * 128 + j * 16 + lq, pos = m & 4095;
;             const float rs = rstd_of(g.ssq_in, m, 1.f / 1024);
;             const int f0 = i * 16 + lg * 4;
;             const f32x4 a = acc[i][j], bq = acc[i + 2][j];
;             float lo[4], hi[4];
; #pragma unroll
;             for (int r = 0; r < 4; ++r) {
;               const float2 cssn = *(const float2*)(p.rope + ((long)pos * 32 + f0 + r) * 2);
;               const float x1 = a[r] * rs, x2 = bq[r] * rs;
;               lo[r] = x1 * cssn.x - x2 * cssn.y;
;               hi[r] = x1 * cssn.y + x2 * cssn.x;
;             }
;             *(u32x2*)(kpe + (long)m * 64 + f0) = pack4(lo[0], lo[1], lo[2], lo[3]);
;             *(u32x2*)(kpe + (long)m * 64 + 32 + f0) = pack4(hi[0], hi[1], hi[2], hi[3]);
;           }
	v_mov_b32_e32 v134, v138
	v_mov_b32_e32 v135, v140
	v_mov_b32_e32 v140, v139
	v_pk_mul_f32 v[138:139], v[56:57], v[176:177] op_sel_hi:[1,0]
	v_pk_mul_f32 v[156:157], v[44:45], v[176:177] op_sel_hi:[1,0]
	v_pk_mul_f32 v[160:161], v[46:47], v[176:177] op_sel_hi:[1,0]
	v_pk_mul_f32 v[158:159], v[58:59], v[176:177] op_sel_hi:[1,0]
	v_pk_mul_f32 v[162:163], v[136:137], v[156:157]
	v_pk_mul_f32 v[136:137], v[136:137], v[138:139]
	v_pk_mul_f32 v[164:165], v[140:141], v[160:161]
	v_pk_mul_f32 v[140:141], v[158:159], v[140:141]
	v_pk_fma_f32 v[138:139], v[154:155], v[138:139], v[162:163] neg_lo:[0,0,1] neg_hi:[0,0,1]
	v_pk_fma_f32 v[136:137], v[154:155], v[156:157], v[136:137]
	v_pk_fma_f32 v[154:155], v[134:135], v[158:159], v[164:165] neg_lo:[0,0,1] neg_hi:[0,0,1]
	v_pk_fma_f32 v[134:135], v[160:161], v[134:135], v[140:141]
	v_cvt_pk_bf16_f32 v138, v138, v139
	v_cvt_pk_bf16_f32 v139, v154, v155
	v_cvt_pk_bf16_f32 v136, v136, v137
	v_cvt_pk_bf16_f32 v137, v134, v135
	global_store_dwordx2 v[142:143], v[138:139], off offset:32
	global_store_dwordx2 v[142:143], v[136:137], off offset:96
	global_load_dwordx4 v[134:137], v166, s[28:29]
	global_load_dwordx4 v[138:141], v166, s[28:29] offset:16
	s_nop 0
	s_nop 0
	s_nop 0
	s_nop 0
	v_lshlrev_b64 v[142:143], 7, v[144:145]
	v_lshl_add_u64 v[142:143], v[130:131], 0, v[142:143]
	s_waitcnt vmcnt(4)
	v_fmamk_f32 v128, v128, 0x3a800000, v152
	s_waitcnt vmcnt(1)
	v_mov_b32_e32 v144, v134
	v_mul_f32_e32 v134, 0x4b800000, v128
	v_cmp_gt_f32_e32 vcc, s67, v128
	v_mov_b32_e32 v145, v136
	v_mov_b32_e32 v136, v135
	v_cndmask_b32_e32 v128, v128, v134, vcc
	v_rsq_f32_e32 v128, v128
	s_waitcnt vmcnt(0)
	v_mov_b32_e32 v134, v138
	v_mov_b32_e32 v135, v140
	v_mov_b32_e32 v140, v139
	v_mul_f32_e32 v138, 0x45800000, v128
	v_cndmask_b32_e32 v128, v128, v138, vcc
	v_mov_b32_e32 v178, v128
	v_pk_mul_f32 v[138:139], v[48:49], v[128:129] op_sel_hi:[1,0]
	v_pk_mul_f32 v[154:155], v[36:37], v[178:179] op_sel_hi:[1,0]
	v_pk_mul_f32 v[158:159], v[38:39], v[178:179] op_sel_hi:[1,0]
	v_pk_mul_f32 v[156:157], v[50:51], v[178:179] op_sel_hi:[1,0]
	v_pk_mul_f32 v[160:161], v[136:137], v[154:155]
	v_pk_mul_f32 v[136:137], v[136:137], v[138:139]
	v_pk_mul_f32 v[162:163], v[140:141], v[158:159]
	v_pk_mul_f32 v[140:141], v[156:157], v[140:141]
	v_pk_fma_f32 v[138:139], v[144:145], v[138:139], v[160:161] neg_lo:[0,0,1] neg_hi:[0,0,1]
	v_pk_fma_f32 v[136:137], v[144:145], v[154:155], v[136:137]
	v_pk_fma_f32 v[144:145], v[134:135], v[156:157], v[162:163] neg_lo:[0,0,1] neg_hi:[0,0,1]
	v_pk_fma_f32 v[134:135], v[158:159], v[134:135], v[140:141]
	v_cvt_pk_bf16_f32 v138, v138, v139
	v_cvt_pk_bf16_f32 v139, v144, v145
	v_cvt_pk_bf16_f32 v136, v136, v137
	v_cvt_pk_bf16_f32 v137, v134, v135
	global_store_dwordx2 v[142:143], v[138:139], off
	global_store_dwordx2 v[142:143], v[136:137], off offset:64
	global_load_dwordx4 v[134:137], v133, s[28:29]
	global_load_dwordx4 v[138:141], v133, s[28:29] offset:16
	s_nop 0
	s_nop 0
	s_nop 0
	v_or_b32_e32 v144, 0x60, v132
	v_lshlrev_b32_e32 v133, 5, v144
	v_and_b32_e32 v133, 0x1fde0, v133
	v_or_b32_e32 v154, v133, v149
	v_lshlrev_b32_e32 v166, 3, v154
	v_ashrrev_i32_e32 v145, 31, v144
	v_lshl_add_u64 v[146:147], v[144:145], 2, s[16:17]
	global_load_dword v128, v[146:147], off
	v_or_b32_e32 v133, v133, v151
	v_lshlrev_b32_e32 v133, 3, v133
	s_waitcnt vmcnt(2)
	v_mov_b32_e32 v154, v134
	v_mov_b32_e32 v155, v136
	v_mov_b32_e32 v136, v135
	s_waitcnt vmcnt(1)
	v_mov_b32_e32 v134, v138
	v_mov_b32_e32 v135, v140
	v_mov_b32_e32 v140, v139
	v_pk_mul_f32 v[138:139], v[40:41], v[178:179] op_sel_hi:[1,0]
	v_pk_mul_f32 v[156:157], v[28:29], v[178:179] op_sel_hi:[1,0]
	v_pk_mul_f32 v[160:161], v[30:31], v[178:179] op_sel_hi:[1,0]
	v_pk_mul_f32 v[158:159], v[42:43], v[178:179] op_sel_hi:[1,0]
	v_pk_mul_f32 v[162:163], v[136:137], v[156:157]
	v_pk_mul_f32 v[136:137], v[136:137], v[138:139]
	v_pk_mul_f32 v[164:165], v[140:141], v[160:161]
	v_pk_mul_f32 v[140:141], v[158:159], v[140:141]
	v_pk_fma_f32 v[138:139], v[154:155], v[138:139], v[162:163] neg_lo:[0,0,1] neg_hi:[0,0,1]
	v_pk_fma_f32 v[136:137], v[154:155], v[156:157], v[136:137]
	v_pk_fma_f32 v[154:155], v[134:135], v[158:159], v[164:165] neg_lo:[0,0,1] neg_hi:[0,0,1]
	v_pk_fma_f32 v[134:135], v[160:161], v[134:135], v[140:141]
	v_cvt_pk_bf16_f32 v138, v138, v139
	v_cvt_pk_bf16_f32 v139, v154, v155
	v_cvt_pk_bf16_f32 v136, v136, v137
	v_cvt_pk_bf16_f32 v137, v134, v135
	global_store_dwordx2 v[142:143], v[138:139], off offset:32
	global_store_dwordx2 v[142:143], v[136:137], off offset:96
	global_load_dwordx4 v[134:137], v166, s[28:29]
	global_load_dwordx4 v[138:141], v166, s[28:29] offset:16
	s_nop 0
	s_nop 0
	s_nop 0
	s_nop 0
	v_lshlrev_b64 v[142:143], 7, v[144:145]
	v_lshl_add_u64 v[142:143], v[130:131], 0, v[142:143]
	s_waitcnt vmcnt(4)
	v_fmamk_f32 v128, v128, 0x3a800000, v152
	s_waitcnt vmcnt(1)
	v_mov_b32_e32 v144, v134
	v_mul_f32_e32 v134, 0x4b800000, v128
	v_cmp_gt_f32_e32 vcc, s67, v128
	v_mov_b32_e32 v145, v136
	v_mov_b32_e32 v136, v135
	v_cndmask_b32_e32 v128, v128, v134, vcc
	v_rsq_f32_e32 v128, v128
	s_waitcnt vmcnt(0)
; DI u32x2 pack4(float a, float b, float c, float d) { u32x2 r; r.x = pack2(a, b); r.y = pack2(c, d); return r; }
; DI float rstd_of(const float* ssq, int m, float invn) { return rsqrtf(ssq[m] * invn + 1e-6f); }
; template <int MODE>
; DI void gemm_phase(const Params& p, const GP& g, unsigned char* smem) {
;     ...
; #pragma unroll
;         for (int j = 0; j < 8; ++j)
; #pragma unroll
;           for (int i = 0; i < 2; ++i) {
;             const int m = m0 + wy * 128 + j * 16 + lq, pos = m & 4095;
;             const float rs = rstd_of(g.ssq_in, m, 1.f / 1024);
;             const int f0 = i * 16 + lg * 4;
;             const f32x4 a = acc[i][j], bq = acc[i + 2][j];
;             float lo[4], hi[4];
; #pragma unroll
;             for (int r = 0; r < 4; ++r) {
;               const float2 cssn = *(const float2*)(p.rope + ((long)pos * 32 + f0 + r) * 2);
;               const float x1 = a[r] * rs, x2 = bq[r] * rs;
;               lo[r] = x1 * cssn.x - x2 * cssn.y;
;               hi[r] = x1 * cssn.y + x2 * cssn.x;
;             }
;             *(u32x2*)(kpe + (long)m * 64 + f0) = pack4(lo[0], lo[1], lo[2], lo[3]);
;             *(u32x2*)(kpe + (long)m * 64 + 32 + f0) = pack4(hi[0], hi[1], hi[2], hi[3]);
;           }
	v_mov_b32_e32 v134, v138
	v_mov_b32_e32 v135, v140
	v_mov_b32_e32 v140, v139
	v_mul_f32_e32 v138, 0x45800000, v128
	v_cndmask_b32_e32 v128, v128, v138, vcc
	v_mov_b32_e32 v184, v128
	v_pk_mul_f32 v[138:139], v[32:33], v[128:129] op_sel_hi:[1,0]
	v_pk_mul_f32 v[154:155], v[20:21], v[184:185] op_sel_hi:[1,0]
	v_pk_mul_f32 v[158:159], v[22:23], v[184:185] op_sel_hi:[1,0]
	v_pk_mul_f32 v[156:157], v[34:35], v[184:185] op_sel_hi:[1,0]
	v_pk_mul_f32 v[160:161], v[136:137], v[154:155]
	v_pk_mul_f32 v[136:137], v[136:137], v[138:139]
	v_pk_mul_f32 v[162:163], v[140:141], v[158:159]
	v_pk_mul_f32 v[140:141], v[156:157], v[140:141]
	v_pk_fma_f32 v[138:139], v[144:145], v[138:139], v[160:161] neg_lo:[0,0,1] neg_hi:[0,0,1]
	v_pk_fma_f32 v[136:137], v[144:145], v[154:155], v[136:137]
	v_pk_fma_f32 v[144:145], v[134:135], v[156:157], v[162:163] neg_lo:[0,0,1] neg_hi:[0,0,1]
	v_pk_fma_f32 v[134:135], v[158:159], v[134:135], v[140:141]
	v_cvt_pk_bf16_f32 v138, v138, v139
	v_cvt_pk_bf16_f32 v139, v144, v145
	v_cvt_pk_bf16_f32 v136, v136, v137
	v_cvt_pk_bf16_f32 v137, v134, v135
	global_store_dwordx2 v[142:143], v[138:139], off
	global_store_dwordx2 v[142:143], v[136:137], off offset:64
	global_load_dwordx4 v[134:137], v133, s[28:29]
	global_load_dwordx4 v[138:141], v133, s[28:29] offset:16
	s_nop 0
	s_nop 0
	s_nop 0
	v_or_b32_e32 v144, 0x70, v132
	v_lshlrev_b32_e32 v132, 5, v144
	v_and_b32_e32 v164, 0x1ffe0, v132
	v_or_b32_e32 v132, v164, v149
	v_lshlrev_b32_e32 v165, 3, v132
	v_ashrrev_i32_e32 v145, 31, v144
	v_lshl_add_u64 v[146:147], v[144:145], 2, s[16:17]
	global_load_dword v128, v[146:147], off
	s_waitcnt vmcnt(2)
	v_mov_b32_e32 v132, v134
	v_mov_b32_e32 v133, v136
	v_mov_b32_e32 v136, v135
	s_waitcnt vmcnt(1)
	v_mov_b32_e32 v134, v138
	v_mov_b32_e32 v135, v140
	v_mov_b32_e32 v140, v139
	v_pk_mul_f32 v[138:139], v[24:25], v[184:185] op_sel_hi:[1,0]
	v_pk_mul_f32 v[154:155], v[12:13], v[184:185] op_sel_hi:[1,0]
	v_pk_mul_f32 v[158:159], v[14:15], v[184:185] op_sel_hi:[1,0]
	v_pk_mul_f32 v[156:157], v[26:27], v[184:185] op_sel_hi:[1,0]
	v_pk_mul_f32 v[160:161], v[136:137], v[154:155]
	v_pk_mul_f32 v[136:137], v[136:137], v[138:139]
	v_pk_mul_f32 v[162:163], v[140:141], v[158:159]
	v_pk_mul_f32 v[140:141], v[156:157], v[140:141]
	v_pk_fma_f32 v[138:139], v[132:133], v[138:139], v[160:161] neg_lo:[0,0,1] neg_hi:[0,0,1]
	v_pk_fma_f32 v[132:133], v[132:133], v[154:155], v[136:137]
	v_pk_fma_f32 v[136:137], v[134:135], v[156:157], v[162:163] neg_lo:[0,0,1] neg_hi:[0,0,1]
	v_pk_fma_f32 v[134:135], v[158:159], v[134:135], v[140:141]
	v_cvt_pk_bf16_f32 v138, v138, v139
	v_cvt_pk_bf16_f32 v139, v136, v137
	v_cvt_pk_bf16_f32 v132, v132, v133
	v_cvt_pk_bf16_f32 v133, v134, v135
	global_store_dwordx2 v[142:143], v[138:139], off offset:32
	global_store_dwordx2 v[142:143], v[132:133], off offset:96
	global_load_dwordx4 v[132:135], v165, s[28:29]
	global_load_dwordx4 v[136:139], v165, s[28:29] offset:16
	global_load_dword v195, v[146:147], off
	s_nop 0
	s_nop 0
	s_nop 0
	s_nop 0
	v_or_b32_e32 v142, v164, v151
	v_lshlrev_b32_e32 v162, 3, v142
	v_lshlrev_b64 v[140:141], 7, v[144:145]
	v_lshl_add_u64 v[140:141], v[130:131], 0, v[140:141]
	s_waitcnt vmcnt(5)
	v_fmamk_f32 v128, v128, 0x3a800000, v152
	s_waitcnt vmcnt(2)
	v_mov_b32_e32 v142, v132
	v_mul_f32_e32 v132, 0x4b800000, v128
	v_cmp_gt_f32_e32 vcc, s67, v128
	v_mov_b32_e32 v143, v134
	v_mov_b32_e32 v134, v133
	v_cndmask_b32_e32 v128, v128, v132, vcc
	v_rsq_f32_e32 v128, v128
	s_waitcnt vmcnt(1)
	v_mov_b32_e32 v132, v136
	v_mov_b32_e32 v133, v138
	v_mov_b32_e32 v138, v137
	v_mul_f32_e32 v136, 0x45800000, v128
	v_cndmask_b32_e32 v128, v128, v136, vcc
	v_mov_b32_e32 v186, v128
	v_pk_mul_f32 v[136:137], v[16:17], v[128:129] op_sel_hi:[1,0]
	v_pk_mul_f32 v[144:145], v[0:1], v[186:187] op_sel_hi:[1,0]
	v_pk_mul_f32 v[156:157], v[2:3], v[186:187] op_sel_hi:[1,0]
	v_pk_mul_f32 v[154:155], v[18:19], v[186:187] op_sel_hi:[1,0]
	v_pk_mul_f32 v[158:159], v[134:135], v[144:145]
	v_pk_mul_f32 v[134:135], v[134:135], v[136:137]
	v_pk_mul_f32 v[160:161], v[138:139], v[156:157]
	v_pk_mul_f32 v[138:139], v[154:155], v[138:139]
	v_pk_fma_f32 v[136:137], v[142:143], v[136:137], v[158:159] neg_lo:[0,0,1] neg_hi:[0,0,1]
	v_pk_fma_f32 v[134:135], v[142:143], v[144:145], v[134:135]
	v_pk_fma_f32 v[142:143], v[132:133], v[154:155], v[160:161] neg_lo:[0,0,1] neg_hi:[0,0,1]
	v_pk_fma_f32 v[132:133], v[156:157], v[132:133], v[138:139]
	v_cvt_pk_bf16_f32 v136, v136, v137
	v_cvt_pk_bf16_f32 v137, v142, v143
	v_cvt_pk_bf16_f32 v134, v134, v135
	v_cvt_pk_bf16_f32 v135, v132, v133
	global_store_dwordx2 v[140:141], v[136:137], off
	global_store_dwordx2 v[140:141], v[134:135], off offset:64
	global_load_dwordx4 v[132:135], v162, s[28:29]
	global_load_dwordx4 v[136:139], v162, s[28:29] offset:16
	s_nop 0
	s_nop 0
	s_nop 0
	s_nop 0
	s_waitcnt vmcnt(4)
	v_fmamk_f32 v128, v195, 0x3a800000, v152
	s_waitcnt vmcnt(1)
	v_mov_b32_e32 v142, v132
	v_mul_f32_e32 v132, 0x4b800000, v128
	v_cmp_gt_f32_e32 vcc, s67, v128
	v_mov_b32_e32 v143, v134
	v_mov_b32_e32 v134, v133
	v_cndmask_b32_e32 v128, v128, v132, vcc
	v_rsq_f32_e32 v128, v128
	s_waitcnt vmcnt(0)
	v_mov_b32_e32 v132, v136
	v_mov_b32_e32 v133, v138
	v_mov_b32_e32 v138, v137
	v_mul_f32_e32 v136, 0x45800000, v128
	v_cndmask_b32_e32 v128, v128, v136, vcc
	v_pk_mul_f32 v[136:137], v[4:5], v[186:187] op_sel_hi:[1,0]
	v_pk_mul_f32 v[144:145], v[8:9], v[186:187] op_sel_hi:[1,0]
	v_pk_mul_f32 v[154:155], v[10:11], v[186:187] op_sel_hi:[1,0]
	v_pk_mul_f32 v[146:147], v[6:7], v[186:187] op_sel_hi:[1,0]
	v_pk_mul_f32 v[156:157], v[134:135], v[144:145]
	v_pk_mul_f32 v[134:135], v[134:135], v[136:137]
	v_pk_mul_f32 v[158:159], v[138:139], v[154:155]
	v_pk_mul_f32 v[138:139], v[146:147], v[138:139]
	v_pk_fma_f32 v[136:137], v[142:143], v[136:137], v[156:157] neg_lo:[0,0,1] neg_hi:[0,0,1]
	v_pk_fma_f32 v[134:135], v[142:143], v[144:145], v[134:135]
	v_pk_fma_f32 v[142:143], v[132:133], v[146:147], v[158:159] neg_lo:[0,0,1] neg_hi:[0,0,1]
	v_pk_fma_f32 v[132:133], v[154:155], v[132:133], v[138:139]
	v_cvt_pk_bf16_f32 v136, v136, v137
	v_cvt_pk_bf16_f32 v137, v142, v143
	v_cvt_pk_bf16_f32 v134, v134, v135
	v_cvt_pk_bf16_f32 v135, v132, v133
	global_store_dwordx2 v[140:141], v[136:137], off offset:32
	global_store_dwordx2 v[140:141], v[134:135], off offset:96

; DI u32x2 pack4(float a, float b, float c, float d) { u32x2 r; r.x = pack2(a, b); r.y = pack2(c, d); return r; }
; #define EPI_END if (i == 3 && (j & 3) == 3) __builtin_amdgcn_sched_barrier(0); }
; DI float rstd_of(const float* ssq, int m, float invn) { return rsqrtf(ssq[m] * invn + 1e-6f); }
; template <int MODE>
; DI void gemm_phase(const Params& p, const GP& g, unsigned char* smem) {
;     ...
;         EPI_STD_BEGIN
;           const float rs = rstd_of(g.ssq_in, m, 1.f / 384);
;           *(u32x2*)(qo + (long)m * 1536 + n4) = pack4(v[0] * rs, v[1] * rs, v[2] * rs, v[3] * rs);
;         EPI_END
.LBB0_396:
	v_lshl_add_u64 v[132:133], v[136:137], 2, s[16:17]
	global_load_dword v130, v[132:133], off
	global_load_dword v186, v[132:133], off offset:64
	global_load_dword v187, v[132:133], off offset:128
	global_load_dword v188, v[132:133], off offset:192
	global_load_dword v189, v[132:133], off offset:256
	global_load_dword v190, v[132:133], off offset:320
	global_load_dword v191, v[132:133], off offset:384
	global_load_dword v192, v[132:133], off offset:448
	v_add_u32_e32 v138, s6, v129
	v_mov_b64_e32 v[134:135], s[20:21]
	v_mad_i64_i32 v[152:153], s[6:7], v136, s60, v[134:135]
	s_waitcnt vmcnt(7)
	v_fmamk_f32 v130, v130, 0x3b2aaaab, v150
	global_load_dword v193, v[132:133], off offset:448
	v_mul_f32_e32 v139, 0x4b800000, v130
	v_cmp_gt_f32_e32 vcc, s61, v130
	s_nop 1
	v_cndmask_b32_e32 v130, v130, v139, vcc
	v_rsq_f32_e32 v130, v130
	v_ashrrev_i32_e32 v139, 31, v138
	v_lshlrev_b64 v[138:139], 1, v[138:139]
	v_lshl_add_u64 v[152:153], v[152:153], 0, v[138:139]
	v_mul_f32_e32 v147, 0x45800000, v130
	v_cndmask_b32_e32 v130, v130, v147, vcc
	v_mov_b32_e32 v158, v130
	v_pk_mul_f32 v[154:155], v[124:125], v[130:131] op_sel_hi:[1,0]
	v_pk_mul_f32 v[156:157], v[126:127], v[158:159] op_sel_hi:[1,0]
	v_cvt_pk_bf16_f32 v154, v154, v155
	v_cvt_pk_bf16_f32 v155, v156, v157
	global_store_dwordx2 v[152:153], v[154:155], off
	s_nop 1
	s_nop 0
	v_pk_mul_f32 v[154:155], v[116:117], v[158:159] op_sel_hi:[1,0]
	v_pk_mul_f32 v[156:157], v[118:119], v[158:159] op_sel_hi:[1,0]
	v_cvt_pk_bf16_f32 v154, v154, v155
	v_cvt_pk_bf16_f32 v155, v156, v157
	global_store_dwordx2 v[152:153], v[154:155], off offset:32
	s_nop 1
	s_nop 0
	v_pk_mul_f32 v[154:155], v[120:121], v[158:159] op_sel_hi:[1,0]
	v_pk_mul_f32 v[156:157], v[122:123], v[158:159] op_sel_hi:[1,0]
	v_cvt_pk_bf16_f32 v154, v154, v155
	v_cvt_pk_bf16_f32 v155, v156, v157
	global_store_dwordx2 v[152:153], v[154:155], off offset:64
	s_nop 1
	s_nop 0
	v_pk_mul_f32 v[154:155], v[108:109], v[158:159] op_sel_hi:[1,0]
	v_pk_mul_f32 v[156:157], v[110:111], v[158:159] op_sel_hi:[1,0]
	v_cvt_pk_bf16_f32 v154, v154, v155
	v_cvt_pk_bf16_f32 v155, v156, v157
	global_store_dwordx2 v[152:153], v[154:155], off offset:96
	s_nop 0
	v_mad_i64_i32 v[152:153], s[6:7], v146, s60, v[134:135]
	v_lshl_add_u64 v[152:153], v[152:153], 0, v[138:139]
	s_waitcnt vmcnt(11)
	v_fmamk_f32 v130, v186, 0x3b2aaaab, v150
	v_mul_f32_e32 v147, 0x4b800000, v130
	v_cmp_gt_f32_e32 vcc, s61, v130
	s_nop 1
	v_cndmask_b32_e32 v130, v130, v147, vcc
	v_rsq_f32_e32 v130, v130
	s_nop 0
	v_mul_f32_e32 v147, 0x45800000, v130
	v_cndmask_b32_e32 v130, v130, v147, vcc
	v_mov_b32_e32 v160, v130
	v_pk_mul_f32 v[154:155], v[112:113], v[130:131] op_sel_hi:[1,0]
	v_pk_mul_f32 v[156:157], v[114:115], v[160:161] op_sel_hi:[1,0]
	v_cvt_pk_bf16_f32 v154, v154, v155
	v_cvt_pk_bf16_f32 v155, v156, v157
	global_store_dwordx2 v[152:153], v[154:155], off
	s_nop 1
	s_nop 0
	v_pk_mul_f32 v[154:155], v[100:101], v[160:161] op_sel_hi:[1,0]
	v_pk_mul_f32 v[156:157], v[102:103], v[160:161] op_sel_hi:[1,0]
	v_cvt_pk_bf16_f32 v154, v154, v155
	v_cvt_pk_bf16_f32 v155, v156, v157
	global_store_dwordx2 v[152:153], v[154:155], off offset:32
	s_nop 1
	s_nop 0
	v_pk_mul_f32 v[154:155], v[104:105], v[160:161] op_sel_hi:[1,0]
	v_pk_mul_f32 v[156:157], v[106:107], v[160:161] op_sel_hi:[1,0]
	v_cvt_pk_bf16_f32 v154, v154, v155
	v_cvt_pk_bf16_f32 v155, v156, v157
	global_store_dwordx2 v[152:153], v[154:155], off offset:64
	s_nop 1
	s_nop 0
	v_pk_mul_f32 v[154:155], v[92:93], v[160:161] op_sel_hi:[1,0]
	v_pk_mul_f32 v[156:157], v[94:95], v[160:161] op_sel_hi:[1,0]
	v_cvt_pk_bf16_f32 v154, v154, v155
	v_cvt_pk_bf16_f32 v155, v156, v157
	global_store_dwordx2 v[152:153], v[154:155], off offset:96
	s_nop 0
	v_mad_i64_i32 v[152:153], s[6:7], v145, s60, v[134:135]
	v_lshl_add_u64 v[152:153], v[152:153], 0, v[138:139]
	s_waitcnt vmcnt(14)
	v_fmamk_f32 v130, v187, 0x3b2aaaab, v150
	v_mul_f32_e32 v147, 0x4b800000, v130
	v_cmp_gt_f32_e32 vcc, s61, v130
	s_nop 1
	v_cndmask_b32_e32 v130, v130, v147, vcc
	v_rsq_f32_e32 v130, v130
	s_nop 0
	v_mul_f32_e32 v147, 0x45800000, v130
	v_cndmask_b32_e32 v130, v130, v147, vcc
	v_mov_b32_e32 v162, v130
	v_pk_mul_f32 v[154:155], v[96:97], v[130:131] op_sel_hi:[1,0]
	v_pk_mul_f32 v[156:157], v[98:99], v[162:163] op_sel_hi:[1,0]
	v_cvt_pk_bf16_f32 v154, v154, v155
	v_cvt_pk_bf16_f32 v155, v156, v157
	global_store_dwordx2 v[152:153], v[154:155], off
	s_nop 1
	s_nop 0
	v_pk_mul_f32 v[154:155], v[84:85], v[162:163] op_sel_hi:[1,0]
	v_pk_mul_f32 v[156:157], v[86:87], v[162:163] op_sel_hi:[1,0]
	v_cvt_pk_bf16_f32 v154, v154, v155
	v_cvt_pk_bf16_f32 v155, v156, v157
	global_store_dwordx2 v[152:153], v[154:155], off offset:32
	s_nop 1
	s_nop 0
	v_pk_mul_f32 v[154:155], v[88:89], v[162:163] op_sel_hi:[1,0]
	v_pk_mul_f32 v[156:157], v[90:91], v[162:163] op_sel_hi:[1,0]
	v_cvt_pk_bf16_f32 v154, v154, v155
	v_cvt_pk_bf16_f32 v155, v156, v157
	global_store_dwordx2 v[152:153], v[154:155], off offset:64
	s_nop 1
	s_nop 0
	v_pk_mul_f32 v[154:155], v[76:77], v[162:163] op_sel_hi:[1,0]
	v_pk_mul_f32 v[156:157], v[78:79], v[162:163] op_sel_hi:[1,0]
	v_cvt_pk_bf16_f32 v154, v154, v155
	v_cvt_pk_bf16_f32 v155, v156, v157
	global_store_dwordx2 v[152:153], v[154:155], off offset:96
	s_nop 0
	v_mad_i64_i32 v[152:153], s[6:7], v144, s60, v[134:135]
	v_lshl_add_u64 v[152:153], v[152:153], 0, v[138:139]
	s_waitcnt vmcnt(17)
; DI u32x2 pack4(float a, float b, float c, float d) { u32x2 r; r.x = pack2(a, b); r.y = pack2(c, d); return r; }
; #define EPI_END if (i == 3 && (j & 3) == 3) __builtin_amdgcn_sched_barrier(0); }
; DI float rstd_of(const float* ssq, int m, float invn) { return rsqrtf(ssq[m] * invn + 1e-6f); }
; template <int MODE>
; DI void gemm_phase(const Params& p, const GP& g, unsigned char* smem) {
;     ...
;         EPI_STD_BEGIN
;           const float rs = rstd_of(g.ssq_in, m, 1.f / 384);
;           *(u32x2*)(qo + (long)m * 1536 + n4) = pack4(v[0] * rs, v[1] * rs, v[2] * rs, v[3] * rs);
;         EPI_END
	v_fmamk_f32 v130, v188, 0x3b2aaaab, v150
	v_mul_f32_e32 v147, 0x4b800000, v130
	v_cmp_gt_f32_e32 vcc, s61, v130
	s_nop 1
	v_cndmask_b32_e32 v130, v130, v147, vcc
	v_rsq_f32_e32 v130, v130
	s_nop 0
	v_mul_f32_e32 v147, 0x45800000, v130
	v_cndmask_b32_e32 v130, v130, v147, vcc
	v_mov_b32_e32 v164, v130
	v_pk_mul_f32 v[154:155], v[80:81], v[130:131] op_sel_hi:[1,0]
	v_pk_mul_f32 v[156:157], v[82:83], v[164:165] op_sel_hi:[1,0]
	v_cvt_pk_bf16_f32 v154, v154, v155
	v_cvt_pk_bf16_f32 v155, v156, v157
	global_store_dwordx2 v[152:153], v[154:155], off
	s_nop 1
	s_nop 0
	v_pk_mul_f32 v[154:155], v[68:69], v[164:165] op_sel_hi:[1,0]
	v_pk_mul_f32 v[156:157], v[70:71], v[164:165] op_sel_hi:[1,0]
	v_cvt_pk_bf16_f32 v154, v154, v155
	v_cvt_pk_bf16_f32 v155, v156, v157
	global_store_dwordx2 v[152:153], v[154:155], off offset:32
	s_nop 1
	s_nop 0
	v_pk_mul_f32 v[154:155], v[72:73], v[164:165] op_sel_hi:[1,0]
	v_pk_mul_f32 v[156:157], v[74:75], v[164:165] op_sel_hi:[1,0]
	v_cvt_pk_bf16_f32 v154, v154, v155
	v_cvt_pk_bf16_f32 v155, v156, v157
	global_store_dwordx2 v[152:153], v[154:155], off offset:64
	s_nop 1
	s_nop 0
	v_pk_mul_f32 v[154:155], v[60:61], v[164:165] op_sel_hi:[1,0]
	v_pk_mul_f32 v[156:157], v[62:63], v[164:165] op_sel_hi:[1,0]
	v_cvt_pk_bf16_f32 v154, v154, v155
	v_cvt_pk_bf16_f32 v155, v156, v157
	global_store_dwordx2 v[152:153], v[154:155], off offset:96
	s_nop 0
	v_mad_i64_i32 v[152:153], s[6:7], v143, s60, v[134:135]
	v_lshl_add_u64 v[152:153], v[152:153], 0, v[138:139]
	s_waitcnt vmcnt(20)
	v_fmamk_f32 v130, v189, 0x3b2aaaab, v150
	v_mul_f32_e32 v147, 0x4b800000, v130
	v_cmp_gt_f32_e32 vcc, s61, v130
	s_nop 1
	v_cndmask_b32_e32 v130, v130, v147, vcc
	v_rsq_f32_e32 v130, v130
	s_nop 0
	v_mul_f32_e32 v147, 0x45800000, v130
	v_cndmask_b32_e32 v130, v130, v147, vcc
	v_mov_b32_e32 v166, v130
	v_pk_mul_f32 v[154:155], v[64:65], v[130:131] op_sel_hi:[1,0]
	v_pk_mul_f32 v[156:157], v[66:67], v[166:167] op_sel_hi:[1,0]
	v_cvt_pk_bf16_f32 v154, v154, v155
	v_cvt_pk_bf16_f32 v155, v156, v157
	global_store_dwordx2 v[152:153], v[154:155], off
	s_nop 1
	s_nop 0
	v_pk_mul_f32 v[154:155], v[52:53], v[166:167] op_sel_hi:[1,0]
	v_pk_mul_f32 v[156:157], v[54:55], v[166:167] op_sel_hi:[1,0]
	v_cvt_pk_bf16_f32 v154, v154, v155
	v_cvt_pk_bf16_f32 v155, v156, v157
	global_store_dwordx2 v[152:153], v[154:155], off offset:32
	s_nop 1
	s_nop 0
	v_pk_mul_f32 v[154:155], v[56:57], v[166:167] op_sel_hi:[1,0]
	v_pk_mul_f32 v[156:157], v[58:59], v[166:167] op_sel_hi:[1,0]
	v_cvt_pk_bf16_f32 v154, v154, v155
	v_cvt_pk_bf16_f32 v155, v156, v157
	global_store_dwordx2 v[152:153], v[154:155], off offset:64
	s_nop 1
	s_nop 0
	v_pk_mul_f32 v[154:155], v[44:45], v[166:167] op_sel_hi:[1,0]
	v_pk_mul_f32 v[156:157], v[46:47], v[166:167] op_sel_hi:[1,0]
	v_cvt_pk_bf16_f32 v154, v154, v155
	v_cvt_pk_bf16_f32 v155, v156, v157
	global_store_dwordx2 v[152:153], v[154:155], off offset:96
	s_nop 0
	v_mad_i64_i32 v[152:153], s[6:7], v142, s60, v[134:135]
	v_lshl_add_u64 v[152:153], v[152:153], 0, v[138:139]
	s_waitcnt vmcnt(23)
	v_fmamk_f32 v130, v190, 0x3b2aaaab, v150
	v_mul_f32_e32 v147, 0x4b800000, v130
	v_cmp_gt_f32_e32 vcc, s61, v130
	s_nop 1
	v_cndmask_b32_e32 v130, v130, v147, vcc
	v_rsq_f32_e32 v130, v130
	s_nop 0
	v_mul_f32_e32 v147, 0x45800000, v130
	v_cndmask_b32_e32 v130, v130, v147, vcc
	v_mov_b32_e32 v168, v130
	v_pk_mul_f32 v[154:155], v[48:49], v[130:131] op_sel_hi:[1,0]
	v_pk_mul_f32 v[156:157], v[50:51], v[168:169] op_sel_hi:[1,0]
	v_cvt_pk_bf16_f32 v154, v154, v155
	v_cvt_pk_bf16_f32 v155, v156, v157
	global_store_dwordx2 v[152:153], v[154:155], off
	s_nop 1
	s_nop 0
	v_pk_mul_f32 v[154:155], v[36:37], v[168:169] op_sel_hi:[1,0]
	v_pk_mul_f32 v[156:157], v[38:39], v[168:169] op_sel_hi:[1,0]
	v_cvt_pk_bf16_f32 v154, v154, v155
	v_cvt_pk_bf16_f32 v155, v156, v157
	global_store_dwordx2 v[152:153], v[154:155], off offset:32
	s_nop 1
	s_nop 0
	v_pk_mul_f32 v[154:155], v[40:41], v[168:169] op_sel_hi:[1,0]
	v_pk_mul_f32 v[156:157], v[42:43], v[168:169] op_sel_hi:[1,0]
	v_cvt_pk_bf16_f32 v154, v154, v155
	v_cvt_pk_bf16_f32 v155, v156, v157
	global_store_dwordx2 v[152:153], v[154:155], off offset:64
	s_nop 1
	s_nop 0
	v_pk_mul_f32 v[154:155], v[28:29], v[168:169] op_sel_hi:[1,0]
	v_pk_mul_f32 v[156:157], v[30:31], v[168:169] op_sel_hi:[1,0]
	v_cvt_pk_bf16_f32 v154, v154, v155
	v_cvt_pk_bf16_f32 v155, v156, v157
	global_store_dwordx2 v[152:153], v[154:155], off offset:96
	s_nop 0
	v_mad_i64_i32 v[152:153], s[6:7], v141, s60, v[134:135]
	v_lshl_add_u64 v[152:153], v[152:153], 0, v[138:139]
	v_mad_i64_i32 v[134:135], s[6:7], v140, s60, v[134:135]
	v_lshl_add_u64 v[134:135], v[134:135], 0, v[138:139]
	s_waitcnt vmcnt(26)
	v_fmamk_f32 v130, v191, 0x3b2aaaab, v150
	v_mul_f32_e32 v147, 0x4b800000, v130
	v_cmp_gt_f32_e32 vcc, s61, v130
	s_nop 1
	v_cndmask_b32_e32 v130, v130, v147, vcc
	v_rsq_f32_e32 v130, v130
	s_nop 0
	v_mul_f32_e32 v147, 0x45800000, v130
	v_cndmask_b32_e32 v130, v130, v147, vcc
	v_mov_b32_e32 v170, v130
	v_pk_mul_f32 v[154:155], v[32:33], v[130:131] op_sel_hi:[1,0]
	v_pk_mul_f32 v[156:157], v[34:35], v[170:171] op_sel_hi:[1,0]
	v_cvt_pk_bf16_f32 v154, v154, v155
	v_cvt_pk_bf16_f32 v155, v156, v157
	global_store_dwordx2 v[152:153], v[154:155], off
	s_nop 1
	s_nop 0
	v_pk_mul_f32 v[154:155], v[20:21], v[170:171] op_sel_hi:[1,0]
	v_pk_mul_f32 v[156:157], v[22:23], v[170:171] op_sel_hi:[1,0]
	v_cvt_pk_bf16_f32 v154, v154, v155
	v_cvt_pk_bf16_f32 v155, v156, v157
	global_store_dwordx2 v[152:153], v[154:155], off offset:32
	s_nop 1
	s_nop 0
	v_pk_mul_f32 v[154:155], v[24:25], v[170:171] op_sel_hi:[1,0]
	v_pk_mul_f32 v[156:157], v[26:27], v[170:171] op_sel_hi:[1,0]
	v_cvt_pk_bf16_f32 v154, v154, v155
	v_cvt_pk_bf16_f32 v155, v156, v157
	global_store_dwordx2 v[152:153], v[154:155], off offset:64
	s_nop 1
	s_nop 0
	v_pk_mul_f32 v[154:155], v[12:13], v[170:171] op_sel_hi:[1,0]
	v_pk_mul_f32 v[156:157], v[14:15], v[170:171] op_sel_hi:[1,0]
	v_cvt_pk_bf16_f32 v154, v154, v155
	v_cvt_pk_bf16_f32 v155, v156, v157
	global_store_dwordx2 v[152:153], v[154:155], off offset:96
	s_nop 0
	s_waitcnt vmcnt(29)
; DI u32x2 pack4(float a, float b, float c, float d) { u32x2 r; r.x = pack2(a, b); r.y = pack2(c, d); return r; }
; #define EPI_END if (i == 3 && (j & 3) == 3) __builtin_amdgcn_sched_barrier(0); }
; DI float rstd_of(const float* ssq, int m, float invn) { return rsqrtf(ssq[m] * invn + 1e-6f); }
; template <int MODE>
; DI void gemm_phase(const Params& p, const GP& g, unsigned char* smem) {
;     ...
;       if (slab % 3 == 2) {
; #pragma unroll
;         for (int j = 0; j < 8; ++j)
; #pragma unroll
;           for (int i = 0; i < 2; ++i) {
;             const int m = m0 + wy * 128 + j * 16 + lq, pos = m & 4095;
;             const float rs = rstd_of(g.ssq_in, m, 1.f / 384);
;             const int f0 = i * 16 + lg * 4;
;             const f32x4 a = acc[i][j], bq = acc[i + 2][j];
;             float lo[4], hi[4];
; #pragma unroll
;             for (int r = 0; r < 4; ++r) {
;               const float2 cssn = *(const float2*)(p.rope + ((long)pos * 32 + f0 + r) * 2);
;               const float x1 = a[r] * rs, x2 = bq[r] * rs;
;               lo[r] = x1 * cssn.x - x2 * cssn.y;
;               hi[r] = x1 * cssn.y + x2 * cssn.x;
;             }
;             *(u32x2*)(qo + (long)m * 1536 + slab * 64 + f0) = pack4(lo[0], lo[1], lo[2], lo[3]);
;             *(u32x2*)(qo + (long)m * 1536 + slab * 64 + 32 + f0) = pack4(hi[0], hi[1], hi[2], hi[3]);
;           }
;     ...
;         EPI_STD_BEGIN
;           const float rs = rstd_of(g.ssq_in, m, 1.f / 384);
;           *(u32x2*)(qo + (long)m * 1536 + n4) = pack4(v[0] * rs, v[1] * rs, v[2] * rs, v[3] * rs);
;         EPI_END
	v_fmamk_f32 v130, v192, 0x3b2aaaab, v150
	v_mul_f32_e32 v147, 0x4b800000, v130
	v_cmp_gt_f32_e32 vcc, s61, v130
	s_nop 1
	v_cndmask_b32_e32 v130, v130, v147, vcc
	v_rsq_f32_e32 v130, v130
	s_nop 0
	v_mul_f32_e32 v138, 0x45800000, v130
	v_cndmask_b32_e32 v130, v130, v138, vcc
	v_mov_b32_e32 v172, v130
	v_pk_mul_f32 v[138:139], v[16:17], v[130:131] op_sel_hi:[1,0]
	v_pk_mul_f32 v[152:153], v[18:19], v[172:173] op_sel_hi:[1,0]
	v_cvt_pk_bf16_f32 v138, v138, v139
	v_cvt_pk_bf16_f32 v139, v152, v153
	global_store_dwordx2 v[134:135], v[138:139], off
	s_nop 1
	s_nop 0
	v_pk_mul_f32 v[138:139], v[0:1], v[172:173] op_sel_hi:[1,0]
	v_pk_mul_f32 v[152:153], v[2:3], v[172:173] op_sel_hi:[1,0]
	v_cvt_pk_bf16_f32 v138, v138, v139
	v_cvt_pk_bf16_f32 v139, v152, v153
	global_store_dwordx2 v[134:135], v[138:139], off offset:32
	s_nop 1
	s_nop 0
	v_pk_mul_f32 v[138:139], v[4:5], v[172:173] op_sel_hi:[1,0]
	v_pk_mul_f32 v[152:153], v[6:7], v[172:173] op_sel_hi:[1,0]
	v_cvt_pk_bf16_f32 v138, v138, v139
	v_cvt_pk_bf16_f32 v139, v152, v153
	global_store_dwordx2 v[134:135], v[138:139], off offset:64
	s_nop 0
	s_waitcnt vmcnt(31)
	v_fmamk_f32 v130, v193, 0x3b2aaaab, v150
	v_mul_f32_e32 v132, 0x4b800000, v130
	v_cmp_gt_f32_e32 vcc, s61, v130
	s_nop 1
	v_cndmask_b32_e32 v130, v130, v132, vcc
	v_rsq_f32_e32 v130, v130
	s_nop 0
	v_mul_f32_e32 v132, 0x45800000, v130
	v_cndmask_b32_e32 v130, v130, v132, vcc
	v_pk_mul_f32 v[132:133], v[8:9], v[172:173] op_sel_hi:[1,0]
	v_pk_mul_f32 v[138:139], v[10:11], v[172:173] op_sel_hi:[1,0]
	v_cvt_pk_bf16_f32 v132, v132, v133
	v_cvt_pk_bf16_f32 v133, v138, v139
	global_store_dwordx2 v[134:135], v[132:133], off offset:96
	s_cbranch_execnz .LBB0_389
.LBB0_397:
	v_lshl_add_u64 v[132:133], v[136:137], 2, s[16:17]
	global_load_dword v138, v[132:133], off
	v_lshlrev_b32_e32 v130, 5, v136
	v_and_b32_e32 v134, 0x1f1e0, v130
	v_or_b32_e32 v130, v134, v128
	v_lshlrev_b32_e32 v130, 3, v130
	global_load_dwordx4 v[152:155], v130, s[24:25]
	global_load_dwordx4 v[156:159], v130, s[24:25] offset:16
	s_lshl_b32 s6, s10, 6
	s_ashr_i32 s7, s6, 31
	s_lshl_b64 s[6:7], s[6:7], 1
	s_add_u32 s6, s20, s6
	v_or_b32_e32 v134, v134, v149
	s_addc_u32 s7, s21, s7
	v_lshlrev_b32_e32 v147, 3, v134
	v_mov_b64_e32 v[134:135], s[6:7]
	v_lshlrev_b32_e32 v130, 1, v128
	v_mad_i64_i32 v[136:137], s[6:7], v136, s60, v[134:135]
	v_lshl_add_u64 v[136:137], v[136:137], 0, v[130:131]
	s_waitcnt vmcnt(2)
	v_fmamk_f32 v138, v138, 0x3b2aaaab, v150
	v_mul_f32_e32 v139, 0x4b800000, v138
	v_cmp_gt_f32_e32 vcc, s61, v138
	s_nop 1
	v_cndmask_b32_e32 v138, v138, v139, vcc
	v_rsq_f32_e32 v151, v138
	s_waitcnt vmcnt(1)
	v_mov_b32_e32 v138, v152
	s_waitcnt vmcnt(0)
	v_mov_b32_e32 v152, v156
	v_mov_b32_e32 v139, v154
	v_mul_f32_e32 v156, 0x45800000, v151
	v_cndmask_b32_e32 v156, v151, v156, vcc
	v_mov_b32_e32 v154, v153
	v_mov_b32_e32 v153, v158
	v_mov_b32_e32 v158, v157
	v_mov_b32_e32 v162, v156
	v_pk_mul_f32 v[120:121], v[120:121], v[156:157] op_sel_hi:[1,0]
	v_pk_mul_f32 v[122:123], v[122:123], v[162:163] op_sel_hi:[1,0]
	v_pk_mul_f32 v[124:125], v[124:125], v[162:163] op_sel_hi:[1,0]
	v_pk_mul_f32 v[126:127], v[126:127], v[162:163] op_sel_hi:[1,0]
	v_pk_mul_f32 v[156:157], v[154:155], v[120:121]
	v_pk_mul_f32 v[160:161], v[158:159], v[122:123]
	v_pk_mul_f32 v[154:155], v[154:155], v[124:125]
	v_pk_mul_f32 v[158:159], v[126:127], v[158:159]
	v_pk_fma_f32 v[124:125], v[138:139], v[124:125], v[156:157] neg_lo:[0,0,1] neg_hi:[0,0,1]
	v_pk_fma_f32 v[126:127], v[152:153], v[126:127], v[160:161] neg_lo:[0,0,1] neg_hi:[0,0,1]
	v_pk_fma_f32 v[120:121], v[138:139], v[120:121], v[154:155]
	v_pk_fma_f32 v[122:123], v[122:123], v[152:153], v[158:159]
	v_cvt_pk_bf16_f32 v124, v124, v125
	v_cvt_pk_bf16_f32 v125, v126, v127
	v_cvt_pk_bf16_f32 v120, v120, v121
	v_cvt_pk_bf16_f32 v121, v122, v123
	global_store_dwordx2 v[136:137], v[124:125], off
	global_store_dwordx2 v[136:137], v[120:121], off offset:64
	global_load_dwordx4 v[120:123], v147, s[24:25]
	global_load_dwordx4 v[124:127], v147, s[24:25] offset:16
	global_load_dword v190, v[132:133], off offset:64
	s_nop 0
	s_nop 0
	s_nop 0
	v_lshlrev_b32_e32 v139, 5, v146
	v_and_b32_e32 v147, 0x1f3e0, v139
	v_or_b32_e32 v139, v147, v128
	v_lshlrev_b32_e32 v151, 3, v139
	s_waitcnt vmcnt(2)
	v_mov_b32_e32 v138, v120
	v_mov_b32_e32 v139, v122
	v_mov_b32_e32 v122, v121
	s_waitcnt vmcnt(1)
	v_mov_b32_e32 v120, v124
	v_mov_b32_e32 v121, v126
	v_mov_b32_e32 v126, v125
	v_pk_mul_f32 v[108:109], v[108:109], v[162:163] op_sel_hi:[1,0]
	v_pk_mul_f32 v[110:111], v[110:111], v[162:163] op_sel_hi:[1,0]
	v_pk_mul_f32 v[116:117], v[116:117], v[162:163] op_sel_hi:[1,0]
	v_pk_mul_f32 v[118:119], v[118:119], v[162:163] op_sel_hi:[1,0]
	v_pk_mul_f32 v[124:125], v[122:123], v[108:109]
	v_pk_mul_f32 v[152:153], v[126:127], v[110:111]
	v_pk_mul_f32 v[122:123], v[122:123], v[116:117]
	v_pk_mul_f32 v[126:127], v[118:119], v[126:127]
	v_pk_fma_f32 v[116:117], v[138:139], v[116:117], v[124:125] neg_lo:[0,0,1] neg_hi:[0,0,1]
	v_pk_fma_f32 v[118:119], v[120:121], v[118:119], v[152:153] neg_lo:[0,0,1] neg_hi:[0,0,1]
	v_pk_fma_f32 v[108:109], v[138:139], v[108:109], v[122:123]
	v_pk_fma_f32 v[110:111], v[110:111], v[120:121], v[126:127]
	v_cvt_pk_bf16_f32 v116, v116, v117
	v_cvt_pk_bf16_f32 v117, v118, v119
	v_cvt_pk_bf16_f32 v108, v108, v109
	v_cvt_pk_bf16_f32 v109, v110, v111
	global_store_dwordx2 v[136:137], v[116:117], off offset:32
	global_store_dwordx2 v[136:137], v[108:109], off offset:96
	global_load_dwordx4 v[108:111], v151, s[24:25]
	global_load_dwordx4 v[116:119], v151, s[24:25] offset:16
	s_nop 0
	s_nop 0
	s_nop 0
	s_nop 0
	v_or_b32_e32 v120, v147, v149
	v_lshlrev_b32_e32 v126, 3, v120
	v_mad_i64_i32 v[120:121], s[6:7], v146, s60, v[134:135]
	v_lshl_add_u64 v[120:121], v[120:121], 0, v[130:131]
	s_waitcnt vmcnt(4)
; DI u32x2 pack4(float a, float b, float c, float d) { u32x2 r; r.x = pack2(a, b); r.y = pack2(c, d); return r; }
; DI float rstd_of(const float* ssq, int m, float invn) { return rsqrtf(ssq[m] * invn + 1e-6f); }
; template <int MODE>
; DI void gemm_phase(const Params& p, const GP& g, unsigned char* smem) {
;     ...
;         for (int j = 0; j < 8; ++j)
; #pragma unroll
;           for (int i = 0; i < 2; ++i) {
;             const int m = m0 + wy * 128 + j * 16 + lq, pos = m & 4095;
;             const float rs = rstd_of(g.ssq_in, m, 1.f / 384);
;             const int f0 = i * 16 + lg * 4;
;             const f32x4 a = acc[i][j], bq = acc[i + 2][j];
;             float lo[4], hi[4];
; #pragma unroll
;             for (int r = 0; r < 4; ++r) {
;               const float2 cssn = *(const float2*)(p.rope + ((long)pos * 32 + f0 + r) * 2);
;               const float x1 = a[r] * rs, x2 = bq[r] * rs;
;               lo[r] = x1 * cssn.x - x2 * cssn.y;
;               hi[r] = x1 * cssn.y + x2 * cssn.x;
;             }
;             *(u32x2*)(qo + (long)m * 1536 + slab * 64 + f0) = pack4(lo[0], lo[1], lo[2], lo[3]);
;             *(u32x2*)(qo + (long)m * 1536 + slab * 64 + 32 + f0) = pack4(hi[0], hi[1], hi[2], hi[3]);
;           }
	v_fmamk_f32 v124, v190, 0x3b2aaaab, v150
	s_waitcnt vmcnt(1)
	v_mov_b32_e32 v122, v108
	v_mul_f32_e32 v108, 0x4b800000, v124
	v_cmp_gt_f32_e32 vcc, s61, v124
	v_mov_b32_e32 v123, v110
	v_mov_b32_e32 v110, v109
	v_cndmask_b32_e32 v108, v124, v108, vcc
	v_rsq_f32_e32 v124, v108
	s_waitcnt vmcnt(0)
	v_mov_b32_e32 v108, v116
	v_mov_b32_e32 v109, v118
	v_mov_b32_e32 v118, v117
	v_mul_f32_e32 v116, 0x45800000, v124
	v_cndmask_b32_e32 v116, v124, v116, vcc
	v_mov_b32_e32 v164, v116
	v_pk_mul_f32 v[112:113], v[112:113], v[116:117] op_sel_hi:[1,0]
	v_pk_mul_f32 v[104:105], v[104:105], v[164:165] op_sel_hi:[1,0]
	v_pk_mul_f32 v[106:107], v[106:107], v[164:165] op_sel_hi:[1,0]
	v_pk_mul_f32 v[114:115], v[114:115], v[164:165] op_sel_hi:[1,0]
	v_pk_mul_f32 v[116:117], v[110:111], v[104:105]
	v_pk_mul_f32 v[110:111], v[110:111], v[112:113]
	v_pk_mul_f32 v[124:125], v[118:119], v[106:107]
	v_pk_mul_f32 v[118:119], v[114:115], v[118:119]
	v_pk_fma_f32 v[112:113], v[122:123], v[112:113], v[116:117] neg_lo:[0,0,1] neg_hi:[0,0,1]
	v_pk_fma_f32 v[104:105], v[122:123], v[104:105], v[110:111]
	v_pk_fma_f32 v[110:111], v[108:109], v[114:115], v[124:125] neg_lo:[0,0,1] neg_hi:[0,0,1]
	v_pk_fma_f32 v[106:107], v[106:107], v[108:109], v[118:119]
	v_cvt_pk_bf16_f32 v108, v112, v113
	v_cvt_pk_bf16_f32 v109, v110, v111
	v_cvt_pk_bf16_f32 v104, v104, v105
	v_cvt_pk_bf16_f32 v105, v106, v107
	global_store_dwordx2 v[120:121], v[108:109], off
	global_store_dwordx2 v[120:121], v[104:105], off offset:64
	global_load_dwordx4 v[104:107], v126, s[24:25]
	global_load_dwordx4 v[108:111], v126, s[24:25] offset:16
	global_load_dword v190, v[132:133], off offset:128
	s_nop 0
	s_nop 0
	s_nop 0
	v_lshlrev_b32_e32 v113, 5, v145
	v_and_b32_e32 v116, 0x1f5e0, v113
	v_or_b32_e32 v113, v116, v128
	v_lshlrev_b32_e32 v117, 3, v113
	s_waitcnt vmcnt(2)
	v_mov_b32_e32 v112, v104
	v_mov_b32_e32 v113, v106
	v_mov_b32_e32 v106, v105
	s_waitcnt vmcnt(1)
	v_mov_b32_e32 v104, v108
	v_mov_b32_e32 v105, v110
	v_mov_b32_e32 v110, v109
	v_pk_mul_f32 v[92:93], v[92:93], v[164:165] op_sel_hi:[1,0]
	v_pk_mul_f32 v[94:95], v[94:95], v[164:165] op_sel_hi:[1,0]
	v_pk_mul_f32 v[100:101], v[100:101], v[164:165] op_sel_hi:[1,0]
	v_pk_mul_f32 v[102:103], v[102:103], v[164:165] op_sel_hi:[1,0]
	v_pk_mul_f32 v[108:109], v[106:107], v[92:93]
	v_pk_mul_f32 v[114:115], v[110:111], v[94:95]
	v_pk_mul_f32 v[106:107], v[106:107], v[100:101]
	v_pk_mul_f32 v[110:111], v[102:103], v[110:111]
	v_pk_fma_f32 v[100:101], v[112:113], v[100:101], v[108:109] neg_lo:[0,0,1] neg_hi:[0,0,1]
	v_pk_fma_f32 v[102:103], v[104:105], v[102:103], v[114:115] neg_lo:[0,0,1] neg_hi:[0,0,1]
	v_pk_fma_f32 v[92:93], v[112:113], v[92:93], v[106:107]
	v_pk_fma_f32 v[94:95], v[94:95], v[104:105], v[110:111]
	v_cvt_pk_bf16_f32 v100, v100, v101
	v_cvt_pk_bf16_f32 v101, v102, v103
	v_cvt_pk_bf16_f32 v92, v92, v93
	v_cvt_pk_bf16_f32 v93, v94, v95
	global_store_dwordx2 v[120:121], v[100:101], off offset:32
	global_store_dwordx2 v[120:121], v[92:93], off offset:96
	global_load_dwordx4 v[92:95], v117, s[24:25]
	global_load_dwordx4 v[100:103], v117, s[24:25] offset:16
	s_nop 0
	s_nop 0
	s_nop 0
	s_nop 0
	v_or_b32_e32 v104, v116, v149
	v_lshlrev_b32_e32 v110, 3, v104
	v_mad_i64_i32 v[104:105], s[6:7], v145, s60, v[134:135]
	v_lshl_add_u64 v[104:105], v[104:105], 0, v[130:131]
	s_waitcnt vmcnt(4)
	v_fmamk_f32 v108, v190, 0x3b2aaaab, v150
	s_waitcnt vmcnt(1)
	v_mov_b32_e32 v106, v92
	v_mul_f32_e32 v92, 0x4b800000, v108
	v_cmp_gt_f32_e32 vcc, s61, v108
	v_mov_b32_e32 v107, v94
	v_mov_b32_e32 v94, v93
	v_cndmask_b32_e32 v92, v108, v92, vcc
	v_rsq_f32_e32 v108, v92
	s_waitcnt vmcnt(0)
	v_mov_b32_e32 v92, v100
	v_mov_b32_e32 v93, v102
	v_mov_b32_e32 v102, v101
	v_mul_f32_e32 v100, 0x45800000, v108
	v_cndmask_b32_e32 v100, v108, v100, vcc
	v_mov_b32_e32 v166, v100
	v_pk_mul_f32 v[96:97], v[96:97], v[100:101] op_sel_hi:[1,0]
	v_pk_mul_f32 v[88:89], v[88:89], v[166:167] op_sel_hi:[1,0]
	v_pk_mul_f32 v[90:91], v[90:91], v[166:167] op_sel_hi:[1,0]
	v_pk_mul_f32 v[98:99], v[98:99], v[166:167] op_sel_hi:[1,0]
	v_pk_mul_f32 v[100:101], v[94:95], v[88:89]
	v_pk_mul_f32 v[94:95], v[94:95], v[96:97]
	v_pk_mul_f32 v[108:109], v[102:103], v[90:91]
	v_pk_mul_f32 v[102:103], v[98:99], v[102:103]
	v_pk_fma_f32 v[96:97], v[106:107], v[96:97], v[100:101] neg_lo:[0,0,1] neg_hi:[0,0,1]
	v_pk_fma_f32 v[88:89], v[106:107], v[88:89], v[94:95]
	v_pk_fma_f32 v[94:95], v[92:93], v[98:99], v[108:109] neg_lo:[0,0,1] neg_hi:[0,0,1]
	v_pk_fma_f32 v[90:91], v[90:91], v[92:93], v[102:103]
	v_cvt_pk_bf16_f32 v92, v96, v97
	v_cvt_pk_bf16_f32 v93, v94, v95
	v_cvt_pk_bf16_f32 v88, v88, v89
	v_cvt_pk_bf16_f32 v89, v90, v91
	global_store_dwordx2 v[104:105], v[92:93], off
	global_store_dwordx2 v[104:105], v[88:89], off offset:64
	global_load_dwordx4 v[88:91], v110, s[24:25]
	global_load_dwordx4 v[92:95], v110, s[24:25] offset:16
	global_load_dword v190, v[132:133], off offset:192
	s_nop 0
	s_nop 0
	s_nop 0
	v_lshlrev_b32_e32 v97, 5, v144
	v_and_b32_e32 v100, 0x1f7e0, v97
	v_or_b32_e32 v97, v100, v128
	v_lshlrev_b32_e32 v101, 3, v97
	s_waitcnt vmcnt(2)
	v_mov_b32_e32 v96, v88
	v_mov_b32_e32 v97, v90
	v_mov_b32_e32 v90, v89
	s_waitcnt vmcnt(1)
; DI u32x2 pack4(float a, float b, float c, float d) { u32x2 r; r.x = pack2(a, b); r.y = pack2(c, d); return r; }
; DI float rstd_of(const float* ssq, int m, float invn) { return rsqrtf(ssq[m] * invn + 1e-6f); }
; template <int MODE>
; DI void gemm_phase(const Params& p, const GP& g, unsigned char* smem) {
;     ...
;         for (int j = 0; j < 8; ++j)
; #pragma unroll
;           for (int i = 0; i < 2; ++i) {
;             const int m = m0 + wy * 128 + j * 16 + lq, pos = m & 4095;
;             const float rs = rstd_of(g.ssq_in, m, 1.f / 384);
;             const int f0 = i * 16 + lg * 4;
;             const f32x4 a = acc[i][j], bq = acc[i + 2][j];
;             float lo[4], hi[4];
; #pragma unroll
;             for (int r = 0; r < 4; ++r) {
;               const float2 cssn = *(const float2*)(p.rope + ((long)pos * 32 + f0 + r) * 2);
;               const float x1 = a[r] * rs, x2 = bq[r] * rs;
;               lo[r] = x1 * cssn.x - x2 * cssn.y;
;               hi[r] = x1 * cssn.y + x2 * cssn.x;
;             }
;             *(u32x2*)(qo + (long)m * 1536 + slab * 64 + f0) = pack4(lo[0], lo[1], lo[2], lo[3]);
;             *(u32x2*)(qo + (long)m * 1536 + slab * 64 + 32 + f0) = pack4(hi[0], hi[1], hi[2], hi[3]);
;           }
	v_mov_b32_e32 v88, v92
	v_mov_b32_e32 v89, v94
	v_mov_b32_e32 v94, v93
	v_pk_mul_f32 v[76:77], v[76:77], v[166:167] op_sel_hi:[1,0]
	v_pk_mul_f32 v[78:79], v[78:79], v[166:167] op_sel_hi:[1,0]
	v_pk_mul_f32 v[84:85], v[84:85], v[166:167] op_sel_hi:[1,0]
	v_pk_mul_f32 v[86:87], v[86:87], v[166:167] op_sel_hi:[1,0]
	v_pk_mul_f32 v[92:93], v[90:91], v[76:77]
	v_pk_mul_f32 v[98:99], v[94:95], v[78:79]
	v_pk_mul_f32 v[90:91], v[90:91], v[84:85]
	v_pk_mul_f32 v[94:95], v[86:87], v[94:95]
	v_pk_fma_f32 v[84:85], v[96:97], v[84:85], v[92:93] neg_lo:[0,0,1] neg_hi:[0,0,1]
	v_pk_fma_f32 v[86:87], v[88:89], v[86:87], v[98:99] neg_lo:[0,0,1] neg_hi:[0,0,1]
	v_pk_fma_f32 v[76:77], v[96:97], v[76:77], v[90:91]
	v_pk_fma_f32 v[78:79], v[78:79], v[88:89], v[94:95]
	v_cvt_pk_bf16_f32 v84, v84, v85
	v_cvt_pk_bf16_f32 v85, v86, v87
	v_cvt_pk_bf16_f32 v76, v76, v77
	v_cvt_pk_bf16_f32 v77, v78, v79
	global_store_dwordx2 v[104:105], v[84:85], off offset:32
	global_store_dwordx2 v[104:105], v[76:77], off offset:96
	global_load_dwordx4 v[76:79], v101, s[24:25]
	global_load_dwordx4 v[84:87], v101, s[24:25] offset:16
	s_nop 0
	s_nop 0
	s_nop 0
	s_nop 0
	v_or_b32_e32 v88, v100, v149
	v_lshlrev_b32_e32 v94, 3, v88
	v_mad_i64_i32 v[88:89], s[6:7], v144, s60, v[134:135]
	v_lshl_add_u64 v[88:89], v[88:89], 0, v[130:131]
	s_waitcnt vmcnt(4)
	v_fmamk_f32 v92, v190, 0x3b2aaaab, v150
	s_waitcnt vmcnt(1)
	v_mov_b32_e32 v90, v76
	v_mul_f32_e32 v76, 0x4b800000, v92
	v_cmp_gt_f32_e32 vcc, s61, v92
	v_mov_b32_e32 v91, v78
	v_mov_b32_e32 v78, v77
	v_cndmask_b32_e32 v76, v92, v76, vcc
	v_rsq_f32_e32 v92, v76
	s_waitcnt vmcnt(0)
	v_mov_b32_e32 v76, v84
	v_mov_b32_e32 v77, v86
	v_mov_b32_e32 v86, v85
	v_mul_f32_e32 v84, 0x45800000, v92
	v_cndmask_b32_e32 v84, v92, v84, vcc
	v_mov_b32_e32 v168, v84
	v_pk_mul_f32 v[80:81], v[80:81], v[84:85] op_sel_hi:[1,0]
	v_pk_mul_f32 v[72:73], v[72:73], v[168:169] op_sel_hi:[1,0]
	v_pk_mul_f32 v[74:75], v[74:75], v[168:169] op_sel_hi:[1,0]
	v_pk_mul_f32 v[82:83], v[82:83], v[168:169] op_sel_hi:[1,0]
	v_pk_mul_f32 v[84:85], v[78:79], v[72:73]
	v_pk_mul_f32 v[78:79], v[78:79], v[80:81]
	v_pk_mul_f32 v[92:93], v[86:87], v[74:75]
	v_pk_mul_f32 v[86:87], v[82:83], v[86:87]
	v_pk_fma_f32 v[80:81], v[90:91], v[80:81], v[84:85] neg_lo:[0,0,1] neg_hi:[0,0,1]
	v_pk_fma_f32 v[72:73], v[90:91], v[72:73], v[78:79]
	v_pk_fma_f32 v[78:79], v[76:77], v[82:83], v[92:93] neg_lo:[0,0,1] neg_hi:[0,0,1]
	v_pk_fma_f32 v[74:75], v[74:75], v[76:77], v[86:87]
	v_cvt_pk_bf16_f32 v76, v80, v81
	v_cvt_pk_bf16_f32 v77, v78, v79
	v_cvt_pk_bf16_f32 v72, v72, v73
	v_cvt_pk_bf16_f32 v73, v74, v75
	global_store_dwordx2 v[88:89], v[76:77], off
	global_store_dwordx2 v[88:89], v[72:73], off offset:64
	global_load_dwordx4 v[72:75], v94, s[24:25]
	global_load_dwordx4 v[76:79], v94, s[24:25] offset:16
	global_load_dword v190, v[132:133], off offset:256
	s_nop 0
	s_nop 0
	s_nop 0
	v_lshlrev_b32_e32 v81, 5, v143
	v_and_b32_e32 v84, 0x1f9e0, v81
	v_or_b32_e32 v81, v84, v128
	v_lshlrev_b32_e32 v85, 3, v81
	s_waitcnt vmcnt(2)
	v_mov_b32_e32 v80, v72
	v_mov_b32_e32 v81, v74
	v_mov_b32_e32 v74, v73
	s_waitcnt vmcnt(1)
	v_mov_b32_e32 v72, v76
	v_mov_b32_e32 v73, v78
	v_mov_b32_e32 v78, v77
	v_pk_mul_f32 v[60:61], v[60:61], v[168:169] op_sel_hi:[1,0]
	v_pk_mul_f32 v[62:63], v[62:63], v[168:169] op_sel_hi:[1,0]
	v_pk_mul_f32 v[68:69], v[68:69], v[168:169] op_sel_hi:[1,0]
	v_pk_mul_f32 v[70:71], v[70:71], v[168:169] op_sel_hi:[1,0]
	v_pk_mul_f32 v[76:77], v[74:75], v[60:61]
	v_pk_mul_f32 v[82:83], v[78:79], v[62:63]
	v_pk_mul_f32 v[74:75], v[74:75], v[68:69]
	v_pk_mul_f32 v[78:79], v[70:71], v[78:79]
	v_pk_fma_f32 v[68:69], v[80:81], v[68:69], v[76:77] neg_lo:[0,0,1] neg_hi:[0,0,1]
	v_pk_fma_f32 v[70:71], v[72:73], v[70:71], v[82:83] neg_lo:[0,0,1] neg_hi:[0,0,1]
	v_pk_fma_f32 v[60:61], v[80:81], v[60:61], v[74:75]
	v_pk_fma_f32 v[62:63], v[62:63], v[72:73], v[78:79]
	v_cvt_pk_bf16_f32 v68, v68, v69
	v_cvt_pk_bf16_f32 v69, v70, v71
	v_cvt_pk_bf16_f32 v60, v60, v61
	v_cvt_pk_bf16_f32 v61, v62, v63
	global_store_dwordx2 v[88:89], v[68:69], off offset:32
	global_store_dwordx2 v[88:89], v[60:61], off offset:96
	global_load_dwordx4 v[60:63], v85, s[24:25]
	global_load_dwordx4 v[68:71], v85, s[24:25] offset:16
	s_nop 0
	s_nop 0
	s_nop 0
	s_nop 0
	v_or_b32_e32 v72, v84, v149
	v_lshlrev_b32_e32 v78, 3, v72
	v_mad_i64_i32 v[72:73], s[6:7], v143, s60, v[134:135]
	v_lshl_add_u64 v[72:73], v[72:73], 0, v[130:131]
	s_waitcnt vmcnt(4)
	v_fmamk_f32 v76, v190, 0x3b2aaaab, v150
	s_waitcnt vmcnt(1)
	v_mov_b32_e32 v74, v60
	v_mul_f32_e32 v60, 0x4b800000, v76
	v_cmp_gt_f32_e32 vcc, s61, v76
	v_mov_b32_e32 v75, v62
	v_mov_b32_e32 v62, v61
	v_cndmask_b32_e32 v60, v76, v60, vcc
	v_rsq_f32_e32 v76, v60
	s_waitcnt vmcnt(0)
	v_mov_b32_e32 v60, v68
	v_mov_b32_e32 v61, v70
	v_mov_b32_e32 v70, v69
	v_mul_f32_e32 v68, 0x45800000, v76
	v_cndmask_b32_e32 v68, v76, v68, vcc
	v_mov_b32_e32 v170, v68
	v_pk_mul_f32 v[64:65], v[64:65], v[68:69] op_sel_hi:[1,0]
	v_pk_mul_f32 v[56:57], v[56:57], v[170:171] op_sel_hi:[1,0]
	v_pk_mul_f32 v[58:59], v[58:59], v[170:171] op_sel_hi:[1,0]
	v_pk_mul_f32 v[66:67], v[66:67], v[170:171] op_sel_hi:[1,0]
	v_pk_mul_f32 v[68:69], v[62:63], v[56:57]
	v_pk_mul_f32 v[62:63], v[62:63], v[64:65]
	v_pk_mul_f32 v[76:77], v[70:71], v[58:59]
	v_pk_mul_f32 v[70:71], v[66:67], v[70:71]
	v_pk_fma_f32 v[64:65], v[74:75], v[64:65], v[68:69] neg_lo:[0,0,1] neg_hi:[0,0,1]
	v_pk_fma_f32 v[56:57], v[74:75], v[56:57], v[62:63]
	v_pk_fma_f32 v[62:63], v[60:61], v[66:67], v[76:77] neg_lo:[0,0,1] neg_hi:[0,0,1]
	v_pk_fma_f32 v[58:59], v[58:59], v[60:61], v[70:71]
	v_cvt_pk_bf16_f32 v60, v64, v65
	v_cvt_pk_bf16_f32 v61, v62, v63
	v_cvt_pk_bf16_f32 v56, v56, v57
	v_cvt_pk_bf16_f32 v57, v58, v59
	global_store_dwordx2 v[72:73], v[60:61], off
	global_store_dwordx2 v[72:73], v[56:57], off offset:64
	global_load_dwordx4 v[56:59], v78, s[24:25]
	global_load_dwordx4 v[60:63], v78, s[24:25] offset:16
	global_load_dword v190, v[132:133], off offset:320
	s_nop 0
	s_nop 0
	s_nop 0
	v_lshlrev_b32_e32 v65, 5, v142
	v_and_b32_e32 v68, 0x1fbe0, v65
	v_or_b32_e32 v65, v68, v128
	v_lshlrev_b32_e32 v69, 3, v65
	s_waitcnt vmcnt(2)
; DI u32x2 pack4(float a, float b, float c, float d) { u32x2 r; r.x = pack2(a, b); r.y = pack2(c, d); return r; }
; DI float rstd_of(const float* ssq, int m, float invn) { return rsqrtf(ssq[m] * invn + 1e-6f); }
; template <int MODE>
; DI void gemm_phase(const Params& p, const GP& g, unsigned char* smem) {
;     ...
;         for (int j = 0; j < 8; ++j)
; #pragma unroll
;           for (int i = 0; i < 2; ++i) {
;             const int m = m0 + wy * 128 + j * 16 + lq, pos = m & 4095;
;             const float rs = rstd_of(g.ssq_in, m, 1.f / 384);
;             const int f0 = i * 16 + lg * 4;
;             const f32x4 a = acc[i][j], bq = acc[i + 2][j];
;             float lo[4], hi[4];
; #pragma unroll
;             for (int r = 0; r < 4; ++r) {
;               const float2 cssn = *(const float2*)(p.rope + ((long)pos * 32 + f0 + r) * 2);
;               const float x1 = a[r] * rs, x2 = bq[r] * rs;
;               lo[r] = x1 * cssn.x - x2 * cssn.y;
;               hi[r] = x1 * cssn.y + x2 * cssn.x;
;             }
;             *(u32x2*)(qo + (long)m * 1536 + slab * 64 + f0) = pack4(lo[0], lo[1], lo[2], lo[3]);
;             *(u32x2*)(qo + (long)m * 1536 + slab * 64 + 32 + f0) = pack4(hi[0], hi[1], hi[2], hi[3]);
;           }
	v_mov_b32_e32 v64, v56
	v_mov_b32_e32 v65, v58
	v_mov_b32_e32 v58, v57
	s_waitcnt vmcnt(1)
	v_mov_b32_e32 v56, v60
	v_mov_b32_e32 v57, v62
	v_mov_b32_e32 v62, v61
	v_pk_mul_f32 v[44:45], v[44:45], v[170:171] op_sel_hi:[1,0]
	v_pk_mul_f32 v[46:47], v[46:47], v[170:171] op_sel_hi:[1,0]
	v_pk_mul_f32 v[52:53], v[52:53], v[170:171] op_sel_hi:[1,0]
	v_pk_mul_f32 v[54:55], v[54:55], v[170:171] op_sel_hi:[1,0]
	v_pk_mul_f32 v[60:61], v[58:59], v[44:45]
	v_pk_mul_f32 v[66:67], v[62:63], v[46:47]
	v_pk_mul_f32 v[58:59], v[58:59], v[52:53]
	v_pk_mul_f32 v[62:63], v[54:55], v[62:63]
	v_pk_fma_f32 v[52:53], v[64:65], v[52:53], v[60:61] neg_lo:[0,0,1] neg_hi:[0,0,1]
	v_pk_fma_f32 v[54:55], v[56:57], v[54:55], v[66:67] neg_lo:[0,0,1] neg_hi:[0,0,1]
	v_pk_fma_f32 v[44:45], v[64:65], v[44:45], v[58:59]
	v_pk_fma_f32 v[46:47], v[46:47], v[56:57], v[62:63]
	v_cvt_pk_bf16_f32 v52, v52, v53
	v_cvt_pk_bf16_f32 v53, v54, v55
	v_cvt_pk_bf16_f32 v44, v44, v45
	v_cvt_pk_bf16_f32 v45, v46, v47
	global_store_dwordx2 v[72:73], v[52:53], off offset:32
	global_store_dwordx2 v[72:73], v[44:45], off offset:96
	global_load_dwordx4 v[44:47], v69, s[24:25]
	global_load_dwordx4 v[52:55], v69, s[24:25] offset:16
	s_nop 0
	s_nop 0
	s_nop 0
	s_nop 0
	v_or_b32_e32 v56, v68, v149
	v_lshlrev_b32_e32 v62, 3, v56
	v_mad_i64_i32 v[56:57], s[6:7], v142, s60, v[134:135]
	v_lshl_add_u64 v[56:57], v[56:57], 0, v[130:131]
	s_waitcnt vmcnt(4)
	v_fmamk_f32 v60, v190, 0x3b2aaaab, v150
	s_waitcnt vmcnt(1)
	v_mov_b32_e32 v58, v44
	v_mul_f32_e32 v44, 0x4b800000, v60
	v_cmp_gt_f32_e32 vcc, s61, v60
	v_mov_b32_e32 v59, v46
	v_mov_b32_e32 v46, v45
	v_cndmask_b32_e32 v44, v60, v44, vcc
	v_rsq_f32_e32 v60, v44
	s_waitcnt vmcnt(0)
	v_mov_b32_e32 v44, v52
	v_mov_b32_e32 v45, v54
	v_mov_b32_e32 v54, v53
	v_mul_f32_e32 v52, 0x45800000, v60
	v_cndmask_b32_e32 v52, v60, v52, vcc
	v_mov_b32_e32 v172, v52
	v_pk_mul_f32 v[48:49], v[48:49], v[52:53] op_sel_hi:[1,0]
	v_pk_mul_f32 v[40:41], v[40:41], v[172:173] op_sel_hi:[1,0]
	v_pk_mul_f32 v[42:43], v[42:43], v[172:173] op_sel_hi:[1,0]
	v_pk_mul_f32 v[50:51], v[50:51], v[172:173] op_sel_hi:[1,0]
	v_pk_mul_f32 v[52:53], v[46:47], v[40:41]
	v_pk_mul_f32 v[46:47], v[46:47], v[48:49]
	v_pk_mul_f32 v[60:61], v[54:55], v[42:43]
	v_pk_mul_f32 v[54:55], v[50:51], v[54:55]
	v_pk_fma_f32 v[48:49], v[58:59], v[48:49], v[52:53] neg_lo:[0,0,1] neg_hi:[0,0,1]
	v_pk_fma_f32 v[40:41], v[58:59], v[40:41], v[46:47]
	v_pk_fma_f32 v[46:47], v[44:45], v[50:51], v[60:61] neg_lo:[0,0,1] neg_hi:[0,0,1]
	v_pk_fma_f32 v[42:43], v[42:43], v[44:45], v[54:55]
	v_cvt_pk_bf16_f32 v44, v48, v49
	v_cvt_pk_bf16_f32 v45, v46, v47
	v_cvt_pk_bf16_f32 v40, v40, v41
	v_cvt_pk_bf16_f32 v41, v42, v43
	global_store_dwordx2 v[56:57], v[44:45], off
	global_store_dwordx2 v[56:57], v[40:41], off offset:64
	global_load_dwordx4 v[40:43], v62, s[24:25]
	global_load_dwordx4 v[44:47], v62, s[24:25] offset:16
	global_load_dword v190, v[132:133], off offset:384
	s_nop 0
	s_nop 0
	s_nop 0
	v_lshlrev_b32_e32 v49, 5, v141
	v_and_b32_e32 v52, 0x1fde0, v49
	v_or_b32_e32 v49, v52, v128
	v_lshlrev_b32_e32 v53, 3, v49
	s_waitcnt vmcnt(2)
	v_mov_b32_e32 v48, v40
	v_mov_b32_e32 v49, v42
	v_mov_b32_e32 v42, v41
	s_waitcnt vmcnt(1)
	v_mov_b32_e32 v40, v44
	v_mov_b32_e32 v41, v46
	v_mov_b32_e32 v46, v45
	v_pk_mul_f32 v[28:29], v[28:29], v[172:173] op_sel_hi:[1,0]
	v_pk_mul_f32 v[30:31], v[30:31], v[172:173] op_sel_hi:[1,0]
	v_pk_mul_f32 v[36:37], v[36:37], v[172:173] op_sel_hi:[1,0]
	v_pk_mul_f32 v[38:39], v[38:39], v[172:173] op_sel_hi:[1,0]
	v_pk_mul_f32 v[44:45], v[42:43], v[28:29]
	v_pk_mul_f32 v[50:51], v[46:47], v[30:31]
	v_pk_mul_f32 v[42:43], v[42:43], v[36:37]
	v_pk_mul_f32 v[46:47], v[38:39], v[46:47]
	v_pk_fma_f32 v[36:37], v[48:49], v[36:37], v[44:45] neg_lo:[0,0,1] neg_hi:[0,0,1]
	v_pk_fma_f32 v[38:39], v[40:41], v[38:39], v[50:51] neg_lo:[0,0,1] neg_hi:[0,0,1]
	v_pk_fma_f32 v[28:29], v[48:49], v[28:29], v[42:43]
	v_pk_fma_f32 v[30:31], v[30:31], v[40:41], v[46:47]
	v_cvt_pk_bf16_f32 v36, v36, v37
	v_cvt_pk_bf16_f32 v37, v38, v39
	v_cvt_pk_bf16_f32 v28, v28, v29
	v_cvt_pk_bf16_f32 v29, v30, v31
	global_store_dwordx2 v[56:57], v[36:37], off offset:32
	global_store_dwordx2 v[56:57], v[28:29], off offset:96
	global_load_dwordx4 v[28:31], v53, s[24:25]
	global_load_dwordx4 v[36:39], v53, s[24:25] offset:16
	s_nop 0
	s_nop 0
	s_nop 0
	s_nop 0
	v_or_b32_e32 v40, v52, v149
	v_lshlrev_b32_e32 v46, 3, v40
	v_mad_i64_i32 v[40:41], s[6:7], v141, s60, v[134:135]
	v_lshl_add_u64 v[40:41], v[40:41], 0, v[130:131]
	s_waitcnt vmcnt(4)
	v_fmamk_f32 v44, v190, 0x3b2aaaab, v150
	s_waitcnt vmcnt(1)
	v_mov_b32_e32 v42, v28
	v_mul_f32_e32 v28, 0x4b800000, v44
	v_cmp_gt_f32_e32 vcc, s61, v44
	v_mov_b32_e32 v43, v30
	v_mov_b32_e32 v30, v29
	v_cndmask_b32_e32 v28, v44, v28, vcc
	v_rsq_f32_e32 v44, v28
	s_waitcnt vmcnt(0)
; DI u32x2 pack4(float a, float b, float c, float d) { u32x2 r; r.x = pack2(a, b); r.y = pack2(c, d); return r; }
; DI float rstd_of(const float* ssq, int m, float invn) { return rsqrtf(ssq[m] * invn + 1e-6f); }
; template <int MODE>
; DI void gemm_phase(const Params& p, const GP& g, unsigned char* smem) {
;     ...
;         for (int j = 0; j < 8; ++j)
; #pragma unroll
;           for (int i = 0; i < 2; ++i) {
;             const int m = m0 + wy * 128 + j * 16 + lq, pos = m & 4095;
;             const float rs = rstd_of(g.ssq_in, m, 1.f / 384);
;             const int f0 = i * 16 + lg * 4;
;             const f32x4 a = acc[i][j], bq = acc[i + 2][j];
;             float lo[4], hi[4];
; #pragma unroll
;             for (int r = 0; r < 4; ++r) {
;               const float2 cssn = *(const float2*)(p.rope + ((long)pos * 32 + f0 + r) * 2);
;               const float x1 = a[r] * rs, x2 = bq[r] * rs;
;               lo[r] = x1 * cssn.x - x2 * cssn.y;
;               hi[r] = x1 * cssn.y + x2 * cssn.x;
;             }
;             *(u32x2*)(qo + (long)m * 1536 + slab * 64 + f0) = pack4(lo[0], lo[1], lo[2], lo[3]);
;             *(u32x2*)(qo + (long)m * 1536 + slab * 64 + 32 + f0) = pack4(hi[0], hi[1], hi[2], hi[3]);
;           }
	v_mov_b32_e32 v28, v36
	v_mov_b32_e32 v29, v38
	v_mov_b32_e32 v38, v37
	v_mul_f32_e32 v36, 0x45800000, v44
	v_cndmask_b32_e32 v36, v44, v36, vcc
	v_mov_b32_e32 v174, v36
	v_pk_mul_f32 v[32:33], v[32:33], v[36:37] op_sel_hi:[1,0]
	v_pk_mul_f32 v[24:25], v[24:25], v[174:175] op_sel_hi:[1,0]
	v_pk_mul_f32 v[26:27], v[26:27], v[174:175] op_sel_hi:[1,0]
	v_pk_mul_f32 v[34:35], v[34:35], v[174:175] op_sel_hi:[1,0]
	v_pk_mul_f32 v[36:37], v[30:31], v[24:25]
	v_pk_mul_f32 v[30:31], v[30:31], v[32:33]
	v_pk_mul_f32 v[44:45], v[38:39], v[26:27]
	v_pk_mul_f32 v[38:39], v[34:35], v[38:39]
	v_pk_fma_f32 v[32:33], v[42:43], v[32:33], v[36:37] neg_lo:[0,0,1] neg_hi:[0,0,1]
	v_pk_fma_f32 v[24:25], v[42:43], v[24:25], v[30:31]
	v_pk_fma_f32 v[30:31], v[28:29], v[34:35], v[44:45] neg_lo:[0,0,1] neg_hi:[0,0,1]
	v_pk_fma_f32 v[26:27], v[26:27], v[28:29], v[38:39]
	v_cvt_pk_bf16_f32 v28, v32, v33
	v_cvt_pk_bf16_f32 v29, v30, v31
	v_cvt_pk_bf16_f32 v24, v24, v25
	v_cvt_pk_bf16_f32 v25, v26, v27
	global_store_dwordx2 v[40:41], v[28:29], off
	global_store_dwordx2 v[40:41], v[24:25], off offset:64
	global_load_dwordx4 v[24:27], v46, s[24:25]
	global_load_dwordx4 v[28:31], v46, s[24:25] offset:16
	global_load_dword v190, v[132:133], off offset:448
	s_nop 0
	s_nop 0
	s_nop 0
	v_lshlrev_b32_e32 v33, 5, v140
	v_and_b32_e32 v36, 0x1ffe0, v33
	v_or_b32_e32 v33, v36, v128
	v_lshlrev_b32_e32 v37, 3, v33
	s_waitcnt vmcnt(2)
	v_mov_b32_e32 v32, v24
	v_mov_b32_e32 v33, v26
	v_mov_b32_e32 v26, v25
	s_waitcnt vmcnt(1)
	v_mov_b32_e32 v24, v28
	v_mov_b32_e32 v25, v30
	v_mov_b32_e32 v30, v29
	v_pk_mul_f32 v[12:13], v[12:13], v[174:175] op_sel_hi:[1,0]
	v_pk_mul_f32 v[14:15], v[14:15], v[174:175] op_sel_hi:[1,0]
	v_pk_mul_f32 v[20:21], v[20:21], v[174:175] op_sel_hi:[1,0]
	v_pk_mul_f32 v[22:23], v[22:23], v[174:175] op_sel_hi:[1,0]
	v_pk_mul_f32 v[28:29], v[26:27], v[12:13]
	v_pk_mul_f32 v[34:35], v[30:31], v[14:15]
	v_pk_mul_f32 v[26:27], v[26:27], v[20:21]
	v_pk_mul_f32 v[30:31], v[22:23], v[30:31]
	v_pk_fma_f32 v[20:21], v[32:33], v[20:21], v[28:29] neg_lo:[0,0,1] neg_hi:[0,0,1]
	v_pk_fma_f32 v[22:23], v[24:25], v[22:23], v[34:35] neg_lo:[0,0,1] neg_hi:[0,0,1]
	v_pk_fma_f32 v[12:13], v[32:33], v[12:13], v[26:27]
	v_pk_fma_f32 v[14:15], v[14:15], v[24:25], v[30:31]
	v_cvt_pk_bf16_f32 v20, v20, v21
	v_cvt_pk_bf16_f32 v21, v22, v23
	v_cvt_pk_bf16_f32 v12, v12, v13
	v_cvt_pk_bf16_f32 v13, v14, v15
	global_store_dwordx2 v[40:41], v[20:21], off offset:32
	global_store_dwordx2 v[40:41], v[12:13], off offset:96
	global_load_dwordx4 v[12:15], v37, s[24:25]
	global_load_dwordx4 v[20:23], v37, s[24:25] offset:16
	global_load_dword v191, v[132:133], off offset:448
	s_nop 0
	s_nop 0
	s_nop 0
	s_nop 0
	v_or_b32_e32 v24, v36, v149
	v_lshlrev_b32_e32 v30, 3, v24
	v_mad_i64_i32 v[24:25], s[6:7], v140, s60, v[134:135]
	v_lshl_add_u64 v[24:25], v[24:25], 0, v[130:131]
	s_waitcnt vmcnt(5)
	v_fmamk_f32 v28, v190, 0x3b2aaaab, v150
	s_waitcnt vmcnt(2)
	v_mov_b32_e32 v26, v12
	v_mul_f32_e32 v12, 0x4b800000, v28
	v_cmp_gt_f32_e32 vcc, s61, v28
	v_mov_b32_e32 v27, v14
	v_mov_b32_e32 v14, v13
	v_cndmask_b32_e32 v12, v28, v12, vcc
	v_rsq_f32_e32 v28, v12
	s_waitcnt vmcnt(1)
	v_mov_b32_e32 v12, v20
	v_mov_b32_e32 v13, v22
	v_mov_b32_e32 v22, v21
	v_mul_f32_e32 v20, 0x45800000, v28
	v_cndmask_b32_e32 v20, v28, v20, vcc
	v_mov_b32_e32 v176, v20
	v_pk_mul_f32 v[16:17], v[16:17], v[20:21] op_sel_hi:[1,0]
	v_pk_mul_f32 v[4:5], v[4:5], v[176:177] op_sel_hi:[1,0]
	v_pk_mul_f32 v[6:7], v[6:7], v[176:177] op_sel_hi:[1,0]
	v_pk_mul_f32 v[18:19], v[18:19], v[176:177] op_sel_hi:[1,0]
	v_pk_mul_f32 v[20:21], v[14:15], v[4:5]
	v_pk_mul_f32 v[14:15], v[14:15], v[16:17]
	v_pk_mul_f32 v[28:29], v[22:23], v[6:7]
	v_pk_mul_f32 v[22:23], v[18:19], v[22:23]
	v_pk_fma_f32 v[16:17], v[26:27], v[16:17], v[20:21] neg_lo:[0,0,1] neg_hi:[0,0,1]
	v_pk_fma_f32 v[4:5], v[26:27], v[4:5], v[14:15]
	v_pk_fma_f32 v[14:15], v[12:13], v[18:19], v[28:29] neg_lo:[0,0,1] neg_hi:[0,0,1]
	v_pk_fma_f32 v[6:7], v[6:7], v[12:13], v[22:23]
	v_cvt_pk_bf16_f32 v12, v16, v17
	v_cvt_pk_bf16_f32 v13, v14, v15
	v_cvt_pk_bf16_f32 v4, v4, v5
	v_cvt_pk_bf16_f32 v5, v6, v7
	global_store_dwordx2 v[24:25], v[12:13], off
	global_store_dwordx2 v[24:25], v[4:5], off offset:64
	global_load_dwordx4 v[4:7], v30, s[24:25]
	global_load_dwordx4 v[12:15], v30, s[24:25] offset:16
	s_nop 0
	s_nop 0
	s_nop 0
	s_nop 0
	s_waitcnt vmcnt(4)
	v_fmamk_f32 v18, v191, 0x3b2aaaab, v150
	s_waitcnt vmcnt(1)
	v_mov_b32_e32 v16, v4
	v_cmp_gt_f32_e32 vcc, s61, v18
	v_mov_b32_e32 v17, v6
	v_mov_b32_e32 v6, v5
	s_waitcnt vmcnt(0)
	v_mov_b32_e32 v4, v12
	v_mov_b32_e32 v5, v14
	v_mov_b32_e32 v14, v13
	v_pk_mul_f32 v[8:9], v[8:9], v[176:177] op_sel_hi:[1,0]
	v_pk_mul_f32 v[10:11], v[10:11], v[176:177] op_sel_hi:[1,0]
	v_pk_mul_f32 v[0:1], v[0:1], v[176:177] op_sel_hi:[1,0]
	v_pk_mul_f32 v[2:3], v[2:3], v[176:177] op_sel_hi:[1,0]
	v_pk_mul_f32 v[12:13], v[6:7], v[8:9]
	v_pk_mul_f32 v[18:19], v[14:15], v[10:11]
	v_pk_mul_f32 v[6:7], v[6:7], v[0:1]
	v_pk_mul_f32 v[14:15], v[2:3], v[14:15]
	v_pk_fma_f32 v[0:1], v[16:17], v[0:1], v[12:13] neg_lo:[0,0,1] neg_hi:[0,0,1]
	v_pk_fma_f32 v[2:3], v[4:5], v[2:3], v[18:19] neg_lo:[0,0,1] neg_hi:[0,0,1]
	v_pk_fma_f32 v[6:7], v[16:17], v[8:9], v[6:7]
	v_pk_fma_f32 v[4:5], v[10:11], v[4:5], v[14:15]
	v_cvt_pk_bf16_f32 v0, v0, v1
	v_cvt_pk_bf16_f32 v1, v2, v3
	v_cvt_pk_bf16_f32 v2, v6, v7
	v_cvt_pk_bf16_f32 v3, v4, v5
	global_store_dwordx2 v[24:25], v[0:1], off offset:32
	global_store_dwordx2 v[24:25], v[2:3], off offset:96
	s_branch .LBB0_389

; DI u32x2 pack4(float a, float b, float c, float d) { u32x2 r; r.x = pack2(a, b); r.y = pack2(c, d); return r; }
; #define EPI_END if (i == 3 && (j & 3) == 3) __builtin_amdgcn_sched_barrier(0); }
; DI float rstd_of(const float* ssq, int m, float invn) { return rsqrtf(ssq[m] * invn + 1e-6f); }
; template <int MODE>
; DI void gemm_phase(const Params& p, const GP& g, unsigned char* smem) {
;     ...
;         u16* kn = (u16*)g.d0;
;         EPI_STD_BEGIN
;           const float rs = rstd_of(g.ssq_in, m, 1.f / 256);
;           *(u32x2*)(kn + (long)m * 1024 + n4) = pack4(v[0] * rs, v[1] * rs, v[2] * rs, v[3] * rs);
;         EPI_END
.LBB0_414:
	v_or_b32_e32 v132, s12, v148
	v_ashrrev_i32_e32 v133, 31, v132
	v_lshl_add_u64 v[130:131], v[132:133], 2, s[30:31]
	global_load_dword v128, v[130:131], off
	global_load_dword v178, v[130:131], off offset:64
	global_load_dword v179, v[130:131], off offset:128
	global_load_dword v184, v[130:131], off offset:192
	global_load_dword v185, v[130:131], off offset:256
	global_load_dword v186, v[130:131], off offset:320
	global_load_dword v187, v[130:131], off offset:384
	global_load_dword v188, v[130:131], off offset:448
	v_lshlrev_b64 v[136:137], 11, v[132:133]
	v_add_u32_e32 v134, s6, v147
	v_ashrrev_i32_e32 v135, 31, v134
	v_lshlrev_b64 v[134:135], 1, v[134:135]
	v_lshl_add_u64 v[136:137], s[24:25], 0, v[136:137]
	v_lshl_add_u64 v[136:137], v[136:137], 0, v[134:135]
	s_waitcnt vmcnt(7)
	v_fmamk_f32 v128, v128, 0x3b800000, v150
	global_load_dword v189, v[130:131], off offset:448
	v_mul_f32_e32 v133, 0x4b800000, v128
	v_cmp_gt_f32_e32 vcc, s74, v128
	s_nop 1
	v_cndmask_b32_e32 v128, v128, v133, vcc
	v_rsq_f32_e32 v128, v128
	s_nop 0
	v_mul_f32_e32 v133, 0x45800000, v128
	v_cndmask_b32_e32 v128, v128, v133, vcc
	v_mov_b32_e32 v154, v128
	v_pk_mul_f32 v[138:139], v[124:125], v[128:129] op_sel_hi:[1,0]
	v_pk_mul_f32 v[140:141], v[126:127], v[154:155] op_sel_hi:[1,0]
	v_cvt_pk_bf16_f32 v138, v138, v139
	v_cvt_pk_bf16_f32 v139, v140, v141
	global_store_dwordx2 v[136:137], v[138:139], off
	s_nop 1
	s_nop 0
	v_pk_mul_f32 v[138:139], v[120:121], v[154:155] op_sel_hi:[1,0]
	v_pk_mul_f32 v[140:141], v[122:123], v[154:155] op_sel_hi:[1,0]
	v_cvt_pk_bf16_f32 v138, v138, v139
	v_cvt_pk_bf16_f32 v139, v140, v141
	global_store_dwordx2 v[136:137], v[138:139], off offset:32
	s_nop 1
	s_nop 0
	v_pk_mul_f32 v[138:139], v[116:117], v[154:155] op_sel_hi:[1,0]
	v_pk_mul_f32 v[140:141], v[118:119], v[154:155] op_sel_hi:[1,0]
	v_cvt_pk_bf16_f32 v138, v138, v139
	v_cvt_pk_bf16_f32 v139, v140, v141
	global_store_dwordx2 v[136:137], v[138:139], off offset:64
	s_nop 1
	s_nop 0
	v_pk_mul_f32 v[138:139], v[108:109], v[154:155] op_sel_hi:[1,0]
	v_pk_mul_f32 v[140:141], v[110:111], v[154:155] op_sel_hi:[1,0]
	v_cvt_pk_bf16_f32 v138, v138, v139
	v_cvt_pk_bf16_f32 v139, v140, v141
	global_store_dwordx2 v[136:137], v[138:139], off offset:96
	s_nop 0
	v_or_b32_e32 v136, 16, v132
	v_ashrrev_i32_e32 v137, 31, v136
	v_lshlrev_b64 v[136:137], 11, v[136:137]
	v_lshl_add_u64 v[136:137], s[24:25], 0, v[136:137]
	v_lshl_add_u64 v[136:137], v[136:137], 0, v[134:135]
	s_waitcnt vmcnt(11)
	v_fmamk_f32 v128, v178, 0x3b800000, v150
	v_mul_f32_e32 v133, 0x4b800000, v128
	v_cmp_gt_f32_e32 vcc, s74, v128
	s_nop 1
	v_cndmask_b32_e32 v128, v128, v133, vcc
	v_rsq_f32_e32 v128, v128
	s_nop 0
	v_mul_f32_e32 v133, 0x45800000, v128
	v_cndmask_b32_e32 v128, v128, v133, vcc
	v_mov_b32_e32 v156, v128
	v_pk_mul_f32 v[138:139], v[112:113], v[128:129] op_sel_hi:[1,0]
	v_pk_mul_f32 v[140:141], v[114:115], v[156:157] op_sel_hi:[1,0]
	v_cvt_pk_bf16_f32 v138, v138, v139
	v_cvt_pk_bf16_f32 v139, v140, v141
	global_store_dwordx2 v[136:137], v[138:139], off
	s_nop 1
	s_nop 0
	v_pk_mul_f32 v[138:139], v[104:105], v[156:157] op_sel_hi:[1,0]
	v_pk_mul_f32 v[140:141], v[106:107], v[156:157] op_sel_hi:[1,0]
	v_cvt_pk_bf16_f32 v138, v138, v139
	v_cvt_pk_bf16_f32 v139, v140, v141
	global_store_dwordx2 v[136:137], v[138:139], off offset:32
	s_nop 1
	s_nop 0
	v_pk_mul_f32 v[138:139], v[100:101], v[156:157] op_sel_hi:[1,0]
	v_pk_mul_f32 v[140:141], v[102:103], v[156:157] op_sel_hi:[1,0]
	v_cvt_pk_bf16_f32 v138, v138, v139
	v_cvt_pk_bf16_f32 v139, v140, v141
	global_store_dwordx2 v[136:137], v[138:139], off offset:64
	s_nop 1
	s_nop 0
	v_pk_mul_f32 v[138:139], v[92:93], v[156:157] op_sel_hi:[1,0]
	v_pk_mul_f32 v[140:141], v[94:95], v[156:157] op_sel_hi:[1,0]
	v_cvt_pk_bf16_f32 v138, v138, v139
	v_cvt_pk_bf16_f32 v139, v140, v141
	global_store_dwordx2 v[136:137], v[138:139], off offset:96
	s_nop 0
	v_or_b32_e32 v136, 32, v132
	v_ashrrev_i32_e32 v137, 31, v136
	v_lshlrev_b64 v[136:137], 11, v[136:137]
	v_lshl_add_u64 v[136:137], s[24:25], 0, v[136:137]
	v_lshl_add_u64 v[136:137], v[136:137], 0, v[134:135]
	s_waitcnt vmcnt(14)
	v_fmamk_f32 v128, v179, 0x3b800000, v150
	v_mul_f32_e32 v133, 0x4b800000, v128
	v_cmp_gt_f32_e32 vcc, s74, v128
	s_nop 1
	v_cndmask_b32_e32 v128, v128, v133, vcc
	v_rsq_f32_e32 v128, v128
	s_nop 0
	v_mul_f32_e32 v133, 0x45800000, v128
	v_cndmask_b32_e32 v128, v128, v133, vcc
	v_mov_b32_e32 v158, v128
	v_pk_mul_f32 v[138:139], v[96:97], v[128:129] op_sel_hi:[1,0]
	v_pk_mul_f32 v[140:141], v[98:99], v[158:159] op_sel_hi:[1,0]
	v_cvt_pk_bf16_f32 v138, v138, v139
	v_cvt_pk_bf16_f32 v139, v140, v141
	global_store_dwordx2 v[136:137], v[138:139], off
	s_nop 1
	s_nop 0
	v_pk_mul_f32 v[138:139], v[88:89], v[158:159] op_sel_hi:[1,0]
	v_pk_mul_f32 v[140:141], v[90:91], v[158:159] op_sel_hi:[1,0]
	v_cvt_pk_bf16_f32 v138, v138, v139
	v_cvt_pk_bf16_f32 v139, v140, v141
	global_store_dwordx2 v[136:137], v[138:139], off offset:32
	s_nop 1
	s_nop 0
	v_pk_mul_f32 v[138:139], v[84:85], v[158:159] op_sel_hi:[1,0]
	v_pk_mul_f32 v[140:141], v[86:87], v[158:159] op_sel_hi:[1,0]
	v_cvt_pk_bf16_f32 v138, v138, v139
	v_cvt_pk_bf16_f32 v139, v140, v141
	global_store_dwordx2 v[136:137], v[138:139], off offset:64
	s_nop 1
	s_nop 0
	v_pk_mul_f32 v[138:139], v[76:77], v[158:159] op_sel_hi:[1,0]
	v_pk_mul_f32 v[140:141], v[78:79], v[158:159] op_sel_hi:[1,0]
	v_cvt_pk_bf16_f32 v138, v138, v139
	v_cvt_pk_bf16_f32 v139, v140, v141
	global_store_dwordx2 v[136:137], v[138:139], off offset:96
	s_nop 0
	v_or_b32_e32 v136, 48, v132
	v_ashrrev_i32_e32 v137, 31, v136
	v_lshlrev_b64 v[136:137], 11, v[136:137]
	v_lshl_add_u64 v[136:137], s[24:25], 0, v[136:137]
	v_lshl_add_u64 v[136:137], v[136:137], 0, v[134:135]
	s_waitcnt vmcnt(17)
; DI u32x2 pack4(float a, float b, float c, float d) { u32x2 r; r.x = pack2(a, b); r.y = pack2(c, d); return r; }
; #define EPI_END if (i == 3 && (j & 3) == 3) __builtin_amdgcn_sched_barrier(0); }
; DI float rstd_of(const float* ssq, int m, float invn) { return rsqrtf(ssq[m] * invn + 1e-6f); }
; template <int MODE>
; DI void gemm_phase(const Params& p, const GP& g, unsigned char* smem) {
;     ...
;         EPI_STD_BEGIN
;           const float rs = rstd_of(g.ssq_in, m, 1.f / 256);
;           *(u32x2*)(kn + (long)m * 1024 + n4) = pack4(v[0] * rs, v[1] * rs, v[2] * rs, v[3] * rs);
;         EPI_END
	v_fmamk_f32 v128, v184, 0x3b800000, v150
	v_mul_f32_e32 v133, 0x4b800000, v128
	v_cmp_gt_f32_e32 vcc, s74, v128
	s_nop 1
	v_cndmask_b32_e32 v128, v128, v133, vcc
	v_rsq_f32_e32 v128, v128
	s_nop 0
	v_mul_f32_e32 v133, 0x45800000, v128
	v_cndmask_b32_e32 v128, v128, v133, vcc
	v_mov_b32_e32 v160, v128
	v_pk_mul_f32 v[138:139], v[80:81], v[128:129] op_sel_hi:[1,0]
	v_pk_mul_f32 v[140:141], v[82:83], v[160:161] op_sel_hi:[1,0]
	v_cvt_pk_bf16_f32 v138, v138, v139
	v_cvt_pk_bf16_f32 v139, v140, v141
	global_store_dwordx2 v[136:137], v[138:139], off
	s_nop 1
	s_nop 0
	v_pk_mul_f32 v[138:139], v[72:73], v[160:161] op_sel_hi:[1,0]
	v_pk_mul_f32 v[140:141], v[74:75], v[160:161] op_sel_hi:[1,0]
	v_cvt_pk_bf16_f32 v138, v138, v139
	v_cvt_pk_bf16_f32 v139, v140, v141
	global_store_dwordx2 v[136:137], v[138:139], off offset:32
	s_nop 1
	s_nop 0
	v_pk_mul_f32 v[138:139], v[68:69], v[160:161] op_sel_hi:[1,0]
	v_pk_mul_f32 v[140:141], v[70:71], v[160:161] op_sel_hi:[1,0]
	v_cvt_pk_bf16_f32 v138, v138, v139
	v_cvt_pk_bf16_f32 v139, v140, v141
	global_store_dwordx2 v[136:137], v[138:139], off offset:64
	s_nop 1
	s_nop 0
	v_pk_mul_f32 v[138:139], v[60:61], v[160:161] op_sel_hi:[1,0]
	v_pk_mul_f32 v[140:141], v[62:63], v[160:161] op_sel_hi:[1,0]
	v_cvt_pk_bf16_f32 v138, v138, v139
	v_cvt_pk_bf16_f32 v139, v140, v141
	global_store_dwordx2 v[136:137], v[138:139], off offset:96
	s_nop 0
	v_or_b32_e32 v136, 64, v132
	v_ashrrev_i32_e32 v137, 31, v136
	v_lshlrev_b64 v[136:137], 11, v[136:137]
	v_lshl_add_u64 v[136:137], s[24:25], 0, v[136:137]
	v_lshl_add_u64 v[136:137], v[136:137], 0, v[134:135]
	s_waitcnt vmcnt(20)
	v_fmamk_f32 v128, v185, 0x3b800000, v150
	v_mul_f32_e32 v133, 0x4b800000, v128
	v_cmp_gt_f32_e32 vcc, s74, v128
	s_nop 1
	v_cndmask_b32_e32 v128, v128, v133, vcc
	v_rsq_f32_e32 v128, v128
	s_nop 0
	v_mul_f32_e32 v133, 0x45800000, v128
	v_cndmask_b32_e32 v128, v128, v133, vcc
	v_mov_b32_e32 v162, v128
	v_pk_mul_f32 v[138:139], v[64:65], v[128:129] op_sel_hi:[1,0]
	v_pk_mul_f32 v[140:141], v[66:67], v[162:163] op_sel_hi:[1,0]
	v_cvt_pk_bf16_f32 v138, v138, v139
	v_cvt_pk_bf16_f32 v139, v140, v141
	global_store_dwordx2 v[136:137], v[138:139], off
	s_nop 1
	s_nop 0
	v_pk_mul_f32 v[138:139], v[56:57], v[162:163] op_sel_hi:[1,0]
	v_pk_mul_f32 v[140:141], v[58:59], v[162:163] op_sel_hi:[1,0]
	v_cvt_pk_bf16_f32 v138, v138, v139
	v_cvt_pk_bf16_f32 v139, v140, v141
	global_store_dwordx2 v[136:137], v[138:139], off offset:32
	s_nop 1
	s_nop 0
	v_pk_mul_f32 v[138:139], v[52:53], v[162:163] op_sel_hi:[1,0]
	v_pk_mul_f32 v[140:141], v[54:55], v[162:163] op_sel_hi:[1,0]
	v_cvt_pk_bf16_f32 v138, v138, v139
	v_cvt_pk_bf16_f32 v139, v140, v141
	global_store_dwordx2 v[136:137], v[138:139], off offset:64
	s_nop 1
	s_nop 0
	v_pk_mul_f32 v[138:139], v[44:45], v[162:163] op_sel_hi:[1,0]
	v_pk_mul_f32 v[140:141], v[46:47], v[162:163] op_sel_hi:[1,0]
	v_cvt_pk_bf16_f32 v138, v138, v139
	v_cvt_pk_bf16_f32 v139, v140, v141
	global_store_dwordx2 v[136:137], v[138:139], off offset:96
	s_nop 0
	v_or_b32_e32 v136, 0x50, v132
	v_ashrrev_i32_e32 v137, 31, v136
	v_lshlrev_b64 v[136:137], 11, v[136:137]
	v_lshl_add_u64 v[136:137], s[24:25], 0, v[136:137]
	v_lshl_add_u64 v[136:137], v[136:137], 0, v[134:135]
	s_waitcnt vmcnt(23)
	v_fmamk_f32 v128, v186, 0x3b800000, v150
	v_mul_f32_e32 v133, 0x4b800000, v128
	v_cmp_gt_f32_e32 vcc, s74, v128
	s_nop 1
	v_cndmask_b32_e32 v128, v128, v133, vcc
	v_rsq_f32_e32 v128, v128
	s_nop 0
	v_mul_f32_e32 v133, 0x45800000, v128
	v_cndmask_b32_e32 v128, v128, v133, vcc
	v_mov_b32_e32 v164, v128
	v_pk_mul_f32 v[138:139], v[48:49], v[128:129] op_sel_hi:[1,0]
	v_pk_mul_f32 v[140:141], v[50:51], v[164:165] op_sel_hi:[1,0]
	v_cvt_pk_bf16_f32 v138, v138, v139
	v_cvt_pk_bf16_f32 v139, v140, v141
	global_store_dwordx2 v[136:137], v[138:139], off
	s_nop 1
	s_nop 0
	v_pk_mul_f32 v[138:139], v[40:41], v[164:165] op_sel_hi:[1,0]
	v_pk_mul_f32 v[140:141], v[42:43], v[164:165] op_sel_hi:[1,0]
	v_cvt_pk_bf16_f32 v138, v138, v139
	v_cvt_pk_bf16_f32 v139, v140, v141
	global_store_dwordx2 v[136:137], v[138:139], off offset:32
	s_nop 1
	s_nop 0
	v_pk_mul_f32 v[138:139], v[36:37], v[164:165] op_sel_hi:[1,0]
	v_pk_mul_f32 v[140:141], v[38:39], v[164:165] op_sel_hi:[1,0]
	v_cvt_pk_bf16_f32 v138, v138, v139
	v_cvt_pk_bf16_f32 v139, v140, v141
	global_store_dwordx2 v[136:137], v[138:139], off offset:64
	s_nop 1
	s_nop 0
	v_pk_mul_f32 v[138:139], v[28:29], v[164:165] op_sel_hi:[1,0]
	v_pk_mul_f32 v[140:141], v[30:31], v[164:165] op_sel_hi:[1,0]
	v_cvt_pk_bf16_f32 v138, v138, v139
	v_cvt_pk_bf16_f32 v139, v140, v141
	global_store_dwordx2 v[136:137], v[138:139], off offset:96
	s_nop 0
	v_or_b32_e32 v136, 0x60, v132
	v_ashrrev_i32_e32 v137, 31, v136
	v_lshlrev_b64 v[136:137], 11, v[136:137]
	v_lshl_add_u64 v[136:137], s[24:25], 0, v[136:137]
	v_lshl_add_u64 v[136:137], v[136:137], 0, v[134:135]
	v_or_b32_e32 v132, 0x70, v132
	s_waitcnt vmcnt(26)
; DI u32x2 pack4(float a, float b, float c, float d) { u32x2 r; r.x = pack2(a, b); r.y = pack2(c, d); return r; }
; #define EPI_END if (i == 3 && (j & 3) == 3) __builtin_amdgcn_sched_barrier(0); }
; DI float rstd_of(const float* ssq, int m, float invn) { return rsqrtf(ssq[m] * invn + 1e-6f); }
; template <int MODE>
; DI void gemm_phase(const Params& p, const GP& g, unsigned char* smem) {
;     ...
;         EPI_TR_BEGIN
;           const int b = m4 >> 12, s = m4 & 4095;
;           *(u32x2*)(Vt + ((long)b * 1024 + (n - 1024)) * 4096 + s) =
;               pack4(v[0] * rstd_of(g.ssq_in, m4, 1.f / 256), v[1] * rstd_of(g.ssq_in, m4 + 1, 1.f / 256),
;                     v[2] * rstd_of(g.ssq_in, m4 + 2, 1.f / 256), v[3] * rstd_of(g.ssq_in, m4 + 3, 1.f / 256));
;     ...
;         EPI_STD_BEGIN
;           const float rs = rstd_of(g.ssq_in, m, 1.f / 256);
;           *(u32x2*)(kn + (long)m * 1024 + n4) = pack4(v[0] * rs, v[1] * rs, v[2] * rs, v[3] * rs);
;         EPI_END
	v_fmamk_f32 v128, v187, 0x3b800000, v150
	v_mul_f32_e32 v133, 0x4b800000, v128
	v_cmp_gt_f32_e32 vcc, s74, v128
	s_nop 1
	v_cndmask_b32_e32 v128, v128, v133, vcc
	v_rsq_f32_e32 v128, v128
	s_nop 0
	v_mul_f32_e32 v133, 0x45800000, v128
	v_cndmask_b32_e32 v128, v128, v133, vcc
	v_mov_b32_e32 v166, v128
	v_pk_mul_f32 v[138:139], v[32:33], v[128:129] op_sel_hi:[1,0]
	v_pk_mul_f32 v[140:141], v[34:35], v[166:167] op_sel_hi:[1,0]
	v_cvt_pk_bf16_f32 v138, v138, v139
	v_cvt_pk_bf16_f32 v139, v140, v141
	global_store_dwordx2 v[136:137], v[138:139], off
	s_nop 1
	s_nop 0
	v_pk_mul_f32 v[138:139], v[24:25], v[166:167] op_sel_hi:[1,0]
	v_pk_mul_f32 v[140:141], v[26:27], v[166:167] op_sel_hi:[1,0]
	v_cvt_pk_bf16_f32 v138, v138, v139
	v_cvt_pk_bf16_f32 v139, v140, v141
	global_store_dwordx2 v[136:137], v[138:139], off offset:32
	s_nop 1
	s_nop 0
	v_pk_mul_f32 v[138:139], v[20:21], v[166:167] op_sel_hi:[1,0]
	v_pk_mul_f32 v[140:141], v[22:23], v[166:167] op_sel_hi:[1,0]
	v_cvt_pk_bf16_f32 v138, v138, v139
	v_cvt_pk_bf16_f32 v139, v140, v141
	global_store_dwordx2 v[136:137], v[138:139], off offset:64
	s_nop 1
	s_nop 0
	v_pk_mul_f32 v[138:139], v[12:13], v[166:167] op_sel_hi:[1,0]
	v_pk_mul_f32 v[140:141], v[14:15], v[166:167] op_sel_hi:[1,0]
	v_cvt_pk_bf16_f32 v138, v138, v139
	v_cvt_pk_bf16_f32 v139, v140, v141
	global_store_dwordx2 v[136:137], v[138:139], off offset:96
	s_nop 0
	v_ashrrev_i32_e32 v133, 31, v132
	v_lshlrev_b64 v[132:133], 11, v[132:133]
	v_lshl_add_u64 v[132:133], s[24:25], 0, v[132:133]
	v_lshl_add_u64 v[132:133], v[132:133], 0, v[134:135]
	s_waitcnt vmcnt(29)
	v_fmamk_f32 v128, v188, 0x3b800000, v150
	v_mul_f32_e32 v136, 0x4b800000, v128
	v_cmp_gt_f32_e32 vcc, s74, v128
	s_nop 1
	v_cndmask_b32_e32 v128, v128, v136, vcc
	v_rsq_f32_e32 v128, v128
	s_nop 0
	v_mul_f32_e32 v134, 0x45800000, v128
	v_cndmask_b32_e32 v128, v128, v134, vcc
	v_mov_b32_e32 v168, v128
	v_pk_mul_f32 v[134:135], v[16:17], v[128:129] op_sel_hi:[1,0]
	v_pk_mul_f32 v[136:137], v[18:19], v[168:169] op_sel_hi:[1,0]
	v_cvt_pk_bf16_f32 v134, v134, v135
	v_cvt_pk_bf16_f32 v135, v136, v137
	global_store_dwordx2 v[132:133], v[134:135], off
	s_nop 1
	s_nop 0
	v_pk_mul_f32 v[134:135], v[4:5], v[168:169] op_sel_hi:[1,0]
	v_pk_mul_f32 v[136:137], v[6:7], v[168:169] op_sel_hi:[1,0]
	v_cvt_pk_bf16_f32 v134, v134, v135
	v_cvt_pk_bf16_f32 v135, v136, v137
	global_store_dwordx2 v[132:133], v[134:135], off offset:32
	s_nop 1
	s_nop 0
	v_pk_mul_f32 v[134:135], v[0:1], v[168:169] op_sel_hi:[1,0]
	v_pk_mul_f32 v[136:137], v[2:3], v[168:169] op_sel_hi:[1,0]
	v_cvt_pk_bf16_f32 v134, v134, v135
	v_cvt_pk_bf16_f32 v135, v136, v137
	global_store_dwordx2 v[132:133], v[134:135], off offset:64
	s_nop 0
	s_waitcnt vmcnt(31)
	v_fmamk_f32 v128, v189, 0x3b800000, v150
	v_mul_f32_e32 v130, 0x4b800000, v128
	v_cmp_gt_f32_e32 vcc, s74, v128
	s_nop 1
	v_cndmask_b32_e32 v128, v128, v130, vcc
	v_rsq_f32_e32 v128, v128
	s_nop 0
	v_mul_f32_e32 v130, 0x45800000, v128
	v_cndmask_b32_e32 v128, v128, v130, vcc
	v_pk_mul_f32 v[130:131], v[8:9], v[168:169] op_sel_hi:[1,0]
	v_pk_mul_f32 v[134:135], v[10:11], v[168:169] op_sel_hi:[1,0]
	v_cvt_pk_bf16_f32 v130, v130, v131
	v_cvt_pk_bf16_f32 v131, v134, v135
	global_store_dwordx2 v[132:133], v[130:131], off offset:96
	s_cbranch_execnz .LBB0_400
.LBB0_415:
	s_add_i32 s7, s12, s72
	v_or_b32_e32 v136, s7, v146
	v_ashrrev_i32_e32 v137, 31, v136
	v_lshl_add_u64 v[132:133], v[136:137], 2, s[30:31]
	global_load_dwordx4 v[138:141], v[132:133], off
	global_load_dwordx4 v[184:187], v[132:133], off offset:64
	global_load_dwordx4 v[188:191], v[132:133], off offset:128
	global_load_dwordx4 v[192:195], v[132:133], off offset:192
	global_load_dwordx4 v[196:199], v[132:133], off
	global_load_dwordx4 v[200:203], v[132:133], off offset:192
	v_add_u32_e32 v134, s6, v149
	v_mov_b64_e32 v[130:131], s[66:67]
	v_ashrrev_i32_e32 v135, 31, v134
	v_lshlrev_b64 v[142:143], 13, v[134:135]
	s_ashr_i32 s6, s7, 12
	v_bitop3_b32 v128, s7, v151, v146 bitop3:0xc8
	s_ashr_i32 s7, s6, 31
	s_lshl_b64 s[6:7], s[6:7], 23
	s_add_u32 s68, s26, s6
	s_addc_u32 s69, s27, s7
	v_lshlrev_b32_e32 v128, 1, v128
	v_lshl_add_u64 v[142:143], s[68:69], 0, v[142:143]
	s_waitcnt vmcnt(5)
	v_pk_fma_f32 v[138:139], v[138:139], s[62:63], v[130:131] op_sel_hi:[1,0,0]
	v_pk_fma_f32 v[140:141], v[140:141], s[62:63], v[130:131] op_sel_hi:[1,0,0]
	v_mul_f32_e32 v135, 0x4b800000, v138
	v_mul_f32_e32 v137, 0x4b800000, v139
	v_mul_f32_e32 v144, 0x4b800000, v140
	v_mul_f32_e32 v145, 0x4b800000, v141
	v_cmp_gt_f32_e32 vcc, s74, v138
	v_cmp_gt_f32_e64 s[12:13], s74, v139
	v_cmp_gt_f32_e64 s[14:15], s74, v140
	v_cmp_gt_f32_e64 s[16:17], s74, v141
	v_cndmask_b32_e32 v135, v138, v135, vcc
	v_cndmask_b32_e64 v137, v139, v137, s[12:13]
	v_cndmask_b32_e64 v140, v140, v144, s[14:15]
	v_cndmask_b32_e64 v141, v141, v145, s[16:17]
	v_rsq_f32_e32 v138, v135
	v_rsq_f32_e32 v139, v137
	v_rsq_f32_e32 v140, v140
	v_rsq_f32_e32 v141, v141
	v_lshl_add_u64 v[144:145], v[142:143], 0, v[128:129]
	v_pk_mul_f32 v[152:153], v[138:139], s[64:65] op_sel_hi:[1,0]
	v_pk_mul_f32 v[154:155], v[140:141], s[64:65] op_sel_hi:[1,0]
	v_cndmask_b32_e64 v139, v139, v153, s[12:13]
	v_cndmask_b32_e32 v138, v138, v152, vcc
	v_cndmask_b32_e64 v141, v141, v155, s[16:17]
	v_cndmask_b32_e64 v140, v140, v154, s[14:15]
	v_mov_b32_e32 v156, v138
	v_mov_b32_e32 v157, v139
	v_pk_mul_f32 v[124:125], v[124:125], v[138:139]
	v_mov_b32_e32 v158, v140
	v_mov_b32_e32 v159, v141
	v_pk_mul_f32 v[126:127], v[126:127], v[140:141]
	v_cvt_pk_bf16_f32 v124, v124, v125
	v_cvt_pk_bf16_f32 v125, v126, v127
	global_store_dwordx2 v[144:145], v[124:125], off
	s_nop 0
	v_bitop3_b32 v124, v136, s75, 16 bitop3:0xc8
	v_mov_b32_e32 v125, v129
	v_lshlrev_b32_e32 v124, 1, v124
	s_waitcnt vmcnt(5)
; DI u32x2 pack4(float a, float b, float c, float d) { u32x2 r; r.x = pack2(a, b); r.y = pack2(c, d); return r; }
; DI float rstd_of(const float* ssq, int m, float invn) { return rsqrtf(ssq[m] * invn + 1e-6f); }
; template <int MODE>
; DI void gemm_phase(const Params& p, const GP& g, unsigned char* smem) {
;     ...
;         EPI_TR_BEGIN
;           const int b = m4 >> 12, s = m4 & 4095;
;           *(u32x2*)(Vt + ((long)b * 1024 + (n - 1024)) * 4096 + s) =
;               pack4(v[0] * rstd_of(g.ssq_in, m4, 1.f / 256), v[1] * rstd_of(g.ssq_in, m4 + 1, 1.f / 256),
;                     v[2] * rstd_of(g.ssq_in, m4 + 2, 1.f / 256), v[3] * rstd_of(g.ssq_in, m4 + 3, 1.f / 256));
	v_pk_fma_f32 v[126:127], v[184:185], s[62:63], v[130:131] op_sel_hi:[1,0,0]
	v_pk_fma_f32 v[138:139], v[186:187], s[62:63], v[130:131] op_sel_hi:[1,0,0]
	v_mul_f32_e32 v135, 0x4b800000, v126
	v_mul_f32_e32 v137, 0x4b800000, v127
	v_mul_f32_e32 v140, 0x4b800000, v138
	v_mul_f32_e32 v141, 0x4b800000, v139
	v_cmp_gt_f32_e32 vcc, s74, v126
	v_cmp_gt_f32_e64 s[12:13], s74, v127
	v_cmp_gt_f32_e64 s[14:15], s74, v138
	v_cmp_gt_f32_e64 s[16:17], s74, v139
	v_cndmask_b32_e32 v126, v126, v135, vcc
	v_cndmask_b32_e64 v127, v127, v137, s[12:13]
	v_cndmask_b32_e64 v135, v138, v140, s[14:15]
	v_cndmask_b32_e64 v137, v139, v141, s[16:17]
	v_rsq_f32_e32 v126, v126
	v_rsq_f32_e32 v127, v127
	v_rsq_f32_e32 v138, v135
	v_rsq_f32_e32 v139, v137
	v_lshl_add_u64 v[140:141], v[142:143], 0, v[124:125]
	v_pk_mul_f32 v[144:145], v[126:127], s[64:65] op_sel_hi:[1,0]
	v_pk_mul_f32 v[152:153], v[138:139], s[64:65] op_sel_hi:[1,0]
	v_cndmask_b32_e64 v127, v127, v145, s[12:13]
	v_cndmask_b32_e32 v126, v126, v144, vcc
	v_cndmask_b32_e64 v139, v139, v153, s[16:17]
	v_cndmask_b32_e64 v138, v138, v152, s[14:15]
	v_mov_b32_e32 v160, v126
	v_mov_b32_e32 v161, v127
	v_pk_mul_f32 v[120:121], v[120:121], v[126:127]
	v_mov_b32_e32 v162, v138
	v_mov_b32_e32 v163, v139
	v_pk_mul_f32 v[122:123], v[122:123], v[138:139]
	v_cvt_pk_bf16_f32 v120, v120, v121
	v_cvt_pk_bf16_f32 v121, v122, v123
	global_store_dwordx2 v[140:141], v[120:121], off
	s_nop 0
	v_bitop3_b32 v120, v136, s76, 32 bitop3:0xc8
	v_mov_b32_e32 v121, v129
	v_lshlrev_b32_e32 v120, 1, v120
	s_waitcnt vmcnt(5)
	v_pk_fma_f32 v[122:123], v[188:189], s[62:63], v[130:131] op_sel_hi:[1,0,0]
	v_pk_fma_f32 v[126:127], v[190:191], s[62:63], v[130:131] op_sel_hi:[1,0,0]
	v_mul_f32_e32 v135, 0x4b800000, v122
	v_mul_f32_e32 v137, 0x4b800000, v123
	v_mul_f32_e32 v138, 0x4b800000, v126
	v_mul_f32_e32 v139, 0x4b800000, v127
	v_cmp_gt_f32_e32 vcc, s74, v122
	v_cmp_gt_f32_e64 s[12:13], s74, v123
	v_cmp_gt_f32_e64 s[14:15], s74, v126
	v_cmp_gt_f32_e64 s[16:17], s74, v127
	v_cndmask_b32_e32 v122, v122, v135, vcc
	v_cndmask_b32_e64 v123, v123, v137, s[12:13]
	v_cndmask_b32_e64 v126, v126, v138, s[14:15]
	v_cndmask_b32_e64 v127, v127, v139, s[16:17]
	v_rsq_f32_e32 v122, v122
	v_rsq_f32_e32 v123, v123
	v_rsq_f32_e32 v126, v126
	v_rsq_f32_e32 v127, v127
	v_lshl_add_u64 v[138:139], v[142:143], 0, v[120:121]
	v_pk_mul_f32 v[140:141], v[122:123], s[64:65] op_sel_hi:[1,0]
	v_pk_mul_f32 v[144:145], v[126:127], s[64:65] op_sel_hi:[1,0]
	v_cndmask_b32_e64 v123, v123, v141, s[12:13]
	v_cndmask_b32_e32 v122, v122, v140, vcc
	v_cndmask_b32_e64 v127, v127, v145, s[16:17]
	v_cndmask_b32_e64 v126, v126, v144, s[14:15]
	v_mov_b32_e32 v164, v122
	v_mov_b32_e32 v165, v123
	v_pk_mul_f32 v[116:117], v[116:117], v[122:123]
	v_mov_b32_e32 v166, v126
	v_mov_b32_e32 v167, v127
	v_pk_mul_f32 v[118:119], v[118:119], v[126:127]
	v_cvt_pk_bf16_f32 v116, v116, v117
	v_cvt_pk_bf16_f32 v117, v118, v119
	global_store_dwordx2 v[138:139], v[116:117], off
	s_nop 0
	v_bitop3_b32 v116, v136, s77, 48 bitop3:0xc8
	v_mov_b32_e32 v117, v129
	v_lshlrev_b32_e32 v116, 1, v116
	s_waitcnt vmcnt(5)
	v_pk_fma_f32 v[118:119], v[192:193], s[62:63], v[130:131] op_sel_hi:[1,0,0]
	v_pk_fma_f32 v[122:123], v[194:195], s[62:63], v[130:131] op_sel_hi:[1,0,0]
	v_mul_f32_e32 v126, 0x4b800000, v118
	v_mul_f32_e32 v127, 0x4b800000, v119
	v_mul_f32_e32 v135, 0x4b800000, v122
	v_mul_f32_e32 v136, 0x4b800000, v123
	v_cmp_gt_f32_e32 vcc, s74, v118
	v_cmp_gt_f32_e64 s[12:13], s74, v119
	v_cmp_gt_f32_e64 s[14:15], s74, v122
	v_cmp_gt_f32_e64 s[16:17], s74, v123
	v_cndmask_b32_e32 v118, v118, v126, vcc
	v_cndmask_b32_e64 v119, v119, v127, s[12:13]
	v_cndmask_b32_e64 v122, v122, v135, s[14:15]
	v_cndmask_b32_e64 v123, v123, v136, s[16:17]
	v_rsq_f32_e32 v118, v118
	v_rsq_f32_e32 v119, v119
	v_rsq_f32_e32 v122, v122
	v_rsq_f32_e32 v123, v123
	v_lshl_add_u64 v[126:127], v[142:143], 0, v[116:117]
	v_pk_mul_f32 v[136:137], v[118:119], s[64:65] op_sel_hi:[1,0]
	v_pk_mul_f32 v[138:139], v[122:123], s[64:65] op_sel_hi:[1,0]
	v_cndmask_b32_e64 v119, v119, v137, s[12:13]
	v_cndmask_b32_e32 v118, v118, v136, vcc
	v_cndmask_b32_e64 v123, v123, v139, s[16:17]
	v_cndmask_b32_e64 v122, v122, v138, s[14:15]
	v_mov_b32_e32 v168, v118
	v_mov_b32_e32 v169, v119
	v_pk_mul_f32 v[108:109], v[108:109], v[118:119]
	v_mov_b32_e32 v170, v122
	v_mov_b32_e32 v171, v123
	v_pk_mul_f32 v[110:111], v[110:111], v[122:123]
	v_cvt_pk_bf16_f32 v108, v108, v109
	v_cvt_pk_bf16_f32 v109, v110, v111
	global_store_dwordx2 v[126:127], v[108:109], off
	s_nop 0
	v_or_b32_e32 v118, 16, v134
	v_ashrrev_i32_e32 v119, 31, v118
	v_lshlrev_b64 v[118:119], 13, v[118:119]
	v_lshl_add_u64 v[118:119], s[68:69], 0, v[118:119]
	s_waitcnt vmcnt(5)
; DI u32x2 pack4(float a, float b, float c, float d) { u32x2 r; r.x = pack2(a, b); r.y = pack2(c, d); return r; }
; DI float rstd_of(const float* ssq, int m, float invn) { return rsqrtf(ssq[m] * invn + 1e-6f); }
; template <int MODE>
; DI void gemm_phase(const Params& p, const GP& g, unsigned char* smem) {
;     ...
;         EPI_TR_BEGIN
;           const int b = m4 >> 12, s = m4 & 4095;
;           *(u32x2*)(Vt + ((long)b * 1024 + (n - 1024)) * 4096 + s) =
;               pack4(v[0] * rstd_of(g.ssq_in, m4, 1.f / 256), v[1] * rstd_of(g.ssq_in, m4 + 1, 1.f / 256),
;                     v[2] * rstd_of(g.ssq_in, m4 + 2, 1.f / 256), v[3] * rstd_of(g.ssq_in, m4 + 3, 1.f / 256));
	v_pk_fma_f32 v[110:111], v[198:199], s[62:63], v[130:131] op_sel_hi:[1,0,0]
	v_mul_f32_e32 v126, 0x4b800000, v110
	v_mul_f32_e32 v127, 0x4b800000, v111
	v_cmp_gt_f32_e64 s[14:15], s74, v110
	v_cmp_gt_f32_e64 s[16:17], s74, v111
	v_cndmask_b32_e64 v110, v110, v126, s[14:15]
	v_cndmask_b32_e64 v111, v111, v127, s[16:17]
	v_rsq_f32_e32 v110, v110
	v_rsq_f32_e32 v111, v111
	v_lshl_add_u64 v[122:123], v[118:119], 0, v[128:129]
	v_pk_mul_f32 v[136:137], v[110:111], s[64:65] op_sel_hi:[1,0]
	v_pk_mul_f32 v[108:109], v[112:113], v[156:157]
	v_pk_mul_f32 v[110:111], v[114:115], v[158:159]
	v_cvt_pk_bf16_f32 v108, v108, v109
	v_cvt_pk_bf16_f32 v109, v110, v111
	global_store_dwordx2 v[122:123], v[108:109], off
	v_lshl_add_u64 v[112:113], v[118:119], 0, v[124:125]
	v_pk_mul_f32 v[104:105], v[104:105], v[160:161]
	v_pk_mul_f32 v[106:107], v[106:107], v[162:163]
	v_cvt_pk_bf16_f32 v104, v104, v105
	v_cvt_pk_bf16_f32 v105, v106, v107
	global_store_dwordx2 v[112:113], v[104:105], off
	v_lshl_add_u64 v[108:109], v[118:119], 0, v[120:121]
	v_pk_mul_f32 v[100:101], v[100:101], v[164:165]
	v_pk_mul_f32 v[102:103], v[102:103], v[166:167]
	v_cvt_pk_bf16_f32 v100, v100, v101
	v_cvt_pk_bf16_f32 v101, v102, v103
	global_store_dwordx2 v[108:109], v[100:101], off
	v_lshl_add_u64 v[104:105], v[118:119], 0, v[116:117]
	v_pk_mul_f32 v[92:93], v[92:93], v[168:169]
	v_pk_mul_f32 v[94:95], v[94:95], v[170:171]
	v_cvt_pk_bf16_f32 v92, v92, v93
	v_cvt_pk_bf16_f32 v93, v94, v95
	global_store_dwordx2 v[104:105], v[92:93], off
	v_or_b32_e32 v100, 32, v134
	v_ashrrev_i32_e32 v101, 31, v100
	v_lshlrev_b64 v[100:101], 13, v[100:101]
	v_lshl_add_u64 v[100:101], s[68:69], 0, v[100:101]
	v_lshl_add_u64 v[102:103], v[100:101], 0, v[128:129]
	v_pk_mul_f32 v[92:93], v[96:97], v[156:157]
	v_pk_mul_f32 v[94:95], v[98:99], v[158:159]
	v_cvt_pk_bf16_f32 v92, v92, v93
	v_cvt_pk_bf16_f32 v93, v94, v95
	global_store_dwordx2 v[102:103], v[92:93], off
	v_lshl_add_u64 v[96:97], v[100:101], 0, v[124:125]
	v_pk_mul_f32 v[88:89], v[88:89], v[160:161]
	v_pk_mul_f32 v[90:91], v[90:91], v[162:163]
	v_cvt_pk_bf16_f32 v88, v88, v89
	v_cvt_pk_bf16_f32 v89, v90, v91
	global_store_dwordx2 v[96:97], v[88:89], off
	v_lshl_add_u64 v[92:93], v[100:101], 0, v[120:121]
	v_pk_mul_f32 v[84:85], v[84:85], v[164:165]
	v_pk_mul_f32 v[86:87], v[86:87], v[166:167]
	v_cvt_pk_bf16_f32 v84, v84, v85
	v_cvt_pk_bf16_f32 v85, v86, v87
	global_store_dwordx2 v[92:93], v[84:85], off
	v_lshl_add_u64 v[88:89], v[100:101], 0, v[116:117]
	v_pk_mul_f32 v[76:77], v[76:77], v[168:169]
	v_pk_mul_f32 v[78:79], v[78:79], v[170:171]
	v_cvt_pk_bf16_f32 v76, v76, v77
	v_cvt_pk_bf16_f32 v77, v78, v79
	global_store_dwordx2 v[88:89], v[76:77], off
	v_or_b32_e32 v84, 48, v134
	v_ashrrev_i32_e32 v85, 31, v84
	v_lshlrev_b64 v[84:85], 13, v[84:85]
	v_lshl_add_u64 v[84:85], s[68:69], 0, v[84:85]
	v_lshl_add_u64 v[86:87], v[84:85], 0, v[128:129]
	v_pk_mul_f32 v[76:77], v[80:81], v[156:157]
	v_pk_mul_f32 v[78:79], v[82:83], v[158:159]
	v_cvt_pk_bf16_f32 v76, v76, v77
	v_cvt_pk_bf16_f32 v77, v78, v79
	global_store_dwordx2 v[86:87], v[76:77], off
	v_lshl_add_u64 v[80:81], v[84:85], 0, v[124:125]
	v_pk_mul_f32 v[72:73], v[72:73], v[160:161]
	v_pk_mul_f32 v[74:75], v[74:75], v[162:163]
	v_cvt_pk_bf16_f32 v72, v72, v73
	v_cvt_pk_bf16_f32 v73, v74, v75
	global_store_dwordx2 v[80:81], v[72:73], off
	v_lshl_add_u64 v[76:77], v[84:85], 0, v[120:121]
	v_pk_mul_f32 v[68:69], v[68:69], v[164:165]
	v_pk_mul_f32 v[70:71], v[70:71], v[166:167]
	v_cvt_pk_bf16_f32 v68, v68, v69
	v_cvt_pk_bf16_f32 v69, v70, v71
	global_store_dwordx2 v[76:77], v[68:69], off
	s_nop 0
	v_pk_mul_f32 v[60:61], v[60:61], v[168:169]
	v_pk_mul_f32 v[62:63], v[62:63], v[170:171]
	v_cvt_pk_bf16_f32 v60, v60, v61
	v_cvt_pk_bf16_f32 v61, v62, v63
	v_lshl_add_u64 v[62:63], v[84:85], 0, v[116:117]
	global_store_dwordx2 v[62:63], v[60:61], off
	v_or_b32_e32 v68, 64, v134
	v_ashrrev_i32_e32 v69, 31, v68
	v_lshlrev_b64 v[68:69], 13, v[68:69]
	v_lshl_add_u64 v[68:69], s[68:69], 0, v[68:69]
	v_lshl_add_u64 v[70:71], v[68:69], 0, v[128:129]
	v_pk_mul_f32 v[60:61], v[64:65], v[156:157]
	v_pk_mul_f32 v[62:63], v[66:67], v[158:159]
	v_cvt_pk_bf16_f32 v60, v60, v61
	v_cvt_pk_bf16_f32 v61, v62, v63
	global_store_dwordx2 v[70:71], v[60:61], off
	v_lshl_add_u64 v[64:65], v[68:69], 0, v[124:125]
	v_pk_mul_f32 v[56:57], v[56:57], v[160:161]
	v_pk_mul_f32 v[58:59], v[58:59], v[162:163]
; DI u32x2 pack4(float a, float b, float c, float d) { u32x2 r; r.x = pack2(a, b); r.y = pack2(c, d); return r; }
; DI float rstd_of(const float* ssq, int m, float invn) { return rsqrtf(ssq[m] * invn + 1e-6f); }
; template <int MODE>
; DI void gemm_phase(const Params& p, const GP& g, unsigned char* smem) {
;     ...
;         EPI_TR_BEGIN
;           const int b = m4 >> 12, s = m4 & 4095;
;           *(u32x2*)(Vt + ((long)b * 1024 + (n - 1024)) * 4096 + s) =
;               pack4(v[0] * rstd_of(g.ssq_in, m4, 1.f / 256), v[1] * rstd_of(g.ssq_in, m4 + 1, 1.f / 256),
;                     v[2] * rstd_of(g.ssq_in, m4 + 2, 1.f / 256), v[3] * rstd_of(g.ssq_in, m4 + 3, 1.f / 256));
	v_cvt_pk_bf16_f32 v56, v56, v57
	v_cvt_pk_bf16_f32 v57, v58, v59
	global_store_dwordx2 v[64:65], v[56:57], off
	v_lshl_add_u64 v[60:61], v[68:69], 0, v[120:121]
	v_pk_mul_f32 v[52:53], v[52:53], v[164:165]
	v_pk_mul_f32 v[54:55], v[54:55], v[166:167]
	v_cvt_pk_bf16_f32 v52, v52, v53
	v_cvt_pk_bf16_f32 v53, v54, v55
	global_store_dwordx2 v[60:61], v[52:53], off
	v_lshl_add_u64 v[56:57], v[68:69], 0, v[116:117]
	v_pk_mul_f32 v[44:45], v[44:45], v[168:169]
	v_pk_mul_f32 v[46:47], v[46:47], v[170:171]
	v_cvt_pk_bf16_f32 v44, v44, v45
	v_cvt_pk_bf16_f32 v45, v46, v47
	global_store_dwordx2 v[56:57], v[44:45], off
	v_or_b32_e32 v52, 0x50, v134
	v_ashrrev_i32_e32 v53, 31, v52
	v_lshlrev_b64 v[52:53], 13, v[52:53]
	v_lshl_add_u64 v[52:53], s[68:69], 0, v[52:53]
	v_lshl_add_u64 v[54:55], v[52:53], 0, v[128:129]
	v_pk_mul_f32 v[44:45], v[48:49], v[156:157]
	v_pk_mul_f32 v[46:47], v[50:51], v[158:159]
	v_cvt_pk_bf16_f32 v44, v44, v45
	v_cvt_pk_bf16_f32 v45, v46, v47
	global_store_dwordx2 v[54:55], v[44:45], off
	v_lshl_add_u64 v[48:49], v[52:53], 0, v[124:125]
	v_pk_mul_f32 v[40:41], v[40:41], v[160:161]
	v_pk_mul_f32 v[42:43], v[42:43], v[162:163]
	v_cvt_pk_bf16_f32 v40, v40, v41
	v_cvt_pk_bf16_f32 v41, v42, v43
	global_store_dwordx2 v[48:49], v[40:41], off
	v_lshl_add_u64 v[44:45], v[52:53], 0, v[120:121]
	v_pk_mul_f32 v[36:37], v[36:37], v[164:165]
	v_pk_mul_f32 v[38:39], v[38:39], v[166:167]
	v_cvt_pk_bf16_f32 v36, v36, v37
	v_cvt_pk_bf16_f32 v37, v38, v39
	global_store_dwordx2 v[44:45], v[36:37], off
	v_lshl_add_u64 v[40:41], v[52:53], 0, v[116:117]
	v_pk_mul_f32 v[28:29], v[28:29], v[168:169]
	v_pk_mul_f32 v[30:31], v[30:31], v[170:171]
	v_cvt_pk_bf16_f32 v28, v28, v29
	v_cvt_pk_bf16_f32 v29, v30, v31
	global_store_dwordx2 v[40:41], v[28:29], off
	v_or_b32_e32 v36, 0x60, v134
	v_ashrrev_i32_e32 v37, 31, v36
	v_lshlrev_b64 v[36:37], 13, v[36:37]
	v_lshl_add_u64 v[36:37], s[68:69], 0, v[36:37]
	v_lshl_add_u64 v[38:39], v[36:37], 0, v[128:129]
	v_pk_mul_f32 v[28:29], v[32:33], v[156:157]
	v_pk_mul_f32 v[30:31], v[34:35], v[158:159]
	v_cvt_pk_bf16_f32 v28, v28, v29
	v_cvt_pk_bf16_f32 v29, v30, v31
	global_store_dwordx2 v[38:39], v[28:29], off
	v_lshl_add_u64 v[32:33], v[36:37], 0, v[124:125]
	v_pk_mul_f32 v[24:25], v[24:25], v[160:161]
	v_pk_mul_f32 v[26:27], v[26:27], v[162:163]
	v_cvt_pk_bf16_f32 v24, v24, v25
	v_cvt_pk_bf16_f32 v25, v26, v27
	global_store_dwordx2 v[32:33], v[24:25], off
	v_lshl_add_u64 v[28:29], v[36:37], 0, v[120:121]
	v_pk_mul_f32 v[20:21], v[20:21], v[164:165]
	v_pk_mul_f32 v[22:23], v[22:23], v[166:167]
	v_cvt_pk_bf16_f32 v20, v20, v21
	v_cvt_pk_bf16_f32 v21, v22, v23
	global_store_dwordx2 v[28:29], v[20:21], off
	v_lshl_add_u64 v[24:25], v[36:37], 0, v[116:117]
	v_pk_mul_f32 v[12:13], v[12:13], v[168:169]
	v_pk_mul_f32 v[14:15], v[14:15], v[170:171]
	v_cvt_pk_bf16_f32 v12, v12, v13
	v_cvt_pk_bf16_f32 v13, v14, v15
	global_store_dwordx2 v[24:25], v[12:13], off
	v_or_b32_e32 v20, 0x70, v134
	v_ashrrev_i32_e32 v21, 31, v20
	v_lshlrev_b64 v[20:21], 13, v[20:21]
	v_lshl_add_u64 v[20:21], s[68:69], 0, v[20:21]
	v_lshl_add_u64 v[22:23], v[20:21], 0, v[128:129]
	v_pk_mul_f32 v[12:13], v[16:17], v[156:157]
	v_pk_mul_f32 v[14:15], v[18:19], v[158:159]
	v_cvt_pk_bf16_f32 v12, v12, v13
	v_cvt_pk_bf16_f32 v13, v14, v15
	global_store_dwordx2 v[22:23], v[12:13], off
	v_lshl_add_u64 v[16:17], v[20:21], 0, v[124:125]
	v_pk_mul_f32 v[4:5], v[4:5], v[160:161]
	v_pk_mul_f32 v[6:7], v[6:7], v[162:163]
	v_cvt_pk_bf16_f32 v4, v4, v5
	v_cvt_pk_bf16_f32 v5, v6, v7
	global_store_dwordx2 v[16:17], v[4:5], off
	v_lshl_add_u64 v[12:13], v[20:21], 0, v[120:121]
	v_pk_mul_f32 v[0:1], v[0:1], v[164:165]
	v_pk_mul_f32 v[2:3], v[2:3], v[166:167]
	v_cvt_pk_bf16_f32 v0, v0, v1
	v_cvt_pk_bf16_f32 v1, v2, v3
	global_store_dwordx2 v[12:13], v[0:1], off
	s_nop 0
	s_waitcnt vmcnt(31)
	v_pk_fma_f32 v[0:1], v[200:201], s[62:63], v[130:131] op_sel_hi:[1,0,0]
	v_pk_fma_f32 v[2:3], v[202:203], s[62:63], v[130:131] op_sel_hi:[1,0,0]
	v_cmp_gt_f32_e32 vcc, s74, v0
	v_cmp_gt_f32_e64 s[12:13], s74, v1
	v_cmp_gt_f32_e64 s[14:15], s74, v2
	v_cmp_gt_f32_e64 s[16:17], s74, v3
	s_nop 0
	v_pk_mul_f32 v[0:1], v[8:9], v[168:169]
	v_pk_mul_f32 v[2:3], v[10:11], v[170:171]
	v_cvt_pk_bf16_f32 v0, v0, v1
	v_cvt_pk_bf16_f32 v1, v2, v3
	v_lshl_add_u64 v[2:3], v[20:21], 0, v[116:117]
	global_store_dwordx2 v[2:3], v[0:1], off
	s_branch .LBB0_400

; DI float bflo(unsigned u) { return __uint_as_float(u << 16); }
; DI float bfhi(unsigned u) { return __uint_as_float(u & 0xffff0000u); }
; DI u32x2 pack4(float a, float b, float c, float d) { u32x2 r; r.x = pack2(a, b); r.y = pack2(c, d); return r; }
; #define EPI_END if (i == 3 && (j & 3) == 3) __builtin_amdgcn_sched_barrier(0); }
; DI float rstd_of(const float* ssq, int m, float invn) { return rsqrtf(ssq[m] * invn + 1e-6f); }
; DI float silu(float v) { return v * __builtin_amdgcn_rcpf(1.f + __expf(-v)); }
; template <int MODE>
; DI void gemm_phase(const Params& p, const GP& g, unsigned char* smem) {
;     ...
;     } else if (MODE == M_ZPASS) {
;       u16* og = (u16*)g.d0;
;       EPI_STD_BEGIN
;         const float rs = rstd_of(g.ssq_in, m, 1.f / 1024);
;         u32x2* op = (u32x2*)(og + (long)m * 1024 + n4);
;         const u32x2 ov = *op;
;         *op = pack4(bflo(ov.x) * silu(v[0] * rs), bfhi(ov.x) * silu(v[1] * rs), bflo(ov.y) * silu(v[2] * rs), bfhi(ov.y) * silu(v[3] * rs));
;       EPI_END
.LBB0_485:
	v_or_b32_e32 v132, s28, v147
	v_ashrrev_i32_e32 v133, 31, v132
	v_lshl_add_u64 v[136:137], v[132:133], 2, s[14:15]
	global_load_dword v128, v[136:137], off
	v_add_u32_e32 v130, s6, v146
	v_ashrrev_i32_e32 v131, 31, v130
	v_lshlrev_b64 v[134:135], 11, v[132:133]
	v_lshlrev_b64 v[130:131], 1, v[130:131]
	v_lshl_add_u64 v[134:135], s[38:39], 0, v[134:135]
	v_lshl_add_u64 v[134:135], v[134:135], 0, v[130:131]
	global_load_dwordx2 v[138:139], v[134:135], off
	global_load_dwordx2 v[140:141], v[134:135], off offset:32
	global_load_dwordx2 v[142:143], v[134:135], off offset:64
	global_load_dwordx2 v[144:145], v[134:135], off offset:96
	s_waitcnt vmcnt(4)
	v_fmamk_f32 v128, v128, 0x3a800000, v148
	v_mul_f32_e32 v133, 0x4b800000, v128
	v_cmp_gt_f32_e32 vcc, s54, v128
	s_waitcnt vmcnt(3)
	v_lshlrev_b32_e32 v150, 16, v138
	v_cndmask_b32_e32 v128, v128, v133, vcc
	v_rsq_f32_e32 v128, v128
	v_and_b32_e32 v151, 0xffff0000, v138
	v_mul_f32_e32 v133, 0x45800000, v128
	v_cndmask_b32_e32 v128, v128, v133, vcc
	v_mov_b32_e32 v156, v128
	v_pk_mul_f32 v[124:125], v[124:125], v[128:129] op_sel_hi:[1,0]
	v_pk_mul_f32 v[126:127], v[126:127], v[156:157] op_sel_hi:[1,0]
	v_mul_f32_e32 v128, 0xbfb8aa3b, v124
	v_mul_f32_e32 v133, 0xbfb8aa3b, v125
	v_mul_f32_e32 v138, 0xbfb8aa3b, v126
	v_mul_f32_e32 v149, 0xbfb8aa3b, v127
	v_exp_f32_e32 v128, v128
	v_exp_f32_e32 v133, v133
	v_exp_f32_e32 v138, v138
	v_exp_f32_e32 v149, v149
	v_add_f32_e32 v128, 1.0, v128
	v_add_f32_e32 v133, 1.0, v133
	v_add_f32_e32 v138, 1.0, v138
	v_add_f32_e32 v149, 1.0, v149
	v_rcp_f32_e32 v152, v128
	v_rcp_f32_e32 v153, v133
	v_rcp_f32_e32 v154, v138
	v_rcp_f32_e32 v155, v149
	v_lshlrev_b32_e32 v138, 16, v139
	v_and_b32_e32 v139, 0xffff0000, v139
	v_pk_mul_f32 v[124:125], v[124:125], v[152:153]
	v_pk_mul_f32 v[126:127], v[126:127], v[154:155]
	v_pk_mul_f32 v[124:125], v[124:125], v[150:151]
	v_pk_mul_f32 v[126:127], v[126:127], v[138:139]
	v_cvt_pk_bf16_f32 v124, v124, v125
	v_cvt_pk_bf16_f32 v125, v126, v127
	global_store_dwordx2 v[134:135], v[124:125], off
	s_nop 1
	s_waitcnt vmcnt(3)
	v_lshlrev_b32_e32 v124, 16, v140
	v_and_b32_e32 v125, 0xffff0000, v140
	v_lshlrev_b32_e32 v140, 16, v141
	v_pk_mul_f32 v[120:121], v[120:121], v[156:157] op_sel_hi:[1,0]
	v_pk_mul_f32 v[122:123], v[122:123], v[156:157] op_sel_hi:[1,0]
	v_mul_f32_e32 v126, 0xbfb8aa3b, v120
	v_mul_f32_e32 v127, 0xbfb8aa3b, v121
	v_mul_f32_e32 v128, 0xbfb8aa3b, v122
	v_mul_f32_e32 v133, 0xbfb8aa3b, v123
	v_exp_f32_e32 v126, v126
	v_exp_f32_e32 v127, v127
	v_exp_f32_e32 v128, v128
	v_exp_f32_e32 v133, v133
	v_add_f32_e32 v126, 1.0, v126
	v_add_f32_e32 v127, 1.0, v127
	v_add_f32_e32 v128, 1.0, v128
	v_add_f32_e32 v133, 1.0, v133
	v_rcp_f32_e32 v126, v126
	v_rcp_f32_e32 v127, v127
	v_rcp_f32_e32 v138, v128
	v_rcp_f32_e32 v139, v133
	v_and_b32_e32 v141, 0xffff0000, v141
	v_pk_mul_f32 v[120:121], v[120:121], v[126:127]
	s_waitcnt vmcnt(2)
	v_lshlrev_b32_e32 v126, 16, v143
	v_pk_mul_f32 v[122:123], v[122:123], v[138:139]
	v_pk_mul_f32 v[120:121], v[120:121], v[124:125]
	v_pk_mul_f32 v[122:123], v[122:123], v[140:141]
	v_cvt_pk_bf16_f32 v120, v120, v121
	v_cvt_pk_bf16_f32 v121, v122, v123
	global_store_dwordx2 v[134:135], v[120:121], off offset:32
	v_and_b32_e32 v127, 0xffff0000, v143
	s_nop 1
	v_lshlrev_b32_e32 v120, 16, v142
	v_and_b32_e32 v121, 0xffff0000, v142
	v_pk_mul_f32 v[116:117], v[116:117], v[156:157] op_sel_hi:[1,0]
	v_pk_mul_f32 v[118:119], v[118:119], v[156:157] op_sel_hi:[1,0]
	v_mul_f32_e32 v122, 0xbfb8aa3b, v116
	v_mul_f32_e32 v123, 0xbfb8aa3b, v117
	v_mul_f32_e32 v124, 0xbfb8aa3b, v118
	v_mul_f32_e32 v125, 0xbfb8aa3b, v119
	v_exp_f32_e32 v122, v122
	v_exp_f32_e32 v123, v123
	v_exp_f32_e32 v124, v124
	v_exp_f32_e32 v125, v125
	v_add_f32_e32 v122, 1.0, v122
	v_add_f32_e32 v123, 1.0, v123
	v_add_f32_e32 v124, 1.0, v124
	v_add_f32_e32 v125, 1.0, v125
	v_rcp_f32_e32 v122, v122
	v_rcp_f32_e32 v123, v123
	v_rcp_f32_e32 v124, v124
	v_rcp_f32_e32 v125, v125
	v_pk_mul_f32 v[116:117], v[116:117], v[122:123]
	s_nop 0
	v_pk_mul_f32 v[116:117], v[116:117], v[120:121]
	v_pk_mul_f32 v[118:119], v[118:119], v[124:125]
	v_cvt_pk_bf16_f32 v116, v116, v117
	v_pk_mul_f32 v[118:119], v[118:119], v[126:127]
	s_waitcnt vmcnt(2)
	v_lshlrev_b32_e32 v120, 16, v144
	v_cvt_pk_bf16_f32 v117, v118, v119
	global_store_dwordx2 v[134:135], v[116:117], off offset:64
	v_and_b32_e32 v121, 0xffff0000, v144
	v_lshlrev_b32_e32 v126, 16, v145
	v_and_b32_e32 v127, 0xffff0000, v145
	v_or_b32_e32 v118, 16, v132
	v_ashrrev_i32_e32 v119, 31, v118
	s_nop 1
	v_lshl_add_u64 v[116:117], v[118:119], 2, s[14:15]
	v_pk_mul_f32 v[112:113], v[112:113], v[156:157] op_sel_hi:[1,0]
	v_pk_mul_f32 v[114:115], v[114:115], v[156:157] op_sel_hi:[1,0]
	v_mul_f32_e32 v122, 0xbfb8aa3b, v112
	v_mul_f32_e32 v123, 0xbfb8aa3b, v113
	v_mul_f32_e32 v124, 0xbfb8aa3b, v114
	v_mul_f32_e32 v125, 0xbfb8aa3b, v115
	v_exp_f32_e32 v122, v122
	v_exp_f32_e32 v123, v123
	v_exp_f32_e32 v124, v124
	v_exp_f32_e32 v125, v125
	v_add_f32_e32 v122, 1.0, v122
	v_add_f32_e32 v123, 1.0, v123
	v_add_f32_e32 v124, 1.0, v124
	v_add_f32_e32 v125, 1.0, v125
	v_rcp_f32_e32 v122, v122
	v_rcp_f32_e32 v123, v123
	v_rcp_f32_e32 v124, v124
	v_rcp_f32_e32 v125, v125
	v_pk_mul_f32 v[112:113], v[112:113], v[122:123]
	s_nop 0
	v_pk_mul_f32 v[112:113], v[112:113], v[120:121]
	global_load_dword v120, v[116:117], off
	v_pk_mul_f32 v[114:115], v[114:115], v[124:125]
	v_cvt_pk_bf16_f32 v112, v112, v113
	v_pk_mul_f32 v[114:115], v[114:115], v[126:127]
	s_nop 0
	v_cvt_pk_bf16_f32 v113, v114, v115
	global_store_dwordx2 v[134:135], v[112:113], off offset:96
	s_nop 0
	v_lshlrev_b64 v[112:113], 11, v[118:119]
	v_lshl_add_u64 v[112:113], s[38:39], 0, v[112:113]
	v_lshl_add_u64 v[112:113], v[112:113], 0, v[130:131]
	global_load_dwordx2 v[114:115], v[112:113], off
	global_load_dwordx2 v[184:185], v[112:113], off offset:32
	global_load_dwordx2 v[186:187], v[112:113], off offset:64
	global_load_dwordx2 v[122:123], v[112:113], off offset:96
	s_waitcnt vmcnt(5)
; DI float bflo(unsigned u) { return __uint_as_float(u << 16); }
; DI float bfhi(unsigned u) { return __uint_as_float(u & 0xffff0000u); }
; DI u32x2 pack4(float a, float b, float c, float d) { u32x2 r; r.x = pack2(a, b); r.y = pack2(c, d); return r; }
; #define EPI_END if (i == 3 && (j & 3) == 3) __builtin_amdgcn_sched_barrier(0); }
; DI float rstd_of(const float* ssq, int m, float invn) { return rsqrtf(ssq[m] * invn + 1e-6f); }
; DI float silu(float v) { return v * __builtin_amdgcn_rcpf(1.f + __expf(-v)); }
; template <int MODE>
; DI void gemm_phase(const Params& p, const GP& g, unsigned char* smem) {
;     ...
;     } else if (MODE == M_ZPASS) {
;       u16* og = (u16*)g.d0;
;       EPI_STD_BEGIN
;         const float rs = rstd_of(g.ssq_in, m, 1.f / 1024);
;         u32x2* op = (u32x2*)(og + (long)m * 1024 + n4);
;         const u32x2 ov = *op;
;         *op = pack4(bflo(ov.x) * silu(v[0] * rs), bfhi(ov.x) * silu(v[1] * rs), bflo(ov.y) * silu(v[2] * rs), bfhi(ov.y) * silu(v[3] * rs));
;       EPI_END
	v_fmamk_f32 v118, v120, 0x3a800000, v148
	v_mul_f32_e32 v119, 0x4b800000, v118
	v_cmp_gt_f32_e32 vcc, s54, v118
	s_waitcnt vmcnt(3)
	v_lshlrev_b32_e32 v124, 16, v114
	v_cndmask_b32_e32 v118, v118, v119, vcc
	v_rsq_f32_e32 v126, v118
	v_and_b32_e32 v125, 0xffff0000, v114
	s_nop 0
	s_nop 0
	s_nop 0
	v_mul_f32_e32 v114, 0x45800000, v126
	v_cndmask_b32_e32 v114, v126, v114, vcc
	v_mov_b32_e32 v158, v114
	v_pk_mul_f32 v[108:109], v[108:109], v[114:115] op_sel_hi:[1,0]
	v_pk_mul_f32 v[110:111], v[110:111], v[158:159] op_sel_hi:[1,0]
	v_mul_f32_e32 v114, 0xbfb8aa3b, v108
	v_mul_f32_e32 v126, 0xbfb8aa3b, v109
	v_mul_f32_e32 v127, 0xbfb8aa3b, v110
	v_mul_f32_e32 v128, 0xbfb8aa3b, v111
	v_exp_f32_e32 v114, v114
	v_exp_f32_e32 v126, v126
	v_exp_f32_e32 v127, v127
	v_exp_f32_e32 v128, v128
	v_add_f32_e32 v114, 1.0, v114
	v_add_f32_e32 v133, 1.0, v126
	v_add_f32_e32 v134, 1.0, v127
	v_add_f32_e32 v128, 1.0, v128
	v_rcp_f32_e32 v126, v114
	v_rcp_f32_e32 v127, v133
	v_rcp_f32_e32 v134, v134
	v_rcp_f32_e32 v135, v128
	v_lshlrev_b32_e32 v114, 16, v115
	v_and_b32_e32 v115, 0xffff0000, v115
	v_pk_mul_f32 v[108:109], v[108:109], v[126:127]
	v_pk_mul_f32 v[110:111], v[110:111], v[134:135]
	v_pk_mul_f32 v[108:109], v[108:109], v[124:125]
	v_pk_mul_f32 v[110:111], v[110:111], v[114:115]
	v_cvt_pk_bf16_f32 v108, v108, v109
	v_cvt_pk_bf16_f32 v109, v110, v111
	global_store_dwordx2 v[112:113], v[108:109], off
	s_nop 1
	s_waitcnt vmcnt(3)
	v_lshlrev_b32_e32 v108, 16, v184
	v_and_b32_e32 v109, 0xffff0000, v184
	v_lshlrev_b32_e32 v118, 16, v185
	v_pk_mul_f32 v[104:105], v[104:105], v[158:159] op_sel_hi:[1,0]
	v_pk_mul_f32 v[106:107], v[106:107], v[158:159] op_sel_hi:[1,0]
	v_mul_f32_e32 v110, 0xbfb8aa3b, v104
	v_mul_f32_e32 v111, 0xbfb8aa3b, v105
	v_mul_f32_e32 v114, 0xbfb8aa3b, v106
	v_mul_f32_e32 v115, 0xbfb8aa3b, v107
	v_exp_f32_e32 v110, v110
	v_exp_f32_e32 v111, v111
	v_exp_f32_e32 v114, v114
	v_exp_f32_e32 v115, v115
	v_add_f32_e32 v110, 1.0, v110
	v_add_f32_e32 v111, 1.0, v111
	v_add_f32_e32 v114, 1.0, v114
	v_add_f32_e32 v115, 1.0, v115
	v_rcp_f32_e32 v110, v110
	v_rcp_f32_e32 v111, v111
	v_rcp_f32_e32 v114, v114
	v_rcp_f32_e32 v115, v115
	v_and_b32_e32 v119, 0xffff0000, v185
	v_pk_mul_f32 v[104:105], v[104:105], v[110:111]
	s_waitcnt vmcnt(2)
	v_lshlrev_b32_e32 v110, 16, v187
	v_pk_mul_f32 v[106:107], v[106:107], v[114:115]
	v_pk_mul_f32 v[104:105], v[104:105], v[108:109]
	v_pk_mul_f32 v[106:107], v[106:107], v[118:119]
	v_cvt_pk_bf16_f32 v104, v104, v105
	v_cvt_pk_bf16_f32 v105, v106, v107
	global_store_dwordx2 v[112:113], v[104:105], off offset:32
	v_and_b32_e32 v111, 0xffff0000, v187
	s_nop 1
	v_lshlrev_b32_e32 v104, 16, v186
	v_and_b32_e32 v105, 0xffff0000, v186
	v_pk_mul_f32 v[100:101], v[100:101], v[158:159] op_sel_hi:[1,0]
	v_pk_mul_f32 v[102:103], v[102:103], v[158:159] op_sel_hi:[1,0]
	v_mul_f32_e32 v106, 0xbfb8aa3b, v100
	v_mul_f32_e32 v107, 0xbfb8aa3b, v101
	v_mul_f32_e32 v108, 0xbfb8aa3b, v102
	v_mul_f32_e32 v109, 0xbfb8aa3b, v103
	v_exp_f32_e32 v106, v106
	v_exp_f32_e32 v107, v107
	v_exp_f32_e32 v108, v108
	v_exp_f32_e32 v109, v109
	v_add_f32_e32 v106, 1.0, v106
	v_add_f32_e32 v107, 1.0, v107
	v_add_f32_e32 v108, 1.0, v108
	v_add_f32_e32 v109, 1.0, v109
	v_rcp_f32_e32 v106, v106
	v_rcp_f32_e32 v107, v107
	v_rcp_f32_e32 v108, v108
	v_rcp_f32_e32 v109, v109
	v_pk_mul_f32 v[100:101], v[100:101], v[106:107]
	s_nop 0
	v_pk_mul_f32 v[100:101], v[100:101], v[104:105]
	v_pk_mul_f32 v[102:103], v[102:103], v[108:109]
	v_cvt_pk_bf16_f32 v100, v100, v101
	v_pk_mul_f32 v[102:103], v[102:103], v[110:111]
	s_waitcnt vmcnt(2)
	v_lshlrev_b32_e32 v104, 16, v122
	v_cvt_pk_bf16_f32 v101, v102, v103
	global_store_dwordx2 v[112:113], v[100:101], off offset:64
	v_and_b32_e32 v105, 0xffff0000, v122
	v_lshlrev_b32_e32 v110, 16, v123
	v_and_b32_e32 v111, 0xffff0000, v123
	v_or_b32_e32 v102, 32, v132
	v_ashrrev_i32_e32 v103, 31, v102
	s_nop 1
	v_lshl_add_u64 v[100:101], v[102:103], 2, s[14:15]
	v_pk_mul_f32 v[96:97], v[96:97], v[158:159] op_sel_hi:[1,0]
	v_pk_mul_f32 v[98:99], v[98:99], v[158:159] op_sel_hi:[1,0]
	v_mul_f32_e32 v106, 0xbfb8aa3b, v96
	v_mul_f32_e32 v107, 0xbfb8aa3b, v97
	v_mul_f32_e32 v108, 0xbfb8aa3b, v98
	v_mul_f32_e32 v109, 0xbfb8aa3b, v99
	v_exp_f32_e32 v106, v106
	v_exp_f32_e32 v107, v107
	v_exp_f32_e32 v108, v108
	v_exp_f32_e32 v109, v109
	v_add_f32_e32 v106, 1.0, v106
	v_add_f32_e32 v107, 1.0, v107
	v_add_f32_e32 v108, 1.0, v108
	v_add_f32_e32 v109, 1.0, v109
	v_rcp_f32_e32 v106, v106
	v_rcp_f32_e32 v107, v107
	v_rcp_f32_e32 v108, v108
	v_rcp_f32_e32 v109, v109
	v_pk_mul_f32 v[96:97], v[96:97], v[106:107]
	s_nop 0
	v_pk_mul_f32 v[96:97], v[96:97], v[104:105]
	global_load_dword v104, v[100:101], off
	v_pk_mul_f32 v[98:99], v[98:99], v[108:109]
	v_cvt_pk_bf16_f32 v96, v96, v97
	v_pk_mul_f32 v[98:99], v[98:99], v[110:111]
	s_nop 0
	v_cvt_pk_bf16_f32 v97, v98, v99
	global_store_dwordx2 v[112:113], v[96:97], off offset:96
	s_nop 0
	v_lshlrev_b64 v[96:97], 11, v[102:103]
	v_lshl_add_u64 v[96:97], s[38:39], 0, v[96:97]
	v_lshl_add_u64 v[96:97], v[96:97], 0, v[130:131]
	global_load_dwordx2 v[98:99], v[96:97], off
	global_load_dwordx2 v[184:185], v[96:97], off offset:32
	global_load_dwordx2 v[186:187], v[96:97], off offset:64
	global_load_dwordx2 v[106:107], v[96:97], off offset:96
	s_waitcnt vmcnt(5)
	v_fmamk_f32 v102, v104, 0x3a800000, v148
	v_mul_f32_e32 v103, 0x4b800000, v102
	v_cmp_gt_f32_e32 vcc, s54, v102
	s_waitcnt vmcnt(3)
; DI float bflo(unsigned u) { return __uint_as_float(u << 16); }
; DI float bfhi(unsigned u) { return __uint_as_float(u & 0xffff0000u); }
; DI u32x2 pack4(float a, float b, float c, float d) { u32x2 r; r.x = pack2(a, b); r.y = pack2(c, d); return r; }
; #define EPI_END if (i == 3 && (j & 3) == 3) __builtin_amdgcn_sched_barrier(0); }
; DI float rstd_of(const float* ssq, int m, float invn) { return rsqrtf(ssq[m] * invn + 1e-6f); }
; DI float silu(float v) { return v * __builtin_amdgcn_rcpf(1.f + __expf(-v)); }
; template <int MODE>
; DI void gemm_phase(const Params& p, const GP& g, unsigned char* smem) {
;     ...
;     } else if (MODE == M_ZPASS) {
;       u16* og = (u16*)g.d0;
;       EPI_STD_BEGIN
;         const float rs = rstd_of(g.ssq_in, m, 1.f / 1024);
;         u32x2* op = (u32x2*)(og + (long)m * 1024 + n4);
;         const u32x2 ov = *op;
;         *op = pack4(bflo(ov.x) * silu(v[0] * rs), bfhi(ov.x) * silu(v[1] * rs), bflo(ov.y) * silu(v[2] * rs), bfhi(ov.y) * silu(v[3] * rs));
;       EPI_END
	v_lshlrev_b32_e32 v108, 16, v98
	v_cndmask_b32_e32 v102, v102, v103, vcc
	v_rsq_f32_e32 v110, v102
	v_and_b32_e32 v109, 0xffff0000, v98
	s_nop 0
	s_nop 0
	s_nop 0
	v_mul_f32_e32 v98, 0x45800000, v110
	v_cndmask_b32_e32 v98, v110, v98, vcc
	v_mov_b32_e32 v160, v98
	v_pk_mul_f32 v[92:93], v[92:93], v[98:99] op_sel_hi:[1,0]
	v_pk_mul_f32 v[94:95], v[94:95], v[160:161] op_sel_hi:[1,0]
	v_mul_f32_e32 v98, 0xbfb8aa3b, v92
	v_mul_f32_e32 v110, 0xbfb8aa3b, v93
	v_mul_f32_e32 v111, 0xbfb8aa3b, v94
	v_mul_f32_e32 v112, 0xbfb8aa3b, v95
	v_exp_f32_e32 v98, v98
	v_exp_f32_e32 v110, v110
	v_exp_f32_e32 v111, v111
	v_exp_f32_e32 v112, v112
	v_add_f32_e32 v98, 1.0, v98
	v_add_f32_e32 v113, 1.0, v110
	v_add_f32_e32 v114, 1.0, v111
	v_add_f32_e32 v115, 1.0, v112
	v_rcp_f32_e32 v110, v98
	v_rcp_f32_e32 v111, v113
	v_rcp_f32_e32 v112, v114
	v_rcp_f32_e32 v113, v115
	v_lshlrev_b32_e32 v98, 16, v99
	v_and_b32_e32 v99, 0xffff0000, v99
	v_pk_mul_f32 v[92:93], v[92:93], v[110:111]
	v_pk_mul_f32 v[94:95], v[94:95], v[112:113]
	v_pk_mul_f32 v[92:93], v[92:93], v[108:109]
	v_pk_mul_f32 v[94:95], v[94:95], v[98:99]
	v_cvt_pk_bf16_f32 v92, v92, v93
	v_cvt_pk_bf16_f32 v93, v94, v95
	global_store_dwordx2 v[96:97], v[92:93], off
	s_nop 1
	s_waitcnt vmcnt(3)
	v_lshlrev_b32_e32 v92, 16, v184
	v_and_b32_e32 v93, 0xffff0000, v184
	v_lshlrev_b32_e32 v102, 16, v185
	v_pk_mul_f32 v[88:89], v[88:89], v[160:161] op_sel_hi:[1,0]
	v_pk_mul_f32 v[90:91], v[90:91], v[160:161] op_sel_hi:[1,0]
	v_mul_f32_e32 v94, 0xbfb8aa3b, v88
	v_mul_f32_e32 v95, 0xbfb8aa3b, v89
	v_mul_f32_e32 v98, 0xbfb8aa3b, v90
	v_mul_f32_e32 v99, 0xbfb8aa3b, v91
	v_exp_f32_e32 v94, v94
	v_exp_f32_e32 v95, v95
	v_exp_f32_e32 v98, v98
	v_exp_f32_e32 v99, v99
	v_add_f32_e32 v94, 1.0, v94
	v_add_f32_e32 v95, 1.0, v95
	v_add_f32_e32 v98, 1.0, v98
	v_add_f32_e32 v99, 1.0, v99
	v_rcp_f32_e32 v94, v94
	v_rcp_f32_e32 v95, v95
	v_rcp_f32_e32 v98, v98
	v_rcp_f32_e32 v99, v99
	v_and_b32_e32 v103, 0xffff0000, v185
	v_pk_mul_f32 v[88:89], v[88:89], v[94:95]
	s_waitcnt vmcnt(2)
	v_lshlrev_b32_e32 v94, 16, v187
	v_pk_mul_f32 v[90:91], v[90:91], v[98:99]
	v_pk_mul_f32 v[88:89], v[88:89], v[92:93]
	v_pk_mul_f32 v[90:91], v[90:91], v[102:103]
	v_cvt_pk_bf16_f32 v88, v88, v89
	v_cvt_pk_bf16_f32 v89, v90, v91
	global_store_dwordx2 v[96:97], v[88:89], off offset:32
	v_and_b32_e32 v95, 0xffff0000, v187
	s_nop 1
	v_lshlrev_b32_e32 v88, 16, v186
	v_and_b32_e32 v89, 0xffff0000, v186
	v_pk_mul_f32 v[84:85], v[84:85], v[160:161] op_sel_hi:[1,0]
	v_pk_mul_f32 v[86:87], v[86:87], v[160:161] op_sel_hi:[1,0]
	v_mul_f32_e32 v90, 0xbfb8aa3b, v84
	v_mul_f32_e32 v91, 0xbfb8aa3b, v85
	v_mul_f32_e32 v92, 0xbfb8aa3b, v86
	v_mul_f32_e32 v93, 0xbfb8aa3b, v87
	v_exp_f32_e32 v90, v90
	v_exp_f32_e32 v91, v91
	v_exp_f32_e32 v92, v92
	v_exp_f32_e32 v93, v93
	v_add_f32_e32 v90, 1.0, v90
	v_add_f32_e32 v91, 1.0, v91
	v_add_f32_e32 v92, 1.0, v92
	v_add_f32_e32 v93, 1.0, v93
	v_rcp_f32_e32 v90, v90
	v_rcp_f32_e32 v91, v91
	v_rcp_f32_e32 v92, v92
	v_rcp_f32_e32 v93, v93
	v_pk_mul_f32 v[84:85], v[84:85], v[90:91]
	s_nop 0
	v_pk_mul_f32 v[84:85], v[84:85], v[88:89]
	v_pk_mul_f32 v[86:87], v[86:87], v[92:93]
	v_cvt_pk_bf16_f32 v84, v84, v85
	v_pk_mul_f32 v[86:87], v[86:87], v[94:95]
	s_waitcnt vmcnt(2)
	v_lshlrev_b32_e32 v88, 16, v106
	v_cvt_pk_bf16_f32 v85, v86, v87
	global_store_dwordx2 v[96:97], v[84:85], off offset:64
	v_and_b32_e32 v89, 0xffff0000, v106
	v_lshlrev_b32_e32 v94, 16, v107
	v_and_b32_e32 v95, 0xffff0000, v107
	v_or_b32_e32 v86, 48, v132
	v_ashrrev_i32_e32 v87, 31, v86
	s_nop 1
	v_lshl_add_u64 v[84:85], v[86:87], 2, s[14:15]
	v_pk_mul_f32 v[80:81], v[80:81], v[160:161] op_sel_hi:[1,0]
	v_pk_mul_f32 v[82:83], v[82:83], v[160:161] op_sel_hi:[1,0]
	v_mul_f32_e32 v90, 0xbfb8aa3b, v80
	v_mul_f32_e32 v91, 0xbfb8aa3b, v81
	v_mul_f32_e32 v92, 0xbfb8aa3b, v82
	v_mul_f32_e32 v93, 0xbfb8aa3b, v83
	v_exp_f32_e32 v90, v90
	v_exp_f32_e32 v91, v91
	v_exp_f32_e32 v92, v92
	v_exp_f32_e32 v93, v93
	v_add_f32_e32 v90, 1.0, v90
	v_add_f32_e32 v91, 1.0, v91
	v_add_f32_e32 v92, 1.0, v92
	v_add_f32_e32 v93, 1.0, v93
	v_rcp_f32_e32 v90, v90
	v_rcp_f32_e32 v91, v91
	v_rcp_f32_e32 v92, v92
	v_rcp_f32_e32 v93, v93
	v_pk_mul_f32 v[80:81], v[80:81], v[90:91]
	s_nop 0
	v_pk_mul_f32 v[80:81], v[80:81], v[88:89]
	global_load_dword v88, v[84:85], off
	v_pk_mul_f32 v[82:83], v[82:83], v[92:93]
	v_cvt_pk_bf16_f32 v80, v80, v81
	v_pk_mul_f32 v[82:83], v[82:83], v[94:95]
	s_nop 0
	v_cvt_pk_bf16_f32 v81, v82, v83
	global_store_dwordx2 v[96:97], v[80:81], off offset:96
	s_nop 0
	v_lshlrev_b64 v[80:81], 11, v[86:87]
	v_lshl_add_u64 v[80:81], s[38:39], 0, v[80:81]
	v_lshl_add_u64 v[80:81], v[80:81], 0, v[130:131]
	global_load_dwordx2 v[82:83], v[80:81], off
	global_load_dwordx2 v[184:185], v[80:81], off offset:32
	global_load_dwordx2 v[186:187], v[80:81], off offset:64
	global_load_dwordx2 v[90:91], v[80:81], off offset:96
	s_waitcnt vmcnt(5)
	v_fmamk_f32 v86, v88, 0x3a800000, v148
	v_mul_f32_e32 v87, 0x4b800000, v86
	v_cmp_gt_f32_e32 vcc, s54, v86
	s_waitcnt vmcnt(3)
	v_lshlrev_b32_e32 v92, 16, v82
	v_cndmask_b32_e32 v86, v86, v87, vcc
	v_rsq_f32_e32 v94, v86
	v_and_b32_e32 v93, 0xffff0000, v82
	s_nop 0
	s_nop 0
	s_nop 0
	v_mul_f32_e32 v82, 0x45800000, v94
	v_cndmask_b32_e32 v82, v94, v82, vcc
	v_mov_b32_e32 v162, v82
	v_pk_mul_f32 v[76:77], v[76:77], v[82:83] op_sel_hi:[1,0]
	v_pk_mul_f32 v[78:79], v[78:79], v[162:163] op_sel_hi:[1,0]
	v_mul_f32_e32 v82, 0xbfb8aa3b, v76
	v_mul_f32_e32 v94, 0xbfb8aa3b, v77
	v_mul_f32_e32 v95, 0xbfb8aa3b, v78
	v_mul_f32_e32 v96, 0xbfb8aa3b, v79
	v_exp_f32_e32 v82, v82
	v_exp_f32_e32 v94, v94
	v_exp_f32_e32 v95, v95
	v_exp_f32_e32 v96, v96
	v_add_f32_e32 v82, 1.0, v82
	v_add_f32_e32 v97, 1.0, v94
	v_add_f32_e32 v98, 1.0, v95
	v_add_f32_e32 v99, 1.0, v96
	v_rcp_f32_e32 v94, v82
	v_rcp_f32_e32 v95, v97
	v_rcp_f32_e32 v96, v98
	v_rcp_f32_e32 v97, v99
	v_lshlrev_b32_e32 v82, 16, v83
	v_and_b32_e32 v83, 0xffff0000, v83
	v_pk_mul_f32 v[76:77], v[76:77], v[94:95]
	v_pk_mul_f32 v[78:79], v[78:79], v[96:97]
	v_pk_mul_f32 v[76:77], v[76:77], v[92:93]
	v_pk_mul_f32 v[78:79], v[78:79], v[82:83]
	v_cvt_pk_bf16_f32 v76, v76, v77
	v_cvt_pk_bf16_f32 v77, v78, v79
	global_store_dwordx2 v[80:81], v[76:77], off
	s_nop 1
	s_waitcnt vmcnt(3)
; DI float bflo(unsigned u) { return __uint_as_float(u << 16); }
; DI float bfhi(unsigned u) { return __uint_as_float(u & 0xffff0000u); }
; DI u32x2 pack4(float a, float b, float c, float d) { u32x2 r; r.x = pack2(a, b); r.y = pack2(c, d); return r; }
; #define EPI_END if (i == 3 && (j & 3) == 3) __builtin_amdgcn_sched_barrier(0); }
; DI float rstd_of(const float* ssq, int m, float invn) { return rsqrtf(ssq[m] * invn + 1e-6f); }
; DI float silu(float v) { return v * __builtin_amdgcn_rcpf(1.f + __expf(-v)); }
; template <int MODE>
; DI void gemm_phase(const Params& p, const GP& g, unsigned char* smem) {
;     ...
;     } else if (MODE == M_ZPASS) {
;       u16* og = (u16*)g.d0;
;       EPI_STD_BEGIN
;         const float rs = rstd_of(g.ssq_in, m, 1.f / 1024);
;         u32x2* op = (u32x2*)(og + (long)m * 1024 + n4);
;         const u32x2 ov = *op;
;         *op = pack4(bflo(ov.x) * silu(v[0] * rs), bfhi(ov.x) * silu(v[1] * rs), bflo(ov.y) * silu(v[2] * rs), bfhi(ov.y) * silu(v[3] * rs));
;       EPI_END
	v_lshlrev_b32_e32 v76, 16, v184
	v_and_b32_e32 v77, 0xffff0000, v184
	v_lshlrev_b32_e32 v86, 16, v185
	v_pk_mul_f32 v[72:73], v[72:73], v[162:163] op_sel_hi:[1,0]
	v_pk_mul_f32 v[74:75], v[74:75], v[162:163] op_sel_hi:[1,0]
	v_mul_f32_e32 v78, 0xbfb8aa3b, v72
	v_mul_f32_e32 v79, 0xbfb8aa3b, v73
	v_mul_f32_e32 v82, 0xbfb8aa3b, v74
	v_mul_f32_e32 v83, 0xbfb8aa3b, v75
	v_exp_f32_e32 v78, v78
	v_exp_f32_e32 v79, v79
	v_exp_f32_e32 v82, v82
	v_exp_f32_e32 v83, v83
	v_add_f32_e32 v78, 1.0, v78
	v_add_f32_e32 v79, 1.0, v79
	v_add_f32_e32 v82, 1.0, v82
	v_add_f32_e32 v83, 1.0, v83
	v_rcp_f32_e32 v78, v78
	v_rcp_f32_e32 v79, v79
	v_rcp_f32_e32 v82, v82
	v_rcp_f32_e32 v83, v83
	v_and_b32_e32 v87, 0xffff0000, v185
	v_pk_mul_f32 v[72:73], v[72:73], v[78:79]
	s_waitcnt vmcnt(2)
	v_lshlrev_b32_e32 v78, 16, v187
	v_pk_mul_f32 v[74:75], v[74:75], v[82:83]
	v_pk_mul_f32 v[72:73], v[72:73], v[76:77]
	v_pk_mul_f32 v[74:75], v[74:75], v[86:87]
	v_cvt_pk_bf16_f32 v72, v72, v73
	v_cvt_pk_bf16_f32 v73, v74, v75
	global_store_dwordx2 v[80:81], v[72:73], off offset:32
	v_and_b32_e32 v79, 0xffff0000, v187
	s_nop 1
	v_lshlrev_b32_e32 v72, 16, v186
	v_and_b32_e32 v73, 0xffff0000, v186
	v_pk_mul_f32 v[68:69], v[68:69], v[162:163] op_sel_hi:[1,0]
	v_pk_mul_f32 v[70:71], v[70:71], v[162:163] op_sel_hi:[1,0]
	v_mul_f32_e32 v74, 0xbfb8aa3b, v68
	v_mul_f32_e32 v75, 0xbfb8aa3b, v69
	v_mul_f32_e32 v76, 0xbfb8aa3b, v70
	v_mul_f32_e32 v77, 0xbfb8aa3b, v71
	v_exp_f32_e32 v74, v74
	v_exp_f32_e32 v75, v75
	v_exp_f32_e32 v76, v76
	v_exp_f32_e32 v77, v77
	v_add_f32_e32 v74, 1.0, v74
	v_add_f32_e32 v75, 1.0, v75
	v_add_f32_e32 v76, 1.0, v76
	v_add_f32_e32 v77, 1.0, v77
	v_rcp_f32_e32 v74, v74
	v_rcp_f32_e32 v75, v75
	v_rcp_f32_e32 v76, v76
	v_rcp_f32_e32 v77, v77
	v_pk_mul_f32 v[68:69], v[68:69], v[74:75]
	s_nop 0
	v_pk_mul_f32 v[68:69], v[68:69], v[72:73]
	v_pk_mul_f32 v[70:71], v[70:71], v[76:77]
	v_cvt_pk_bf16_f32 v68, v68, v69
	v_pk_mul_f32 v[70:71], v[70:71], v[78:79]
	s_waitcnt vmcnt(2)
	v_lshlrev_b32_e32 v74, 16, v91
	v_cvt_pk_bf16_f32 v69, v70, v71
	global_store_dwordx2 v[80:81], v[68:69], off offset:64
	v_and_b32_e32 v75, 0xffff0000, v91
	s_nop 1
	v_lshlrev_b32_e32 v68, 16, v90
	v_and_b32_e32 v69, 0xffff0000, v90
	v_pk_mul_f32 v[64:65], v[64:65], v[162:163] op_sel_hi:[1,0]
	v_pk_mul_f32 v[66:67], v[66:67], v[162:163] op_sel_hi:[1,0]
	v_mul_f32_e32 v70, 0xbfb8aa3b, v64
	v_mul_f32_e32 v71, 0xbfb8aa3b, v65
	v_mul_f32_e32 v72, 0xbfb8aa3b, v66
	v_mul_f32_e32 v73, 0xbfb8aa3b, v67
	v_exp_f32_e32 v70, v70
	v_exp_f32_e32 v71, v71
	v_exp_f32_e32 v72, v72
	v_exp_f32_e32 v73, v73
	v_add_f32_e32 v70, 1.0, v70
	v_add_f32_e32 v71, 1.0, v71
	v_add_f32_e32 v72, 1.0, v72
	v_add_f32_e32 v73, 1.0, v73
	v_rcp_f32_e32 v70, v70
	v_rcp_f32_e32 v71, v71
	v_rcp_f32_e32 v72, v72
	v_rcp_f32_e32 v73, v73
	v_pk_mul_f32 v[64:65], v[64:65], v[70:71]
	s_nop 0
	v_pk_mul_f32 v[64:65], v[64:65], v[68:69]
	v_pk_mul_f32 v[66:67], v[66:67], v[72:73]
	v_cvt_pk_bf16_f32 v64, v64, v65
	v_pk_mul_f32 v[66:67], v[66:67], v[74:75]
	s_nop 0
	v_cvt_pk_bf16_f32 v65, v66, v67
	global_store_dwordx2 v[80:81], v[64:65], off offset:96
	v_or_b32_e32 v64, 64, v132
	v_ashrrev_i32_e32 v65, 31, v64
	v_lshl_add_u64 v[66:67], v[64:65], 2, s[14:15]
	global_load_dword v70, v[66:67], off
	v_lshlrev_b64 v[64:65], 11, v[64:65]
	v_lshl_add_u64 v[64:65], s[38:39], 0, v[64:65]
	v_lshl_add_u64 v[64:65], v[64:65], 0, v[130:131]
	global_load_dwordx2 v[68:69], v[64:65], off
	global_load_dwordx2 v[184:185], v[64:65], off offset:32
	global_load_dwordx2 v[72:73], v[64:65], off offset:64
	global_load_dwordx2 v[74:75], v[64:65], off offset:96
	s_waitcnt vmcnt(4)
	v_fmamk_f32 v70, v70, 0x3a800000, v148
	v_mul_f32_e32 v71, 0x4b800000, v70
	v_cmp_gt_f32_e32 vcc, s54, v70
	s_waitcnt vmcnt(3)
	v_lshlrev_b32_e32 v76, 16, v68
	v_cndmask_b32_e32 v70, v70, v71, vcc
	v_rsq_f32_e32 v78, v70
	v_and_b32_e32 v77, 0xffff0000, v68
	s_nop 0
	s_nop 0
	s_nop 0
	v_mul_f32_e32 v68, 0x45800000, v78
	v_cndmask_b32_e32 v68, v78, v68, vcc
	v_mov_b32_e32 v164, v68
	v_pk_mul_f32 v[60:61], v[60:61], v[68:69] op_sel_hi:[1,0]
	v_pk_mul_f32 v[62:63], v[62:63], v[164:165] op_sel_hi:[1,0]
	v_mul_f32_e32 v68, 0xbfb8aa3b, v60
	v_mul_f32_e32 v78, 0xbfb8aa3b, v61
	v_mul_f32_e32 v79, 0xbfb8aa3b, v62
	v_mul_f32_e32 v80, 0xbfb8aa3b, v63
	v_exp_f32_e32 v68, v68
	v_exp_f32_e32 v78, v78
	v_exp_f32_e32 v79, v79
	v_exp_f32_e32 v80, v80
	v_add_f32_e32 v68, 1.0, v68
	v_add_f32_e32 v81, 1.0, v78
	v_add_f32_e32 v82, 1.0, v79
	v_add_f32_e32 v83, 1.0, v80
	v_rcp_f32_e32 v78, v68
	v_rcp_f32_e32 v79, v81
	v_rcp_f32_e32 v80, v82
	v_rcp_f32_e32 v81, v83
	v_lshlrev_b32_e32 v68, 16, v69
	v_and_b32_e32 v69, 0xffff0000, v69
	v_pk_mul_f32 v[60:61], v[60:61], v[78:79]
	v_pk_mul_f32 v[62:63], v[62:63], v[80:81]
	v_pk_mul_f32 v[60:61], v[60:61], v[76:77]
	v_pk_mul_f32 v[62:63], v[62:63], v[68:69]
	v_cvt_pk_bf16_f32 v60, v60, v61
	v_cvt_pk_bf16_f32 v61, v62, v63
	global_store_dwordx2 v[64:65], v[60:61], off
	s_nop 1
	s_waitcnt vmcnt(3)
	v_lshlrev_b32_e32 v60, 16, v184
	v_and_b32_e32 v61, 0xffff0000, v184
	v_lshlrev_b32_e32 v70, 16, v185
	v_pk_mul_f32 v[56:57], v[56:57], v[164:165] op_sel_hi:[1,0]
	v_pk_mul_f32 v[58:59], v[58:59], v[164:165] op_sel_hi:[1,0]
	v_mul_f32_e32 v62, 0xbfb8aa3b, v56
	v_mul_f32_e32 v63, 0xbfb8aa3b, v57
	v_mul_f32_e32 v68, 0xbfb8aa3b, v58
	v_mul_f32_e32 v69, 0xbfb8aa3b, v59
	v_exp_f32_e32 v62, v62
	v_exp_f32_e32 v63, v63
	v_exp_f32_e32 v68, v68
	v_exp_f32_e32 v69, v69
	v_add_f32_e32 v62, 1.0, v62
	v_add_f32_e32 v63, 1.0, v63
	v_add_f32_e32 v68, 1.0, v68
	v_add_f32_e32 v69, 1.0, v69
	v_rcp_f32_e32 v62, v62
	v_rcp_f32_e32 v63, v63
	v_rcp_f32_e32 v68, v68
	v_rcp_f32_e32 v69, v69
	v_and_b32_e32 v71, 0xffff0000, v185
	v_pk_mul_f32 v[56:57], v[56:57], v[62:63]
	s_waitcnt vmcnt(2)
; DI float bflo(unsigned u) { return __uint_as_float(u << 16); }
; DI float bfhi(unsigned u) { return __uint_as_float(u & 0xffff0000u); }
; DI u32x2 pack4(float a, float b, float c, float d) { u32x2 r; r.x = pack2(a, b); r.y = pack2(c, d); return r; }
; #define EPI_END if (i == 3 && (j & 3) == 3) __builtin_amdgcn_sched_barrier(0); }
; DI float rstd_of(const float* ssq, int m, float invn) { return rsqrtf(ssq[m] * invn + 1e-6f); }
; DI float silu(float v) { return v * __builtin_amdgcn_rcpf(1.f + __expf(-v)); }
; template <int MODE>
; DI void gemm_phase(const Params& p, const GP& g, unsigned char* smem) {
;     ...
;     } else if (MODE == M_ZPASS) {
;       u16* og = (u16*)g.d0;
;       EPI_STD_BEGIN
;         const float rs = rstd_of(g.ssq_in, m, 1.f / 1024);
;         u32x2* op = (u32x2*)(og + (long)m * 1024 + n4);
;         const u32x2 ov = *op;
;         *op = pack4(bflo(ov.x) * silu(v[0] * rs), bfhi(ov.x) * silu(v[1] * rs), bflo(ov.y) * silu(v[2] * rs), bfhi(ov.y) * silu(v[3] * rs));
;       EPI_END
	v_lshlrev_b32_e32 v62, 16, v73
	v_pk_mul_f32 v[58:59], v[58:59], v[68:69]
	v_pk_mul_f32 v[56:57], v[56:57], v[60:61]
	v_pk_mul_f32 v[58:59], v[58:59], v[70:71]
	v_cvt_pk_bf16_f32 v56, v56, v57
	v_cvt_pk_bf16_f32 v57, v58, v59
	global_store_dwordx2 v[64:65], v[56:57], off offset:32
	v_and_b32_e32 v63, 0xffff0000, v73
	s_nop 1
	v_lshlrev_b32_e32 v56, 16, v72
	v_and_b32_e32 v57, 0xffff0000, v72
	v_pk_mul_f32 v[52:53], v[52:53], v[164:165] op_sel_hi:[1,0]
	v_pk_mul_f32 v[54:55], v[54:55], v[164:165] op_sel_hi:[1,0]
	v_mul_f32_e32 v58, 0xbfb8aa3b, v52
	v_mul_f32_e32 v59, 0xbfb8aa3b, v53
	v_mul_f32_e32 v60, 0xbfb8aa3b, v54
	v_mul_f32_e32 v61, 0xbfb8aa3b, v55
	v_exp_f32_e32 v58, v58
	v_exp_f32_e32 v59, v59
	v_exp_f32_e32 v60, v60
	v_exp_f32_e32 v61, v61
	v_add_f32_e32 v58, 1.0, v58
	v_add_f32_e32 v59, 1.0, v59
	v_add_f32_e32 v60, 1.0, v60
	v_add_f32_e32 v61, 1.0, v61
	v_rcp_f32_e32 v58, v58
	v_rcp_f32_e32 v59, v59
	v_rcp_f32_e32 v60, v60
	v_rcp_f32_e32 v61, v61
	v_pk_mul_f32 v[52:53], v[52:53], v[58:59]
	s_nop 0
	v_pk_mul_f32 v[52:53], v[52:53], v[56:57]
	v_pk_mul_f32 v[54:55], v[54:55], v[60:61]
	v_cvt_pk_bf16_f32 v52, v52, v53
	v_pk_mul_f32 v[54:55], v[54:55], v[62:63]
	s_waitcnt vmcnt(2)
	v_lshlrev_b32_e32 v56, 16, v74
	v_cvt_pk_bf16_f32 v53, v54, v55
	global_store_dwordx2 v[64:65], v[52:53], off offset:64
	v_and_b32_e32 v57, 0xffff0000, v74
	v_lshlrev_b32_e32 v62, 16, v75
	v_and_b32_e32 v63, 0xffff0000, v75
	v_or_b32_e32 v54, 0x50, v132
	v_ashrrev_i32_e32 v55, 31, v54
	s_nop 1
	v_lshl_add_u64 v[52:53], v[54:55], 2, s[14:15]
	v_pk_mul_f32 v[48:49], v[48:49], v[164:165] op_sel_hi:[1,0]
	v_pk_mul_f32 v[50:51], v[50:51], v[164:165] op_sel_hi:[1,0]
	v_mul_f32_e32 v58, 0xbfb8aa3b, v48
	v_mul_f32_e32 v59, 0xbfb8aa3b, v49
	v_mul_f32_e32 v60, 0xbfb8aa3b, v50
	v_mul_f32_e32 v61, 0xbfb8aa3b, v51
	v_exp_f32_e32 v58, v58
	v_exp_f32_e32 v59, v59
	v_exp_f32_e32 v60, v60
	v_exp_f32_e32 v61, v61
	v_add_f32_e32 v58, 1.0, v58
	v_add_f32_e32 v59, 1.0, v59
	v_add_f32_e32 v60, 1.0, v60
	v_add_f32_e32 v61, 1.0, v61
	v_rcp_f32_e32 v58, v58
	v_rcp_f32_e32 v59, v59
	v_rcp_f32_e32 v60, v60
	v_rcp_f32_e32 v61, v61
	v_pk_mul_f32 v[48:49], v[48:49], v[58:59]
	s_nop 0
	v_pk_mul_f32 v[48:49], v[48:49], v[56:57]
	global_load_dword v56, v[52:53], off
	v_pk_mul_f32 v[50:51], v[50:51], v[60:61]
	v_cvt_pk_bf16_f32 v48, v48, v49
	v_pk_mul_f32 v[50:51], v[50:51], v[62:63]
	s_nop 0
	v_cvt_pk_bf16_f32 v49, v50, v51
	global_store_dwordx2 v[64:65], v[48:49], off offset:96
	s_nop 0
	v_lshlrev_b64 v[48:49], 11, v[54:55]
	v_lshl_add_u64 v[48:49], s[38:39], 0, v[48:49]
	v_lshl_add_u64 v[48:49], v[48:49], 0, v[130:131]
	global_load_dwordx2 v[50:51], v[48:49], off
	global_load_dwordx2 v[184:185], v[48:49], off offset:32
	global_load_dwordx2 v[186:187], v[48:49], off offset:64
	global_load_dwordx2 v[58:59], v[48:49], off offset:96
	s_waitcnt vmcnt(5)
	v_fmamk_f32 v54, v56, 0x3a800000, v148
	v_mul_f32_e32 v55, 0x4b800000, v54
	v_cmp_gt_f32_e32 vcc, s54, v54
	s_waitcnt vmcnt(3)
	v_lshlrev_b32_e32 v60, 16, v50
	v_cndmask_b32_e32 v54, v54, v55, vcc
	v_rsq_f32_e32 v62, v54
	v_and_b32_e32 v61, 0xffff0000, v50
	s_nop 0
	s_nop 0
	s_nop 0
	v_mul_f32_e32 v50, 0x45800000, v62
	v_cndmask_b32_e32 v50, v62, v50, vcc
	v_mov_b32_e32 v166, v50
	v_pk_mul_f32 v[44:45], v[44:45], v[50:51] op_sel_hi:[1,0]
	v_pk_mul_f32 v[46:47], v[46:47], v[166:167] op_sel_hi:[1,0]
	v_mul_f32_e32 v50, 0xbfb8aa3b, v44
	v_mul_f32_e32 v62, 0xbfb8aa3b, v45
	v_mul_f32_e32 v63, 0xbfb8aa3b, v46
	v_mul_f32_e32 v64, 0xbfb8aa3b, v47
	v_exp_f32_e32 v50, v50
	v_exp_f32_e32 v62, v62
	v_exp_f32_e32 v63, v63
	v_exp_f32_e32 v64, v64
	v_add_f32_e32 v50, 1.0, v50
	v_add_f32_e32 v65, 1.0, v62
	v_add_f32_e32 v66, 1.0, v63
	v_add_f32_e32 v67, 1.0, v64
	v_rcp_f32_e32 v62, v50
	v_rcp_f32_e32 v63, v65
	v_rcp_f32_e32 v64, v66
	v_rcp_f32_e32 v65, v67
	v_lshlrev_b32_e32 v50, 16, v51
	v_and_b32_e32 v51, 0xffff0000, v51
	v_pk_mul_f32 v[44:45], v[44:45], v[62:63]
	v_pk_mul_f32 v[46:47], v[46:47], v[64:65]
	v_pk_mul_f32 v[44:45], v[44:45], v[60:61]
	v_pk_mul_f32 v[46:47], v[46:47], v[50:51]
	v_cvt_pk_bf16_f32 v44, v44, v45
	v_cvt_pk_bf16_f32 v45, v46, v47
	global_store_dwordx2 v[48:49], v[44:45], off
	s_nop 1
	s_waitcnt vmcnt(3)
	v_lshlrev_b32_e32 v44, 16, v184
	v_and_b32_e32 v45, 0xffff0000, v184
	v_lshlrev_b32_e32 v54, 16, v185
	v_pk_mul_f32 v[40:41], v[40:41], v[166:167] op_sel_hi:[1,0]
	v_pk_mul_f32 v[42:43], v[42:43], v[166:167] op_sel_hi:[1,0]
	v_mul_f32_e32 v46, 0xbfb8aa3b, v40
	v_mul_f32_e32 v47, 0xbfb8aa3b, v41
	v_mul_f32_e32 v50, 0xbfb8aa3b, v42
	v_mul_f32_e32 v51, 0xbfb8aa3b, v43
	v_exp_f32_e32 v46, v46
	v_exp_f32_e32 v47, v47
	v_exp_f32_e32 v50, v50
	v_exp_f32_e32 v51, v51
	v_add_f32_e32 v46, 1.0, v46
	v_add_f32_e32 v47, 1.0, v47
	v_add_f32_e32 v50, 1.0, v50
	v_add_f32_e32 v51, 1.0, v51
	v_rcp_f32_e32 v46, v46
	v_rcp_f32_e32 v47, v47
	v_rcp_f32_e32 v50, v50
	v_rcp_f32_e32 v51, v51
	v_and_b32_e32 v55, 0xffff0000, v185
	v_pk_mul_f32 v[40:41], v[40:41], v[46:47]
	s_waitcnt vmcnt(2)
	v_lshlrev_b32_e32 v46, 16, v187
	v_pk_mul_f32 v[42:43], v[42:43], v[50:51]
	v_pk_mul_f32 v[40:41], v[40:41], v[44:45]
	v_pk_mul_f32 v[42:43], v[42:43], v[54:55]
	v_cvt_pk_bf16_f32 v40, v40, v41
	v_cvt_pk_bf16_f32 v41, v42, v43
	global_store_dwordx2 v[48:49], v[40:41], off offset:32
	v_and_b32_e32 v47, 0xffff0000, v187
	s_nop 1
	v_lshlrev_b32_e32 v40, 16, v186
	v_and_b32_e32 v41, 0xffff0000, v186
	v_pk_mul_f32 v[36:37], v[36:37], v[166:167] op_sel_hi:[1,0]
	v_pk_mul_f32 v[38:39], v[38:39], v[166:167] op_sel_hi:[1,0]
	v_mul_f32_e32 v42, 0xbfb8aa3b, v36
	v_mul_f32_e32 v43, 0xbfb8aa3b, v37
	v_mul_f32_e32 v44, 0xbfb8aa3b, v38
	v_mul_f32_e32 v45, 0xbfb8aa3b, v39
	v_exp_f32_e32 v42, v42
	v_exp_f32_e32 v43, v43
	v_exp_f32_e32 v44, v44
	v_exp_f32_e32 v45, v45
	v_add_f32_e32 v42, 1.0, v42
	v_add_f32_e32 v43, 1.0, v43
	v_add_f32_e32 v44, 1.0, v44
	v_add_f32_e32 v45, 1.0, v45
	v_rcp_f32_e32 v42, v42
	v_rcp_f32_e32 v43, v43
	v_rcp_f32_e32 v44, v44
	v_rcp_f32_e32 v45, v45
	v_pk_mul_f32 v[36:37], v[36:37], v[42:43]
	s_nop 0
	v_pk_mul_f32 v[36:37], v[36:37], v[40:41]
	v_pk_mul_f32 v[38:39], v[38:39], v[44:45]
	v_cvt_pk_bf16_f32 v36, v36, v37
	v_pk_mul_f32 v[38:39], v[38:39], v[46:47]
	s_waitcnt vmcnt(2)
; DI float bflo(unsigned u) { return __uint_as_float(u << 16); }
; DI float bfhi(unsigned u) { return __uint_as_float(u & 0xffff0000u); }
; DI u32x2 pack4(float a, float b, float c, float d) { u32x2 r; r.x = pack2(a, b); r.y = pack2(c, d); return r; }
; #define EPI_END if (i == 3 && (j & 3) == 3) __builtin_amdgcn_sched_barrier(0); }
; DI float rstd_of(const float* ssq, int m, float invn) { return rsqrtf(ssq[m] * invn + 1e-6f); }
; DI float silu(float v) { return v * __builtin_amdgcn_rcpf(1.f + __expf(-v)); }
; template <int MODE>
; DI void gemm_phase(const Params& p, const GP& g, unsigned char* smem) {
;     ...
;     } else if (MODE == M_ZPASS) {
;       u16* og = (u16*)g.d0;
;       EPI_STD_BEGIN
;         const float rs = rstd_of(g.ssq_in, m, 1.f / 1024);
;         u32x2* op = (u32x2*)(og + (long)m * 1024 + n4);
;         const u32x2 ov = *op;
;         *op = pack4(bflo(ov.x) * silu(v[0] * rs), bfhi(ov.x) * silu(v[1] * rs), bflo(ov.y) * silu(v[2] * rs), bfhi(ov.y) * silu(v[3] * rs));
;       EPI_END
	v_lshlrev_b32_e32 v40, 16, v58
	v_cvt_pk_bf16_f32 v37, v38, v39
	global_store_dwordx2 v[48:49], v[36:37], off offset:64
	v_and_b32_e32 v41, 0xffff0000, v58
	v_lshlrev_b32_e32 v46, 16, v59
	v_and_b32_e32 v47, 0xffff0000, v59
	v_or_b32_e32 v38, 0x60, v132
	v_ashrrev_i32_e32 v39, 31, v38
	s_nop 1
	v_lshl_add_u64 v[36:37], v[38:39], 2, s[14:15]
	v_pk_mul_f32 v[32:33], v[32:33], v[166:167] op_sel_hi:[1,0]
	v_pk_mul_f32 v[34:35], v[34:35], v[166:167] op_sel_hi:[1,0]
	v_mul_f32_e32 v42, 0xbfb8aa3b, v32
	v_mul_f32_e32 v43, 0xbfb8aa3b, v33
	v_mul_f32_e32 v44, 0xbfb8aa3b, v34
	v_mul_f32_e32 v45, 0xbfb8aa3b, v35
	v_exp_f32_e32 v42, v42
	v_exp_f32_e32 v43, v43
	v_exp_f32_e32 v44, v44
	v_exp_f32_e32 v45, v45
	v_add_f32_e32 v42, 1.0, v42
	v_add_f32_e32 v43, 1.0, v43
	v_add_f32_e32 v44, 1.0, v44
	v_add_f32_e32 v45, 1.0, v45
	v_rcp_f32_e32 v42, v42
	v_rcp_f32_e32 v43, v43
	v_rcp_f32_e32 v44, v44
	v_rcp_f32_e32 v45, v45
	v_pk_mul_f32 v[32:33], v[32:33], v[42:43]
	s_nop 0
	v_pk_mul_f32 v[32:33], v[32:33], v[40:41]
	global_load_dword v40, v[36:37], off
	v_pk_mul_f32 v[34:35], v[34:35], v[44:45]
	v_cvt_pk_bf16_f32 v32, v32, v33
	v_pk_mul_f32 v[34:35], v[34:35], v[46:47]
	s_nop 0
	v_cvt_pk_bf16_f32 v33, v34, v35
	global_store_dwordx2 v[48:49], v[32:33], off offset:96
	s_nop 0
	v_lshlrev_b64 v[32:33], 11, v[38:39]
	v_lshl_add_u64 v[32:33], s[38:39], 0, v[32:33]
	v_lshl_add_u64 v[32:33], v[32:33], 0, v[130:131]
	global_load_dwordx2 v[34:35], v[32:33], off
	global_load_dwordx2 v[184:185], v[32:33], off offset:32
	global_load_dwordx2 v[186:187], v[32:33], off offset:64
	global_load_dwordx2 v[42:43], v[32:33], off offset:96
	s_waitcnt vmcnt(5)
	v_fmamk_f32 v38, v40, 0x3a800000, v148
	v_mul_f32_e32 v39, 0x4b800000, v38
	v_cmp_gt_f32_e32 vcc, s54, v38
	s_waitcnt vmcnt(3)
	v_lshlrev_b32_e32 v44, 16, v34
	v_cndmask_b32_e32 v38, v38, v39, vcc
	v_rsq_f32_e32 v46, v38
	v_and_b32_e32 v45, 0xffff0000, v34
	s_nop 0
	s_nop 0
	s_nop 0
	v_mul_f32_e32 v34, 0x45800000, v46
	v_cndmask_b32_e32 v34, v46, v34, vcc
	v_mov_b32_e32 v168, v34
	v_pk_mul_f32 v[28:29], v[28:29], v[34:35] op_sel_hi:[1,0]
	v_pk_mul_f32 v[30:31], v[30:31], v[168:169] op_sel_hi:[1,0]
	v_mul_f32_e32 v34, 0xbfb8aa3b, v28
	v_mul_f32_e32 v46, 0xbfb8aa3b, v29
	v_mul_f32_e32 v47, 0xbfb8aa3b, v30
	v_mul_f32_e32 v48, 0xbfb8aa3b, v31
	v_exp_f32_e32 v34, v34
	v_exp_f32_e32 v46, v46
	v_exp_f32_e32 v47, v47
	v_exp_f32_e32 v48, v48
	v_add_f32_e32 v34, 1.0, v34
	v_add_f32_e32 v49, 1.0, v46
	v_add_f32_e32 v50, 1.0, v47
	v_add_f32_e32 v51, 1.0, v48
	v_rcp_f32_e32 v46, v34
	v_rcp_f32_e32 v47, v49
	v_rcp_f32_e32 v48, v50
	v_rcp_f32_e32 v49, v51
	v_lshlrev_b32_e32 v34, 16, v35
	v_and_b32_e32 v35, 0xffff0000, v35
	v_pk_mul_f32 v[28:29], v[28:29], v[46:47]
	v_pk_mul_f32 v[30:31], v[30:31], v[48:49]
	v_pk_mul_f32 v[28:29], v[28:29], v[44:45]
	v_pk_mul_f32 v[30:31], v[30:31], v[34:35]
	v_cvt_pk_bf16_f32 v28, v28, v29
	v_cvt_pk_bf16_f32 v29, v30, v31
	global_store_dwordx2 v[32:33], v[28:29], off
	s_nop 1
	s_waitcnt vmcnt(3)
	v_lshlrev_b32_e32 v28, 16, v184
	v_and_b32_e32 v29, 0xffff0000, v184
	v_lshlrev_b32_e32 v38, 16, v185
	v_pk_mul_f32 v[24:25], v[24:25], v[168:169] op_sel_hi:[1,0]
	v_pk_mul_f32 v[26:27], v[26:27], v[168:169] op_sel_hi:[1,0]
	v_mul_f32_e32 v30, 0xbfb8aa3b, v24
	v_mul_f32_e32 v31, 0xbfb8aa3b, v25
	v_mul_f32_e32 v34, 0xbfb8aa3b, v26
	v_mul_f32_e32 v35, 0xbfb8aa3b, v27
	v_exp_f32_e32 v30, v30
	v_exp_f32_e32 v31, v31
	v_exp_f32_e32 v34, v34
	v_exp_f32_e32 v35, v35
	v_add_f32_e32 v30, 1.0, v30
	v_add_f32_e32 v31, 1.0, v31
	v_add_f32_e32 v34, 1.0, v34
	v_add_f32_e32 v35, 1.0, v35
	v_rcp_f32_e32 v30, v30
	v_rcp_f32_e32 v31, v31
	v_rcp_f32_e32 v34, v34
	v_rcp_f32_e32 v35, v35
	v_and_b32_e32 v39, 0xffff0000, v185
	v_pk_mul_f32 v[24:25], v[24:25], v[30:31]
	s_waitcnt vmcnt(2)
	v_lshlrev_b32_e32 v30, 16, v187
	v_pk_mul_f32 v[26:27], v[26:27], v[34:35]
	v_pk_mul_f32 v[24:25], v[24:25], v[28:29]
	v_pk_mul_f32 v[26:27], v[26:27], v[38:39]
	v_cvt_pk_bf16_f32 v24, v24, v25
	v_cvt_pk_bf16_f32 v25, v26, v27
	global_store_dwordx2 v[32:33], v[24:25], off offset:32
	v_and_b32_e32 v31, 0xffff0000, v187
	s_nop 1
	v_lshlrev_b32_e32 v24, 16, v186
	v_and_b32_e32 v25, 0xffff0000, v186
	v_pk_mul_f32 v[20:21], v[20:21], v[168:169] op_sel_hi:[1,0]
	v_pk_mul_f32 v[22:23], v[22:23], v[168:169] op_sel_hi:[1,0]
	v_mul_f32_e32 v26, 0xbfb8aa3b, v20
	v_mul_f32_e32 v27, 0xbfb8aa3b, v21
	v_mul_f32_e32 v28, 0xbfb8aa3b, v22
	v_mul_f32_e32 v29, 0xbfb8aa3b, v23
	v_exp_f32_e32 v26, v26
	v_exp_f32_e32 v27, v27
	v_exp_f32_e32 v28, v28
	v_exp_f32_e32 v29, v29
	v_add_f32_e32 v26, 1.0, v26
	v_add_f32_e32 v27, 1.0, v27
	v_add_f32_e32 v28, 1.0, v28
	v_add_f32_e32 v29, 1.0, v29
	v_rcp_f32_e32 v26, v26
	v_rcp_f32_e32 v27, v27
	v_rcp_f32_e32 v28, v28
	v_rcp_f32_e32 v29, v29
	v_pk_mul_f32 v[20:21], v[20:21], v[26:27]
	s_nop 0
	v_pk_mul_f32 v[20:21], v[20:21], v[24:25]
	v_pk_mul_f32 v[22:23], v[22:23], v[28:29]
	v_cvt_pk_bf16_f32 v20, v20, v21
	v_pk_mul_f32 v[22:23], v[22:23], v[30:31]
	s_waitcnt vmcnt(2)
; DI float bflo(unsigned u) { return __uint_as_float(u << 16); }
; DI float bfhi(unsigned u) { return __uint_as_float(u & 0xffff0000u); }
; DI u32x2 pack4(float a, float b, float c, float d) { u32x2 r; r.x = pack2(a, b); r.y = pack2(c, d); return r; }
; #define EPI_END if (i == 3 && (j & 3) == 3) __builtin_amdgcn_sched_barrier(0); }
; DI float rstd_of(const float* ssq, int m, float invn) { return rsqrtf(ssq[m] * invn + 1e-6f); }
; DI float silu(float v) { return v * __builtin_amdgcn_rcpf(1.f + __expf(-v)); }
; template <int MODE>
; DI void gemm_phase(const Params& p, const GP& g, unsigned char* smem) {
;     ...
;     } else if (MODE == M_ZPASS) {
;       u16* og = (u16*)g.d0;
;       EPI_STD_BEGIN
;         const float rs = rstd_of(g.ssq_in, m, 1.f / 1024);
;         u32x2* op = (u32x2*)(og + (long)m * 1024 + n4);
;         const u32x2 ov = *op;
;         *op = pack4(bflo(ov.x) * silu(v[0] * rs), bfhi(ov.x) * silu(v[1] * rs), bflo(ov.y) * silu(v[2] * rs), bfhi(ov.y) * silu(v[3] * rs));
;       EPI_END
	v_lshlrev_b32_e32 v24, 16, v42
	v_cvt_pk_bf16_f32 v21, v22, v23
	global_store_dwordx2 v[32:33], v[20:21], off offset:64
	v_and_b32_e32 v25, 0xffff0000, v42
	v_lshlrev_b32_e32 v30, 16, v43
	v_and_b32_e32 v31, 0xffff0000, v43
	v_or_b32_e32 v22, 0x70, v132
	v_ashrrev_i32_e32 v23, 31, v22
	s_nop 1
	v_lshl_add_u64 v[20:21], v[22:23], 2, s[14:15]
	v_pk_mul_f32 v[16:17], v[16:17], v[168:169] op_sel_hi:[1,0]
	v_pk_mul_f32 v[18:19], v[18:19], v[168:169] op_sel_hi:[1,0]
	v_mul_f32_e32 v26, 0xbfb8aa3b, v16
	v_mul_f32_e32 v27, 0xbfb8aa3b, v17
	v_mul_f32_e32 v28, 0xbfb8aa3b, v18
	v_mul_f32_e32 v29, 0xbfb8aa3b, v19
	v_exp_f32_e32 v26, v26
	v_exp_f32_e32 v27, v27
	v_exp_f32_e32 v28, v28
	v_exp_f32_e32 v29, v29
	v_add_f32_e32 v26, 1.0, v26
	v_add_f32_e32 v27, 1.0, v27
	v_add_f32_e32 v28, 1.0, v28
	v_add_f32_e32 v29, 1.0, v29
	v_rcp_f32_e32 v26, v26
	v_rcp_f32_e32 v27, v27
	v_rcp_f32_e32 v28, v28
	v_rcp_f32_e32 v29, v29
	v_pk_mul_f32 v[16:17], v[16:17], v[26:27]
	s_nop 0
	v_pk_mul_f32 v[16:17], v[16:17], v[24:25]
	global_load_dword v24, v[20:21], off
	v_pk_mul_f32 v[18:19], v[18:19], v[28:29]
	v_cvt_pk_bf16_f32 v16, v16, v17
	v_pk_mul_f32 v[18:19], v[18:19], v[30:31]
	s_nop 0
	v_cvt_pk_bf16_f32 v17, v18, v19
	global_store_dwordx2 v[32:33], v[16:17], off offset:96
	s_nop 0
	v_lshlrev_b64 v[16:17], 11, v[22:23]
	v_lshl_add_u64 v[16:17], s[38:39], 0, v[16:17]
	v_lshl_add_u64 v[16:17], v[16:17], 0, v[130:131]
	global_load_dwordx2 v[18:19], v[16:17], off
	global_load_dwordx2 v[184:185], v[16:17], off offset:32
	global_load_dwordx2 v[186:187], v[16:17], off offset:64
	global_load_dwordx2 v[26:27], v[16:17], off offset:96
	global_load_dword v188, v[20:21], off
	s_waitcnt vmcnt(6)
	v_fmamk_f32 v22, v24, 0x3a800000, v148
	v_mul_f32_e32 v23, 0x4b800000, v22
	v_cmp_gt_f32_e32 vcc, s54, v22
	s_waitcnt vmcnt(4)
	v_lshlrev_b32_e32 v28, 16, v18
	v_cndmask_b32_e32 v22, v22, v23, vcc
	v_rsq_f32_e32 v30, v22
	v_and_b32_e32 v29, 0xffff0000, v18
	s_nop 0
	s_nop 0
	s_nop 0
	v_mul_f32_e32 v18, 0x45800000, v30
	v_cndmask_b32_e32 v18, v30, v18, vcc
	v_mov_b32_e32 v170, v18
	v_pk_mul_f32 v[12:13], v[12:13], v[18:19] op_sel_hi:[1,0]
	v_pk_mul_f32 v[14:15], v[14:15], v[170:171] op_sel_hi:[1,0]
	v_mul_f32_e32 v18, 0xbfb8aa3b, v12
	v_mul_f32_e32 v30, 0xbfb8aa3b, v13
	v_mul_f32_e32 v31, 0xbfb8aa3b, v14
	v_mul_f32_e32 v32, 0xbfb8aa3b, v15
	v_exp_f32_e32 v18, v18
	v_exp_f32_e32 v30, v30
	v_exp_f32_e32 v31, v31
	v_exp_f32_e32 v32, v32
	v_add_f32_e32 v18, 1.0, v18
	v_add_f32_e32 v33, 1.0, v30
	v_add_f32_e32 v34, 1.0, v31
	v_add_f32_e32 v35, 1.0, v32
	v_rcp_f32_e32 v30, v18
	v_rcp_f32_e32 v31, v33
	v_rcp_f32_e32 v32, v34
	v_rcp_f32_e32 v33, v35
	v_lshlrev_b32_e32 v18, 16, v19
	v_and_b32_e32 v19, 0xffff0000, v19
	v_pk_mul_f32 v[12:13], v[12:13], v[30:31]
	v_pk_mul_f32 v[14:15], v[14:15], v[32:33]
	v_pk_mul_f32 v[12:13], v[12:13], v[28:29]
	v_pk_mul_f32 v[14:15], v[14:15], v[18:19]
	v_cvt_pk_bf16_f32 v12, v12, v13
	v_cvt_pk_bf16_f32 v13, v14, v15
	global_store_dwordx2 v[16:17], v[12:13], off
	s_nop 1
	s_waitcnt vmcnt(4)
	v_lshlrev_b32_e32 v12, 16, v184
	v_and_b32_e32 v13, 0xffff0000, v184
	v_lshlrev_b32_e32 v22, 16, v185
	v_pk_mul_f32 v[8:9], v[8:9], v[170:171] op_sel_hi:[1,0]
	v_pk_mul_f32 v[10:11], v[10:11], v[170:171] op_sel_hi:[1,0]
	v_mul_f32_e32 v14, 0xbfb8aa3b, v8
	v_mul_f32_e32 v15, 0xbfb8aa3b, v9
	v_mul_f32_e32 v18, 0xbfb8aa3b, v10
	v_mul_f32_e32 v19, 0xbfb8aa3b, v11
	v_exp_f32_e32 v14, v14
	v_exp_f32_e32 v15, v15
	v_exp_f32_e32 v18, v18
	v_exp_f32_e32 v19, v19
	v_add_f32_e32 v14, 1.0, v14
	v_add_f32_e32 v15, 1.0, v15
	v_add_f32_e32 v18, 1.0, v18
	v_add_f32_e32 v19, 1.0, v19
	v_rcp_f32_e32 v14, v14
	v_rcp_f32_e32 v15, v15
	v_rcp_f32_e32 v18, v18
	v_rcp_f32_e32 v19, v19
	v_and_b32_e32 v23, 0xffff0000, v185
	v_pk_mul_f32 v[8:9], v[8:9], v[14:15]
	s_waitcnt vmcnt(3)
	v_lshlrev_b32_e32 v14, 16, v187
	v_pk_mul_f32 v[10:11], v[10:11], v[18:19]
	v_pk_mul_f32 v[8:9], v[8:9], v[12:13]
	v_pk_mul_f32 v[10:11], v[10:11], v[22:23]
	v_cvt_pk_bf16_f32 v8, v8, v9
	v_cvt_pk_bf16_f32 v9, v10, v11
	global_store_dwordx2 v[16:17], v[8:9], off offset:32
	v_and_b32_e32 v15, 0xffff0000, v187
	s_nop 1
	v_lshlrev_b32_e32 v8, 16, v186
	v_and_b32_e32 v9, 0xffff0000, v186
	v_pk_mul_f32 v[0:1], v[0:1], v[170:171] op_sel_hi:[1,0]
	v_pk_mul_f32 v[2:3], v[2:3], v[170:171] op_sel_hi:[1,0]
	v_mul_f32_e32 v10, 0xbfb8aa3b, v0
	v_mul_f32_e32 v11, 0xbfb8aa3b, v1
	v_mul_f32_e32 v12, 0xbfb8aa3b, v2
	v_mul_f32_e32 v13, 0xbfb8aa3b, v3
	v_exp_f32_e32 v10, v10
	v_exp_f32_e32 v11, v11
	v_exp_f32_e32 v12, v12
	v_exp_f32_e32 v13, v13
	v_add_f32_e32 v10, 1.0, v10
	v_add_f32_e32 v11, 1.0, v11
	v_add_f32_e32 v12, 1.0, v12
	v_add_f32_e32 v13, 1.0, v13
	v_rcp_f32_e32 v10, v10
	v_rcp_f32_e32 v11, v11
	v_rcp_f32_e32 v12, v12
	v_rcp_f32_e32 v13, v13
	v_pk_mul_f32 v[0:1], v[0:1], v[10:11]
	s_nop 0
	v_pk_mul_f32 v[0:1], v[0:1], v[8:9]
	v_pk_mul_f32 v[2:3], v[2:3], v[12:13]
	v_cvt_pk_bf16_f32 v0, v0, v1
	v_pk_mul_f32 v[2:3], v[2:3], v[14:15]
	s_waitcnt vmcnt(3)
	v_lshlrev_b32_e32 v10, 16, v27
	v_cvt_pk_bf16_f32 v1, v2, v3
	global_store_dwordx2 v[16:17], v[0:1], off offset:64
	s_nop 0
	v_and_b32_e32 v11, 0xffff0000, v27
	s_waitcnt vmcnt(3)
	v_fmamk_f32 v0, v188, 0x3a800000, v148
	v_cmp_gt_f32_e32 vcc, s54, v0
	s_nop 1
	v_lshlrev_b32_e32 v0, 16, v26
	v_and_b32_e32 v1, 0xffff0000, v26
	v_pk_mul_f32 v[4:5], v[4:5], v[170:171] op_sel_hi:[1,0]
	v_pk_mul_f32 v[2:3], v[6:7], v[170:171] op_sel_hi:[1,0]
	v_mul_f32_e32 v6, 0xbfb8aa3b, v4
	v_mul_f32_e32 v7, 0xbfb8aa3b, v5
	v_mul_f32_e32 v8, 0xbfb8aa3b, v2
	v_mul_f32_e32 v9, 0xbfb8aa3b, v3
	v_exp_f32_e32 v6, v6
	v_exp_f32_e32 v7, v7
	v_exp_f32_e32 v8, v8
	v_exp_f32_e32 v9, v9
	v_add_f32_e32 v6, 1.0, v6
	v_add_f32_e32 v7, 1.0, v7
	v_add_f32_e32 v8, 1.0, v8
	v_add_f32_e32 v9, 1.0, v9
	v_rcp_f32_e32 v6, v6
	v_rcp_f32_e32 v7, v7
	v_rcp_f32_e32 v8, v8
	v_rcp_f32_e32 v9, v9
	v_pk_mul_f32 v[4:5], v[4:5], v[6:7]
	s_nop 0
	v_pk_mul_f32 v[0:1], v[4:5], v[0:1]
	v_pk_mul_f32 v[2:3], v[2:3], v[8:9]
	v_cvt_pk_bf16_f32 v0, v0, v1
	v_pk_mul_f32 v[2:3], v[2:3], v[10:11]
	s_nop 0
	v_cvt_pk_bf16_f32 v1, v2, v3
	global_store_dwordx2 v[16:17], v[0:1], off offset:96
	s_add_i32 s55, s55, s94
	s_cmpk_lt_u32 s55, 0xa0
	s_cbranch_scc0 .LBB0_490

; DI u32x2 pack4(float a, float b, float c, float d) { u32x2 r; r.x = pack2(a, b); r.y = pack2(c, d); return r; }
; #define EPI_END if (i == 3 && (j & 3) == 3) __builtin_amdgcn_sched_barrier(0); }
; DI float rstd_of(const float* ssq, int m, float invn) { return rsqrtf(ssq[m] * invn + 1e-6f); }
; DI float silu(float v) { return v * __builtin_amdgcn_rcpf(1.f + __expf(-v)); }
; template <int MODE>
; DI void gemm_phase(const Params& p, const GP& g, unsigned char* smem) {
;     ...
;       } else if (nt < 4) {
;         u16* qo = (u16*)g.d0;
;         EPI_STD_BEGIN
;           const float rs = rstd_of(g.ssq_in, m, 1.f / 1024);
;           *(u32x2*)(qo + (long)m * 1024 + n4) = pack4(silu(v[0] * rs), silu(v[1] * rs), silu(v[2] * rs), silu(v[3] * rs));
;         EPI_END
.LBB0_575:
	s_andn2_b64 vcc, exec, s[10:11]
	s_cbranch_vccnz .LBB0_577
	v_lshl_add_u64 v[136:137], v[130:131], 2, s[26:27]
	global_load_dword v128, v[136:137], off
	v_lshlrev_b64 v[138:139], 11, v[130:131]
	v_add_u32_e32 v134, s65, v148
	v_ashrrev_i32_e32 v135, 31, v134
	v_lshl_add_u64 v[138:139], s[20:21], 0, v[138:139]
	v_lshlrev_b64 v[134:135], 1, v[134:135]
	v_lshl_add_u64 v[138:139], v[138:139], 0, v[134:135]
	s_waitcnt vmcnt(0)
	v_fmamk_f32 v128, v128, 0x3a800000, v151
	v_mul_f32_e32 v133, 0x4b800000, v128
	v_cmp_gt_f32_e32 vcc, s68, v128
	s_nop 1
	v_cndmask_b32_e32 v128, v128, v133, vcc
	v_rsq_f32_e32 v128, v128
	s_nop 0
	v_mul_f32_e32 v131, 0x45800000, v128
	v_cndmask_b32_e32 v128, v128, v131, vcc
	v_mov_b32_e32 v156, v128
	v_pk_mul_f32 v[140:141], v[124:125], v[128:129] op_sel_hi:[1,0]
	v_pk_mul_f32 v[142:143], v[126:127], v[156:157] op_sel_hi:[1,0]
	v_mul_f32_e32 v128, 0xbfb8aa3b, v140
	v_mul_f32_e32 v131, 0xbfb8aa3b, v141
	v_mul_f32_e32 v133, 0xbfb8aa3b, v142
	v_mul_f32_e32 v144, 0xbfb8aa3b, v143
	v_exp_f32_e32 v128, v128
	v_exp_f32_e32 v131, v131
	v_exp_f32_e32 v133, v133
	v_exp_f32_e32 v144, v144
	v_add_f32_e32 v128, 1.0, v128
	v_add_f32_e32 v131, 1.0, v131
	v_add_f32_e32 v133, 1.0, v133
	v_add_f32_e32 v155, 1.0, v144
	v_rcp_f32_e32 v144, v128
	v_rcp_f32_e32 v145, v131
	v_rcp_f32_e32 v154, v133
	v_rcp_f32_e32 v155, v155
	v_pk_mul_f32 v[140:141], v[140:141], v[144:145]
	s_nop 0
	v_cvt_pk_bf16_f32 v140, v140, v141
	v_pk_mul_f32 v[142:143], v[142:143], v[154:155]
	s_nop 0
	v_cvt_pk_bf16_f32 v141, v142, v143
	global_store_dwordx2 v[138:139], v[140:141], off
	s_nop 1
	s_nop 0
	v_pk_mul_f32 v[140:141], v[120:121], v[156:157] op_sel_hi:[1,0]
	v_pk_mul_f32 v[142:143], v[122:123], v[156:157] op_sel_hi:[1,0]
	v_mul_f32_e32 v128, 0xbfb8aa3b, v140
	v_mul_f32_e32 v131, 0xbfb8aa3b, v141
	v_mul_f32_e32 v133, 0xbfb8aa3b, v142
	v_mul_f32_e32 v144, 0xbfb8aa3b, v143
	v_exp_f32_e32 v128, v128
	v_exp_f32_e32 v131, v131
	v_exp_f32_e32 v133, v133
	v_exp_f32_e32 v144, v144
	v_add_f32_e32 v128, 1.0, v128
	v_add_f32_e32 v131, 1.0, v131
	v_add_f32_e32 v133, 1.0, v133
	v_add_f32_e32 v155, 1.0, v144
	v_rcp_f32_e32 v144, v128
	v_rcp_f32_e32 v145, v131
	v_rcp_f32_e32 v154, v133
	v_rcp_f32_e32 v155, v155
	v_pk_mul_f32 v[140:141], v[140:141], v[144:145]
	s_nop 0
	v_cvt_pk_bf16_f32 v140, v140, v141
	v_pk_mul_f32 v[142:143], v[142:143], v[154:155]
	s_nop 0
	v_cvt_pk_bf16_f32 v141, v142, v143
	global_store_dwordx2 v[138:139], v[140:141], off offset:32
	s_nop 1
	s_nop 0
	v_pk_mul_f32 v[140:141], v[116:117], v[156:157] op_sel_hi:[1,0]
	v_pk_mul_f32 v[142:143], v[118:119], v[156:157] op_sel_hi:[1,0]
	v_mul_f32_e32 v128, 0xbfb8aa3b, v140
	v_mul_f32_e32 v131, 0xbfb8aa3b, v141
	v_mul_f32_e32 v133, 0xbfb8aa3b, v142
	v_mul_f32_e32 v144, 0xbfb8aa3b, v143
	v_exp_f32_e32 v128, v128
	v_exp_f32_e32 v131, v131
	v_exp_f32_e32 v133, v133
	v_exp_f32_e32 v144, v144
	v_add_f32_e32 v128, 1.0, v128
	v_add_f32_e32 v131, 1.0, v131
	v_add_f32_e32 v133, 1.0, v133
	v_add_f32_e32 v155, 1.0, v144
	v_rcp_f32_e32 v144, v128
	v_rcp_f32_e32 v145, v131
	v_rcp_f32_e32 v154, v133
	v_rcp_f32_e32 v155, v155
	v_pk_mul_f32 v[140:141], v[140:141], v[144:145]
	s_nop 0
	v_cvt_pk_bf16_f32 v140, v140, v141
	v_pk_mul_f32 v[142:143], v[142:143], v[154:155]
	s_nop 0
	v_cvt_pk_bf16_f32 v141, v142, v143
	global_store_dwordx2 v[138:139], v[140:141], off offset:64
	s_nop 1
	s_nop 0
	v_pk_mul_f32 v[136:137], v[108:109], v[156:157] op_sel_hi:[1,0]
	v_pk_mul_f32 v[140:141], v[110:111], v[156:157] op_sel_hi:[1,0]
	v_mul_f32_e32 v128, 0xbfb8aa3b, v136
	v_mul_f32_e32 v131, 0xbfb8aa3b, v137
	v_mul_f32_e32 v133, 0xbfb8aa3b, v140
	v_mul_f32_e32 v142, 0xbfb8aa3b, v141
	v_exp_f32_e32 v128, v128
	v_exp_f32_e32 v131, v131
	v_exp_f32_e32 v133, v133
	v_exp_f32_e32 v142, v142
	v_add_f32_e32 v128, 1.0, v128
	v_add_f32_e32 v131, 1.0, v131
	v_add_f32_e32 v133, 1.0, v133
	v_add_f32_e32 v145, 1.0, v142
	v_rcp_f32_e32 v142, v128
	v_rcp_f32_e32 v143, v131
	v_rcp_f32_e32 v144, v133
	v_rcp_f32_e32 v145, v145
	v_ashrrev_i32_e32 v133, 31, v132
	v_pk_mul_f32 v[136:137], v[136:137], v[142:143]
	v_lshl_add_u64 v[154:155], v[132:133], 2, s[26:27]
	global_load_dword v128, v[154:155], off
	v_pk_mul_f32 v[140:141], v[140:141], v[144:145]
	v_cvt_pk_bf16_f32 v136, v136, v137
	v_cvt_pk_bf16_f32 v137, v140, v141
	global_store_dwordx2 v[138:139], v[136:137], off offset:96
	s_nop 0
	v_lshlrev_b64 v[132:133], 11, v[132:133]
	v_lshl_add_u64 v[132:133], s[20:21], 0, v[132:133]
	v_lshl_add_u64 v[132:133], v[132:133], 0, v[134:135]
	s_waitcnt vmcnt(1)
; DI float silu(float v) { return v * __builtin_amdgcn_rcpf(1.f + __expf(-v)); }
; DI u32x2 pack4(float a, float b, float c, float d) { u32x2 r; r.x = pack2(a, b); r.y = pack2(c, d); return r; }
; #define EPI_END if (i == 3 && (j & 3) == 3) __builtin_amdgcn_sched_barrier(0); }
; DI float rstd_of(const float* ssq, int m, float invn) { return rsqrtf(ssq[m] * invn + 1e-6f); }
; template <int MODE>
; DI void gemm_phase(const Params& p, const GP& g, unsigned char* smem) {
;     ...
;       } else if (nt < 4) {
;         u16* qo = (u16*)g.d0;
;         EPI_STD_BEGIN
;           const float rs = rstd_of(g.ssq_in, m, 1.f / 1024);
;           *(u32x2*)(qo + (long)m * 1024 + n4) = pack4(silu(v[0] * rs), silu(v[1] * rs), silu(v[2] * rs), silu(v[3] * rs));
;         EPI_END
	v_fmamk_f32 v128, v128, 0x3a800000, v151
	v_mul_f32_e32 v131, 0x4b800000, v128
	v_cmp_gt_f32_e32 vcc, s68, v128
	s_nop 1
	v_cndmask_b32_e32 v128, v128, v131, vcc
	v_rsq_f32_e32 v128, v128
	s_nop 0
	v_mul_f32_e32 v131, 0x45800000, v128
	v_cndmask_b32_e32 v128, v128, v131, vcc
	v_mov_b32_e32 v158, v128
	v_pk_mul_f32 v[136:137], v[112:113], v[128:129] op_sel_hi:[1,0]
	v_pk_mul_f32 v[138:139], v[114:115], v[158:159] op_sel_hi:[1,0]
	v_mul_f32_e32 v128, 0xbfb8aa3b, v136
	v_mul_f32_e32 v131, 0xbfb8aa3b, v137
	v_mul_f32_e32 v140, 0xbfb8aa3b, v138
	v_mul_f32_e32 v141, 0xbfb8aa3b, v139
	v_exp_f32_e32 v128, v128
	v_exp_f32_e32 v131, v131
	v_exp_f32_e32 v140, v140
	v_exp_f32_e32 v141, v141
	v_add_f32_e32 v128, 1.0, v128
	v_add_f32_e32 v131, 1.0, v131
	v_add_f32_e32 v142, 1.0, v140
	v_add_f32_e32 v143, 1.0, v141
	v_rcp_f32_e32 v140, v128
	v_rcp_f32_e32 v141, v131
	v_rcp_f32_e32 v142, v142
	v_rcp_f32_e32 v143, v143
	v_pk_mul_f32 v[136:137], v[136:137], v[140:141]
	s_nop 0
	v_cvt_pk_bf16_f32 v136, v136, v137
	v_pk_mul_f32 v[138:139], v[138:139], v[142:143]
	s_nop 0
	v_cvt_pk_bf16_f32 v137, v138, v139
	global_store_dwordx2 v[132:133], v[136:137], off
	s_nop 1
	s_nop 0
	v_pk_mul_f32 v[136:137], v[104:105], v[158:159] op_sel_hi:[1,0]
	v_pk_mul_f32 v[138:139], v[106:107], v[158:159] op_sel_hi:[1,0]
	v_mul_f32_e32 v128, 0xbfb8aa3b, v136
	v_mul_f32_e32 v131, 0xbfb8aa3b, v137
	v_mul_f32_e32 v140, 0xbfb8aa3b, v138
	v_mul_f32_e32 v141, 0xbfb8aa3b, v139
	v_exp_f32_e32 v128, v128
	v_exp_f32_e32 v131, v131
	v_exp_f32_e32 v140, v140
	v_exp_f32_e32 v141, v141
	v_add_f32_e32 v128, 1.0, v128
	v_add_f32_e32 v131, 1.0, v131
	v_add_f32_e32 v142, 1.0, v140
	v_add_f32_e32 v143, 1.0, v141
	v_rcp_f32_e32 v140, v128
	v_rcp_f32_e32 v141, v131
	v_rcp_f32_e32 v142, v142
	v_rcp_f32_e32 v143, v143
	v_pk_mul_f32 v[136:137], v[136:137], v[140:141]
	s_nop 0
	v_cvt_pk_bf16_f32 v136, v136, v137
	v_pk_mul_f32 v[138:139], v[138:139], v[142:143]
	s_nop 0
	v_cvt_pk_bf16_f32 v137, v138, v139
	global_store_dwordx2 v[132:133], v[136:137], off offset:32
	s_nop 1
	s_nop 0
	v_pk_mul_f32 v[136:137], v[100:101], v[158:159] op_sel_hi:[1,0]
	v_pk_mul_f32 v[138:139], v[102:103], v[158:159] op_sel_hi:[1,0]
	v_mul_f32_e32 v128, 0xbfb8aa3b, v136
	v_mul_f32_e32 v131, 0xbfb8aa3b, v137
	v_mul_f32_e32 v140, 0xbfb8aa3b, v138
	v_mul_f32_e32 v141, 0xbfb8aa3b, v139
	v_exp_f32_e32 v128, v128
	v_exp_f32_e32 v131, v131
	v_exp_f32_e32 v140, v140
	v_exp_f32_e32 v141, v141
	v_add_f32_e32 v128, 1.0, v128
	v_add_f32_e32 v131, 1.0, v131
	v_add_f32_e32 v142, 1.0, v140
	v_add_f32_e32 v143, 1.0, v141
	v_rcp_f32_e32 v140, v128
	v_rcp_f32_e32 v141, v131
	v_rcp_f32_e32 v142, v142
	v_rcp_f32_e32 v143, v143
	v_pk_mul_f32 v[136:137], v[136:137], v[140:141]
	s_nop 0
	v_cvt_pk_bf16_f32 v136, v136, v137
	v_pk_mul_f32 v[138:139], v[138:139], v[142:143]
	s_nop 0
	v_cvt_pk_bf16_f32 v137, v138, v139
	global_store_dwordx2 v[132:133], v[136:137], off offset:64
	v_or_b32_e32 v136, 32, v130
	s_nop 1
	s_nop 0
	v_pk_mul_f32 v[138:139], v[92:93], v[158:159] op_sel_hi:[1,0]
	v_pk_mul_f32 v[140:141], v[94:95], v[158:159] op_sel_hi:[1,0]
	v_mul_f32_e32 v128, 0xbfb8aa3b, v138
	v_mul_f32_e32 v131, 0xbfb8aa3b, v139
	v_mul_f32_e32 v137, 0xbfb8aa3b, v140
	v_mul_f32_e32 v142, 0xbfb8aa3b, v141
	v_exp_f32_e32 v128, v128
	v_exp_f32_e32 v131, v131
	v_exp_f32_e32 v137, v137
	v_exp_f32_e32 v142, v142
	v_add_f32_e32 v128, 1.0, v128
	v_add_f32_e32 v131, 1.0, v131
	v_add_f32_e32 v137, 1.0, v137
	v_add_f32_e32 v145, 1.0, v142
	v_rcp_f32_e32 v142, v128
	v_rcp_f32_e32 v143, v131
	v_rcp_f32_e32 v144, v137
	v_rcp_f32_e32 v145, v145
	v_ashrrev_i32_e32 v137, 31, v136
	v_pk_mul_f32 v[138:139], v[138:139], v[142:143]
	v_lshl_add_u64 v[154:155], v[136:137], 2, s[26:27]
	global_load_dword v128, v[154:155], off
	v_pk_mul_f32 v[140:141], v[140:141], v[144:145]
	v_cvt_pk_bf16_f32 v138, v138, v139
	v_cvt_pk_bf16_f32 v139, v140, v141
	global_store_dwordx2 v[132:133], v[138:139], off offset:96
	s_nop 0
	v_lshlrev_b64 v[132:133], 11, v[136:137]
	v_lshl_add_u64 v[132:133], s[20:21], 0, v[132:133]
	v_lshl_add_u64 v[132:133], v[132:133], 0, v[134:135]
	s_waitcnt vmcnt(1)
	v_fmamk_f32 v128, v128, 0x3a800000, v151
	v_mul_f32_e32 v131, 0x4b800000, v128
	v_cmp_gt_f32_e32 vcc, s68, v128
	s_nop 1
	v_cndmask_b32_e32 v128, v128, v131, vcc
	v_rsq_f32_e32 v128, v128
	s_nop 0
	v_mul_f32_e32 v131, 0x45800000, v128
	v_cndmask_b32_e32 v128, v128, v131, vcc
	v_mov_b32_e32 v160, v128
	v_pk_mul_f32 v[136:137], v[96:97], v[128:129] op_sel_hi:[1,0]
	v_pk_mul_f32 v[138:139], v[98:99], v[160:161] op_sel_hi:[1,0]
	v_mul_f32_e32 v128, 0xbfb8aa3b, v136
	v_mul_f32_e32 v131, 0xbfb8aa3b, v137
	v_mul_f32_e32 v140, 0xbfb8aa3b, v138
	v_mul_f32_e32 v141, 0xbfb8aa3b, v139
	v_exp_f32_e32 v128, v128
	v_exp_f32_e32 v131, v131
	v_exp_f32_e32 v140, v140
	v_exp_f32_e32 v141, v141
	v_add_f32_e32 v128, 1.0, v128
	v_add_f32_e32 v131, 1.0, v131
	v_add_f32_e32 v142, 1.0, v140
	v_add_f32_e32 v143, 1.0, v141
	v_rcp_f32_e32 v140, v128
	v_rcp_f32_e32 v141, v131
	v_rcp_f32_e32 v142, v142
	v_rcp_f32_e32 v143, v143
	v_pk_mul_f32 v[136:137], v[136:137], v[140:141]
	s_nop 0
	v_cvt_pk_bf16_f32 v136, v136, v137
	v_pk_mul_f32 v[138:139], v[138:139], v[142:143]
	s_nop 0
	v_cvt_pk_bf16_f32 v137, v138, v139
	global_store_dwordx2 v[132:133], v[136:137], off
	s_nop 1
	s_nop 0
	v_pk_mul_f32 v[136:137], v[88:89], v[160:161] op_sel_hi:[1,0]
	v_pk_mul_f32 v[138:139], v[90:91], v[160:161] op_sel_hi:[1,0]
	v_mul_f32_e32 v128, 0xbfb8aa3b, v136
	v_mul_f32_e32 v131, 0xbfb8aa3b, v137
	v_mul_f32_e32 v140, 0xbfb8aa3b, v138
	v_mul_f32_e32 v141, 0xbfb8aa3b, v139
	v_exp_f32_e32 v128, v128
	v_exp_f32_e32 v131, v131
	v_exp_f32_e32 v140, v140
; DI float silu(float v) { return v * __builtin_amdgcn_rcpf(1.f + __expf(-v)); }
; DI u32x2 pack4(float a, float b, float c, float d) { u32x2 r; r.x = pack2(a, b); r.y = pack2(c, d); return r; }
; #define EPI_END if (i == 3 && (j & 3) == 3) __builtin_amdgcn_sched_barrier(0); }
; DI float rstd_of(const float* ssq, int m, float invn) { return rsqrtf(ssq[m] * invn + 1e-6f); }
; template <int MODE>
; DI void gemm_phase(const Params& p, const GP& g, unsigned char* smem) {
;     ...
;       } else if (nt < 4) {
;         u16* qo = (u16*)g.d0;
;         EPI_STD_BEGIN
;           const float rs = rstd_of(g.ssq_in, m, 1.f / 1024);
;           *(u32x2*)(qo + (long)m * 1024 + n4) = pack4(silu(v[0] * rs), silu(v[1] * rs), silu(v[2] * rs), silu(v[3] * rs));
;         EPI_END
	v_exp_f32_e32 v141, v141
	v_add_f32_e32 v128, 1.0, v128
	v_add_f32_e32 v131, 1.0, v131
	v_add_f32_e32 v142, 1.0, v140
	v_add_f32_e32 v143, 1.0, v141
	v_rcp_f32_e32 v140, v128
	v_rcp_f32_e32 v141, v131
	v_rcp_f32_e32 v142, v142
	v_rcp_f32_e32 v143, v143
	v_pk_mul_f32 v[136:137], v[136:137], v[140:141]
	s_nop 0
	v_cvt_pk_bf16_f32 v136, v136, v137
	v_pk_mul_f32 v[138:139], v[138:139], v[142:143]
	s_nop 0
	v_cvt_pk_bf16_f32 v137, v138, v139
	global_store_dwordx2 v[132:133], v[136:137], off offset:32
	s_nop 1
	s_nop 0
	v_pk_mul_f32 v[136:137], v[84:85], v[160:161] op_sel_hi:[1,0]
	v_pk_mul_f32 v[138:139], v[86:87], v[160:161] op_sel_hi:[1,0]
	v_mul_f32_e32 v128, 0xbfb8aa3b, v136
	v_mul_f32_e32 v131, 0xbfb8aa3b, v137
	v_mul_f32_e32 v140, 0xbfb8aa3b, v138
	v_mul_f32_e32 v141, 0xbfb8aa3b, v139
	v_exp_f32_e32 v128, v128
	v_exp_f32_e32 v131, v131
	v_exp_f32_e32 v140, v140
	v_exp_f32_e32 v141, v141
	v_add_f32_e32 v128, 1.0, v128
	v_add_f32_e32 v131, 1.0, v131
	v_add_f32_e32 v142, 1.0, v140
	v_add_f32_e32 v143, 1.0, v141
	v_rcp_f32_e32 v140, v128
	v_rcp_f32_e32 v141, v131
	v_rcp_f32_e32 v142, v142
	v_rcp_f32_e32 v143, v143
	v_pk_mul_f32 v[136:137], v[136:137], v[140:141]
	s_nop 0
	v_cvt_pk_bf16_f32 v136, v136, v137
	v_pk_mul_f32 v[138:139], v[138:139], v[142:143]
	s_nop 0
	v_cvt_pk_bf16_f32 v137, v138, v139
	global_store_dwordx2 v[132:133], v[136:137], off offset:64
	v_or_b32_e32 v136, 48, v130
	s_nop 1
	s_nop 0
	v_pk_mul_f32 v[138:139], v[76:77], v[160:161] op_sel_hi:[1,0]
	v_pk_mul_f32 v[140:141], v[78:79], v[160:161] op_sel_hi:[1,0]
	v_mul_f32_e32 v128, 0xbfb8aa3b, v138
	v_mul_f32_e32 v131, 0xbfb8aa3b, v139
	v_mul_f32_e32 v137, 0xbfb8aa3b, v140
	v_mul_f32_e32 v142, 0xbfb8aa3b, v141
	v_exp_f32_e32 v128, v128
	v_exp_f32_e32 v131, v131
	v_exp_f32_e32 v137, v137
	v_exp_f32_e32 v142, v142
	v_add_f32_e32 v128, 1.0, v128
	v_add_f32_e32 v131, 1.0, v131
	v_add_f32_e32 v137, 1.0, v137
	v_add_f32_e32 v145, 1.0, v142
	v_rcp_f32_e32 v142, v128
	v_rcp_f32_e32 v143, v131
	v_rcp_f32_e32 v144, v137
	v_rcp_f32_e32 v145, v145
	v_ashrrev_i32_e32 v137, 31, v136
	v_pk_mul_f32 v[138:139], v[138:139], v[142:143]
	v_lshl_add_u64 v[154:155], v[136:137], 2, s[26:27]
	global_load_dword v128, v[154:155], off
	v_pk_mul_f32 v[140:141], v[140:141], v[144:145]
	v_cvt_pk_bf16_f32 v138, v138, v139
	v_cvt_pk_bf16_f32 v139, v140, v141
	global_store_dwordx2 v[132:133], v[138:139], off offset:96
	s_nop 0
	v_lshlrev_b64 v[132:133], 11, v[136:137]
	v_lshl_add_u64 v[132:133], s[20:21], 0, v[132:133]
	v_lshl_add_u64 v[132:133], v[132:133], 0, v[134:135]
	s_waitcnt vmcnt(1)
	v_fmamk_f32 v128, v128, 0x3a800000, v151
	v_mul_f32_e32 v131, 0x4b800000, v128
	v_cmp_gt_f32_e32 vcc, s68, v128
	s_nop 1
	v_cndmask_b32_e32 v128, v128, v131, vcc
	v_rsq_f32_e32 v128, v128
	s_nop 0
	v_mul_f32_e32 v131, 0x45800000, v128
	v_cndmask_b32_e32 v128, v128, v131, vcc
	v_mov_b32_e32 v162, v128
	v_pk_mul_f32 v[136:137], v[80:81], v[128:129] op_sel_hi:[1,0]
	v_pk_mul_f32 v[138:139], v[82:83], v[162:163] op_sel_hi:[1,0]
	v_mul_f32_e32 v128, 0xbfb8aa3b, v136
	v_mul_f32_e32 v131, 0xbfb8aa3b, v137
	v_mul_f32_e32 v140, 0xbfb8aa3b, v138
	v_mul_f32_e32 v141, 0xbfb8aa3b, v139
	v_exp_f32_e32 v128, v128
	v_exp_f32_e32 v131, v131
	v_exp_f32_e32 v140, v140
	v_exp_f32_e32 v141, v141
	v_add_f32_e32 v128, 1.0, v128
	v_add_f32_e32 v131, 1.0, v131
	v_add_f32_e32 v142, 1.0, v140
	v_add_f32_e32 v143, 1.0, v141
	v_rcp_f32_e32 v140, v128
	v_rcp_f32_e32 v141, v131
	v_rcp_f32_e32 v142, v142
	v_rcp_f32_e32 v143, v143
	v_pk_mul_f32 v[136:137], v[136:137], v[140:141]
	s_nop 0
	v_cvt_pk_bf16_f32 v136, v136, v137
	v_pk_mul_f32 v[138:139], v[138:139], v[142:143]
	s_nop 0
	v_cvt_pk_bf16_f32 v137, v138, v139
	global_store_dwordx2 v[132:133], v[136:137], off
	s_nop 1
	s_nop 0
	v_pk_mul_f32 v[136:137], v[72:73], v[162:163] op_sel_hi:[1,0]
	v_pk_mul_f32 v[138:139], v[74:75], v[162:163] op_sel_hi:[1,0]
	v_mul_f32_e32 v128, 0xbfb8aa3b, v136
	v_mul_f32_e32 v131, 0xbfb8aa3b, v137
	v_mul_f32_e32 v140, 0xbfb8aa3b, v138
	v_mul_f32_e32 v141, 0xbfb8aa3b, v139
	v_exp_f32_e32 v128, v128
	v_exp_f32_e32 v131, v131
	v_exp_f32_e32 v140, v140
	v_exp_f32_e32 v141, v141
	v_add_f32_e32 v128, 1.0, v128
	v_add_f32_e32 v131, 1.0, v131
	v_add_f32_e32 v142, 1.0, v140
	v_add_f32_e32 v143, 1.0, v141
	v_rcp_f32_e32 v140, v128
	v_rcp_f32_e32 v141, v131
	v_rcp_f32_e32 v142, v142
	v_rcp_f32_e32 v143, v143
	v_pk_mul_f32 v[136:137], v[136:137], v[140:141]
	s_nop 0
	v_cvt_pk_bf16_f32 v136, v136, v137
	v_pk_mul_f32 v[138:139], v[138:139], v[142:143]
	s_nop 0
	v_cvt_pk_bf16_f32 v137, v138, v139
	global_store_dwordx2 v[132:133], v[136:137], off offset:32
	s_nop 1
	s_nop 0
	v_pk_mul_f32 v[136:137], v[68:69], v[162:163] op_sel_hi:[1,0]
	v_pk_mul_f32 v[138:139], v[70:71], v[162:163] op_sel_hi:[1,0]
	v_mul_f32_e32 v128, 0xbfb8aa3b, v136
	v_mul_f32_e32 v131, 0xbfb8aa3b, v137
	v_mul_f32_e32 v140, 0xbfb8aa3b, v138
	v_mul_f32_e32 v141, 0xbfb8aa3b, v139
	v_exp_f32_e32 v128, v128
	v_exp_f32_e32 v131, v131
	v_exp_f32_e32 v140, v140
	v_exp_f32_e32 v141, v141
	v_add_f32_e32 v128, 1.0, v128
	v_add_f32_e32 v131, 1.0, v131
	v_add_f32_e32 v142, 1.0, v140
	v_add_f32_e32 v143, 1.0, v141
	v_rcp_f32_e32 v140, v128
	v_rcp_f32_e32 v141, v131
	v_rcp_f32_e32 v142, v142
	v_rcp_f32_e32 v143, v143
	v_pk_mul_f32 v[136:137], v[136:137], v[140:141]
	s_nop 0
	v_cvt_pk_bf16_f32 v136, v136, v137
	v_pk_mul_f32 v[138:139], v[138:139], v[142:143]
	s_nop 0
	v_cvt_pk_bf16_f32 v137, v138, v139
	global_store_dwordx2 v[132:133], v[136:137], off offset:64
	s_nop 1
	s_nop 0
	v_pk_mul_f32 v[136:137], v[60:61], v[162:163] op_sel_hi:[1,0]
	v_pk_mul_f32 v[138:139], v[62:63], v[162:163] op_sel_hi:[1,0]
	v_mul_f32_e32 v128, 0xbfb8aa3b, v136
	v_mul_f32_e32 v131, 0xbfb8aa3b, v137
	v_mul_f32_e32 v140, 0xbfb8aa3b, v138
	v_mul_f32_e32 v141, 0xbfb8aa3b, v139
	v_exp_f32_e32 v128, v128
	v_exp_f32_e32 v131, v131
	v_exp_f32_e32 v140, v140
	v_exp_f32_e32 v141, v141
	v_add_f32_e32 v128, 1.0, v128
	v_add_f32_e32 v131, 1.0, v131
	v_add_f32_e32 v142, 1.0, v140
	v_add_f32_e32 v143, 1.0, v141
	v_rcp_f32_e32 v140, v128
	v_rcp_f32_e32 v141, v131
	v_rcp_f32_e32 v142, v142
	v_rcp_f32_e32 v143, v143
	v_pk_mul_f32 v[136:137], v[136:137], v[140:141]
	s_nop 0
	v_cvt_pk_bf16_f32 v136, v136, v137
	v_pk_mul_f32 v[138:139], v[138:139], v[142:143]
	s_nop 0
	v_cvt_pk_bf16_f32 v137, v138, v139
	global_store_dwordx2 v[132:133], v[136:137], off offset:96
	v_or_b32_e32 v132, 64, v130
	v_ashrrev_i32_e32 v133, 31, v132
	v_lshl_add_u64 v[136:137], v[132:133], 2, s[26:27]
	global_load_dword v128, v[136:137], off
	v_lshlrev_b64 v[132:133], 11, v[132:133]
	v_lshl_add_u64 v[132:133], s[20:21], 0, v[132:133]
	v_lshl_add_u64 v[132:133], v[132:133], 0, v[134:135]
	s_waitcnt vmcnt(0)
; DI float silu(float v) { return v * __builtin_amdgcn_rcpf(1.f + __expf(-v)); }
; DI u32x2 pack4(float a, float b, float c, float d) { u32x2 r; r.x = pack2(a, b); r.y = pack2(c, d); return r; }
; #define EPI_END if (i == 3 && (j & 3) == 3) __builtin_amdgcn_sched_barrier(0); }
; DI float rstd_of(const float* ssq, int m, float invn) { return rsqrtf(ssq[m] * invn + 1e-6f); }
; template <int MODE>
; DI void gemm_phase(const Params& p, const GP& g, unsigned char* smem) {
;     ...
;       } else if (nt < 4) {
;         u16* qo = (u16*)g.d0;
;         EPI_STD_BEGIN
;           const float rs = rstd_of(g.ssq_in, m, 1.f / 1024);
;           *(u32x2*)(qo + (long)m * 1024 + n4) = pack4(silu(v[0] * rs), silu(v[1] * rs), silu(v[2] * rs), silu(v[3] * rs));
;         EPI_END
	v_fmamk_f32 v128, v128, 0x3a800000, v151
	v_mul_f32_e32 v131, 0x4b800000, v128
	v_cmp_gt_f32_e32 vcc, s68, v128
	s_nop 1
	v_cndmask_b32_e32 v128, v128, v131, vcc
	v_rsq_f32_e32 v128, v128
	s_nop 0
	v_mul_f32_e32 v131, 0x45800000, v128
	v_cndmask_b32_e32 v128, v128, v131, vcc
	v_mov_b32_e32 v164, v128
	v_pk_mul_f32 v[138:139], v[64:65], v[128:129] op_sel_hi:[1,0]
	v_pk_mul_f32 v[140:141], v[66:67], v[164:165] op_sel_hi:[1,0]
	v_mul_f32_e32 v128, 0xbfb8aa3b, v138
	v_mul_f32_e32 v131, 0xbfb8aa3b, v139
	v_mul_f32_e32 v142, 0xbfb8aa3b, v140
	v_mul_f32_e32 v143, 0xbfb8aa3b, v141
	v_exp_f32_e32 v128, v128
	v_exp_f32_e32 v131, v131
	v_exp_f32_e32 v142, v142
	v_exp_f32_e32 v143, v143
	v_add_f32_e32 v128, 1.0, v128
	v_add_f32_e32 v131, 1.0, v131
	v_add_f32_e32 v144, 1.0, v142
	v_add_f32_e32 v145, 1.0, v143
	v_rcp_f32_e32 v142, v128
	v_rcp_f32_e32 v143, v131
	v_rcp_f32_e32 v144, v144
	v_rcp_f32_e32 v145, v145
	v_pk_mul_f32 v[138:139], v[138:139], v[142:143]
	s_nop 0
	v_cvt_pk_bf16_f32 v138, v138, v139
	v_pk_mul_f32 v[140:141], v[140:141], v[144:145]
	s_nop 0
	v_cvt_pk_bf16_f32 v139, v140, v141
	global_store_dwordx2 v[132:133], v[138:139], off
	s_nop 1
	s_nop 0
	v_pk_mul_f32 v[138:139], v[56:57], v[164:165] op_sel_hi:[1,0]
	v_pk_mul_f32 v[140:141], v[58:59], v[164:165] op_sel_hi:[1,0]
	v_mul_f32_e32 v128, 0xbfb8aa3b, v138
	v_mul_f32_e32 v131, 0xbfb8aa3b, v139
	v_mul_f32_e32 v142, 0xbfb8aa3b, v140
	v_mul_f32_e32 v143, 0xbfb8aa3b, v141
	v_exp_f32_e32 v128, v128
	v_exp_f32_e32 v131, v131
	v_exp_f32_e32 v142, v142
	v_exp_f32_e32 v143, v143
	v_add_f32_e32 v128, 1.0, v128
	v_add_f32_e32 v131, 1.0, v131
	v_add_f32_e32 v144, 1.0, v142
	v_add_f32_e32 v145, 1.0, v143
	v_rcp_f32_e32 v142, v128
	v_rcp_f32_e32 v143, v131
	v_rcp_f32_e32 v144, v144
	v_rcp_f32_e32 v145, v145
	v_pk_mul_f32 v[138:139], v[138:139], v[142:143]
	s_nop 0
	v_cvt_pk_bf16_f32 v138, v138, v139
	v_pk_mul_f32 v[140:141], v[140:141], v[144:145]
	s_nop 0
	v_cvt_pk_bf16_f32 v139, v140, v141
	global_store_dwordx2 v[132:133], v[138:139], off offset:32
	s_nop 1
	s_nop 0
	v_pk_mul_f32 v[138:139], v[52:53], v[164:165] op_sel_hi:[1,0]
	v_pk_mul_f32 v[140:141], v[54:55], v[164:165] op_sel_hi:[1,0]
	v_mul_f32_e32 v128, 0xbfb8aa3b, v138
	v_mul_f32_e32 v131, 0xbfb8aa3b, v139
	v_mul_f32_e32 v142, 0xbfb8aa3b, v140
	v_mul_f32_e32 v143, 0xbfb8aa3b, v141
	v_exp_f32_e32 v128, v128
	v_exp_f32_e32 v131, v131
	v_exp_f32_e32 v142, v142
	v_exp_f32_e32 v143, v143
	v_add_f32_e32 v128, 1.0, v128
	v_add_f32_e32 v131, 1.0, v131
	v_add_f32_e32 v144, 1.0, v142
	v_add_f32_e32 v145, 1.0, v143
	v_rcp_f32_e32 v142, v128
	v_rcp_f32_e32 v143, v131
	v_rcp_f32_e32 v144, v144
	v_rcp_f32_e32 v145, v145
	v_pk_mul_f32 v[138:139], v[138:139], v[142:143]
	s_nop 0
	v_cvt_pk_bf16_f32 v138, v138, v139
	v_pk_mul_f32 v[140:141], v[140:141], v[144:145]
	s_nop 0
	v_cvt_pk_bf16_f32 v139, v140, v141
	global_store_dwordx2 v[132:133], v[138:139], off offset:64
	v_or_b32_e32 v136, 0x50, v130
	s_nop 1
	s_nop 0
	v_pk_mul_f32 v[138:139], v[44:45], v[164:165] op_sel_hi:[1,0]
	v_pk_mul_f32 v[140:141], v[46:47], v[164:165] op_sel_hi:[1,0]
	v_mul_f32_e32 v128, 0xbfb8aa3b, v138
	v_mul_f32_e32 v131, 0xbfb8aa3b, v139
	v_mul_f32_e32 v137, 0xbfb8aa3b, v140
	v_mul_f32_e32 v142, 0xbfb8aa3b, v141
	v_exp_f32_e32 v128, v128
	v_exp_f32_e32 v131, v131
	v_exp_f32_e32 v137, v137
	v_exp_f32_e32 v142, v142
	v_add_f32_e32 v128, 1.0, v128
	v_add_f32_e32 v131, 1.0, v131
	v_add_f32_e32 v137, 1.0, v137
	v_add_f32_e32 v145, 1.0, v142
	v_rcp_f32_e32 v142, v128
	v_rcp_f32_e32 v143, v131
	v_rcp_f32_e32 v144, v137
	v_rcp_f32_e32 v145, v145
	v_ashrrev_i32_e32 v137, 31, v136
	v_pk_mul_f32 v[138:139], v[138:139], v[142:143]
	v_lshl_add_u64 v[154:155], v[136:137], 2, s[26:27]
	global_load_dword v128, v[154:155], off
	v_pk_mul_f32 v[140:141], v[140:141], v[144:145]
	v_cvt_pk_bf16_f32 v138, v138, v139
	v_cvt_pk_bf16_f32 v139, v140, v141
	global_store_dwordx2 v[132:133], v[138:139], off offset:96
	s_nop 0
	v_lshlrev_b64 v[132:133], 11, v[136:137]
	v_lshl_add_u64 v[132:133], s[20:21], 0, v[132:133]
	v_lshl_add_u64 v[132:133], v[132:133], 0, v[134:135]
	s_waitcnt vmcnt(1)
	v_fmamk_f32 v128, v128, 0x3a800000, v151
	v_mul_f32_e32 v131, 0x4b800000, v128
	v_cmp_gt_f32_e32 vcc, s68, v128
	s_nop 1
	v_cndmask_b32_e32 v128, v128, v131, vcc
	v_rsq_f32_e32 v128, v128
	s_nop 0
	v_mul_f32_e32 v131, 0x45800000, v128
	v_cndmask_b32_e32 v128, v128, v131, vcc
	v_mov_b32_e32 v166, v128
	v_pk_mul_f32 v[136:137], v[48:49], v[128:129] op_sel_hi:[1,0]
	v_pk_mul_f32 v[138:139], v[50:51], v[166:167] op_sel_hi:[1,0]
	v_mul_f32_e32 v128, 0xbfb8aa3b, v136
	v_mul_f32_e32 v131, 0xbfb8aa3b, v137
	v_mul_f32_e32 v140, 0xbfb8aa3b, v138
	v_mul_f32_e32 v141, 0xbfb8aa3b, v139
	v_exp_f32_e32 v128, v128
	v_exp_f32_e32 v131, v131
	v_exp_f32_e32 v140, v140
	v_exp_f32_e32 v141, v141
	v_add_f32_e32 v128, 1.0, v128
	v_add_f32_e32 v131, 1.0, v131
	v_add_f32_e32 v142, 1.0, v140
	v_add_f32_e32 v143, 1.0, v141
	v_rcp_f32_e32 v140, v128
	v_rcp_f32_e32 v141, v131
	v_rcp_f32_e32 v142, v142
	v_rcp_f32_e32 v143, v143
	v_pk_mul_f32 v[136:137], v[136:137], v[140:141]
	s_nop 0
	v_cvt_pk_bf16_f32 v136, v136, v137
	v_pk_mul_f32 v[138:139], v[138:139], v[142:143]
	s_nop 0
	v_cvt_pk_bf16_f32 v137, v138, v139
	global_store_dwordx2 v[132:133], v[136:137], off
	s_nop 1
	s_nop 0
	v_pk_mul_f32 v[136:137], v[40:41], v[166:167] op_sel_hi:[1,0]
	v_pk_mul_f32 v[138:139], v[42:43], v[166:167] op_sel_hi:[1,0]
	v_mul_f32_e32 v128, 0xbfb8aa3b, v136
	v_mul_f32_e32 v131, 0xbfb8aa3b, v137
	v_mul_f32_e32 v140, 0xbfb8aa3b, v138
	v_mul_f32_e32 v141, 0xbfb8aa3b, v139
	v_exp_f32_e32 v128, v128
	v_exp_f32_e32 v131, v131
	v_exp_f32_e32 v140, v140
	v_exp_f32_e32 v141, v141
; DI float silu(float v) { return v * __builtin_amdgcn_rcpf(1.f + __expf(-v)); }
; DI u32x2 pack4(float a, float b, float c, float d) { u32x2 r; r.x = pack2(a, b); r.y = pack2(c, d); return r; }
; #define EPI_END if (i == 3 && (j & 3) == 3) __builtin_amdgcn_sched_barrier(0); }
; DI float rstd_of(const float* ssq, int m, float invn) { return rsqrtf(ssq[m] * invn + 1e-6f); }
; template <int MODE>
; DI void gemm_phase(const Params& p, const GP& g, unsigned char* smem) {
;     ...
;       } else if (nt < 4) {
;         u16* qo = (u16*)g.d0;
;         EPI_STD_BEGIN
;           const float rs = rstd_of(g.ssq_in, m, 1.f / 1024);
;           *(u32x2*)(qo + (long)m * 1024 + n4) = pack4(silu(v[0] * rs), silu(v[1] * rs), silu(v[2] * rs), silu(v[3] * rs));
;         EPI_END
	v_add_f32_e32 v128, 1.0, v128
	v_add_f32_e32 v131, 1.0, v131
	v_add_f32_e32 v142, 1.0, v140
	v_add_f32_e32 v143, 1.0, v141
	v_rcp_f32_e32 v140, v128
	v_rcp_f32_e32 v141, v131
	v_rcp_f32_e32 v142, v142
	v_rcp_f32_e32 v143, v143
	v_pk_mul_f32 v[136:137], v[136:137], v[140:141]
	s_nop 0
	v_cvt_pk_bf16_f32 v136, v136, v137
	v_pk_mul_f32 v[138:139], v[138:139], v[142:143]
	s_nop 0
	v_cvt_pk_bf16_f32 v137, v138, v139
	global_store_dwordx2 v[132:133], v[136:137], off offset:32
	s_nop 1
	s_nop 0
	v_pk_mul_f32 v[136:137], v[36:37], v[166:167] op_sel_hi:[1,0]
	v_pk_mul_f32 v[138:139], v[38:39], v[166:167] op_sel_hi:[1,0]
	v_mul_f32_e32 v128, 0xbfb8aa3b, v136
	v_mul_f32_e32 v131, 0xbfb8aa3b, v137
	v_mul_f32_e32 v140, 0xbfb8aa3b, v138
	v_mul_f32_e32 v141, 0xbfb8aa3b, v139
	v_exp_f32_e32 v128, v128
	v_exp_f32_e32 v131, v131
	v_exp_f32_e32 v140, v140
	v_exp_f32_e32 v141, v141
	v_add_f32_e32 v128, 1.0, v128
	v_add_f32_e32 v131, 1.0, v131
	v_add_f32_e32 v142, 1.0, v140
	v_add_f32_e32 v143, 1.0, v141
	v_rcp_f32_e32 v140, v128
	v_rcp_f32_e32 v141, v131
	v_rcp_f32_e32 v142, v142
	v_rcp_f32_e32 v143, v143
	v_pk_mul_f32 v[136:137], v[136:137], v[140:141]
	s_nop 0
	v_cvt_pk_bf16_f32 v136, v136, v137
	v_pk_mul_f32 v[138:139], v[138:139], v[142:143]
	s_nop 0
	v_cvt_pk_bf16_f32 v137, v138, v139
	global_store_dwordx2 v[132:133], v[136:137], off offset:64
	v_or_b32_e32 v136, 0x60, v130
	v_or_b32_e32 v130, 0x70, v130
	s_nop 1
	s_nop 0
	v_pk_mul_f32 v[138:139], v[28:29], v[166:167] op_sel_hi:[1,0]
	v_pk_mul_f32 v[140:141], v[30:31], v[166:167] op_sel_hi:[1,0]
	v_mul_f32_e32 v128, 0xbfb8aa3b, v138
	v_mul_f32_e32 v131, 0xbfb8aa3b, v139
	v_mul_f32_e32 v137, 0xbfb8aa3b, v140
	v_mul_f32_e32 v142, 0xbfb8aa3b, v141
	v_exp_f32_e32 v128, v128
	v_exp_f32_e32 v131, v131
	v_exp_f32_e32 v137, v137
	v_exp_f32_e32 v142, v142
	v_add_f32_e32 v128, 1.0, v128
	v_add_f32_e32 v131, 1.0, v131
	v_add_f32_e32 v137, 1.0, v137
	v_add_f32_e32 v145, 1.0, v142
	v_rcp_f32_e32 v142, v128
	v_rcp_f32_e32 v143, v131
	v_rcp_f32_e32 v144, v137
	v_rcp_f32_e32 v145, v145
	v_ashrrev_i32_e32 v137, 31, v136
	v_pk_mul_f32 v[138:139], v[138:139], v[142:143]
	v_lshl_add_u64 v[154:155], v[136:137], 2, s[26:27]
	global_load_dword v128, v[154:155], off
	v_pk_mul_f32 v[140:141], v[140:141], v[144:145]
	v_cvt_pk_bf16_f32 v138, v138, v139
	v_cvt_pk_bf16_f32 v139, v140, v141
	global_store_dwordx2 v[132:133], v[138:139], off offset:96
	s_nop 0
	v_lshlrev_b64 v[132:133], 11, v[136:137]
	v_lshl_add_u64 v[132:133], s[20:21], 0, v[132:133]
	v_lshl_add_u64 v[132:133], v[132:133], 0, v[134:135]
	s_waitcnt vmcnt(1)
	v_fmamk_f32 v128, v128, 0x3a800000, v151
	v_mul_f32_e32 v131, 0x4b800000, v128
	v_cmp_gt_f32_e32 vcc, s68, v128
	s_nop 1
	v_cndmask_b32_e32 v128, v128, v131, vcc
	v_rsq_f32_e32 v128, v128
	s_nop 0
	v_mul_f32_e32 v131, 0x45800000, v128
	v_cndmask_b32_e32 v128, v128, v131, vcc
	v_mov_b32_e32 v168, v128
	v_pk_mul_f32 v[136:137], v[32:33], v[128:129] op_sel_hi:[1,0]
	v_pk_mul_f32 v[138:139], v[34:35], v[168:169] op_sel_hi:[1,0]
	v_mul_f32_e32 v128, 0xbfb8aa3b, v136
	v_mul_f32_e32 v131, 0xbfb8aa3b, v137
	v_mul_f32_e32 v140, 0xbfb8aa3b, v138
	v_mul_f32_e32 v141, 0xbfb8aa3b, v139
	v_exp_f32_e32 v128, v128
	v_exp_f32_e32 v131, v131
	v_exp_f32_e32 v140, v140
	v_exp_f32_e32 v141, v141
	v_add_f32_e32 v128, 1.0, v128
	v_add_f32_e32 v131, 1.0, v131
	v_add_f32_e32 v142, 1.0, v140
	v_add_f32_e32 v143, 1.0, v141
	v_rcp_f32_e32 v140, v128
	v_rcp_f32_e32 v141, v131
	v_rcp_f32_e32 v142, v142
	v_rcp_f32_e32 v143, v143
	v_pk_mul_f32 v[136:137], v[136:137], v[140:141]
	s_nop 0
	v_cvt_pk_bf16_f32 v136, v136, v137
	v_pk_mul_f32 v[138:139], v[138:139], v[142:143]
	s_nop 0
	v_cvt_pk_bf16_f32 v137, v138, v139
	global_store_dwordx2 v[132:133], v[136:137], off
	s_nop 1
	s_nop 0
	v_pk_mul_f32 v[136:137], v[24:25], v[168:169] op_sel_hi:[1,0]
	v_pk_mul_f32 v[138:139], v[26:27], v[168:169] op_sel_hi:[1,0]
	v_mul_f32_e32 v128, 0xbfb8aa3b, v136
	v_mul_f32_e32 v131, 0xbfb8aa3b, v137
	v_mul_f32_e32 v140, 0xbfb8aa3b, v138
	v_mul_f32_e32 v141, 0xbfb8aa3b, v139
	v_exp_f32_e32 v128, v128
	v_exp_f32_e32 v131, v131
	v_exp_f32_e32 v140, v140
	v_exp_f32_e32 v141, v141
	v_add_f32_e32 v128, 1.0, v128
	v_add_f32_e32 v131, 1.0, v131
	v_add_f32_e32 v142, 1.0, v140
	v_add_f32_e32 v143, 1.0, v141
	v_rcp_f32_e32 v140, v128
	v_rcp_f32_e32 v141, v131
	v_rcp_f32_e32 v142, v142
	v_rcp_f32_e32 v143, v143
	v_pk_mul_f32 v[136:137], v[136:137], v[140:141]
	s_nop 0
	v_cvt_pk_bf16_f32 v136, v136, v137
	v_pk_mul_f32 v[138:139], v[138:139], v[142:143]
	s_nop 0
	v_cvt_pk_bf16_f32 v137, v138, v139
	global_store_dwordx2 v[132:133], v[136:137], off offset:32
	s_nop 1
	s_nop 0
	v_pk_mul_f32 v[136:137], v[20:21], v[168:169] op_sel_hi:[1,0]
	v_pk_mul_f32 v[138:139], v[22:23], v[168:169] op_sel_hi:[1,0]
	v_mul_f32_e32 v128, 0xbfb8aa3b, v136
	v_mul_f32_e32 v131, 0xbfb8aa3b, v137
	v_mul_f32_e32 v140, 0xbfb8aa3b, v138
	v_mul_f32_e32 v141, 0xbfb8aa3b, v139
	v_exp_f32_e32 v128, v128
	v_exp_f32_e32 v131, v131
	v_exp_f32_e32 v140, v140
	v_exp_f32_e32 v141, v141
	v_add_f32_e32 v128, 1.0, v128
	v_add_f32_e32 v131, 1.0, v131
	v_add_f32_e32 v142, 1.0, v140
	v_add_f32_e32 v143, 1.0, v141
	v_rcp_f32_e32 v140, v128
	v_rcp_f32_e32 v141, v131
	v_rcp_f32_e32 v142, v142
	v_rcp_f32_e32 v143, v143
	v_pk_mul_f32 v[136:137], v[136:137], v[140:141]
	s_nop 0
	v_cvt_pk_bf16_f32 v136, v136, v137
	v_pk_mul_f32 v[138:139], v[138:139], v[142:143]
	s_nop 0
	v_cvt_pk_bf16_f32 v137, v138, v139
	global_store_dwordx2 v[132:133], v[136:137], off offset:64
	s_nop 1
	s_nop 0
	v_pk_mul_f32 v[136:137], v[12:13], v[168:169] op_sel_hi:[1,0]
	v_pk_mul_f32 v[138:139], v[14:15], v[168:169] op_sel_hi:[1,0]
	v_mul_f32_e32 v128, 0xbfb8aa3b, v136
	v_mul_f32_e32 v131, 0xbfb8aa3b, v137
	v_mul_f32_e32 v140, 0xbfb8aa3b, v138
	v_mul_f32_e32 v141, 0xbfb8aa3b, v139
	v_exp_f32_e32 v128, v128
	v_exp_f32_e32 v131, v131
	v_exp_f32_e32 v140, v140
	v_exp_f32_e32 v141, v141
	v_add_f32_e32 v128, 1.0, v128
	v_add_f32_e32 v131, 1.0, v131
	v_add_f32_e32 v142, 1.0, v140
	v_add_f32_e32 v143, 1.0, v141
	v_rcp_f32_e32 v140, v128
	v_rcp_f32_e32 v141, v131
	v_rcp_f32_e32 v142, v142
	v_rcp_f32_e32 v143, v143
	v_ashrrev_i32_e32 v131, 31, v130
	v_pk_mul_f32 v[136:137], v[136:137], v[140:141]
	v_lshl_add_u64 v[144:145], v[130:131], 2, s[26:27]
	global_load_dword v128, v[144:145], off
	global_load_dword v184, v[144:145], off
	v_pk_mul_f32 v[138:139], v[138:139], v[142:143]
	v_cvt_pk_bf16_f32 v136, v136, v137
	v_cvt_pk_bf16_f32 v137, v138, v139
	global_store_dwordx2 v[132:133], v[136:137], off offset:96
	s_nop 0
	v_lshlrev_b64 v[130:131], 11, v[130:131]
	v_lshl_add_u64 v[130:131], s[20:21], 0, v[130:131]
	v_lshl_add_u64 v[130:131], v[130:131], 0, v[134:135]
	s_waitcnt vmcnt(2)
; DI float silu(float v) { return v * __builtin_amdgcn_rcpf(1.f + __expf(-v)); }
; DI u32x2 pack4(float a, float b, float c, float d) { u32x2 r; r.x = pack2(a, b); r.y = pack2(c, d); return r; }
; #define EPI_END if (i == 3 && (j & 3) == 3) __builtin_amdgcn_sched_barrier(0); }
; DI float rstd_of(const float* ssq, int m, float invn) { return rsqrtf(ssq[m] * invn + 1e-6f); }
; template <int MODE>
; DI void gemm_phase(const Params& p, const GP& g, unsigned char* smem) {
;     ...
;       } else if (nt < 4) {
;         u16* qo = (u16*)g.d0;
;         EPI_STD_BEGIN
;           const float rs = rstd_of(g.ssq_in, m, 1.f / 1024);
;           *(u32x2*)(qo + (long)m * 1024 + n4) = pack4(silu(v[0] * rs), silu(v[1] * rs), silu(v[2] * rs), silu(v[3] * rs));
;         EPI_END
	v_fmamk_f32 v128, v128, 0x3a800000, v151
	v_mul_f32_e32 v132, 0x4b800000, v128
	v_cmp_gt_f32_e32 vcc, s68, v128
	s_nop 1
	v_cndmask_b32_e32 v128, v128, v132, vcc
	v_rsq_f32_e32 v128, v128
	s_nop 0
	v_mul_f32_e32 v132, 0x45800000, v128
	v_cndmask_b32_e32 v128, v128, v132, vcc
	v_mov_b32_e32 v170, v128
	v_pk_mul_f32 v[132:133], v[16:17], v[128:129] op_sel_hi:[1,0]
	v_pk_mul_f32 v[136:137], v[18:19], v[170:171] op_sel_hi:[1,0]
	v_mul_f32_e32 v128, 0xbfb8aa3b, v132
	v_mul_f32_e32 v138, 0xbfb8aa3b, v133
	v_mul_f32_e32 v139, 0xbfb8aa3b, v136
	v_mul_f32_e32 v140, 0xbfb8aa3b, v137
	v_exp_f32_e32 v128, v128
	v_exp_f32_e32 v138, v138
	v_exp_f32_e32 v139, v139
	v_exp_f32_e32 v140, v140
	v_add_f32_e32 v128, 1.0, v128
	v_add_f32_e32 v141, 1.0, v138
	v_add_f32_e32 v142, 1.0, v139
	v_add_f32_e32 v143, 1.0, v140
	v_rcp_f32_e32 v138, v128
	v_rcp_f32_e32 v139, v141
	v_rcp_f32_e32 v140, v142
	v_rcp_f32_e32 v141, v143
	v_pk_mul_f32 v[132:133], v[132:133], v[138:139]
	s_nop 0
	v_cvt_pk_bf16_f32 v132, v132, v133
	v_pk_mul_f32 v[134:135], v[136:137], v[140:141]
	s_nop 0
	v_cvt_pk_bf16_f32 v133, v134, v135
	global_store_dwordx2 v[130:131], v[132:133], off
	s_nop 1
	s_nop 0
	v_pk_mul_f32 v[132:133], v[4:5], v[170:171] op_sel_hi:[1,0]
	v_pk_mul_f32 v[134:135], v[6:7], v[170:171] op_sel_hi:[1,0]
	v_mul_f32_e32 v128, 0xbfb8aa3b, v132
	v_mul_f32_e32 v136, 0xbfb8aa3b, v133
	v_mul_f32_e32 v137, 0xbfb8aa3b, v134
	v_mul_f32_e32 v138, 0xbfb8aa3b, v135
	v_exp_f32_e32 v128, v128
	v_exp_f32_e32 v136, v136
	v_exp_f32_e32 v137, v137
	v_exp_f32_e32 v138, v138
	v_add_f32_e32 v128, 1.0, v128
	v_add_f32_e32 v139, 1.0, v136
	v_add_f32_e32 v140, 1.0, v137
	v_add_f32_e32 v141, 1.0, v138
	v_rcp_f32_e32 v136, v128
	v_rcp_f32_e32 v137, v139
	v_rcp_f32_e32 v138, v140
	v_rcp_f32_e32 v139, v141
	v_pk_mul_f32 v[132:133], v[132:133], v[136:137]
	s_nop 0
	v_cvt_pk_bf16_f32 v132, v132, v133
	v_pk_mul_f32 v[134:135], v[134:135], v[138:139]
	s_nop 0
	v_cvt_pk_bf16_f32 v133, v134, v135
	global_store_dwordx2 v[130:131], v[132:133], off offset:32
	s_nop 1
	s_nop 0
	v_pk_mul_f32 v[132:133], v[0:1], v[170:171] op_sel_hi:[1,0]
	v_pk_mul_f32 v[134:135], v[2:3], v[170:171] op_sel_hi:[1,0]
	v_mul_f32_e32 v128, 0xbfb8aa3b, v132
	v_mul_f32_e32 v136, 0xbfb8aa3b, v133
	v_mul_f32_e32 v137, 0xbfb8aa3b, v134
	v_mul_f32_e32 v138, 0xbfb8aa3b, v135
	v_exp_f32_e32 v128, v128
	v_exp_f32_e32 v136, v136
	v_exp_f32_e32 v137, v137
	v_exp_f32_e32 v138, v138
	v_add_f32_e32 v128, 1.0, v128
	v_add_f32_e32 v139, 1.0, v136
	v_add_f32_e32 v140, 1.0, v137
	v_add_f32_e32 v141, 1.0, v138
	v_rcp_f32_e32 v136, v128
	v_rcp_f32_e32 v137, v139
	v_rcp_f32_e32 v138, v140
	v_rcp_f32_e32 v139, v141
	v_pk_mul_f32 v[132:133], v[132:133], v[136:137]
	s_nop 0
	v_cvt_pk_bf16_f32 v132, v132, v133
	v_pk_mul_f32 v[134:135], v[134:135], v[138:139]
	s_nop 0
	v_cvt_pk_bf16_f32 v133, v134, v135
	global_store_dwordx2 v[130:131], v[132:133], off offset:64
	s_nop 0
	s_waitcnt vmcnt(4)
	v_fmamk_f32 v128, v184, 0x3a800000, v151
	v_cmp_gt_f32_e32 vcc, s68, v128
	s_nop 1
	s_nop 0
	v_pk_mul_f32 v[132:133], v[8:9], v[170:171] op_sel_hi:[1,0]
	v_pk_mul_f32 v[134:135], v[10:11], v[170:171] op_sel_hi:[1,0]
	v_mul_f32_e32 v128, 0xbfb8aa3b, v132
	v_mul_f32_e32 v136, 0xbfb8aa3b, v133
	v_mul_f32_e32 v137, 0xbfb8aa3b, v134
	v_mul_f32_e32 v138, 0xbfb8aa3b, v135
	v_exp_f32_e32 v128, v128
	v_exp_f32_e32 v136, v136
	v_exp_f32_e32 v137, v137
	v_exp_f32_e32 v138, v138
	v_add_f32_e32 v128, 1.0, v128
	v_add_f32_e32 v139, 1.0, v136
	v_add_f32_e32 v140, 1.0, v137
	v_add_f32_e32 v141, 1.0, v138
	v_rcp_f32_e32 v136, v128
	v_rcp_f32_e32 v137, v139
	v_rcp_f32_e32 v138, v140
	v_rcp_f32_e32 v139, v141
	v_pk_mul_f32 v[132:133], v[132:133], v[136:137]
	s_nop 0
	v_cvt_pk_bf16_f32 v132, v132, v133
	v_pk_mul_f32 v[134:135], v[134:135], v[138:139]
	s_nop 0
	v_cvt_pk_bf16_f32 v133, v134, v135
	global_store_dwordx2 v[130:131], v[132:133], off offset:96

; DI u32x2 pack4(float a, float b, float c, float d) { u32x2 r; r.x = pack2(a, b); r.y = pack2(c, d); return r; }
; #define EPI_END if (i == 3 && (j & 3) == 3) __builtin_amdgcn_sched_barrier(0); }
; DI float rstd_of(const float* ssq, int m, float invn) { return rsqrtf(ssq[m] * invn + 1e-6f); }
; template <int MODE>
; DI void gemm_phase(const Params& p, const GP& g, unsigned char* smem) {
;     ...
;       if (transposed) {
;         u16* iT = (u16*)g.d3;
;         EPI_TR_BEGIN
;           const int b = m4 >> 12, s = m4 & 4095;
;           *(u32x2*)(iT + ((long)b * 1024 + (n - 3072)) * 4096 + s) =
;               pack4(v[0] * rstd_of(g.ssq_in, m4, 1.f / 1024), v[1] * rstd_of(g.ssq_in, m4 + 1, 1.f / 1024),
;                     v[2] * rstd_of(g.ssq_in, m4 + 2, 1.f / 1024), v[3] * rstd_of(g.ssq_in, m4 + 3, 1.f / 1024));
;         EPI_END
.LBB0_578:
	s_add_i32 s7, s64, s61
	v_or_b32_e32 v138, s7, v146
	v_ashrrev_i32_e32 v139, 31, v138
	v_lshl_add_u64 v[134:135], v[138:139], 2, s[26:27]
	global_load_dwordx4 v[140:143], v[134:135], off
	v_add_u32_e32 v136, s65, v150
	v_mov_b64_e32 v[130:131], s[62:63]
	v_ashrrev_i32_e32 v137, 31, v136
	v_lshlrev_b64 v[144:145], 13, v[136:137]
	s_ashr_i32 s6, s7, 12
	v_bitop3_b32 v128, s7, v153, v146 bitop3:0xc8
	s_ashr_i32 s7, s6, 31
	s_lshl_b64 s[6:7], s[6:7], 23
	s_add_u32 s64, s22, s6
	s_addc_u32 s65, s23, s7
	v_lshlrev_b32_e32 v128, 1, v128
	v_or_b32_e32 v132, 16, v138
	v_lshl_add_u64 v[144:145], s[64:65], 0, v[144:145]
	v_ashrrev_i32_e32 v133, 31, v132
	v_lshl_add_u64 v[132:133], v[132:133], 2, s[26:27]
	global_load_dwordx2 v[188:189], v[132:133], off
	global_load_dwordx2 v[190:191], v[132:133], off offset:8
	s_waitcnt vmcnt(2)
	v_pk_fma_f32 v[140:141], v[140:141], s[58:59], v[130:131] op_sel_hi:[1,0,0]
	v_pk_fma_f32 v[142:143], v[142:143], s[58:59], v[130:131] op_sel_hi:[1,0,0]
	v_mul_f32_e32 v137, 0x4b800000, v140
	v_mul_f32_e32 v139, 0x4b800000, v141
	v_mul_f32_e32 v154, 0x4b800000, v142
	v_mul_f32_e32 v155, 0x4b800000, v143
	v_cmp_gt_f32_e32 vcc, s68, v140
	v_cmp_gt_f32_e64 s[10:11], s68, v141
	v_cmp_gt_f32_e64 s[12:13], s68, v142
	v_cmp_gt_f32_e64 s[14:15], s68, v143
	v_cndmask_b32_e32 v137, v140, v137, vcc
	v_cndmask_b32_e64 v139, v141, v139, s[10:11]
	v_cndmask_b32_e64 v142, v142, v154, s[12:13]
	v_cndmask_b32_e64 v143, v143, v155, s[14:15]
	v_rsq_f32_e32 v140, v137
	v_rsq_f32_e32 v141, v139
	v_rsq_f32_e32 v142, v142
	v_rsq_f32_e32 v143, v143
	v_lshl_add_u64 v[154:155], v[144:145], 0, v[128:129]
	v_pk_mul_f32 v[156:157], v[140:141], s[60:61] op_sel_hi:[1,0]
	v_pk_mul_f32 v[158:159], v[142:143], s[60:61] op_sel_hi:[1,0]
	v_cndmask_b32_e64 v141, v141, v157, s[10:11]
	v_cndmask_b32_e32 v140, v140, v156, vcc
	v_cndmask_b32_e64 v143, v143, v159, s[14:15]
	v_cndmask_b32_e64 v142, v142, v158, s[12:13]
	v_mov_b32_e32 v160, v140
	v_mov_b32_e32 v161, v141
	v_pk_mul_f32 v[124:125], v[124:125], v[140:141]
	v_mov_b32_e32 v162, v142
	v_mov_b32_e32 v163, v143
	v_pk_mul_f32 v[126:127], v[126:127], v[142:143]
	v_cvt_pk_bf16_f32 v124, v124, v125
	v_cvt_pk_bf16_f32 v125, v126, v127
	global_store_dwordx2 v[154:155], v[124:125], off
	s_nop 0
	s_nop 0
	s_nop 0
	v_bitop3_b32 v126, v138, s71, 16 bitop3:0xc8
	v_or_b32_e32 v142, 32, v138
	v_mov_b32_e32 v127, v129
	v_lshlrev_b32_e32 v126, 1, v126
	v_ashrrev_i32_e32 v143, 31, v142
	s_waitcnt vmcnt(2)
	v_pk_fma_f32 v[124:125], v[188:189], s[58:59], v[130:131] op_sel_hi:[1,0,0]
	s_waitcnt vmcnt(1)
	v_pk_fma_f32 v[140:141], v[190:191], s[58:59], v[130:131] op_sel_hi:[1,0,0]
	v_mul_f32_e32 v137, 0x4b800000, v124
	v_mul_f32_e32 v139, 0x4b800000, v125
	v_mul_f32_e32 v154, 0x4b800000, v140
	v_mul_f32_e32 v155, 0x4b800000, v141
	v_cmp_gt_f32_e32 vcc, s68, v124
	v_cmp_gt_f32_e64 s[10:11], s68, v125
	v_cmp_gt_f32_e64 s[12:13], s68, v140
	v_cmp_gt_f32_e64 s[14:15], s68, v141
	v_cndmask_b32_e32 v124, v124, v137, vcc
	v_cndmask_b32_e64 v125, v125, v139, s[10:11]
	v_cndmask_b32_e64 v137, v140, v154, s[12:13]
	v_cndmask_b32_e64 v139, v141, v155, s[14:15]
	v_rsq_f32_e32 v140, v124
	v_rsq_f32_e32 v141, v125
	v_rsq_f32_e32 v154, v137
	v_rsq_f32_e32 v155, v139
	v_lshl_add_u64 v[124:125], v[142:143], 2, s[26:27]
	global_load_dwordx2 v[188:189], v[124:125], off
	global_load_dwordx2 v[190:191], v[124:125], off offset:8
	v_pk_mul_f32 v[156:157], v[140:141], s[60:61] op_sel_hi:[1,0]
	v_lshl_add_u64 v[142:143], v[144:145], 0, v[126:127]
	v_pk_mul_f32 v[158:159], v[154:155], s[60:61] op_sel_hi:[1,0]
	v_cndmask_b32_e64 v141, v141, v157, s[10:11]
	v_cndmask_b32_e32 v140, v140, v156, vcc
	v_cndmask_b32_e64 v155, v155, v159, s[14:15]
	v_cndmask_b32_e64 v154, v154, v158, s[12:13]
	v_mov_b32_e32 v164, v140
	v_mov_b32_e32 v165, v141
	v_pk_mul_f32 v[120:121], v[120:121], v[140:141]
	v_mov_b32_e32 v166, v154
	v_mov_b32_e32 v167, v155
	v_pk_mul_f32 v[122:123], v[122:123], v[154:155]
	v_cvt_pk_bf16_f32 v120, v120, v121
	v_cvt_pk_bf16_f32 v121, v122, v123
	global_store_dwordx2 v[142:143], v[120:121], off
	s_nop 0
	s_nop 0
	s_nop 0
	v_bitop3_b32 v122, v138, s72, 32 bitop3:0xc8
	v_or_b32_e32 v142, 48, v138
	v_mov_b32_e32 v123, v129
	v_lshlrev_b32_e32 v122, 1, v122
	v_ashrrev_i32_e32 v143, 31, v142
	s_waitcnt vmcnt(2)
	v_pk_fma_f32 v[120:121], v[188:189], s[58:59], v[130:131] op_sel_hi:[1,0,0]
	s_waitcnt vmcnt(1)
	v_pk_fma_f32 v[140:141], v[190:191], s[58:59], v[130:131] op_sel_hi:[1,0,0]
	v_mul_f32_e32 v137, 0x4b800000, v120
	v_mul_f32_e32 v139, 0x4b800000, v121
	v_mul_f32_e32 v154, 0x4b800000, v140
	v_mul_f32_e32 v155, 0x4b800000, v141
	v_cmp_gt_f32_e32 vcc, s68, v120
	v_cmp_gt_f32_e64 s[10:11], s68, v121
	v_cmp_gt_f32_e64 s[12:13], s68, v140
	v_cmp_gt_f32_e64 s[14:15], s68, v141
	v_cndmask_b32_e32 v120, v120, v137, vcc
	v_cndmask_b32_e64 v121, v121, v139, s[10:11]
	v_cndmask_b32_e64 v137, v140, v154, s[12:13]
	v_cndmask_b32_e64 v139, v141, v155, s[14:15]
	v_rsq_f32_e32 v140, v120
	v_rsq_f32_e32 v141, v121
	v_rsq_f32_e32 v154, v137
	v_rsq_f32_e32 v155, v139
	v_lshl_add_u64 v[120:121], v[142:143], 2, s[26:27]
	global_load_dwordx2 v[188:189], v[120:121], off
	global_load_dwordx2 v[190:191], v[120:121], off offset:8
	global_load_dwordx4 v[192:195], v[134:135], off
	global_load_dwordx2 v[196:197], v[132:133], off offset:8
	global_load_dwordx2 v[198:199], v[120:121], off
	global_load_dwordx2 v[200:201], v[120:121], off offset:8
	v_pk_mul_f32 v[156:157], v[140:141], s[60:61] op_sel_hi:[1,0]
	v_lshl_add_u64 v[142:143], v[144:145], 0, v[122:123]
	v_pk_mul_f32 v[158:159], v[154:155], s[60:61] op_sel_hi:[1,0]
	v_cndmask_b32_e64 v141, v141, v157, s[10:11]
	v_cndmask_b32_e32 v140, v140, v156, vcc
	v_cndmask_b32_e64 v155, v155, v159, s[14:15]
	v_cndmask_b32_e64 v154, v154, v158, s[12:13]
	v_mov_b32_e32 v168, v140
	v_mov_b32_e32 v169, v141
	v_pk_mul_f32 v[116:117], v[116:117], v[140:141]
	v_mov_b32_e32 v170, v154
	v_mov_b32_e32 v171, v155
	v_pk_mul_f32 v[118:119], v[118:119], v[154:155]
	v_cvt_pk_bf16_f32 v116, v116, v117
	v_cvt_pk_bf16_f32 v117, v118, v119
	global_store_dwordx2 v[142:143], v[116:117], off
	s_nop 0
	s_nop 0
	v_bitop3_b32 v116, v138, s73, 48 bitop3:0xc8
	v_mov_b32_e32 v117, v129
	v_lshlrev_b32_e32 v116, 1, v116
	s_waitcnt vmcnt(6)
; DI u32x2 pack4(float a, float b, float c, float d) { u32x2 r; r.x = pack2(a, b); r.y = pack2(c, d); return r; }
; #define EPI_END if (i == 3 && (j & 3) == 3) __builtin_amdgcn_sched_barrier(0); }
; DI float rstd_of(const float* ssq, int m, float invn) { return rsqrtf(ssq[m] * invn + 1e-6f); }
; template <int MODE>
; DI void gemm_phase(const Params& p, const GP& g, unsigned char* smem) {
;     ...
;       if (transposed) {
;         u16* iT = (u16*)g.d3;
;         EPI_TR_BEGIN
;           const int b = m4 >> 12, s = m4 & 4095;
;           *(u32x2*)(iT + ((long)b * 1024 + (n - 3072)) * 4096 + s) =
;               pack4(v[0] * rstd_of(g.ssq_in, m4, 1.f / 1024), v[1] * rstd_of(g.ssq_in, m4 + 1, 1.f / 1024),
;                     v[2] * rstd_of(g.ssq_in, m4 + 2, 1.f / 1024), v[3] * rstd_of(g.ssq_in, m4 + 3, 1.f / 1024));
;         EPI_END
	v_pk_fma_f32 v[118:119], v[188:189], s[58:59], v[130:131] op_sel_hi:[1,0,0]
	s_waitcnt vmcnt(5)
	v_pk_fma_f32 v[138:139], v[190:191], s[58:59], v[130:131] op_sel_hi:[1,0,0]
	v_mul_f32_e32 v137, 0x4b800000, v118
	v_mul_f32_e32 v140, 0x4b800000, v119
	v_mul_f32_e32 v141, 0x4b800000, v138
	v_mul_f32_e32 v142, 0x4b800000, v139
	v_cmp_gt_f32_e32 vcc, s68, v118
	v_cmp_gt_f32_e64 s[10:11], s68, v119
	v_cmp_gt_f32_e64 s[12:13], s68, v138
	v_cmp_gt_f32_e64 s[14:15], s68, v139
	v_cndmask_b32_e32 v118, v118, v137, vcc
	v_cndmask_b32_e64 v119, v119, v140, s[10:11]
	v_cndmask_b32_e64 v137, v138, v141, s[12:13]
	v_cndmask_b32_e64 v139, v139, v142, s[14:15]
	v_rsq_f32_e32 v118, v118
	v_rsq_f32_e32 v119, v119
	v_rsq_f32_e32 v138, v137
	v_rsq_f32_e32 v139, v139
	v_lshl_add_u64 v[140:141], v[144:145], 0, v[116:117]
	v_pk_mul_f32 v[142:143], v[118:119], s[60:61] op_sel_hi:[1,0]
	v_pk_mul_f32 v[144:145], v[138:139], s[60:61] op_sel_hi:[1,0]
	v_cndmask_b32_e64 v119, v119, v143, s[10:11]
	v_cndmask_b32_e32 v118, v118, v142, vcc
	v_cndmask_b32_e64 v139, v139, v145, s[14:15]
	v_cndmask_b32_e64 v138, v138, v144, s[12:13]
	v_mov_b32_e32 v172, v118
	v_mov_b32_e32 v173, v119
	v_pk_mul_f32 v[108:109], v[108:109], v[118:119]
	v_mov_b32_e32 v174, v138
	v_mov_b32_e32 v175, v139
	v_pk_mul_f32 v[110:111], v[110:111], v[138:139]
	v_cvt_pk_bf16_f32 v108, v108, v109
	v_cvt_pk_bf16_f32 v109, v110, v111
	global_store_dwordx2 v[140:141], v[108:109], off
	s_nop 0
	v_or_b32_e32 v118, 16, v136
	v_ashrrev_i32_e32 v119, 31, v118
	v_lshlrev_b64 v[118:119], 13, v[118:119]
	v_lshl_add_u64 v[118:119], s[64:65], 0, v[118:119]
	s_waitcnt vmcnt(5)
	v_pk_fma_f32 v[108:109], v[192:193], s[58:59], v[130:131] op_sel_hi:[1,0,0]
	v_pk_fma_f32 v[110:111], v[194:195], s[58:59], v[130:131] op_sel_hi:[1,0,0]
	v_mul_f32_e32 v137, 0x4b800000, v108
	v_mul_f32_e32 v138, 0x4b800000, v109
	v_mul_f32_e32 v139, 0x4b800000, v110
	v_mul_f32_e32 v140, 0x4b800000, v111
	v_cmp_gt_f32_e32 vcc, s68, v108
	v_cmp_gt_f32_e64 s[10:11], s68, v109
	v_cmp_gt_f32_e64 s[12:13], s68, v110
	v_cmp_gt_f32_e64 s[14:15], s68, v111
	v_cndmask_b32_e32 v108, v108, v137, vcc
	v_cndmask_b32_e64 v109, v109, v138, s[10:11]
	v_cndmask_b32_e64 v110, v110, v139, s[12:13]
	v_cndmask_b32_e64 v111, v111, v140, s[14:15]
	v_rsq_f32_e32 v108, v108
	v_rsq_f32_e32 v109, v109
	v_rsq_f32_e32 v110, v110
	v_rsq_f32_e32 v111, v111
	v_lshl_add_u64 v[138:139], v[118:119], 0, v[128:129]
	v_pk_mul_f32 v[140:141], v[108:109], s[60:61] op_sel_hi:[1,0]
	v_pk_mul_f32 v[142:143], v[110:111], s[60:61] op_sel_hi:[1,0]
	v_pk_mul_f32 v[108:109], v[112:113], v[160:161]
	v_pk_mul_f32 v[110:111], v[114:115], v[162:163]
	v_cvt_pk_bf16_f32 v108, v108, v109
	v_cvt_pk_bf16_f32 v109, v110, v111
	global_store_dwordx2 v[138:139], v[108:109], off
	s_nop 0
	s_nop 0
	s_waitcnt vmcnt(5)
	v_pk_fma_f32 v[110:111], v[196:197], s[58:59], v[130:131] op_sel_hi:[1,0,0]
	v_mul_f32_e32 v114, 0x4b800000, v110
	v_mul_f32_e32 v115, 0x4b800000, v111
	v_cmp_gt_f32_e64 s[12:13], s68, v110
	v_cmp_gt_f32_e64 s[14:15], s68, v111
	v_cndmask_b32_e64 v110, v110, v114, s[12:13]
	v_cndmask_b32_e64 v111, v111, v115, s[14:15]
	v_rsq_f32_e32 v110, v110
	v_rsq_f32_e32 v111, v111
	v_lshl_add_u64 v[112:113], v[118:119], 0, v[126:127]
	v_pk_mul_f32 v[138:139], v[110:111], s[60:61] op_sel_hi:[1,0]
	v_pk_mul_f32 v[104:105], v[104:105], v[164:165]
	v_pk_mul_f32 v[106:107], v[106:107], v[166:167]
	v_cvt_pk_bf16_f32 v104, v104, v105
	v_cvt_pk_bf16_f32 v105, v106, v107
	global_store_dwordx2 v[112:113], v[104:105], off
	s_nop 0
	v_lshl_add_u64 v[108:109], v[118:119], 0, v[122:123]
	v_pk_mul_f32 v[100:101], v[100:101], v[168:169]
	v_pk_mul_f32 v[102:103], v[102:103], v[170:171]
	v_cvt_pk_bf16_f32 v100, v100, v101
	v_cvt_pk_bf16_f32 v101, v102, v103
	global_store_dwordx2 v[108:109], v[100:101], off
	s_nop 0
	v_lshl_add_u64 v[104:105], v[118:119], 0, v[116:117]
	v_pk_mul_f32 v[92:93], v[92:93], v[172:173]
	v_pk_mul_f32 v[94:95], v[94:95], v[174:175]
	v_cvt_pk_bf16_f32 v92, v92, v93
	v_cvt_pk_bf16_f32 v93, v94, v95
	global_store_dwordx2 v[104:105], v[92:93], off
	v_or_b32_e32 v100, 32, v136
	v_ashrrev_i32_e32 v101, 31, v100
	v_lshlrev_b64 v[100:101], 13, v[100:101]
	v_lshl_add_u64 v[100:101], s[64:65], 0, v[100:101]
	v_lshl_add_u64 v[102:103], v[100:101], 0, v[128:129]
	v_pk_mul_f32 v[92:93], v[96:97], v[160:161]
	v_pk_mul_f32 v[94:95], v[98:99], v[162:163]
	v_cvt_pk_bf16_f32 v92, v92, v93
	v_cvt_pk_bf16_f32 v93, v94, v95
	global_store_dwordx2 v[102:103], v[92:93], off
	s_nop 0
	v_lshl_add_u64 v[96:97], v[100:101], 0, v[126:127]
	v_pk_mul_f32 v[88:89], v[88:89], v[164:165]
	v_pk_mul_f32 v[90:91], v[90:91], v[166:167]
	v_cvt_pk_bf16_f32 v88, v88, v89
	v_cvt_pk_bf16_f32 v89, v90, v91
	global_store_dwordx2 v[96:97], v[88:89], off
	s_nop 0
	v_lshl_add_u64 v[92:93], v[100:101], 0, v[122:123]
	v_pk_mul_f32 v[84:85], v[84:85], v[168:169]
	v_pk_mul_f32 v[86:87], v[86:87], v[170:171]
	v_cvt_pk_bf16_f32 v84, v84, v85
	v_cvt_pk_bf16_f32 v85, v86, v87
	global_store_dwordx2 v[92:93], v[84:85], off
	s_nop 0
	v_lshl_add_u64 v[88:89], v[100:101], 0, v[116:117]
	v_pk_mul_f32 v[76:77], v[76:77], v[172:173]
	v_pk_mul_f32 v[78:79], v[78:79], v[174:175]
	v_cvt_pk_bf16_f32 v76, v76, v77
	v_cvt_pk_bf16_f32 v77, v78, v79
	global_store_dwordx2 v[88:89], v[76:77], off
	v_or_b32_e32 v84, 48, v136
	v_ashrrev_i32_e32 v85, 31, v84
	v_lshlrev_b64 v[84:85], 13, v[84:85]
	v_lshl_add_u64 v[84:85], s[64:65], 0, v[84:85]
	v_lshl_add_u64 v[86:87], v[84:85], 0, v[128:129]
	v_pk_mul_f32 v[76:77], v[80:81], v[160:161]
	v_pk_mul_f32 v[78:79], v[82:83], v[162:163]
	v_cvt_pk_bf16_f32 v76, v76, v77
	v_cvt_pk_bf16_f32 v77, v78, v79
	global_store_dwordx2 v[86:87], v[76:77], off
; DI u32x2 pack4(float a, float b, float c, float d) { u32x2 r; r.x = pack2(a, b); r.y = pack2(c, d); return r; }
; #define EPI_END if (i == 3 && (j & 3) == 3) __builtin_amdgcn_sched_barrier(0); }
; DI float rstd_of(const float* ssq, int m, float invn) { return rsqrtf(ssq[m] * invn + 1e-6f); }
; template <int MODE>
; DI void gemm_phase(const Params& p, const GP& g, unsigned char* smem) {
;     ...
;       if (transposed) {
;         u16* iT = (u16*)g.d3;
;         EPI_TR_BEGIN
;           const int b = m4 >> 12, s = m4 & 4095;
;           *(u32x2*)(iT + ((long)b * 1024 + (n - 3072)) * 4096 + s) =
;               pack4(v[0] * rstd_of(g.ssq_in, m4, 1.f / 1024), v[1] * rstd_of(g.ssq_in, m4 + 1, 1.f / 1024),
;                     v[2] * rstd_of(g.ssq_in, m4 + 2, 1.f / 1024), v[3] * rstd_of(g.ssq_in, m4 + 3, 1.f / 1024));
;         EPI_END
	s_nop 0
	v_lshl_add_u64 v[80:81], v[84:85], 0, v[126:127]
	v_pk_mul_f32 v[72:73], v[72:73], v[164:165]
	v_pk_mul_f32 v[74:75], v[74:75], v[166:167]
	v_cvt_pk_bf16_f32 v72, v72, v73
	v_cvt_pk_bf16_f32 v73, v74, v75
	global_store_dwordx2 v[80:81], v[72:73], off
	s_nop 0
	v_lshl_add_u64 v[76:77], v[84:85], 0, v[122:123]
	v_pk_mul_f32 v[68:69], v[68:69], v[168:169]
	v_pk_mul_f32 v[70:71], v[70:71], v[170:171]
	v_cvt_pk_bf16_f32 v68, v68, v69
	v_cvt_pk_bf16_f32 v69, v70, v71
	global_store_dwordx2 v[76:77], v[68:69], off
	s_nop 0
	s_nop 0
	v_pk_mul_f32 v[60:61], v[60:61], v[172:173]
	v_pk_mul_f32 v[62:63], v[62:63], v[174:175]
	v_cvt_pk_bf16_f32 v60, v60, v61
	v_cvt_pk_bf16_f32 v61, v62, v63
	v_lshl_add_u64 v[62:63], v[84:85], 0, v[116:117]
	global_store_dwordx2 v[62:63], v[60:61], off
	v_or_b32_e32 v68, 64, v136
	v_ashrrev_i32_e32 v69, 31, v68
	v_lshlrev_b64 v[68:69], 13, v[68:69]
	v_lshl_add_u64 v[68:69], s[64:65], 0, v[68:69]
	v_lshl_add_u64 v[70:71], v[68:69], 0, v[128:129]
	v_pk_mul_f32 v[60:61], v[64:65], v[160:161]
	v_pk_mul_f32 v[62:63], v[66:67], v[162:163]
	v_cvt_pk_bf16_f32 v60, v60, v61
	v_cvt_pk_bf16_f32 v61, v62, v63
	global_store_dwordx2 v[70:71], v[60:61], off
	s_nop 0
	v_lshl_add_u64 v[64:65], v[68:69], 0, v[126:127]
	v_pk_mul_f32 v[56:57], v[56:57], v[164:165]
	v_pk_mul_f32 v[58:59], v[58:59], v[166:167]
	v_cvt_pk_bf16_f32 v56, v56, v57
	v_cvt_pk_bf16_f32 v57, v58, v59
	global_store_dwordx2 v[64:65], v[56:57], off
	s_nop 0
	v_lshl_add_u64 v[60:61], v[68:69], 0, v[122:123]
	v_pk_mul_f32 v[52:53], v[52:53], v[168:169]
	v_pk_mul_f32 v[54:55], v[54:55], v[170:171]
	v_cvt_pk_bf16_f32 v52, v52, v53
	v_cvt_pk_bf16_f32 v53, v54, v55
	global_store_dwordx2 v[60:61], v[52:53], off
	s_nop 0
	v_lshl_add_u64 v[56:57], v[68:69], 0, v[116:117]
	v_pk_mul_f32 v[44:45], v[44:45], v[172:173]
	v_pk_mul_f32 v[46:47], v[46:47], v[174:175]
	v_cvt_pk_bf16_f32 v44, v44, v45
	v_cvt_pk_bf16_f32 v45, v46, v47
	global_store_dwordx2 v[56:57], v[44:45], off
	v_or_b32_e32 v52, 0x50, v136
	v_ashrrev_i32_e32 v53, 31, v52
	v_lshlrev_b64 v[52:53], 13, v[52:53]
	v_lshl_add_u64 v[52:53], s[64:65], 0, v[52:53]
	v_lshl_add_u64 v[54:55], v[52:53], 0, v[128:129]
	v_pk_mul_f32 v[44:45], v[48:49], v[160:161]
	v_pk_mul_f32 v[46:47], v[50:51], v[162:163]
	v_cvt_pk_bf16_f32 v44, v44, v45
	v_cvt_pk_bf16_f32 v45, v46, v47
	global_store_dwordx2 v[54:55], v[44:45], off
	s_nop 0
	v_lshl_add_u64 v[48:49], v[52:53], 0, v[126:127]
	v_pk_mul_f32 v[40:41], v[40:41], v[164:165]
	v_pk_mul_f32 v[42:43], v[42:43], v[166:167]
	v_cvt_pk_bf16_f32 v40, v40, v41
	v_cvt_pk_bf16_f32 v41, v42, v43
	global_store_dwordx2 v[48:49], v[40:41], off
	s_nop 0
	v_lshl_add_u64 v[44:45], v[52:53], 0, v[122:123]
	v_pk_mul_f32 v[36:37], v[36:37], v[168:169]
	v_pk_mul_f32 v[38:39], v[38:39], v[170:171]
	v_cvt_pk_bf16_f32 v36, v36, v37
	v_cvt_pk_bf16_f32 v37, v38, v39
	global_store_dwordx2 v[44:45], v[36:37], off
	s_nop 0
	v_lshl_add_u64 v[40:41], v[52:53], 0, v[116:117]
	v_pk_mul_f32 v[28:29], v[28:29], v[172:173]
	v_pk_mul_f32 v[30:31], v[30:31], v[174:175]
	v_cvt_pk_bf16_f32 v28, v28, v29
	v_cvt_pk_bf16_f32 v29, v30, v31
	global_store_dwordx2 v[40:41], v[28:29], off
	v_or_b32_e32 v36, 0x60, v136
	v_ashrrev_i32_e32 v37, 31, v36
	v_lshlrev_b64 v[36:37], 13, v[36:37]
	v_lshl_add_u64 v[36:37], s[64:65], 0, v[36:37]
	v_lshl_add_u64 v[38:39], v[36:37], 0, v[128:129]
	v_pk_mul_f32 v[28:29], v[32:33], v[160:161]
	v_pk_mul_f32 v[30:31], v[34:35], v[162:163]
	v_cvt_pk_bf16_f32 v28, v28, v29
	v_cvt_pk_bf16_f32 v29, v30, v31
	global_store_dwordx2 v[38:39], v[28:29], off
	s_nop 0
	v_lshl_add_u64 v[32:33], v[36:37], 0, v[126:127]
	v_pk_mul_f32 v[24:25], v[24:25], v[164:165]
	v_pk_mul_f32 v[26:27], v[26:27], v[166:167]
	v_cvt_pk_bf16_f32 v24, v24, v25
	v_cvt_pk_bf16_f32 v25, v26, v27
	global_store_dwordx2 v[32:33], v[24:25], off
	s_nop 0
	v_lshl_add_u64 v[28:29], v[36:37], 0, v[122:123]
	v_pk_mul_f32 v[20:21], v[20:21], v[168:169]
	v_pk_mul_f32 v[22:23], v[22:23], v[170:171]
	v_cvt_pk_bf16_f32 v20, v20, v21
	v_cvt_pk_bf16_f32 v21, v22, v23
	global_store_dwordx2 v[28:29], v[20:21], off
	s_nop 0
	v_lshl_add_u64 v[24:25], v[36:37], 0, v[116:117]
	v_pk_mul_f32 v[12:13], v[12:13], v[172:173]
	v_pk_mul_f32 v[14:15], v[14:15], v[174:175]
	v_cvt_pk_bf16_f32 v12, v12, v13
	v_cvt_pk_bf16_f32 v13, v14, v15
	global_store_dwordx2 v[24:25], v[12:13], off
	v_or_b32_e32 v20, 0x70, v136
	v_ashrrev_i32_e32 v21, 31, v20
	v_lshlrev_b64 v[20:21], 13, v[20:21]
	v_lshl_add_u64 v[20:21], s[64:65], 0, v[20:21]
	v_lshl_add_u64 v[22:23], v[20:21], 0, v[128:129]
	v_pk_mul_f32 v[12:13], v[16:17], v[160:161]
	v_pk_mul_f32 v[14:15], v[18:19], v[162:163]
	v_cvt_pk_bf16_f32 v12, v12, v13
	v_cvt_pk_bf16_f32 v13, v14, v15
	global_store_dwordx2 v[22:23], v[12:13], off
	s_nop 0
	v_lshl_add_u64 v[16:17], v[20:21], 0, v[126:127]
	v_pk_mul_f32 v[4:5], v[4:5], v[164:165]
	v_pk_mul_f32 v[6:7], v[6:7], v[166:167]
	v_cvt_pk_bf16_f32 v4, v4, v5
	v_cvt_pk_bf16_f32 v5, v6, v7
	global_store_dwordx2 v[16:17], v[4:5], off
	s_nop 0
	v_lshl_add_u64 v[12:13], v[20:21], 0, v[122:123]
	v_pk_mul_f32 v[0:1], v[0:1], v[168:169]
	v_pk_mul_f32 v[2:3], v[2:3], v[170:171]
	v_cvt_pk_bf16_f32 v0, v0, v1
	v_cvt_pk_bf16_f32 v1, v2, v3
	global_store_dwordx2 v[12:13], v[0:1], off
	s_nop 0
	s_nop 0
	s_nop 0
	s_waitcnt vmcnt(30)
	v_pk_fma_f32 v[0:1], v[198:199], s[58:59], v[130:131] op_sel_hi:[1,0,0]
	s_waitcnt vmcnt(29)
	v_pk_fma_f32 v[2:3], v[200:201], s[58:59], v[130:131] op_sel_hi:[1,0,0]
	v_cmp_gt_f32_e32 vcc, s68, v0
	v_cmp_gt_f32_e64 s[10:11], s68, v1
	v_cmp_gt_f32_e64 s[12:13], s68, v2
	v_cmp_gt_f32_e64 s[14:15], s68, v3
	s_nop 0
	v_pk_mul_f32 v[0:1], v[8:9], v[172:173]
	v_pk_mul_f32 v[2:3], v[10:11], v[174:175]
	v_cvt_pk_bf16_f32 v0, v0, v1
	v_cvt_pk_bf16_f32 v1, v2, v3
	v_lshl_add_u64 v[2:3], v[20:21], 0, v[116:117]
	global_store_dwordx2 v[2:3], v[0:1], off
	s_branch .LBB0_559

; DI float bflo(unsigned u) { return __uint_as_float(u << 16); }
; DI float bfhi(unsigned u) { return __uint_as_float(u & 0xffff0000u); }
; DI float silu(float v) { return v * __builtin_amdgcn_rcpf(1.f + __expf(-v)); }
; DI u32x2 pack4(float a, float b, float c, float d) { u32x2 r; r.x = pack2(a, b); r.y = pack2(c, d); return r; }
; #define EPI_END if (i == 3 && (j & 3) == 3) __builtin_amdgcn_sched_barrier(0); }
; DI float rstd_of(const float* ssq, int m, float invn) { return rsqrtf(ssq[m] * invn + 1e-6f); }
; template <int MODE>
; DI void gemm_phase(const Params& p, const GP& g, unsigned char* smem) {
;     ...
;     } else if (MODE == M_ZPASS) {
;       u16* og = (u16*)g.d0;
;       EPI_STD_BEGIN
;         const float rs = rstd_of(g.ssq_in, m, 1.f / 1024);
;         u32x2* op = (u32x2*)(og + (long)m * 1024 + n4);
;         const u32x2 ov = *op;
;         *op = pack4(bflo(ov.x) * silu(v[0] * rs), bfhi(ov.x) * silu(v[1] * rs), bflo(ov.y) * silu(v[2] * rs), bfhi(ov.y) * silu(v[3] * rs));
;       EPI_END
.LBB0_638:
	v_or_b32_e32 v132, s22, v147
	v_ashrrev_i32_e32 v133, 31, v132
	v_lshl_add_u64 v[136:137], v[132:133], 2, s[12:13]
	global_load_dword v128, v[136:137], off
	v_add_u32_e32 v130, s6, v146
	v_ashrrev_i32_e32 v131, 31, v130
	v_lshlrev_b64 v[134:135], 11, v[132:133]
	v_lshlrev_b64 v[130:131], 1, v[130:131]
	v_lshl_add_u64 v[134:135], s[36:37], 0, v[134:135]
	v_lshl_add_u64 v[134:135], v[134:135], 0, v[130:131]
	global_load_dwordx2 v[138:139], v[134:135], off
	global_load_dwordx2 v[140:141], v[134:135], off offset:32
	global_load_dwordx2 v[142:143], v[134:135], off offset:64
	global_load_dwordx2 v[144:145], v[134:135], off offset:96
	s_waitcnt vmcnt(4)
	v_fmamk_f32 v128, v128, 0x3a800000, v148
	v_mul_f32_e32 v133, 0x4b800000, v128
	v_cmp_gt_f32_e32 vcc, s26, v128
	s_waitcnt vmcnt(3)
	v_lshlrev_b32_e32 v150, 16, v138
	v_cndmask_b32_e32 v128, v128, v133, vcc
	v_rsq_f32_e32 v128, v128
	v_and_b32_e32 v151, 0xffff0000, v138
	v_mul_f32_e32 v133, 0x45800000, v128
	v_cndmask_b32_e32 v128, v128, v133, vcc
	v_mov_b32_e32 v156, v128
	v_pk_mul_f32 v[124:125], v[124:125], v[128:129] op_sel_hi:[1,0]
	v_pk_mul_f32 v[126:127], v[126:127], v[156:157] op_sel_hi:[1,0]
	v_mul_f32_e32 v128, 0xbfb8aa3b, v124
	v_mul_f32_e32 v133, 0xbfb8aa3b, v125
	v_mul_f32_e32 v138, 0xbfb8aa3b, v126
	v_mul_f32_e32 v149, 0xbfb8aa3b, v127
	v_exp_f32_e32 v128, v128
	v_exp_f32_e32 v133, v133
	v_exp_f32_e32 v138, v138
	v_exp_f32_e32 v149, v149
	v_add_f32_e32 v128, 1.0, v128
	v_add_f32_e32 v133, 1.0, v133
	v_add_f32_e32 v138, 1.0, v138
	v_add_f32_e32 v149, 1.0, v149
	v_rcp_f32_e32 v152, v128
	v_rcp_f32_e32 v153, v133
	v_rcp_f32_e32 v154, v138
	v_rcp_f32_e32 v155, v149
	v_lshlrev_b32_e32 v138, 16, v139
	v_and_b32_e32 v139, 0xffff0000, v139
	v_pk_mul_f32 v[124:125], v[124:125], v[152:153]
	v_pk_mul_f32 v[126:127], v[126:127], v[154:155]
	v_pk_mul_f32 v[124:125], v[124:125], v[150:151]
	v_pk_mul_f32 v[126:127], v[126:127], v[138:139]
	v_cvt_pk_bf16_f32 v124, v124, v125
	v_cvt_pk_bf16_f32 v125, v126, v127
	global_store_dwordx2 v[134:135], v[124:125], off
	s_nop 1
	s_waitcnt vmcnt(3)
	v_lshlrev_b32_e32 v124, 16, v140
	v_and_b32_e32 v125, 0xffff0000, v140
	v_lshlrev_b32_e32 v140, 16, v141
	v_pk_mul_f32 v[120:121], v[120:121], v[156:157] op_sel_hi:[1,0]
	v_pk_mul_f32 v[122:123], v[122:123], v[156:157] op_sel_hi:[1,0]
	v_mul_f32_e32 v126, 0xbfb8aa3b, v120
	v_mul_f32_e32 v127, 0xbfb8aa3b, v121
	v_mul_f32_e32 v128, 0xbfb8aa3b, v122
	v_mul_f32_e32 v133, 0xbfb8aa3b, v123
	v_exp_f32_e32 v126, v126
	v_exp_f32_e32 v127, v127
	v_exp_f32_e32 v128, v128
	v_exp_f32_e32 v133, v133
	v_add_f32_e32 v126, 1.0, v126
	v_add_f32_e32 v127, 1.0, v127
	v_add_f32_e32 v128, 1.0, v128
	v_add_f32_e32 v133, 1.0, v133
	v_rcp_f32_e32 v126, v126
	v_rcp_f32_e32 v127, v127
	v_rcp_f32_e32 v138, v128
	v_rcp_f32_e32 v139, v133
	v_and_b32_e32 v141, 0xffff0000, v141
	v_pk_mul_f32 v[120:121], v[120:121], v[126:127]
	s_waitcnt vmcnt(2)
	v_lshlrev_b32_e32 v126, 16, v143
	v_pk_mul_f32 v[122:123], v[122:123], v[138:139]
	v_pk_mul_f32 v[120:121], v[120:121], v[124:125]
	v_pk_mul_f32 v[122:123], v[122:123], v[140:141]
	v_cvt_pk_bf16_f32 v120, v120, v121
	v_cvt_pk_bf16_f32 v121, v122, v123
	global_store_dwordx2 v[134:135], v[120:121], off offset:32
	v_and_b32_e32 v127, 0xffff0000, v143
	s_nop 1
	v_lshlrev_b32_e32 v120, 16, v142
	v_and_b32_e32 v121, 0xffff0000, v142
	v_pk_mul_f32 v[116:117], v[116:117], v[156:157] op_sel_hi:[1,0]
	v_pk_mul_f32 v[118:119], v[118:119], v[156:157] op_sel_hi:[1,0]
	v_mul_f32_e32 v122, 0xbfb8aa3b, v116
	v_mul_f32_e32 v123, 0xbfb8aa3b, v117
	v_mul_f32_e32 v124, 0xbfb8aa3b, v118
	v_mul_f32_e32 v125, 0xbfb8aa3b, v119
	v_exp_f32_e32 v122, v122
	v_exp_f32_e32 v123, v123
	v_exp_f32_e32 v124, v124
	v_exp_f32_e32 v125, v125
	v_add_f32_e32 v122, 1.0, v122
	v_add_f32_e32 v123, 1.0, v123
	v_add_f32_e32 v124, 1.0, v124
	v_add_f32_e32 v125, 1.0, v125
	v_rcp_f32_e32 v122, v122
	v_rcp_f32_e32 v123, v123
	v_rcp_f32_e32 v124, v124
	v_rcp_f32_e32 v125, v125
	v_pk_mul_f32 v[116:117], v[116:117], v[122:123]
	s_nop 0
	v_pk_mul_f32 v[116:117], v[116:117], v[120:121]
	v_pk_mul_f32 v[118:119], v[118:119], v[124:125]
	v_cvt_pk_bf16_f32 v116, v116, v117
	v_pk_mul_f32 v[118:119], v[118:119], v[126:127]
	s_waitcnt vmcnt(2)
	v_lshlrev_b32_e32 v120, 16, v144
	v_cvt_pk_bf16_f32 v117, v118, v119
	global_store_dwordx2 v[134:135], v[116:117], off offset:64
	v_and_b32_e32 v121, 0xffff0000, v144
	v_lshlrev_b32_e32 v126, 16, v145
	v_and_b32_e32 v127, 0xffff0000, v145
	v_or_b32_e32 v118, 16, v132
	v_ashrrev_i32_e32 v119, 31, v118
	s_nop 1
	v_lshl_add_u64 v[116:117], v[118:119], 2, s[12:13]
	v_pk_mul_f32 v[112:113], v[112:113], v[156:157] op_sel_hi:[1,0]
	v_pk_mul_f32 v[114:115], v[114:115], v[156:157] op_sel_hi:[1,0]
	v_mul_f32_e32 v122, 0xbfb8aa3b, v112
	v_mul_f32_e32 v123, 0xbfb8aa3b, v113
	v_mul_f32_e32 v124, 0xbfb8aa3b, v114
	v_mul_f32_e32 v125, 0xbfb8aa3b, v115
	v_exp_f32_e32 v122, v122
	v_exp_f32_e32 v123, v123
	v_exp_f32_e32 v124, v124
	v_exp_f32_e32 v125, v125
	v_add_f32_e32 v122, 1.0, v122
	v_add_f32_e32 v123, 1.0, v123
	v_add_f32_e32 v124, 1.0, v124
	v_add_f32_e32 v125, 1.0, v125
	v_rcp_f32_e32 v122, v122
	v_rcp_f32_e32 v123, v123
	v_rcp_f32_e32 v124, v124
	v_rcp_f32_e32 v125, v125
	v_pk_mul_f32 v[112:113], v[112:113], v[122:123]
	s_nop 0
	v_pk_mul_f32 v[112:113], v[112:113], v[120:121]
	global_load_dword v120, v[116:117], off
	v_pk_mul_f32 v[114:115], v[114:115], v[124:125]
	v_cvt_pk_bf16_f32 v112, v112, v113
	v_pk_mul_f32 v[114:115], v[114:115], v[126:127]
	s_nop 0
	v_cvt_pk_bf16_f32 v113, v114, v115
	global_store_dwordx2 v[134:135], v[112:113], off offset:96
	s_nop 0
	v_lshlrev_b64 v[112:113], 11, v[118:119]
	v_lshl_add_u64 v[112:113], s[36:37], 0, v[112:113]
	v_lshl_add_u64 v[112:113], v[112:113], 0, v[130:131]
	global_load_dwordx2 v[114:115], v[112:113], off
	global_load_dwordx2 v[184:185], v[112:113], off offset:32
	global_load_dwordx2 v[186:187], v[112:113], off offset:64
	global_load_dwordx2 v[122:123], v[112:113], off offset:96
	s_waitcnt vmcnt(5)
; DI float bflo(unsigned u) { return __uint_as_float(u << 16); }
; DI float bfhi(unsigned u) { return __uint_as_float(u & 0xffff0000u); }
; DI float silu(float v) { return v * __builtin_amdgcn_rcpf(1.f + __expf(-v)); }
; DI u32x2 pack4(float a, float b, float c, float d) { u32x2 r; r.x = pack2(a, b); r.y = pack2(c, d); return r; }
; #define EPI_END if (i == 3 && (j & 3) == 3) __builtin_amdgcn_sched_barrier(0); }
; DI float rstd_of(const float* ssq, int m, float invn) { return rsqrtf(ssq[m] * invn + 1e-6f); }
; template <int MODE>
; DI void gemm_phase(const Params& p, const GP& g, unsigned char* smem) {
;     ...
;     } else if (MODE == M_ZPASS) {
;       u16* og = (u16*)g.d0;
;       EPI_STD_BEGIN
;         const float rs = rstd_of(g.ssq_in, m, 1.f / 1024);
;         u32x2* op = (u32x2*)(og + (long)m * 1024 + n4);
;         const u32x2 ov = *op;
;         *op = pack4(bflo(ov.x) * silu(v[0] * rs), bfhi(ov.x) * silu(v[1] * rs), bflo(ov.y) * silu(v[2] * rs), bfhi(ov.y) * silu(v[3] * rs));
;       EPI_END
	v_fmamk_f32 v118, v120, 0x3a800000, v148
	v_mul_f32_e32 v119, 0x4b800000, v118
	v_cmp_gt_f32_e32 vcc, s26, v118
	s_waitcnt vmcnt(3)
	v_lshlrev_b32_e32 v124, 16, v114
	v_cndmask_b32_e32 v118, v118, v119, vcc
	v_rsq_f32_e32 v126, v118
	v_and_b32_e32 v125, 0xffff0000, v114
	s_nop 0
	s_nop 0
	s_nop 0
	v_mul_f32_e32 v114, 0x45800000, v126
	v_cndmask_b32_e32 v114, v126, v114, vcc
	v_mov_b32_e32 v158, v114
	v_pk_mul_f32 v[108:109], v[108:109], v[114:115] op_sel_hi:[1,0]
	v_pk_mul_f32 v[110:111], v[110:111], v[158:159] op_sel_hi:[1,0]
	v_mul_f32_e32 v114, 0xbfb8aa3b, v108
	v_mul_f32_e32 v126, 0xbfb8aa3b, v109
	v_mul_f32_e32 v127, 0xbfb8aa3b, v110
	v_mul_f32_e32 v128, 0xbfb8aa3b, v111
	v_exp_f32_e32 v114, v114
	v_exp_f32_e32 v126, v126
	v_exp_f32_e32 v127, v127
	v_exp_f32_e32 v128, v128
	v_add_f32_e32 v114, 1.0, v114
	v_add_f32_e32 v133, 1.0, v126
	v_add_f32_e32 v134, 1.0, v127
	v_add_f32_e32 v128, 1.0, v128
	v_rcp_f32_e32 v126, v114
	v_rcp_f32_e32 v127, v133
	v_rcp_f32_e32 v134, v134
	v_rcp_f32_e32 v135, v128
	v_lshlrev_b32_e32 v114, 16, v115
	v_and_b32_e32 v115, 0xffff0000, v115
	v_pk_mul_f32 v[108:109], v[108:109], v[126:127]
	v_pk_mul_f32 v[110:111], v[110:111], v[134:135]
	v_pk_mul_f32 v[108:109], v[108:109], v[124:125]
	v_pk_mul_f32 v[110:111], v[110:111], v[114:115]
	v_cvt_pk_bf16_f32 v108, v108, v109
	v_cvt_pk_bf16_f32 v109, v110, v111
	global_store_dwordx2 v[112:113], v[108:109], off
	s_nop 1
	s_waitcnt vmcnt(3)
	v_lshlrev_b32_e32 v108, 16, v184
	v_and_b32_e32 v109, 0xffff0000, v184
	v_lshlrev_b32_e32 v118, 16, v185
	v_pk_mul_f32 v[104:105], v[104:105], v[158:159] op_sel_hi:[1,0]
	v_pk_mul_f32 v[106:107], v[106:107], v[158:159] op_sel_hi:[1,0]
	v_mul_f32_e32 v110, 0xbfb8aa3b, v104
	v_mul_f32_e32 v111, 0xbfb8aa3b, v105
	v_mul_f32_e32 v114, 0xbfb8aa3b, v106
	v_mul_f32_e32 v115, 0xbfb8aa3b, v107
	v_exp_f32_e32 v110, v110
	v_exp_f32_e32 v111, v111
	v_exp_f32_e32 v114, v114
	v_exp_f32_e32 v115, v115
	v_add_f32_e32 v110, 1.0, v110
	v_add_f32_e32 v111, 1.0, v111
	v_add_f32_e32 v114, 1.0, v114
	v_add_f32_e32 v115, 1.0, v115
	v_rcp_f32_e32 v110, v110
	v_rcp_f32_e32 v111, v111
	v_rcp_f32_e32 v114, v114
	v_rcp_f32_e32 v115, v115
	v_and_b32_e32 v119, 0xffff0000, v185
	v_pk_mul_f32 v[104:105], v[104:105], v[110:111]
	s_waitcnt vmcnt(2)
	v_lshlrev_b32_e32 v110, 16, v187
	v_pk_mul_f32 v[106:107], v[106:107], v[114:115]
	v_pk_mul_f32 v[104:105], v[104:105], v[108:109]
	v_pk_mul_f32 v[106:107], v[106:107], v[118:119]
	v_cvt_pk_bf16_f32 v104, v104, v105
	v_cvt_pk_bf16_f32 v105, v106, v107
	global_store_dwordx2 v[112:113], v[104:105], off offset:32
	v_and_b32_e32 v111, 0xffff0000, v187
	s_nop 1
	v_lshlrev_b32_e32 v104, 16, v186
	v_and_b32_e32 v105, 0xffff0000, v186
	v_pk_mul_f32 v[100:101], v[100:101], v[158:159] op_sel_hi:[1,0]
	v_pk_mul_f32 v[102:103], v[102:103], v[158:159] op_sel_hi:[1,0]
	v_mul_f32_e32 v106, 0xbfb8aa3b, v100
	v_mul_f32_e32 v107, 0xbfb8aa3b, v101
	v_mul_f32_e32 v108, 0xbfb8aa3b, v102
	v_mul_f32_e32 v109, 0xbfb8aa3b, v103
	v_exp_f32_e32 v106, v106
	v_exp_f32_e32 v107, v107
	v_exp_f32_e32 v108, v108
	v_exp_f32_e32 v109, v109
	v_add_f32_e32 v106, 1.0, v106
	v_add_f32_e32 v107, 1.0, v107
	v_add_f32_e32 v108, 1.0, v108
	v_add_f32_e32 v109, 1.0, v109
	v_rcp_f32_e32 v106, v106
	v_rcp_f32_e32 v107, v107
	v_rcp_f32_e32 v108, v108
	v_rcp_f32_e32 v109, v109
	v_pk_mul_f32 v[100:101], v[100:101], v[106:107]
	s_nop 0
	v_pk_mul_f32 v[100:101], v[100:101], v[104:105]
	v_pk_mul_f32 v[102:103], v[102:103], v[108:109]
	v_cvt_pk_bf16_f32 v100, v100, v101
	v_pk_mul_f32 v[102:103], v[102:103], v[110:111]
	s_waitcnt vmcnt(2)
	v_lshlrev_b32_e32 v104, 16, v122
	v_cvt_pk_bf16_f32 v101, v102, v103
	global_store_dwordx2 v[112:113], v[100:101], off offset:64
	v_and_b32_e32 v105, 0xffff0000, v122
	v_lshlrev_b32_e32 v110, 16, v123
	v_and_b32_e32 v111, 0xffff0000, v123
	v_or_b32_e32 v102, 32, v132
	v_ashrrev_i32_e32 v103, 31, v102
	s_nop 1
	v_lshl_add_u64 v[100:101], v[102:103], 2, s[12:13]
	v_pk_mul_f32 v[96:97], v[96:97], v[158:159] op_sel_hi:[1,0]
	v_pk_mul_f32 v[98:99], v[98:99], v[158:159] op_sel_hi:[1,0]
	v_mul_f32_e32 v106, 0xbfb8aa3b, v96
	v_mul_f32_e32 v107, 0xbfb8aa3b, v97
	v_mul_f32_e32 v108, 0xbfb8aa3b, v98
	v_mul_f32_e32 v109, 0xbfb8aa3b, v99
	v_exp_f32_e32 v106, v106
	v_exp_f32_e32 v107, v107
	v_exp_f32_e32 v108, v108
	v_exp_f32_e32 v109, v109
	v_add_f32_e32 v106, 1.0, v106
	v_add_f32_e32 v107, 1.0, v107
	v_add_f32_e32 v108, 1.0, v108
	v_add_f32_e32 v109, 1.0, v109
	v_rcp_f32_e32 v106, v106
	v_rcp_f32_e32 v107, v107
	v_rcp_f32_e32 v108, v108
	v_rcp_f32_e32 v109, v109
	v_pk_mul_f32 v[96:97], v[96:97], v[106:107]
	s_nop 0
	v_pk_mul_f32 v[96:97], v[96:97], v[104:105]
	global_load_dword v104, v[100:101], off
	v_pk_mul_f32 v[98:99], v[98:99], v[108:109]
	v_cvt_pk_bf16_f32 v96, v96, v97
	v_pk_mul_f32 v[98:99], v[98:99], v[110:111]
	s_nop 0
	v_cvt_pk_bf16_f32 v97, v98, v99
	global_store_dwordx2 v[112:113], v[96:97], off offset:96
	s_nop 0
	v_lshlrev_b64 v[96:97], 11, v[102:103]
	v_lshl_add_u64 v[96:97], s[36:37], 0, v[96:97]
	v_lshl_add_u64 v[96:97], v[96:97], 0, v[130:131]
	global_load_dwordx2 v[98:99], v[96:97], off
	global_load_dwordx2 v[184:185], v[96:97], off offset:32
	global_load_dwordx2 v[186:187], v[96:97], off offset:64
	global_load_dwordx2 v[106:107], v[96:97], off offset:96
	s_waitcnt vmcnt(5)
	v_fmamk_f32 v102, v104, 0x3a800000, v148
	v_mul_f32_e32 v103, 0x4b800000, v102
	v_cmp_gt_f32_e32 vcc, s26, v102
	s_waitcnt vmcnt(3)
; DI float bflo(unsigned u) { return __uint_as_float(u << 16); }
; DI float bfhi(unsigned u) { return __uint_as_float(u & 0xffff0000u); }
; DI float silu(float v) { return v * __builtin_amdgcn_rcpf(1.f + __expf(-v)); }
; DI u32x2 pack4(float a, float b, float c, float d) { u32x2 r; r.x = pack2(a, b); r.y = pack2(c, d); return r; }
; #define EPI_END if (i == 3 && (j & 3) == 3) __builtin_amdgcn_sched_barrier(0); }
; DI float rstd_of(const float* ssq, int m, float invn) { return rsqrtf(ssq[m] * invn + 1e-6f); }
; template <int MODE>
; DI void gemm_phase(const Params& p, const GP& g, unsigned char* smem) {
;     ...
;     } else if (MODE == M_ZPASS) {
;       u16* og = (u16*)g.d0;
;       EPI_STD_BEGIN
;         const float rs = rstd_of(g.ssq_in, m, 1.f / 1024);
;         u32x2* op = (u32x2*)(og + (long)m * 1024 + n4);
;         const u32x2 ov = *op;
;         *op = pack4(bflo(ov.x) * silu(v[0] * rs), bfhi(ov.x) * silu(v[1] * rs), bflo(ov.y) * silu(v[2] * rs), bfhi(ov.y) * silu(v[3] * rs));
;       EPI_END
	v_lshlrev_b32_e32 v108, 16, v98
	v_cndmask_b32_e32 v102, v102, v103, vcc
	v_rsq_f32_e32 v110, v102
	v_and_b32_e32 v109, 0xffff0000, v98
	s_nop 0
	s_nop 0
	s_nop 0
	v_mul_f32_e32 v98, 0x45800000, v110
	v_cndmask_b32_e32 v98, v110, v98, vcc
	v_mov_b32_e32 v160, v98
	v_pk_mul_f32 v[92:93], v[92:93], v[98:99] op_sel_hi:[1,0]
	v_pk_mul_f32 v[94:95], v[94:95], v[160:161] op_sel_hi:[1,0]
	v_mul_f32_e32 v98, 0xbfb8aa3b, v92
	v_mul_f32_e32 v110, 0xbfb8aa3b, v93
	v_mul_f32_e32 v111, 0xbfb8aa3b, v94
	v_mul_f32_e32 v112, 0xbfb8aa3b, v95
	v_exp_f32_e32 v98, v98
	v_exp_f32_e32 v110, v110
	v_exp_f32_e32 v111, v111
	v_exp_f32_e32 v112, v112
	v_add_f32_e32 v98, 1.0, v98
	v_add_f32_e32 v113, 1.0, v110
	v_add_f32_e32 v114, 1.0, v111
	v_add_f32_e32 v115, 1.0, v112
	v_rcp_f32_e32 v110, v98
	v_rcp_f32_e32 v111, v113
	v_rcp_f32_e32 v112, v114
	v_rcp_f32_e32 v113, v115
	v_lshlrev_b32_e32 v98, 16, v99
	v_and_b32_e32 v99, 0xffff0000, v99
	v_pk_mul_f32 v[92:93], v[92:93], v[110:111]
	v_pk_mul_f32 v[94:95], v[94:95], v[112:113]
	v_pk_mul_f32 v[92:93], v[92:93], v[108:109]
	v_pk_mul_f32 v[94:95], v[94:95], v[98:99]
	v_cvt_pk_bf16_f32 v92, v92, v93
	v_cvt_pk_bf16_f32 v93, v94, v95
	global_store_dwordx2 v[96:97], v[92:93], off
	s_nop 1
	s_waitcnt vmcnt(3)
	v_lshlrev_b32_e32 v92, 16, v184
	v_and_b32_e32 v93, 0xffff0000, v184
	v_lshlrev_b32_e32 v102, 16, v185
	v_pk_mul_f32 v[88:89], v[88:89], v[160:161] op_sel_hi:[1,0]
	v_pk_mul_f32 v[90:91], v[90:91], v[160:161] op_sel_hi:[1,0]
	v_mul_f32_e32 v94, 0xbfb8aa3b, v88
	v_mul_f32_e32 v95, 0xbfb8aa3b, v89
	v_mul_f32_e32 v98, 0xbfb8aa3b, v90
	v_mul_f32_e32 v99, 0xbfb8aa3b, v91
	v_exp_f32_e32 v94, v94
	v_exp_f32_e32 v95, v95
	v_exp_f32_e32 v98, v98
	v_exp_f32_e32 v99, v99
	v_add_f32_e32 v94, 1.0, v94
	v_add_f32_e32 v95, 1.0, v95
	v_add_f32_e32 v98, 1.0, v98
	v_add_f32_e32 v99, 1.0, v99
	v_rcp_f32_e32 v94, v94
	v_rcp_f32_e32 v95, v95
	v_rcp_f32_e32 v98, v98
	v_rcp_f32_e32 v99, v99
	v_and_b32_e32 v103, 0xffff0000, v185
	v_pk_mul_f32 v[88:89], v[88:89], v[94:95]
	s_waitcnt vmcnt(2)
	v_lshlrev_b32_e32 v94, 16, v187
	v_pk_mul_f32 v[90:91], v[90:91], v[98:99]
	v_pk_mul_f32 v[88:89], v[88:89], v[92:93]
	v_pk_mul_f32 v[90:91], v[90:91], v[102:103]
	v_cvt_pk_bf16_f32 v88, v88, v89
	v_cvt_pk_bf16_f32 v89, v90, v91
	global_store_dwordx2 v[96:97], v[88:89], off offset:32
	v_and_b32_e32 v95, 0xffff0000, v187
	s_nop 1
	v_lshlrev_b32_e32 v88, 16, v186
	v_and_b32_e32 v89, 0xffff0000, v186
	v_pk_mul_f32 v[84:85], v[84:85], v[160:161] op_sel_hi:[1,0]
	v_pk_mul_f32 v[86:87], v[86:87], v[160:161] op_sel_hi:[1,0]
	v_mul_f32_e32 v90, 0xbfb8aa3b, v84
	v_mul_f32_e32 v91, 0xbfb8aa3b, v85
	v_mul_f32_e32 v92, 0xbfb8aa3b, v86
	v_mul_f32_e32 v93, 0xbfb8aa3b, v87
	v_exp_f32_e32 v90, v90
	v_exp_f32_e32 v91, v91
	v_exp_f32_e32 v92, v92
	v_exp_f32_e32 v93, v93
	v_add_f32_e32 v90, 1.0, v90
	v_add_f32_e32 v91, 1.0, v91
	v_add_f32_e32 v92, 1.0, v92
	v_add_f32_e32 v93, 1.0, v93
	v_rcp_f32_e32 v90, v90
	v_rcp_f32_e32 v91, v91
	v_rcp_f32_e32 v92, v92
	v_rcp_f32_e32 v93, v93
	v_pk_mul_f32 v[84:85], v[84:85], v[90:91]
	s_nop 0
	v_pk_mul_f32 v[84:85], v[84:85], v[88:89]
	v_pk_mul_f32 v[86:87], v[86:87], v[92:93]
	v_cvt_pk_bf16_f32 v84, v84, v85
	v_pk_mul_f32 v[86:87], v[86:87], v[94:95]
	s_waitcnt vmcnt(2)
	v_lshlrev_b32_e32 v88, 16, v106
	v_cvt_pk_bf16_f32 v85, v86, v87
	global_store_dwordx2 v[96:97], v[84:85], off offset:64
	v_and_b32_e32 v89, 0xffff0000, v106
	v_lshlrev_b32_e32 v94, 16, v107
	v_and_b32_e32 v95, 0xffff0000, v107
	v_or_b32_e32 v86, 48, v132
	v_ashrrev_i32_e32 v87, 31, v86
	s_nop 1
	v_lshl_add_u64 v[84:85], v[86:87], 2, s[12:13]
	v_pk_mul_f32 v[80:81], v[80:81], v[160:161] op_sel_hi:[1,0]
	v_pk_mul_f32 v[82:83], v[82:83], v[160:161] op_sel_hi:[1,0]
	v_mul_f32_e32 v90, 0xbfb8aa3b, v80
	v_mul_f32_e32 v91, 0xbfb8aa3b, v81
	v_mul_f32_e32 v92, 0xbfb8aa3b, v82
	v_mul_f32_e32 v93, 0xbfb8aa3b, v83
	v_exp_f32_e32 v90, v90
	v_exp_f32_e32 v91, v91
	v_exp_f32_e32 v92, v92
	v_exp_f32_e32 v93, v93
	v_add_f32_e32 v90, 1.0, v90
	v_add_f32_e32 v91, 1.0, v91
	v_add_f32_e32 v92, 1.0, v92
	v_add_f32_e32 v93, 1.0, v93
	v_rcp_f32_e32 v90, v90
	v_rcp_f32_e32 v91, v91
	v_rcp_f32_e32 v92, v92
	v_rcp_f32_e32 v93, v93
	v_pk_mul_f32 v[80:81], v[80:81], v[90:91]
	s_nop 0
	v_pk_mul_f32 v[80:81], v[80:81], v[88:89]
	global_load_dword v88, v[84:85], off
	v_pk_mul_f32 v[82:83], v[82:83], v[92:93]
	v_cvt_pk_bf16_f32 v80, v80, v81
	v_pk_mul_f32 v[82:83], v[82:83], v[94:95]
	s_nop 0
	v_cvt_pk_bf16_f32 v81, v82, v83
	global_store_dwordx2 v[96:97], v[80:81], off offset:96
	s_nop 0
	v_lshlrev_b64 v[80:81], 11, v[86:87]
	v_lshl_add_u64 v[80:81], s[36:37], 0, v[80:81]
	v_lshl_add_u64 v[80:81], v[80:81], 0, v[130:131]
	global_load_dwordx2 v[82:83], v[80:81], off
	global_load_dwordx2 v[184:185], v[80:81], off offset:32
	global_load_dwordx2 v[186:187], v[80:81], off offset:64
	global_load_dwordx2 v[90:91], v[80:81], off offset:96
	s_waitcnt vmcnt(5)
	v_fmamk_f32 v86, v88, 0x3a800000, v148
	v_mul_f32_e32 v87, 0x4b800000, v86
	v_cmp_gt_f32_e32 vcc, s26, v86
	s_waitcnt vmcnt(3)
	v_lshlrev_b32_e32 v92, 16, v82
	v_cndmask_b32_e32 v86, v86, v87, vcc
	v_rsq_f32_e32 v94, v86
	v_and_b32_e32 v93, 0xffff0000, v82
	s_nop 0
	s_nop 0
	s_nop 0
	v_mul_f32_e32 v82, 0x45800000, v94
	v_cndmask_b32_e32 v82, v94, v82, vcc
	v_mov_b32_e32 v162, v82
	v_pk_mul_f32 v[76:77], v[76:77], v[82:83] op_sel_hi:[1,0]
	v_pk_mul_f32 v[78:79], v[78:79], v[162:163] op_sel_hi:[1,0]
	v_mul_f32_e32 v82, 0xbfb8aa3b, v76
	v_mul_f32_e32 v94, 0xbfb8aa3b, v77
	v_mul_f32_e32 v95, 0xbfb8aa3b, v78
	v_mul_f32_e32 v96, 0xbfb8aa3b, v79
	v_exp_f32_e32 v82, v82
	v_exp_f32_e32 v94, v94
	v_exp_f32_e32 v95, v95
	v_exp_f32_e32 v96, v96
	v_add_f32_e32 v82, 1.0, v82
	v_add_f32_e32 v97, 1.0, v94
	v_add_f32_e32 v98, 1.0, v95
	v_add_f32_e32 v99, 1.0, v96
	v_rcp_f32_e32 v94, v82
	v_rcp_f32_e32 v95, v97
	v_rcp_f32_e32 v96, v98
	v_rcp_f32_e32 v97, v99
	v_lshlrev_b32_e32 v82, 16, v83
	v_and_b32_e32 v83, 0xffff0000, v83
	v_pk_mul_f32 v[76:77], v[76:77], v[94:95]
	v_pk_mul_f32 v[78:79], v[78:79], v[96:97]
	v_pk_mul_f32 v[76:77], v[76:77], v[92:93]
	v_pk_mul_f32 v[78:79], v[78:79], v[82:83]
	v_cvt_pk_bf16_f32 v76, v76, v77
	v_cvt_pk_bf16_f32 v77, v78, v79
	global_store_dwordx2 v[80:81], v[76:77], off
	s_nop 1
	s_waitcnt vmcnt(3)
; DI float bflo(unsigned u) { return __uint_as_float(u << 16); }
; DI float bfhi(unsigned u) { return __uint_as_float(u & 0xffff0000u); }
; DI float silu(float v) { return v * __builtin_amdgcn_rcpf(1.f + __expf(-v)); }
; DI u32x2 pack4(float a, float b, float c, float d) { u32x2 r; r.x = pack2(a, b); r.y = pack2(c, d); return r; }
; #define EPI_END if (i == 3 && (j & 3) == 3) __builtin_amdgcn_sched_barrier(0); }
; DI float rstd_of(const float* ssq, int m, float invn) { return rsqrtf(ssq[m] * invn + 1e-6f); }
; template <int MODE>
; DI void gemm_phase(const Params& p, const GP& g, unsigned char* smem) {
;     ...
;     } else if (MODE == M_ZPASS) {
;       u16* og = (u16*)g.d0;
;       EPI_STD_BEGIN
;         const float rs = rstd_of(g.ssq_in, m, 1.f / 1024);
;         u32x2* op = (u32x2*)(og + (long)m * 1024 + n4);
;         const u32x2 ov = *op;
;         *op = pack4(bflo(ov.x) * silu(v[0] * rs), bfhi(ov.x) * silu(v[1] * rs), bflo(ov.y) * silu(v[2] * rs), bfhi(ov.y) * silu(v[3] * rs));
;       EPI_END
	v_lshlrev_b32_e32 v76, 16, v184
	v_and_b32_e32 v77, 0xffff0000, v184
	v_lshlrev_b32_e32 v86, 16, v185
	v_pk_mul_f32 v[72:73], v[72:73], v[162:163] op_sel_hi:[1,0]
	v_pk_mul_f32 v[74:75], v[74:75], v[162:163] op_sel_hi:[1,0]
	v_mul_f32_e32 v78, 0xbfb8aa3b, v72
	v_mul_f32_e32 v79, 0xbfb8aa3b, v73
	v_mul_f32_e32 v82, 0xbfb8aa3b, v74
	v_mul_f32_e32 v83, 0xbfb8aa3b, v75
	v_exp_f32_e32 v78, v78
	v_exp_f32_e32 v79, v79
	v_exp_f32_e32 v82, v82
	v_exp_f32_e32 v83, v83
	v_add_f32_e32 v78, 1.0, v78
	v_add_f32_e32 v79, 1.0, v79
	v_add_f32_e32 v82, 1.0, v82
	v_add_f32_e32 v83, 1.0, v83
	v_rcp_f32_e32 v78, v78
	v_rcp_f32_e32 v79, v79
	v_rcp_f32_e32 v82, v82
	v_rcp_f32_e32 v83, v83
	v_and_b32_e32 v87, 0xffff0000, v185
	v_pk_mul_f32 v[72:73], v[72:73], v[78:79]
	s_waitcnt vmcnt(2)
	v_lshlrev_b32_e32 v78, 16, v187
	v_pk_mul_f32 v[74:75], v[74:75], v[82:83]
	v_pk_mul_f32 v[72:73], v[72:73], v[76:77]
	v_pk_mul_f32 v[74:75], v[74:75], v[86:87]
	v_cvt_pk_bf16_f32 v72, v72, v73
	v_cvt_pk_bf16_f32 v73, v74, v75
	global_store_dwordx2 v[80:81], v[72:73], off offset:32
	v_and_b32_e32 v79, 0xffff0000, v187
	s_nop 1
	v_lshlrev_b32_e32 v72, 16, v186
	v_and_b32_e32 v73, 0xffff0000, v186
	v_pk_mul_f32 v[68:69], v[68:69], v[162:163] op_sel_hi:[1,0]
	v_pk_mul_f32 v[70:71], v[70:71], v[162:163] op_sel_hi:[1,0]
	v_mul_f32_e32 v74, 0xbfb8aa3b, v68
	v_mul_f32_e32 v75, 0xbfb8aa3b, v69
	v_mul_f32_e32 v76, 0xbfb8aa3b, v70
	v_mul_f32_e32 v77, 0xbfb8aa3b, v71
	v_exp_f32_e32 v74, v74
	v_exp_f32_e32 v75, v75
	v_exp_f32_e32 v76, v76
	v_exp_f32_e32 v77, v77
	v_add_f32_e32 v74, 1.0, v74
	v_add_f32_e32 v75, 1.0, v75
	v_add_f32_e32 v76, 1.0, v76
	v_add_f32_e32 v77, 1.0, v77
	v_rcp_f32_e32 v74, v74
	v_rcp_f32_e32 v75, v75
	v_rcp_f32_e32 v76, v76
	v_rcp_f32_e32 v77, v77
	v_pk_mul_f32 v[68:69], v[68:69], v[74:75]
	s_nop 0
	v_pk_mul_f32 v[68:69], v[68:69], v[72:73]
	v_pk_mul_f32 v[70:71], v[70:71], v[76:77]
	v_cvt_pk_bf16_f32 v68, v68, v69
	v_pk_mul_f32 v[70:71], v[70:71], v[78:79]
	s_waitcnt vmcnt(2)
	v_lshlrev_b32_e32 v74, 16, v91
	v_cvt_pk_bf16_f32 v69, v70, v71
	global_store_dwordx2 v[80:81], v[68:69], off offset:64
	v_and_b32_e32 v75, 0xffff0000, v91
	s_nop 1
	v_lshlrev_b32_e32 v68, 16, v90
	v_and_b32_e32 v69, 0xffff0000, v90
	v_pk_mul_f32 v[64:65], v[64:65], v[162:163] op_sel_hi:[1,0]
	v_pk_mul_f32 v[66:67], v[66:67], v[162:163] op_sel_hi:[1,0]
	v_mul_f32_e32 v70, 0xbfb8aa3b, v64
	v_mul_f32_e32 v71, 0xbfb8aa3b, v65
	v_mul_f32_e32 v72, 0xbfb8aa3b, v66
	v_mul_f32_e32 v73, 0xbfb8aa3b, v67
	v_exp_f32_e32 v70, v70
	v_exp_f32_e32 v71, v71
	v_exp_f32_e32 v72, v72
	v_exp_f32_e32 v73, v73
	v_add_f32_e32 v70, 1.0, v70
	v_add_f32_e32 v71, 1.0, v71
	v_add_f32_e32 v72, 1.0, v72
	v_add_f32_e32 v73, 1.0, v73
	v_rcp_f32_e32 v70, v70
	v_rcp_f32_e32 v71, v71
	v_rcp_f32_e32 v72, v72
	v_rcp_f32_e32 v73, v73
	v_pk_mul_f32 v[64:65], v[64:65], v[70:71]
	s_nop 0
	v_pk_mul_f32 v[64:65], v[64:65], v[68:69]
	v_pk_mul_f32 v[66:67], v[66:67], v[72:73]
	v_cvt_pk_bf16_f32 v64, v64, v65
	v_pk_mul_f32 v[66:67], v[66:67], v[74:75]
	s_nop 0
	v_cvt_pk_bf16_f32 v65, v66, v67
	global_store_dwordx2 v[80:81], v[64:65], off offset:96
	v_or_b32_e32 v64, 64, v132
	v_ashrrev_i32_e32 v65, 31, v64
	v_lshl_add_u64 v[66:67], v[64:65], 2, s[12:13]
	global_load_dword v70, v[66:67], off
	v_lshlrev_b64 v[64:65], 11, v[64:65]
	v_lshl_add_u64 v[64:65], s[36:37], 0, v[64:65]
	v_lshl_add_u64 v[64:65], v[64:65], 0, v[130:131]
	global_load_dwordx2 v[68:69], v[64:65], off
	global_load_dwordx2 v[184:185], v[64:65], off offset:32
	global_load_dwordx2 v[72:73], v[64:65], off offset:64
	global_load_dwordx2 v[74:75], v[64:65], off offset:96
	s_waitcnt vmcnt(4)
	v_fmamk_f32 v70, v70, 0x3a800000, v148
	v_mul_f32_e32 v71, 0x4b800000, v70
	v_cmp_gt_f32_e32 vcc, s26, v70
	s_waitcnt vmcnt(3)
	v_lshlrev_b32_e32 v76, 16, v68
	v_cndmask_b32_e32 v70, v70, v71, vcc
	v_rsq_f32_e32 v78, v70
	v_and_b32_e32 v77, 0xffff0000, v68
	s_nop 0
	s_nop 0
	s_nop 0
	v_mul_f32_e32 v68, 0x45800000, v78
	v_cndmask_b32_e32 v68, v78, v68, vcc
	v_mov_b32_e32 v164, v68
	v_pk_mul_f32 v[60:61], v[60:61], v[68:69] op_sel_hi:[1,0]
	v_pk_mul_f32 v[62:63], v[62:63], v[164:165] op_sel_hi:[1,0]
	v_mul_f32_e32 v68, 0xbfb8aa3b, v60
	v_mul_f32_e32 v78, 0xbfb8aa3b, v61
	v_mul_f32_e32 v79, 0xbfb8aa3b, v62
	v_mul_f32_e32 v80, 0xbfb8aa3b, v63
	v_exp_f32_e32 v68, v68
	v_exp_f32_e32 v78, v78
	v_exp_f32_e32 v79, v79
	v_exp_f32_e32 v80, v80
	v_add_f32_e32 v68, 1.0, v68
	v_add_f32_e32 v81, 1.0, v78
	v_add_f32_e32 v82, 1.0, v79
	v_add_f32_e32 v83, 1.0, v80
	v_rcp_f32_e32 v78, v68
	v_rcp_f32_e32 v79, v81
	v_rcp_f32_e32 v80, v82
	v_rcp_f32_e32 v81, v83
	v_lshlrev_b32_e32 v68, 16, v69
	v_and_b32_e32 v69, 0xffff0000, v69
	v_pk_mul_f32 v[60:61], v[60:61], v[78:79]
	v_pk_mul_f32 v[62:63], v[62:63], v[80:81]
	v_pk_mul_f32 v[60:61], v[60:61], v[76:77]
	v_pk_mul_f32 v[62:63], v[62:63], v[68:69]
	v_cvt_pk_bf16_f32 v60, v60, v61
	v_cvt_pk_bf16_f32 v61, v62, v63
	global_store_dwordx2 v[64:65], v[60:61], off
	s_nop 1
	s_waitcnt vmcnt(3)
	v_lshlrev_b32_e32 v60, 16, v184
	v_and_b32_e32 v61, 0xffff0000, v184
	v_lshlrev_b32_e32 v70, 16, v185
	v_pk_mul_f32 v[56:57], v[56:57], v[164:165] op_sel_hi:[1,0]
	v_pk_mul_f32 v[58:59], v[58:59], v[164:165] op_sel_hi:[1,0]
	v_mul_f32_e32 v62, 0xbfb8aa3b, v56
	v_mul_f32_e32 v63, 0xbfb8aa3b, v57
	v_mul_f32_e32 v68, 0xbfb8aa3b, v58
	v_mul_f32_e32 v69, 0xbfb8aa3b, v59
	v_exp_f32_e32 v62, v62
	v_exp_f32_e32 v63, v63
	v_exp_f32_e32 v68, v68
	v_exp_f32_e32 v69, v69
	v_add_f32_e32 v62, 1.0, v62
	v_add_f32_e32 v63, 1.0, v63
	v_add_f32_e32 v68, 1.0, v68
	v_add_f32_e32 v69, 1.0, v69
	v_rcp_f32_e32 v62, v62
	v_rcp_f32_e32 v63, v63
	v_rcp_f32_e32 v68, v68
	v_rcp_f32_e32 v69, v69
	v_and_b32_e32 v71, 0xffff0000, v185
	v_pk_mul_f32 v[56:57], v[56:57], v[62:63]
	s_waitcnt vmcnt(2)
; DI float bflo(unsigned u) { return __uint_as_float(u << 16); }
; DI float bfhi(unsigned u) { return __uint_as_float(u & 0xffff0000u); }
; DI float silu(float v) { return v * __builtin_amdgcn_rcpf(1.f + __expf(-v)); }
; DI u32x2 pack4(float a, float b, float c, float d) { u32x2 r; r.x = pack2(a, b); r.y = pack2(c, d); return r; }
; #define EPI_END if (i == 3 && (j & 3) == 3) __builtin_amdgcn_sched_barrier(0); }
; DI float rstd_of(const float* ssq, int m, float invn) { return rsqrtf(ssq[m] * invn + 1e-6f); }
; template <int MODE>
; DI void gemm_phase(const Params& p, const GP& g, unsigned char* smem) {
;     ...
;       EPI_STD_BEGIN
;         const float rs = rstd_of(g.ssq_in, m, 1.f / 1024);
;         u32x2* op = (u32x2*)(og + (long)m * 1024 + n4);
;         const u32x2 ov = *op;
;         *op = pack4(bflo(ov.x) * silu(v[0] * rs), bfhi(ov.x) * silu(v[1] * rs), bflo(ov.y) * silu(v[2] * rs), bfhi(ov.y) * silu(v[3] * rs));
;       EPI_END
	v_lshlrev_b32_e32 v62, 16, v73
	v_pk_mul_f32 v[58:59], v[58:59], v[68:69]
	v_pk_mul_f32 v[56:57], v[56:57], v[60:61]
	v_pk_mul_f32 v[58:59], v[58:59], v[70:71]
	v_cvt_pk_bf16_f32 v56, v56, v57
	v_cvt_pk_bf16_f32 v57, v58, v59
	global_store_dwordx2 v[64:65], v[56:57], off offset:32
	v_and_b32_e32 v63, 0xffff0000, v73
	s_nop 1
	v_lshlrev_b32_e32 v56, 16, v72
	v_and_b32_e32 v57, 0xffff0000, v72
	v_pk_mul_f32 v[52:53], v[52:53], v[164:165] op_sel_hi:[1,0]
	v_pk_mul_f32 v[54:55], v[54:55], v[164:165] op_sel_hi:[1,0]
	v_mul_f32_e32 v58, 0xbfb8aa3b, v52
	v_mul_f32_e32 v59, 0xbfb8aa3b, v53
	v_mul_f32_e32 v60, 0xbfb8aa3b, v54
	v_mul_f32_e32 v61, 0xbfb8aa3b, v55
	v_exp_f32_e32 v58, v58
	v_exp_f32_e32 v59, v59
	v_exp_f32_e32 v60, v60
	v_exp_f32_e32 v61, v61
	v_add_f32_e32 v58, 1.0, v58
	v_add_f32_e32 v59, 1.0, v59
	v_add_f32_e32 v60, 1.0, v60
	v_add_f32_e32 v61, 1.0, v61
	v_rcp_f32_e32 v58, v58
	v_rcp_f32_e32 v59, v59
	v_rcp_f32_e32 v60, v60
	v_rcp_f32_e32 v61, v61
	v_pk_mul_f32 v[52:53], v[52:53], v[58:59]
	s_nop 0
	v_pk_mul_f32 v[52:53], v[52:53], v[56:57]
	v_pk_mul_f32 v[54:55], v[54:55], v[60:61]
	v_cvt_pk_bf16_f32 v52, v52, v53
	v_pk_mul_f32 v[54:55], v[54:55], v[62:63]
	s_waitcnt vmcnt(2)
	v_lshlrev_b32_e32 v56, 16, v74
	v_cvt_pk_bf16_f32 v53, v54, v55
	global_store_dwordx2 v[64:65], v[52:53], off offset:64
	v_and_b32_e32 v57, 0xffff0000, v74
	v_lshlrev_b32_e32 v62, 16, v75
	v_and_b32_e32 v63, 0xffff0000, v75
	v_or_b32_e32 v54, 0x50, v132
	v_ashrrev_i32_e32 v55, 31, v54
	s_nop 1
	v_lshl_add_u64 v[52:53], v[54:55], 2, s[12:13]
	v_pk_mul_f32 v[48:49], v[48:49], v[164:165] op_sel_hi:[1,0]
	v_pk_mul_f32 v[50:51], v[50:51], v[164:165] op_sel_hi:[1,0]
	v_mul_f32_e32 v58, 0xbfb8aa3b, v48
	v_mul_f32_e32 v59, 0xbfb8aa3b, v49
	v_mul_f32_e32 v60, 0xbfb8aa3b, v50
	v_mul_f32_e32 v61, 0xbfb8aa3b, v51
	v_exp_f32_e32 v58, v58
	v_exp_f32_e32 v59, v59
	v_exp_f32_e32 v60, v60
	v_exp_f32_e32 v61, v61
	v_add_f32_e32 v58, 1.0, v58
	v_add_f32_e32 v59, 1.0, v59
	v_add_f32_e32 v60, 1.0, v60
	v_add_f32_e32 v61, 1.0, v61
	v_rcp_f32_e32 v58, v58
	v_rcp_f32_e32 v59, v59
	v_rcp_f32_e32 v60, v60
	v_rcp_f32_e32 v61, v61
	v_pk_mul_f32 v[48:49], v[48:49], v[58:59]
	s_nop 0
	v_pk_mul_f32 v[48:49], v[48:49], v[56:57]
	global_load_dword v56, v[52:53], off
	v_pk_mul_f32 v[50:51], v[50:51], v[60:61]
	v_cvt_pk_bf16_f32 v48, v48, v49
	v_pk_mul_f32 v[50:51], v[50:51], v[62:63]
	s_nop 0
	v_cvt_pk_bf16_f32 v49, v50, v51
	global_store_dwordx2 v[64:65], v[48:49], off offset:96
	s_nop 0
	v_lshlrev_b64 v[48:49], 11, v[54:55]
	v_lshl_add_u64 v[48:49], s[36:37], 0, v[48:49]
	v_lshl_add_u64 v[48:49], v[48:49], 0, v[130:131]
	global_load_dwordx2 v[50:51], v[48:49], off
	global_load_dwordx2 v[184:185], v[48:49], off offset:32
	global_load_dwordx2 v[186:187], v[48:49], off offset:64
	global_load_dwordx2 v[58:59], v[48:49], off offset:96
	s_waitcnt vmcnt(5)
	v_fmamk_f32 v54, v56, 0x3a800000, v148
	v_mul_f32_e32 v55, 0x4b800000, v54
	v_cmp_gt_f32_e32 vcc, s26, v54
	s_waitcnt vmcnt(3)
	v_lshlrev_b32_e32 v60, 16, v50
	v_cndmask_b32_e32 v54, v54, v55, vcc
	v_rsq_f32_e32 v62, v54
	v_and_b32_e32 v61, 0xffff0000, v50
	s_nop 0
	s_nop 0
	s_nop 0
	v_mul_f32_e32 v50, 0x45800000, v62
	v_cndmask_b32_e32 v50, v62, v50, vcc
	v_mov_b32_e32 v166, v50
	v_pk_mul_f32 v[44:45], v[44:45], v[50:51] op_sel_hi:[1,0]
	v_pk_mul_f32 v[46:47], v[46:47], v[166:167] op_sel_hi:[1,0]
	v_mul_f32_e32 v50, 0xbfb8aa3b, v44
	v_mul_f32_e32 v62, 0xbfb8aa3b, v45
	v_mul_f32_e32 v63, 0xbfb8aa3b, v46
	v_mul_f32_e32 v64, 0xbfb8aa3b, v47
	v_exp_f32_e32 v50, v50
	v_exp_f32_e32 v62, v62
	v_exp_f32_e32 v63, v63
	v_exp_f32_e32 v64, v64
	v_add_f32_e32 v50, 1.0, v50
	v_add_f32_e32 v65, 1.0, v62
	v_add_f32_e32 v66, 1.0, v63
	v_add_f32_e32 v67, 1.0, v64
	v_rcp_f32_e32 v62, v50
	v_rcp_f32_e32 v63, v65
	v_rcp_f32_e32 v64, v66
	v_rcp_f32_e32 v65, v67
	v_lshlrev_b32_e32 v50, 16, v51
	v_and_b32_e32 v51, 0xffff0000, v51
	v_pk_mul_f32 v[44:45], v[44:45], v[62:63]
	v_pk_mul_f32 v[46:47], v[46:47], v[64:65]
	v_pk_mul_f32 v[44:45], v[44:45], v[60:61]
	v_pk_mul_f32 v[46:47], v[46:47], v[50:51]
	v_cvt_pk_bf16_f32 v44, v44, v45
	v_cvt_pk_bf16_f32 v45, v46, v47
	global_store_dwordx2 v[48:49], v[44:45], off
	s_nop 1
	s_waitcnt vmcnt(3)
	v_lshlrev_b32_e32 v44, 16, v184
	v_and_b32_e32 v45, 0xffff0000, v184
	v_lshlrev_b32_e32 v54, 16, v185
	v_pk_mul_f32 v[40:41], v[40:41], v[166:167] op_sel_hi:[1,0]
	v_pk_mul_f32 v[42:43], v[42:43], v[166:167] op_sel_hi:[1,0]
	v_mul_f32_e32 v46, 0xbfb8aa3b, v40
	v_mul_f32_e32 v47, 0xbfb8aa3b, v41
	v_mul_f32_e32 v50, 0xbfb8aa3b, v42
	v_mul_f32_e32 v51, 0xbfb8aa3b, v43
	v_exp_f32_e32 v46, v46
	v_exp_f32_e32 v47, v47
	v_exp_f32_e32 v50, v50
	v_exp_f32_e32 v51, v51
	v_add_f32_e32 v46, 1.0, v46
	v_add_f32_e32 v47, 1.0, v47
	v_add_f32_e32 v50, 1.0, v50
	v_add_f32_e32 v51, 1.0, v51
	v_rcp_f32_e32 v46, v46
	v_rcp_f32_e32 v47, v47
	v_rcp_f32_e32 v50, v50
	v_rcp_f32_e32 v51, v51
	v_and_b32_e32 v55, 0xffff0000, v185
	v_pk_mul_f32 v[40:41], v[40:41], v[46:47]
	s_waitcnt vmcnt(2)
	v_lshlrev_b32_e32 v46, 16, v187
	v_pk_mul_f32 v[42:43], v[42:43], v[50:51]
	v_pk_mul_f32 v[40:41], v[40:41], v[44:45]
	v_pk_mul_f32 v[42:43], v[42:43], v[54:55]
	v_cvt_pk_bf16_f32 v40, v40, v41
	v_cvt_pk_bf16_f32 v41, v42, v43
	global_store_dwordx2 v[48:49], v[40:41], off offset:32
	v_and_b32_e32 v47, 0xffff0000, v187
	s_nop 1
	v_lshlrev_b32_e32 v40, 16, v186
	v_and_b32_e32 v41, 0xffff0000, v186
	v_pk_mul_f32 v[36:37], v[36:37], v[166:167] op_sel_hi:[1,0]
	v_pk_mul_f32 v[38:39], v[38:39], v[166:167] op_sel_hi:[1,0]
	v_mul_f32_e32 v42, 0xbfb8aa3b, v36
	v_mul_f32_e32 v43, 0xbfb8aa3b, v37
	v_mul_f32_e32 v44, 0xbfb8aa3b, v38
	v_mul_f32_e32 v45, 0xbfb8aa3b, v39
	v_exp_f32_e32 v42, v42
	v_exp_f32_e32 v43, v43
	v_exp_f32_e32 v44, v44
	v_exp_f32_e32 v45, v45
	v_add_f32_e32 v42, 1.0, v42
	v_add_f32_e32 v43, 1.0, v43
	v_add_f32_e32 v44, 1.0, v44
	v_add_f32_e32 v45, 1.0, v45
	v_rcp_f32_e32 v42, v42
	v_rcp_f32_e32 v43, v43
	v_rcp_f32_e32 v44, v44
	v_rcp_f32_e32 v45, v45
	v_pk_mul_f32 v[36:37], v[36:37], v[42:43]
	s_nop 0
	v_pk_mul_f32 v[36:37], v[36:37], v[40:41]
	v_pk_mul_f32 v[38:39], v[38:39], v[44:45]
	v_cvt_pk_bf16_f32 v36, v36, v37
	v_pk_mul_f32 v[38:39], v[38:39], v[46:47]
	s_waitcnt vmcnt(2)
; DI float bflo(unsigned u) { return __uint_as_float(u << 16); }
; DI float bfhi(unsigned u) { return __uint_as_float(u & 0xffff0000u); }
; DI float silu(float v) { return v * __builtin_amdgcn_rcpf(1.f + __expf(-v)); }
; DI u32x2 pack4(float a, float b, float c, float d) { u32x2 r; r.x = pack2(a, b); r.y = pack2(c, d); return r; }
; #define EPI_END if (i == 3 && (j & 3) == 3) __builtin_amdgcn_sched_barrier(0); }
; DI float rstd_of(const float* ssq, int m, float invn) { return rsqrtf(ssq[m] * invn + 1e-6f); }
; template <int MODE>
; DI void gemm_phase(const Params& p, const GP& g, unsigned char* smem) {
;     ...
;       EPI_STD_BEGIN
;         const float rs = rstd_of(g.ssq_in, m, 1.f / 1024);
;         u32x2* op = (u32x2*)(og + (long)m * 1024 + n4);
;         const u32x2 ov = *op;
;         *op = pack4(bflo(ov.x) * silu(v[0] * rs), bfhi(ov.x) * silu(v[1] * rs), bflo(ov.y) * silu(v[2] * rs), bfhi(ov.y) * silu(v[3] * rs));
;       EPI_END
	v_lshlrev_b32_e32 v40, 16, v58
	v_cvt_pk_bf16_f32 v37, v38, v39
	global_store_dwordx2 v[48:49], v[36:37], off offset:64
	v_and_b32_e32 v41, 0xffff0000, v58
	v_lshlrev_b32_e32 v46, 16, v59
	v_and_b32_e32 v47, 0xffff0000, v59
	v_or_b32_e32 v38, 0x60, v132
	v_ashrrev_i32_e32 v39, 31, v38
	s_nop 1
	v_lshl_add_u64 v[36:37], v[38:39], 2, s[12:13]
	v_pk_mul_f32 v[32:33], v[32:33], v[166:167] op_sel_hi:[1,0]
	v_pk_mul_f32 v[34:35], v[34:35], v[166:167] op_sel_hi:[1,0]
	v_mul_f32_e32 v42, 0xbfb8aa3b, v32
	v_mul_f32_e32 v43, 0xbfb8aa3b, v33
	v_mul_f32_e32 v44, 0xbfb8aa3b, v34
	v_mul_f32_e32 v45, 0xbfb8aa3b, v35
	v_exp_f32_e32 v42, v42
	v_exp_f32_e32 v43, v43
	v_exp_f32_e32 v44, v44
	v_exp_f32_e32 v45, v45
	v_add_f32_e32 v42, 1.0, v42
	v_add_f32_e32 v43, 1.0, v43
	v_add_f32_e32 v44, 1.0, v44
	v_add_f32_e32 v45, 1.0, v45
	v_rcp_f32_e32 v42, v42
	v_rcp_f32_e32 v43, v43
	v_rcp_f32_e32 v44, v44
	v_rcp_f32_e32 v45, v45
	v_pk_mul_f32 v[32:33], v[32:33], v[42:43]
	s_nop 0
	v_pk_mul_f32 v[32:33], v[32:33], v[40:41]
	global_load_dword v40, v[36:37], off
	v_pk_mul_f32 v[34:35], v[34:35], v[44:45]
	v_cvt_pk_bf16_f32 v32, v32, v33
	v_pk_mul_f32 v[34:35], v[34:35], v[46:47]
	s_nop 0
	v_cvt_pk_bf16_f32 v33, v34, v35
	global_store_dwordx2 v[48:49], v[32:33], off offset:96
	s_nop 0
	v_lshlrev_b64 v[32:33], 11, v[38:39]
	v_lshl_add_u64 v[32:33], s[36:37], 0, v[32:33]
	v_lshl_add_u64 v[32:33], v[32:33], 0, v[130:131]
	global_load_dwordx2 v[34:35], v[32:33], off
	global_load_dwordx2 v[184:185], v[32:33], off offset:32
	global_load_dwordx2 v[186:187], v[32:33], off offset:64
	global_load_dwordx2 v[42:43], v[32:33], off offset:96
	s_waitcnt vmcnt(5)
	v_fmamk_f32 v38, v40, 0x3a800000, v148
	v_mul_f32_e32 v39, 0x4b800000, v38
	v_cmp_gt_f32_e32 vcc, s26, v38
	s_waitcnt vmcnt(3)
	v_lshlrev_b32_e32 v44, 16, v34
	v_cndmask_b32_e32 v38, v38, v39, vcc
	v_rsq_f32_e32 v46, v38
	v_and_b32_e32 v45, 0xffff0000, v34
	s_nop 0
	s_nop 0
	s_nop 0
	v_mul_f32_e32 v34, 0x45800000, v46
	v_cndmask_b32_e32 v34, v46, v34, vcc
	v_mov_b32_e32 v168, v34
	v_pk_mul_f32 v[28:29], v[28:29], v[34:35] op_sel_hi:[1,0]
	v_pk_mul_f32 v[30:31], v[30:31], v[168:169] op_sel_hi:[1,0]
	v_mul_f32_e32 v34, 0xbfb8aa3b, v28
	v_mul_f32_e32 v46, 0xbfb8aa3b, v29
	v_mul_f32_e32 v47, 0xbfb8aa3b, v30
	v_mul_f32_e32 v48, 0xbfb8aa3b, v31
	v_exp_f32_e32 v34, v34
	v_exp_f32_e32 v46, v46
	v_exp_f32_e32 v47, v47
	v_exp_f32_e32 v48, v48
	v_add_f32_e32 v34, 1.0, v34
	v_add_f32_e32 v49, 1.0, v46
	v_add_f32_e32 v50, 1.0, v47
	v_add_f32_e32 v51, 1.0, v48
	v_rcp_f32_e32 v46, v34
	v_rcp_f32_e32 v47, v49
	v_rcp_f32_e32 v48, v50
	v_rcp_f32_e32 v49, v51
	v_lshlrev_b32_e32 v34, 16, v35
	v_and_b32_e32 v35, 0xffff0000, v35
	v_pk_mul_f32 v[28:29], v[28:29], v[46:47]
	v_pk_mul_f32 v[30:31], v[30:31], v[48:49]
	v_pk_mul_f32 v[28:29], v[28:29], v[44:45]
	v_pk_mul_f32 v[30:31], v[30:31], v[34:35]
	v_cvt_pk_bf16_f32 v28, v28, v29
	v_cvt_pk_bf16_f32 v29, v30, v31
	global_store_dwordx2 v[32:33], v[28:29], off
	s_nop 1
	s_waitcnt vmcnt(3)
	v_lshlrev_b32_e32 v28, 16, v184
	v_and_b32_e32 v29, 0xffff0000, v184
	v_lshlrev_b32_e32 v38, 16, v185
	v_pk_mul_f32 v[24:25], v[24:25], v[168:169] op_sel_hi:[1,0]
	v_pk_mul_f32 v[26:27], v[26:27], v[168:169] op_sel_hi:[1,0]
	v_mul_f32_e32 v30, 0xbfb8aa3b, v24
	v_mul_f32_e32 v31, 0xbfb8aa3b, v25
	v_mul_f32_e32 v34, 0xbfb8aa3b, v26
	v_mul_f32_e32 v35, 0xbfb8aa3b, v27
	v_exp_f32_e32 v30, v30
	v_exp_f32_e32 v31, v31
	v_exp_f32_e32 v34, v34
	v_exp_f32_e32 v35, v35
	v_add_f32_e32 v30, 1.0, v30
	v_add_f32_e32 v31, 1.0, v31
	v_add_f32_e32 v34, 1.0, v34
	v_add_f32_e32 v35, 1.0, v35
	v_rcp_f32_e32 v30, v30
	v_rcp_f32_e32 v31, v31
	v_rcp_f32_e32 v34, v34
	v_rcp_f32_e32 v35, v35
	v_and_b32_e32 v39, 0xffff0000, v185
	v_pk_mul_f32 v[24:25], v[24:25], v[30:31]
	s_waitcnt vmcnt(2)
	v_lshlrev_b32_e32 v30, 16, v187
	v_pk_mul_f32 v[26:27], v[26:27], v[34:35]
	v_pk_mul_f32 v[24:25], v[24:25], v[28:29]
	v_pk_mul_f32 v[26:27], v[26:27], v[38:39]
	v_cvt_pk_bf16_f32 v24, v24, v25
	v_cvt_pk_bf16_f32 v25, v26, v27
	global_store_dwordx2 v[32:33], v[24:25], off offset:32
	v_and_b32_e32 v31, 0xffff0000, v187
	s_nop 1
	v_lshlrev_b32_e32 v24, 16, v186
	v_and_b32_e32 v25, 0xffff0000, v186
	v_pk_mul_f32 v[20:21], v[20:21], v[168:169] op_sel_hi:[1,0]
	v_pk_mul_f32 v[22:23], v[22:23], v[168:169] op_sel_hi:[1,0]
	v_mul_f32_e32 v26, 0xbfb8aa3b, v20
	v_mul_f32_e32 v27, 0xbfb8aa3b, v21
	v_mul_f32_e32 v28, 0xbfb8aa3b, v22
	v_mul_f32_e32 v29, 0xbfb8aa3b, v23
	v_exp_f32_e32 v26, v26
	v_exp_f32_e32 v27, v27
	v_exp_f32_e32 v28, v28
	v_exp_f32_e32 v29, v29
	v_add_f32_e32 v26, 1.0, v26
	v_add_f32_e32 v27, 1.0, v27
	v_add_f32_e32 v28, 1.0, v28
	v_add_f32_e32 v29, 1.0, v29
	v_rcp_f32_e32 v26, v26
	v_rcp_f32_e32 v27, v27
	v_rcp_f32_e32 v28, v28
	v_rcp_f32_e32 v29, v29
	v_pk_mul_f32 v[20:21], v[20:21], v[26:27]
	s_nop 0
	v_pk_mul_f32 v[20:21], v[20:21], v[24:25]
	v_pk_mul_f32 v[22:23], v[22:23], v[28:29]
	v_cvt_pk_bf16_f32 v20, v20, v21
	v_pk_mul_f32 v[22:23], v[22:23], v[30:31]
	s_waitcnt vmcnt(2)
; DI float bflo(unsigned u) { return __uint_as_float(u << 16); }
; DI float bfhi(unsigned u) { return __uint_as_float(u & 0xffff0000u); }
; DI float silu(float v) { return v * __builtin_amdgcn_rcpf(1.f + __expf(-v)); }
; DI u32x2 pack4(float a, float b, float c, float d) { u32x2 r; r.x = pack2(a, b); r.y = pack2(c, d); return r; }
; #define EPI_END if (i == 3 && (j & 3) == 3) __builtin_amdgcn_sched_barrier(0); }
; DI float rstd_of(const float* ssq, int m, float invn) { return rsqrtf(ssq[m] * invn + 1e-6f); }
; template <int MODE>
; DI void gemm_phase(const Params& p, const GP& g, unsigned char* smem) {
;     ...
;       EPI_STD_BEGIN
;         const float rs = rstd_of(g.ssq_in, m, 1.f / 1024);
;         u32x2* op = (u32x2*)(og + (long)m * 1024 + n4);
;         const u32x2 ov = *op;
;         *op = pack4(bflo(ov.x) * silu(v[0] * rs), bfhi(ov.x) * silu(v[1] * rs), bflo(ov.y) * silu(v[2] * rs), bfhi(ov.y) * silu(v[3] * rs));
;       EPI_END
	v_lshlrev_b32_e32 v24, 16, v42
	v_cvt_pk_bf16_f32 v21, v22, v23
	global_store_dwordx2 v[32:33], v[20:21], off offset:64
	v_and_b32_e32 v25, 0xffff0000, v42
	v_lshlrev_b32_e32 v30, 16, v43
	v_and_b32_e32 v31, 0xffff0000, v43
	v_or_b32_e32 v22, 0x70, v132
	v_ashrrev_i32_e32 v23, 31, v22
	s_nop 1
	v_lshl_add_u64 v[20:21], v[22:23], 2, s[12:13]
	v_pk_mul_f32 v[16:17], v[16:17], v[168:169] op_sel_hi:[1,0]
	v_pk_mul_f32 v[18:19], v[18:19], v[168:169] op_sel_hi:[1,0]
	v_mul_f32_e32 v26, 0xbfb8aa3b, v16
	v_mul_f32_e32 v27, 0xbfb8aa3b, v17
	v_mul_f32_e32 v28, 0xbfb8aa3b, v18
	v_mul_f32_e32 v29, 0xbfb8aa3b, v19
	v_exp_f32_e32 v26, v26
	v_exp_f32_e32 v27, v27
	v_exp_f32_e32 v28, v28
	v_exp_f32_e32 v29, v29
	v_add_f32_e32 v26, 1.0, v26
	v_add_f32_e32 v27, 1.0, v27
	v_add_f32_e32 v28, 1.0, v28
	v_add_f32_e32 v29, 1.0, v29
	v_rcp_f32_e32 v26, v26
	v_rcp_f32_e32 v27, v27
	v_rcp_f32_e32 v28, v28
	v_rcp_f32_e32 v29, v29
	v_pk_mul_f32 v[16:17], v[16:17], v[26:27]
	s_nop 0
	v_pk_mul_f32 v[16:17], v[16:17], v[24:25]
	global_load_dword v24, v[20:21], off
	v_pk_mul_f32 v[18:19], v[18:19], v[28:29]
	v_cvt_pk_bf16_f32 v16, v16, v17
	v_pk_mul_f32 v[18:19], v[18:19], v[30:31]
	s_nop 0
	v_cvt_pk_bf16_f32 v17, v18, v19
	global_store_dwordx2 v[32:33], v[16:17], off offset:96
	s_nop 0
	v_lshlrev_b64 v[16:17], 11, v[22:23]
	v_lshl_add_u64 v[16:17], s[36:37], 0, v[16:17]
	v_lshl_add_u64 v[16:17], v[16:17], 0, v[130:131]
	global_load_dwordx2 v[18:19], v[16:17], off
	global_load_dwordx2 v[184:185], v[16:17], off offset:32
	global_load_dwordx2 v[186:187], v[16:17], off offset:64
	global_load_dwordx2 v[26:27], v[16:17], off offset:96
	global_load_dword v188, v[20:21], off
	s_waitcnt vmcnt(6)
	v_fmamk_f32 v22, v24, 0x3a800000, v148
	v_mul_f32_e32 v23, 0x4b800000, v22
	v_cmp_gt_f32_e32 vcc, s26, v22
	s_waitcnt vmcnt(4)
	v_lshlrev_b32_e32 v28, 16, v18
	v_cndmask_b32_e32 v22, v22, v23, vcc
	v_rsq_f32_e32 v30, v22
	v_and_b32_e32 v29, 0xffff0000, v18
	s_nop 0
	s_nop 0
	s_nop 0
	v_mul_f32_e32 v18, 0x45800000, v30
	v_cndmask_b32_e32 v18, v30, v18, vcc
	v_mov_b32_e32 v170, v18
	v_pk_mul_f32 v[12:13], v[12:13], v[18:19] op_sel_hi:[1,0]
	v_pk_mul_f32 v[14:15], v[14:15], v[170:171] op_sel_hi:[1,0]
	v_mul_f32_e32 v18, 0xbfb8aa3b, v12
	v_mul_f32_e32 v30, 0xbfb8aa3b, v13
	v_mul_f32_e32 v31, 0xbfb8aa3b, v14
	v_mul_f32_e32 v32, 0xbfb8aa3b, v15
	v_exp_f32_e32 v18, v18
	v_exp_f32_e32 v30, v30
	v_exp_f32_e32 v31, v31
	v_exp_f32_e32 v32, v32
	v_add_f32_e32 v18, 1.0, v18
	v_add_f32_e32 v33, 1.0, v30
	v_add_f32_e32 v34, 1.0, v31
	v_add_f32_e32 v35, 1.0, v32
	v_rcp_f32_e32 v30, v18
	v_rcp_f32_e32 v31, v33
	v_rcp_f32_e32 v32, v34
	v_rcp_f32_e32 v33, v35
	v_lshlrev_b32_e32 v18, 16, v19
	v_and_b32_e32 v19, 0xffff0000, v19
	v_pk_mul_f32 v[12:13], v[12:13], v[30:31]
	v_pk_mul_f32 v[14:15], v[14:15], v[32:33]
	v_pk_mul_f32 v[12:13], v[12:13], v[28:29]
	v_pk_mul_f32 v[14:15], v[14:15], v[18:19]
	v_cvt_pk_bf16_f32 v12, v12, v13
	v_cvt_pk_bf16_f32 v13, v14, v15
	global_store_dwordx2 v[16:17], v[12:13], off
	s_nop 1
	s_waitcnt vmcnt(4)
	v_lshlrev_b32_e32 v12, 16, v184
	v_and_b32_e32 v13, 0xffff0000, v184
	v_lshlrev_b32_e32 v22, 16, v185
	v_pk_mul_f32 v[8:9], v[8:9], v[170:171] op_sel_hi:[1,0]
	v_pk_mul_f32 v[10:11], v[10:11], v[170:171] op_sel_hi:[1,0]
	v_mul_f32_e32 v14, 0xbfb8aa3b, v8
	v_mul_f32_e32 v15, 0xbfb8aa3b, v9
	v_mul_f32_e32 v18, 0xbfb8aa3b, v10
	v_mul_f32_e32 v19, 0xbfb8aa3b, v11
	v_exp_f32_e32 v14, v14
	v_exp_f32_e32 v15, v15
	v_exp_f32_e32 v18, v18
	v_exp_f32_e32 v19, v19
	v_add_f32_e32 v14, 1.0, v14
	v_add_f32_e32 v15, 1.0, v15
	v_add_f32_e32 v18, 1.0, v18
	v_add_f32_e32 v19, 1.0, v19
	v_rcp_f32_e32 v14, v14
	v_rcp_f32_e32 v15, v15
	v_rcp_f32_e32 v18, v18
	v_rcp_f32_e32 v19, v19
	v_and_b32_e32 v23, 0xffff0000, v185
	v_pk_mul_f32 v[8:9], v[8:9], v[14:15]
	s_waitcnt vmcnt(3)
	v_lshlrev_b32_e32 v14, 16, v187
	v_pk_mul_f32 v[10:11], v[10:11], v[18:19]
	v_pk_mul_f32 v[8:9], v[8:9], v[12:13]
	v_pk_mul_f32 v[10:11], v[10:11], v[22:23]
	v_cvt_pk_bf16_f32 v8, v8, v9
	v_cvt_pk_bf16_f32 v9, v10, v11
	global_store_dwordx2 v[16:17], v[8:9], off offset:32
	v_and_b32_e32 v15, 0xffff0000, v187
	s_nop 1
	v_lshlrev_b32_e32 v8, 16, v186
	v_and_b32_e32 v9, 0xffff0000, v186
	v_pk_mul_f32 v[0:1], v[0:1], v[170:171] op_sel_hi:[1,0]
	v_pk_mul_f32 v[2:3], v[2:3], v[170:171] op_sel_hi:[1,0]
	v_mul_f32_e32 v10, 0xbfb8aa3b, v0
	v_mul_f32_e32 v11, 0xbfb8aa3b, v1
	v_mul_f32_e32 v12, 0xbfb8aa3b, v2
	v_mul_f32_e32 v13, 0xbfb8aa3b, v3
	v_exp_f32_e32 v10, v10
	v_exp_f32_e32 v11, v11
	v_exp_f32_e32 v12, v12
	v_exp_f32_e32 v13, v13
	v_add_f32_e32 v10, 1.0, v10
	v_add_f32_e32 v11, 1.0, v11
	v_add_f32_e32 v12, 1.0, v12
	v_add_f32_e32 v13, 1.0, v13
	v_rcp_f32_e32 v10, v10
	v_rcp_f32_e32 v11, v11
	v_rcp_f32_e32 v12, v12
	v_rcp_f32_e32 v13, v13
	v_pk_mul_f32 v[0:1], v[0:1], v[10:11]
	s_nop 0
	v_pk_mul_f32 v[0:1], v[0:1], v[8:9]
	v_pk_mul_f32 v[2:3], v[2:3], v[12:13]
	v_cvt_pk_bf16_f32 v0, v0, v1
	v_pk_mul_f32 v[2:3], v[2:3], v[14:15]
	s_waitcnt vmcnt(3)
	v_lshlrev_b32_e32 v10, 16, v27
	v_cvt_pk_bf16_f32 v1, v2, v3
	global_store_dwordx2 v[16:17], v[0:1], off offset:64
	s_nop 0
	v_and_b32_e32 v11, 0xffff0000, v27
	s_waitcnt vmcnt(3)
	v_fmamk_f32 v0, v188, 0x3a800000, v148
	v_cmp_gt_f32_e32 vcc, s26, v0
	s_nop 1
	v_lshlrev_b32_e32 v0, 16, v26
	v_and_b32_e32 v1, 0xffff0000, v26
	v_pk_mul_f32 v[4:5], v[4:5], v[170:171] op_sel_hi:[1,0]
	v_pk_mul_f32 v[2:3], v[6:7], v[170:171] op_sel_hi:[1,0]
	v_mul_f32_e32 v6, 0xbfb8aa3b, v4
	v_mul_f32_e32 v7, 0xbfb8aa3b, v5
	v_mul_f32_e32 v8, 0xbfb8aa3b, v2
	v_mul_f32_e32 v9, 0xbfb8aa3b, v3
	v_exp_f32_e32 v6, v6
	v_exp_f32_e32 v7, v7
	v_exp_f32_e32 v8, v8
	v_exp_f32_e32 v9, v9
	v_add_f32_e32 v6, 1.0, v6
	v_add_f32_e32 v7, 1.0, v7
	v_add_f32_e32 v8, 1.0, v8
	v_add_f32_e32 v9, 1.0, v9
	v_rcp_f32_e32 v6, v6
	v_rcp_f32_e32 v7, v7
	v_rcp_f32_e32 v8, v8
	v_rcp_f32_e32 v9, v9
	v_pk_mul_f32 v[4:5], v[4:5], v[6:7]
	s_nop 0
	v_pk_mul_f32 v[0:1], v[4:5], v[0:1]
	v_pk_mul_f32 v[2:3], v[2:3], v[8:9]
	v_cvt_pk_bf16_f32 v0, v0, v1
	v_pk_mul_f32 v[2:3], v[2:3], v[10:11]
	s_nop 0
	v_cvt_pk_bf16_f32 v1, v2, v3
	global_store_dwordx2 v[16:17], v[0:1], off offset:96
	s_add_i32 s27, s27, s94
	s_cmpk_lt_u32 s27, 0xa0
	s_cbranch_scc0 .LBB0_643
